# prep phase hand-written: 8-row prefetch ring per pass, exact counted waits, zero padding via buffer range check, stores never waited
# speedup vs baseline: 1.0298x; 1.0014x over previous
; __device__ __forceinline__ void prep_phase(const Params& p) {
;     const int lane = threadIdx.x & 63, wid = threadIdx.x >> 6, c = lane * 16;
;     const u16* ZS = (const u16*)(p.ws + O_ZS);
;     float* R = (float*)(p.ws + O_R); float* A = (float*)(p.ws + O_A); u16* V = (u16*)(p.ws + O_V); u16* Kb = (u16*)(p.ws + O_K); u16* AL = (u16*)(p.ws + O_AL); float* BON = (float*)(p.ws + O_BON);
;     for (int t0 = (blockIdx.x * 8 + wid) * 16; t0 < NTOK; t0 += gridDim.x * 8 * 16) {
;         const int tt0 = t0 & (SEQ - 1);
;         {
;             float mpk[16], mnk[16], kkc[16]; ld16f(p.mu_prev + 1024 + c, mpk); ld16f(p.mu_next + 1024 + c, mnk); ld16f(p.k_k + c, kkc);
;             const u16* zc = ZS + (size_t)t0 * 3328 + 1024 + c;
;             Z16 kp = tt0 > 0 ? ldz(zc - 3328) : zz(), kc = ldz(zc);
; #pragma unroll 2
;             for (int i = 0; i < 16; ++i) {
;                 const bool hn = (tt0 + i) < SEQ - 1; const Z16 kn = hn ? ldz(zc + (size_t)(i + 1) * 3328) : zz();
.LBB0_204:
	s_cmp_lt_i32 s58, 3
	s_cselect_b64 s[0:1], -1, 0
	s_cmp_gt_i32 s59, 2
	s_cselect_b64 s[4:5], -1, 0
	s_and_b64 s[0:1], s[0:1], s[4:5]
	s_andn2_b64 vcc, exec, s[0:1]
	s_cbranch_vccnz .LBB0_336
	v_readfirstlane_b32 s0, v254
	s_nop 3
	s_lshr_b32 s1, s0, 6
	s_lshl_b32 s0, s2, 3
	s_add_u32 s0, s0, s1
	s_lshl_b32 s0, s0, 4
	s_mov_b32 s68, s56
	s_and_b32 s69, s57, 0xffff
	s_brev_b32 s70, -2
	s_mov_b32 s71, 0x27000
	v_and_b32_e32 v240, 63, v254
	v_mov_b32_e32 v241, 0x7fffffff
	v_lshlrev_b32_e32 v224, 6, v240
	v_lshlrev_b32_e32 v225, 5, v240
	v_add_u32_e32 v234, 0x24800000, v224
	v_add_u32_e32 v235, 0x1c800000, v224
	v_add_u32_e32 v236, 0x30800000, v225
	v_add_u32_e32 v237, 0x2c800000, v225
	v_bfe_u32 v226, v240, 4, 1
	v_lshlrev_b32_e32 v226, 8, v226
	v_lshrrev_b32_e32 v227, 5, v240
	v_lshlrev_b32_e32 v227, 7, v227
	v_and_b32_e32 v228, 15, v240
	v_lshlrev_b32_e32 v228, 3, v228
	v_add3_u32 v238, v226, v227, v228
	v_add_u32_e32 v238, 0x34800000, v238
	v_lshrrev_b32_e32 v226, 2, v240
	v_lshlrev_b32_e32 v226, 2, v226
	v_add_u32_e32 v226, 0x35800000, v226
	v_and_b32_e32 v227, 3, v240
	v_mov_b32_e32 v228, 0xfffffff0
	v_cmp_eq_u32_e32 vcc, 0, v227
	s_nop 1
	v_cndmask_b32_e32 v239, v228, v226, vcc
.Lmy_prep_item:
	s_cmpk_gt_i32 s0, 0x7fff
	s_cbranch_scc1 .Lmy_prep_end
	s_lshr_b32 s4, s0, 14
	s_mul_i32 s4, s4, 0x6800000
	s_add_u32 s4, s4, 0xb800000
	s_add_u32 s64, s56, s4
	s_addc_u32 s65, s57, 0
	s_and_b32 s65, s65, 0xffff
	s_mov_b32 s66, 0x6800000
	s_mov_b32 s67, 0x27000
	s_and_b32 s5, s0, 0x3fff
	s_add_i32 s5, s5, -1
	s_mul_i32 s5, s5, 6656
	v_lshl_add_u32 v232, v240, 5, s5
	v_lshlrev_b32_e32 v224, 6, v240
	v_add_u32_e32 v226, 0x1000, v224
	global_load_dwordx4 v[96:99], v226, s[20:21] offset:0
	global_load_dwordx4 v[100:103], v226, s[20:21] offset:16
	global_load_dwordx4 v[104:107], v226, s[20:21] offset:32
	global_load_dwordx4 v[108:111], v226, s[20:21] offset:48
	global_load_dwordx4 v[112:115], v226, s[22:23] offset:0
	global_load_dwordx4 v[116:119], v226, s[22:23] offset:16
	global_load_dwordx4 v[120:123], v226, s[22:23] offset:32
	global_load_dwordx4 v[124:127], v226, s[22:23] offset:48
	global_load_dwordx4 v[128:131], v224, s[40:41] offset:0
	global_load_dwordx4 v[132:135], v224, s[40:41] offset:16
	global_load_dwordx4 v[136:139], v224, s[40:41] offset:32
	global_load_dwordx4 v[140:143], v224, s[40:41] offset:48
	buffer_load_dwordx4 v[0:3], v232, s[64:67], 0 offen offset:2048
	buffer_load_dwordx4 v[4:7], v232, s[64:67], 0 offen offset:2064
	v_add_u32_e32 v232, 6656, v232
	buffer_load_dwordx4 v[12:15], v232, s[64:67], 0 offen offset:2048
	buffer_load_dwordx4 v[16:19], v232, s[64:67], 0 offen offset:2064
	v_add_u32_e32 v232, 6656, v232
	buffer_load_dwordx4 v[24:27], v232, s[64:67], 0 offen offset:2048
	buffer_load_dwordx4 v[28:31], v232, s[64:67], 0 offen offset:2064
	v_add_u32_e32 v232, 6656, v232
	buffer_load_dwordx4 v[36:39], v232, s[64:67], 0 offen offset:2048
	buffer_load_dwordx4 v[40:43], v232, s[64:67], 0 offen offset:2064
	v_add_u32_e32 v232, 6656, v232
	buffer_load_dwordx4 v[48:51], v232, s[64:67], 0 offen offset:2048
	buffer_load_dwordx4 v[52:55], v232, s[64:67], 0 offen offset:2064
	v_add_u32_e32 v232, 6656, v232
	buffer_load_dwordx4 v[60:63], v232, s[64:67], 0 offen offset:2048
	buffer_load_dwordx4 v[64:67], v232, s[64:67], 0 offen offset:2064
	v_add_u32_e32 v232, 6656, v232
	buffer_load_dwordx4 v[72:75], v232, s[64:67], 0 offen offset:2048
	buffer_load_dwordx4 v[76:79], v232, s[64:67], 0 offen offset:2064
	v_add_u32_e32 v232, 6656, v232
	buffer_load_dwordx4 v[84:87], v232, s[64:67], 0 offen offset:2048
	buffer_load_dwordx4 v[88:91], v232, s[64:67], 0 offen offset:2064
	v_add_u32_e32 v232, 6656, v232
	s_lshl_b32 s72, s0, 12
	s_lshl_b32 s73, s0, 11
	s_lshl_b32 s74, s0, 9
	s_lshl_b32 s75, s0, 6
	s_waitcnt vmcnt(10)
	v_lshlrev_b32_e32 v144, 16, v0
	v_and_b32_e32 v145, 0xffff0000, v0
	v_lshlrev_b32_e32 v146, 16, v1
	v_and_b32_e32 v147, 0xffff0000, v1
	v_lshlrev_b32_e32 v148, 16, v2
	v_and_b32_e32 v149, 0xffff0000, v2
	v_lshlrev_b32_e32 v150, 16, v3
	v_and_b32_e32 v151, 0xffff0000, v3
	v_lshlrev_b32_e32 v152, 16, v4
	v_and_b32_e32 v153, 0xffff0000, v4
	v_lshlrev_b32_e32 v154, 16, v5
	v_and_b32_e32 v155, 0xffff0000, v5
	v_lshlrev_b32_e32 v156, 16, v6
	v_and_b32_e32 v157, 0xffff0000, v6
	v_lshlrev_b32_e32 v158, 16, v7
	v_and_b32_e32 v159, 0xffff0000, v7
	v_lshlrev_b32_e32 v160, 16, v12
	v_and_b32_e32 v161, 0xffff0000, v12
	v_lshlrev_b32_e32 v162, 16, v13
	v_and_b32_e32 v163, 0xffff0000, v13
	v_lshlrev_b32_e32 v164, 16, v14
	v_and_b32_e32 v165, 0xffff0000, v14
	v_lshlrev_b32_e32 v166, 16, v15
	v_and_b32_e32 v167, 0xffff0000, v15
	v_lshlrev_b32_e32 v168, 16, v16
	v_and_b32_e32 v169, 0xffff0000, v16
	v_lshlrev_b32_e32 v170, 16, v17
	v_and_b32_e32 v171, 0xffff0000, v17
	v_lshlrev_b32_e32 v172, 16, v18
	v_and_b32_e32 v173, 0xffff0000, v18
	v_lshlrev_b32_e32 v174, 16, v19
	v_and_b32_e32 v175, 0xffff0000, v19
	v_lshlrev_b32_e32 v176, 16, v24
	v_and_b32_e32 v177, 0xffff0000, v24
	v_lshlrev_b32_e32 v178, 16, v25
	v_and_b32_e32 v179, 0xffff0000, v25
	v_lshlrev_b32_e32 v180, 16, v26
	v_and_b32_e32 v181, 0xffff0000, v26
	v_lshlrev_b32_e32 v182, 16, v27
	v_and_b32_e32 v183, 0xffff0000, v27
	v_lshlrev_b32_e32 v184, 16, v28
	v_and_b32_e32 v185, 0xffff0000, v28
	v_lshlrev_b32_e32 v186, 16, v29
	v_and_b32_e32 v187, 0xffff0000, v29
	v_lshlrev_b32_e32 v188, 16, v30
	v_and_b32_e32 v189, 0xffff0000, v30
	v_lshlrev_b32_e32 v190, 16, v31
	v_and_b32_e32 v191, 0xffff0000, v31
	buffer_load_dwordx4 v[0:3], v232, s[64:67], 0 offen offset:2048
	buffer_load_dwordx4 v[4:7], v232, s[64:67], 0 offen offset:2064
	v_add_u32_e32 v232, 6656, v232
; __device__ __forceinline__ void prep_phase(const Params& p) {
;     ...
;                 float k[16], kk[16]; mix16(kp, kc, kn, mpk, mnk, k);
;                 float s2 = 0.f;
; #pragma unroll
;                 for (int q = 0; q < 16; ++q) { kk[q] = k[q] * kkc[q]; s2 += kk[q] * kk[q]; }
;                 s2 += __shfl_xor(s2, 1); s2 += __shfl_xor(s2, 2);
;                 const float inv = -1.0f / fmaxf(sqrtf(s2), 1e-12f);
;                 const size_t o = (size_t)(t0 + i) * RW + c;
; #pragma unroll
;                 for (int j4 = 0; j4 < 4; ++j4) *(f32x4*)(A + o + j4 * 4) = (f32x4){kk[j4 * 4] * inv, kk[j4 * 4 + 1] * inv, kk[j4 * 4 + 2] * inv, kk[j4 * 4 + 3] * inv};
;                 st16bf(Kb + o, k);
;                 kp = kc; kc = kn;
;             }
	v_pk_add_f32 v[224:225], v[144:145], v[160:161] neg_lo:[0,1] neg_hi:[0,1]
	v_pk_add_f32 v[226:227], v[176:177], v[160:161] neg_lo:[0,1] neg_hi:[0,1]
	v_pk_fma_f32 v[192:193], v[96:97], v[224:225], v[160:161]
	v_pk_fma_f32 v[192:193], v[112:113], v[226:227], v[192:193]
	v_pk_add_f32 v[224:225], v[146:147], v[162:163] neg_lo:[0,1] neg_hi:[0,1]
	v_pk_add_f32 v[226:227], v[178:179], v[162:163] neg_lo:[0,1] neg_hi:[0,1]
	v_pk_fma_f32 v[194:195], v[98:99], v[224:225], v[162:163]
	v_pk_fma_f32 v[194:195], v[114:115], v[226:227], v[194:195]
	v_pk_add_f32 v[224:225], v[148:149], v[164:165] neg_lo:[0,1] neg_hi:[0,1]
	v_pk_add_f32 v[226:227], v[180:181], v[164:165] neg_lo:[0,1] neg_hi:[0,1]
	v_pk_fma_f32 v[196:197], v[100:101], v[224:225], v[164:165]
	v_pk_fma_f32 v[196:197], v[116:117], v[226:227], v[196:197]
	v_pk_add_f32 v[224:225], v[150:151], v[166:167] neg_lo:[0,1] neg_hi:[0,1]
	v_pk_add_f32 v[226:227], v[182:183], v[166:167] neg_lo:[0,1] neg_hi:[0,1]
	v_pk_fma_f32 v[198:199], v[102:103], v[224:225], v[166:167]
	v_pk_fma_f32 v[198:199], v[118:119], v[226:227], v[198:199]
	v_pk_add_f32 v[224:225], v[152:153], v[168:169] neg_lo:[0,1] neg_hi:[0,1]
	v_pk_add_f32 v[226:227], v[184:185], v[168:169] neg_lo:[0,1] neg_hi:[0,1]
	v_pk_fma_f32 v[200:201], v[104:105], v[224:225], v[168:169]
	v_pk_fma_f32 v[200:201], v[120:121], v[226:227], v[200:201]
	v_pk_add_f32 v[224:225], v[154:155], v[170:171] neg_lo:[0,1] neg_hi:[0,1]
	v_pk_add_f32 v[226:227], v[186:187], v[170:171] neg_lo:[0,1] neg_hi:[0,1]
	v_pk_fma_f32 v[202:203], v[106:107], v[224:225], v[170:171]
	v_pk_fma_f32 v[202:203], v[122:123], v[226:227], v[202:203]
	v_pk_add_f32 v[224:225], v[156:157], v[172:173] neg_lo:[0,1] neg_hi:[0,1]
	v_pk_add_f32 v[226:227], v[188:189], v[172:173] neg_lo:[0,1] neg_hi:[0,1]
	v_pk_fma_f32 v[204:205], v[108:109], v[224:225], v[172:173]
	v_pk_fma_f32 v[204:205], v[124:125], v[226:227], v[204:205]
	v_pk_add_f32 v[224:225], v[158:159], v[174:175] neg_lo:[0,1] neg_hi:[0,1]
	v_pk_add_f32 v[226:227], v[190:191], v[174:175] neg_lo:[0,1] neg_hi:[0,1]
	v_pk_fma_f32 v[206:207], v[110:111], v[224:225], v[174:175]
	v_pk_fma_f32 v[206:207], v[126:127], v[226:227], v[206:207]
	v_pk_mul_f32 v[208:209], v[192:193], v[128:129]
	v_pk_mul_f32 v[210:211], v[194:195], v[130:131]
	v_pk_mul_f32 v[212:213], v[196:197], v[132:133]
	v_pk_mul_f32 v[214:215], v[198:199], v[134:135]
	v_pk_mul_f32 v[216:217], v[200:201], v[136:137]
	v_pk_mul_f32 v[218:219], v[202:203], v[138:139]
	v_pk_mul_f32 v[220:221], v[204:205], v[140:141]
	v_pk_mul_f32 v[222:223], v[206:207], v[142:143]
	v_mul_f32_e32 v224, v208, v208
	v_fmac_f32_e32 v224, v209, v209
	v_fmac_f32_e32 v224, v210, v210
	v_fmac_f32_e32 v224, v211, v211
	v_fmac_f32_e32 v224, v212, v212
	v_fmac_f32_e32 v224, v213, v213
	v_fmac_f32_e32 v224, v214, v214
	v_fmac_f32_e32 v224, v215, v215
	v_fmac_f32_e32 v224, v216, v216
	v_fmac_f32_e32 v224, v217, v217
	v_fmac_f32_e32 v224, v218, v218
	v_fmac_f32_e32 v224, v219, v219
	v_fmac_f32_e32 v224, v220, v220
	v_fmac_f32_e32 v224, v221, v221
	v_fmac_f32_e32 v224, v222, v222
	v_fmac_f32_e32 v224, v223, v223
	s_nop 1
	v_add_f32_dpp v224, v224, v224 quad_perm:[1,0,3,2] row_mask:0xf bank_mask:0xf
	s_nop 1
	v_add_f32_dpp v224, v224, v224 quad_perm:[2,3,0,1] row_mask:0xf bank_mask:0xf
	v_sqrt_f32_e32 v224, v224
	s_nop 0
	v_max_f32_e32 v224, 0x2b8cbccc, v224
	v_rcp_f32_e32 v224, v224
	s_nop 0
	v_xor_b32_e32 v224, 0x80000000, v224
	v_mov_b32_e32 v225, v224
	v_cvt_pk_bf16_f32 v144, v192, v193
	v_cvt_pk_bf16_f32 v145, v194, v195
	v_cvt_pk_bf16_f32 v146, v196, v197
	v_cvt_pk_bf16_f32 v147, v198, v199
	v_cvt_pk_bf16_f32 v148, v200, v201
	v_cvt_pk_bf16_f32 v149, v202, v203
	v_cvt_pk_bf16_f32 v150, v204, v205
	v_cvt_pk_bf16_f32 v151, v206, v207
	v_pk_mul_f32 v[208:209], v[208:209], v[224:225]
	v_pk_mul_f32 v[210:211], v[210:211], v[224:225]
	v_pk_mul_f32 v[212:213], v[212:213], v[224:225]
	v_pk_mul_f32 v[214:215], v[214:215], v[224:225]
	v_pk_mul_f32 v[216:217], v[216:217], v[224:225]
	v_pk_mul_f32 v[218:219], v[218:219], v[224:225]
	v_pk_mul_f32 v[220:221], v[220:221], v[224:225]
	v_pk_mul_f32 v[222:223], v[222:223], v[224:225]
	buffer_store_dwordx4 v[208:211], v234, s[68:71], s72 offen offset:0
	buffer_store_dwordx4 v[212:215], v234, s[68:71], s72 offen offset:16
	buffer_store_dwordx4 v[216:219], v234, s[68:71], s72 offen offset:32
	buffer_store_dwordx4 v[220:223], v234, s[68:71], s72 offen offset:48
	buffer_store_dwordx4 v[144:147], v236, s[68:71], s73 offen offset:0
	buffer_store_dwordx4 v[148:151], v236, s[68:71], s73 offen offset:16
	s_add_u32 s72, s72, 0x1000
	s_add_u32 s73, s73, 0x800
	s_add_u32 s74, s74, 0x200
	s_add_u32 s75, s75, 0x40
	s_waitcnt vmcnt(16)
; __device__ __forceinline__ void prep_phase(const Params& p) {
;     ...
;             float mpk[16], mnk[16], kkc[16]; ld16f(p.mu_prev + 1024 + c, mpk); ld16f(p.mu_next + 1024 + c, mnk); ld16f(p.k_k + c, kkc);
;             const u16* zc = ZS + (size_t)t0 * 3328 + 1024 + c;
;             Z16 kp = tt0 > 0 ? ldz(zc - 3328) : zz(), kc = ldz(zc);
; #pragma unroll 2
;             for (int i = 0; i < 16; ++i) {
;                 const bool hn = (tt0 + i) < SEQ - 1; const Z16 kn = hn ? ldz(zc + (size_t)(i + 1) * 3328) : zz();
;                 float k[16], kk[16]; mix16(kp, kc, kn, mpk, mnk, k);
;                 float s2 = 0.f;
; #pragma unroll
;                 for (int q = 0; q < 16; ++q) { kk[q] = k[q] * kkc[q]; s2 += kk[q] * kk[q]; }
;                 s2 += __shfl_xor(s2, 1); s2 += __shfl_xor(s2, 2);
;                 const float inv = -1.0f / fmaxf(sqrtf(s2), 1e-12f);
;                 const size_t o = (size_t)(t0 + i) * RW + c;
; #pragma unroll
;                 for (int j4 = 0; j4 < 4; ++j4) *(f32x4*)(A + o + j4 * 4) = (f32x4){kk[j4 * 4] * inv, kk[j4 * 4 + 1] * inv, kk[j4 * 4 + 2] * inv, kk[j4 * 4 + 3] * inv};
;                 st16bf(Kb + o, k);
;                 kp = kc; kc = kn;
;             }
	v_lshlrev_b32_e32 v144, 16, v12
	v_and_b32_e32 v145, 0xffff0000, v12
	v_lshlrev_b32_e32 v146, 16, v13
	v_and_b32_e32 v147, 0xffff0000, v13
	v_lshlrev_b32_e32 v148, 16, v14
	v_and_b32_e32 v149, 0xffff0000, v14
	v_lshlrev_b32_e32 v150, 16, v15
	v_and_b32_e32 v151, 0xffff0000, v15
	v_lshlrev_b32_e32 v152, 16, v16
	v_and_b32_e32 v153, 0xffff0000, v16
	v_lshlrev_b32_e32 v154, 16, v17
	v_and_b32_e32 v155, 0xffff0000, v17
	v_lshlrev_b32_e32 v156, 16, v18
	v_and_b32_e32 v157, 0xffff0000, v18
	v_lshlrev_b32_e32 v158, 16, v19
	v_and_b32_e32 v159, 0xffff0000, v19
	v_lshlrev_b32_e32 v160, 16, v24
	v_and_b32_e32 v161, 0xffff0000, v24
	v_lshlrev_b32_e32 v162, 16, v25
	v_and_b32_e32 v163, 0xffff0000, v25
	v_lshlrev_b32_e32 v164, 16, v26
	v_and_b32_e32 v165, 0xffff0000, v26
	v_lshlrev_b32_e32 v166, 16, v27
	v_and_b32_e32 v167, 0xffff0000, v27
	v_lshlrev_b32_e32 v168, 16, v28
	v_and_b32_e32 v169, 0xffff0000, v28
	v_lshlrev_b32_e32 v170, 16, v29
	v_and_b32_e32 v171, 0xffff0000, v29
	v_lshlrev_b32_e32 v172, 16, v30
	v_and_b32_e32 v173, 0xffff0000, v30
	v_lshlrev_b32_e32 v174, 16, v31
	v_and_b32_e32 v175, 0xffff0000, v31
	v_lshlrev_b32_e32 v176, 16, v36
	v_and_b32_e32 v177, 0xffff0000, v36
	v_lshlrev_b32_e32 v178, 16, v37
	v_and_b32_e32 v179, 0xffff0000, v37
	v_lshlrev_b32_e32 v180, 16, v38
	v_and_b32_e32 v181, 0xffff0000, v38
	v_lshlrev_b32_e32 v182, 16, v39
	v_and_b32_e32 v183, 0xffff0000, v39
	v_lshlrev_b32_e32 v184, 16, v40
	v_and_b32_e32 v185, 0xffff0000, v40
	v_lshlrev_b32_e32 v186, 16, v41
	v_and_b32_e32 v187, 0xffff0000, v41
	v_lshlrev_b32_e32 v188, 16, v42
	v_and_b32_e32 v189, 0xffff0000, v42
	v_lshlrev_b32_e32 v190, 16, v43
	v_and_b32_e32 v191, 0xffff0000, v43
	buffer_load_dwordx4 v[12:15], v232, s[64:67], 0 offen offset:2048
	buffer_load_dwordx4 v[16:19], v232, s[64:67], 0 offen offset:2064
	v_add_u32_e32 v232, 6656, v232
	v_pk_add_f32 v[224:225], v[144:145], v[160:161] neg_lo:[0,1] neg_hi:[0,1]
	v_pk_add_f32 v[226:227], v[176:177], v[160:161] neg_lo:[0,1] neg_hi:[0,1]
	v_pk_fma_f32 v[192:193], v[96:97], v[224:225], v[160:161]
	v_pk_fma_f32 v[192:193], v[112:113], v[226:227], v[192:193]
	v_pk_add_f32 v[224:225], v[146:147], v[162:163] neg_lo:[0,1] neg_hi:[0,1]
	v_pk_add_f32 v[226:227], v[178:179], v[162:163] neg_lo:[0,1] neg_hi:[0,1]
	v_pk_fma_f32 v[194:195], v[98:99], v[224:225], v[162:163]
	v_pk_fma_f32 v[194:195], v[114:115], v[226:227], v[194:195]
	v_pk_add_f32 v[224:225], v[148:149], v[164:165] neg_lo:[0,1] neg_hi:[0,1]
	v_pk_add_f32 v[226:227], v[180:181], v[164:165] neg_lo:[0,1] neg_hi:[0,1]
	v_pk_fma_f32 v[196:197], v[100:101], v[224:225], v[164:165]
	v_pk_fma_f32 v[196:197], v[116:117], v[226:227], v[196:197]
	v_pk_add_f32 v[224:225], v[150:151], v[166:167] neg_lo:[0,1] neg_hi:[0,1]
	v_pk_add_f32 v[226:227], v[182:183], v[166:167] neg_lo:[0,1] neg_hi:[0,1]
	v_pk_fma_f32 v[198:199], v[102:103], v[224:225], v[166:167]
	v_pk_fma_f32 v[198:199], v[118:119], v[226:227], v[198:199]
	v_pk_add_f32 v[224:225], v[152:153], v[168:169] neg_lo:[0,1] neg_hi:[0,1]
	v_pk_add_f32 v[226:227], v[184:185], v[168:169] neg_lo:[0,1] neg_hi:[0,1]
	v_pk_fma_f32 v[200:201], v[104:105], v[224:225], v[168:169]
	v_pk_fma_f32 v[200:201], v[120:121], v[226:227], v[200:201]
	v_pk_add_f32 v[224:225], v[154:155], v[170:171] neg_lo:[0,1] neg_hi:[0,1]
	v_pk_add_f32 v[226:227], v[186:187], v[170:171] neg_lo:[0,1] neg_hi:[0,1]
	v_pk_fma_f32 v[202:203], v[106:107], v[224:225], v[170:171]
	v_pk_fma_f32 v[202:203], v[122:123], v[226:227], v[202:203]
	v_pk_add_f32 v[224:225], v[156:157], v[172:173] neg_lo:[0,1] neg_hi:[0,1]
	v_pk_add_f32 v[226:227], v[188:189], v[172:173] neg_lo:[0,1] neg_hi:[0,1]
	v_pk_fma_f32 v[204:205], v[108:109], v[224:225], v[172:173]
	v_pk_fma_f32 v[204:205], v[124:125], v[226:227], v[204:205]
	v_pk_add_f32 v[224:225], v[158:159], v[174:175] neg_lo:[0,1] neg_hi:[0,1]
	v_pk_add_f32 v[226:227], v[190:191], v[174:175] neg_lo:[0,1] neg_hi:[0,1]
	v_pk_fma_f32 v[206:207], v[110:111], v[224:225], v[174:175]
	v_pk_fma_f32 v[206:207], v[126:127], v[226:227], v[206:207]
	v_pk_mul_f32 v[208:209], v[192:193], v[128:129]
	v_pk_mul_f32 v[210:211], v[194:195], v[130:131]
	v_pk_mul_f32 v[212:213], v[196:197], v[132:133]
	v_pk_mul_f32 v[214:215], v[198:199], v[134:135]
	v_pk_mul_f32 v[216:217], v[200:201], v[136:137]
	v_pk_mul_f32 v[218:219], v[202:203], v[138:139]
	v_pk_mul_f32 v[220:221], v[204:205], v[140:141]
	v_pk_mul_f32 v[222:223], v[206:207], v[142:143]
	v_mul_f32_e32 v224, v208, v208
	v_fmac_f32_e32 v224, v209, v209
	v_fmac_f32_e32 v224, v210, v210
	v_fmac_f32_e32 v224, v211, v211
	v_fmac_f32_e32 v224, v212, v212
	v_fmac_f32_e32 v224, v213, v213
	v_fmac_f32_e32 v224, v214, v214
	v_fmac_f32_e32 v224, v215, v215
	v_fmac_f32_e32 v224, v216, v216
	v_fmac_f32_e32 v224, v217, v217
	v_fmac_f32_e32 v224, v218, v218
	v_fmac_f32_e32 v224, v219, v219
	v_fmac_f32_e32 v224, v220, v220
	v_fmac_f32_e32 v224, v221, v221
	v_fmac_f32_e32 v224, v222, v222
	v_fmac_f32_e32 v224, v223, v223
	s_nop 1
	v_add_f32_dpp v224, v224, v224 quad_perm:[1,0,3,2] row_mask:0xf bank_mask:0xf
	s_nop 1
	v_add_f32_dpp v224, v224, v224 quad_perm:[2,3,0,1] row_mask:0xf bank_mask:0xf
	v_sqrt_f32_e32 v224, v224
	s_nop 0
	v_max_f32_e32 v224, 0x2b8cbccc, v224
	v_rcp_f32_e32 v224, v224
	s_nop 0
	v_xor_b32_e32 v224, 0x80000000, v224
	v_mov_b32_e32 v225, v224
	v_cvt_pk_bf16_f32 v144, v192, v193
	v_cvt_pk_bf16_f32 v145, v194, v195
	v_cvt_pk_bf16_f32 v146, v196, v197
	v_cvt_pk_bf16_f32 v147, v198, v199
	v_cvt_pk_bf16_f32 v148, v200, v201
	v_cvt_pk_bf16_f32 v149, v202, v203
	v_cvt_pk_bf16_f32 v150, v204, v205
	v_cvt_pk_bf16_f32 v151, v206, v207
	v_pk_mul_f32 v[208:209], v[208:209], v[224:225]
	v_pk_mul_f32 v[210:211], v[210:211], v[224:225]
	v_pk_mul_f32 v[212:213], v[212:213], v[224:225]
	v_pk_mul_f32 v[214:215], v[214:215], v[224:225]
	v_pk_mul_f32 v[216:217], v[216:217], v[224:225]
	v_pk_mul_f32 v[218:219], v[218:219], v[224:225]
	v_pk_mul_f32 v[220:221], v[220:221], v[224:225]
	v_pk_mul_f32 v[222:223], v[222:223], v[224:225]
	buffer_store_dwordx4 v[208:211], v234, s[68:71], s72 offen offset:0
	buffer_store_dwordx4 v[212:215], v234, s[68:71], s72 offen offset:16
	buffer_store_dwordx4 v[216:219], v234, s[68:71], s72 offen offset:32
	buffer_store_dwordx4 v[220:223], v234, s[68:71], s72 offen offset:48
	buffer_store_dwordx4 v[144:147], v236, s[68:71], s73 offen offset:0
	buffer_store_dwordx4 v[148:151], v236, s[68:71], s73 offen offset:16
	s_add_u32 s72, s72, 0x1000
	s_add_u32 s73, s73, 0x800
	s_add_u32 s74, s74, 0x200
	s_add_u32 s75, s75, 0x40
	s_waitcnt vmcnt(22)
; __device__ __forceinline__ void prep_phase(const Params& p) {
;     ...
;             float mpk[16], mnk[16], kkc[16]; ld16f(p.mu_prev + 1024 + c, mpk); ld16f(p.mu_next + 1024 + c, mnk); ld16f(p.k_k + c, kkc);
;             const u16* zc = ZS + (size_t)t0 * 3328 + 1024 + c;
;             Z16 kp = tt0 > 0 ? ldz(zc - 3328) : zz(), kc = ldz(zc);
; #pragma unroll 2
;             for (int i = 0; i < 16; ++i) {
;                 const bool hn = (tt0 + i) < SEQ - 1; const Z16 kn = hn ? ldz(zc + (size_t)(i + 1) * 3328) : zz();
;                 float k[16], kk[16]; mix16(kp, kc, kn, mpk, mnk, k);
;                 float s2 = 0.f;
; #pragma unroll
;                 for (int q = 0; q < 16; ++q) { kk[q] = k[q] * kkc[q]; s2 += kk[q] * kk[q]; }
;                 s2 += __shfl_xor(s2, 1); s2 += __shfl_xor(s2, 2);
;                 const float inv = -1.0f / fmaxf(sqrtf(s2), 1e-12f);
;                 const size_t o = (size_t)(t0 + i) * RW + c;
; #pragma unroll
;                 for (int j4 = 0; j4 < 4; ++j4) *(f32x4*)(A + o + j4 * 4) = (f32x4){kk[j4 * 4] * inv, kk[j4 * 4 + 1] * inv, kk[j4 * 4 + 2] * inv, kk[j4 * 4 + 3] * inv};
;                 st16bf(Kb + o, k);
;                 kp = kc; kc = kn;
;             }
	v_lshlrev_b32_e32 v144, 16, v24
	v_and_b32_e32 v145, 0xffff0000, v24
	v_lshlrev_b32_e32 v146, 16, v25
	v_and_b32_e32 v147, 0xffff0000, v25
	v_lshlrev_b32_e32 v148, 16, v26
	v_and_b32_e32 v149, 0xffff0000, v26
	v_lshlrev_b32_e32 v150, 16, v27
	v_and_b32_e32 v151, 0xffff0000, v27
	v_lshlrev_b32_e32 v152, 16, v28
	v_and_b32_e32 v153, 0xffff0000, v28
	v_lshlrev_b32_e32 v154, 16, v29
	v_and_b32_e32 v155, 0xffff0000, v29
	v_lshlrev_b32_e32 v156, 16, v30
	v_and_b32_e32 v157, 0xffff0000, v30
	v_lshlrev_b32_e32 v158, 16, v31
	v_and_b32_e32 v159, 0xffff0000, v31
	v_lshlrev_b32_e32 v160, 16, v36
	v_and_b32_e32 v161, 0xffff0000, v36
	v_lshlrev_b32_e32 v162, 16, v37
	v_and_b32_e32 v163, 0xffff0000, v37
	v_lshlrev_b32_e32 v164, 16, v38
	v_and_b32_e32 v165, 0xffff0000, v38
	v_lshlrev_b32_e32 v166, 16, v39
	v_and_b32_e32 v167, 0xffff0000, v39
	v_lshlrev_b32_e32 v168, 16, v40
	v_and_b32_e32 v169, 0xffff0000, v40
	v_lshlrev_b32_e32 v170, 16, v41
	v_and_b32_e32 v171, 0xffff0000, v41
	v_lshlrev_b32_e32 v172, 16, v42
	v_and_b32_e32 v173, 0xffff0000, v42
	v_lshlrev_b32_e32 v174, 16, v43
	v_and_b32_e32 v175, 0xffff0000, v43
	v_lshlrev_b32_e32 v176, 16, v48
	v_and_b32_e32 v177, 0xffff0000, v48
	v_lshlrev_b32_e32 v178, 16, v49
	v_and_b32_e32 v179, 0xffff0000, v49
	v_lshlrev_b32_e32 v180, 16, v50
	v_and_b32_e32 v181, 0xffff0000, v50
	v_lshlrev_b32_e32 v182, 16, v51
	v_and_b32_e32 v183, 0xffff0000, v51
	v_lshlrev_b32_e32 v184, 16, v52
	v_and_b32_e32 v185, 0xffff0000, v52
	v_lshlrev_b32_e32 v186, 16, v53
	v_and_b32_e32 v187, 0xffff0000, v53
	v_lshlrev_b32_e32 v188, 16, v54
	v_and_b32_e32 v189, 0xffff0000, v54
	v_lshlrev_b32_e32 v190, 16, v55
	v_and_b32_e32 v191, 0xffff0000, v55
	buffer_load_dwordx4 v[24:27], v232, s[64:67], 0 offen offset:2048
	buffer_load_dwordx4 v[28:31], v232, s[64:67], 0 offen offset:2064
	v_add_u32_e32 v232, 6656, v232
	v_pk_add_f32 v[224:225], v[144:145], v[160:161] neg_lo:[0,1] neg_hi:[0,1]
	v_pk_add_f32 v[226:227], v[176:177], v[160:161] neg_lo:[0,1] neg_hi:[0,1]
	v_pk_fma_f32 v[192:193], v[96:97], v[224:225], v[160:161]
	v_pk_fma_f32 v[192:193], v[112:113], v[226:227], v[192:193]
	v_pk_add_f32 v[224:225], v[146:147], v[162:163] neg_lo:[0,1] neg_hi:[0,1]
	v_pk_add_f32 v[226:227], v[178:179], v[162:163] neg_lo:[0,1] neg_hi:[0,1]
	v_pk_fma_f32 v[194:195], v[98:99], v[224:225], v[162:163]
	v_pk_fma_f32 v[194:195], v[114:115], v[226:227], v[194:195]
	v_pk_add_f32 v[224:225], v[148:149], v[164:165] neg_lo:[0,1] neg_hi:[0,1]
	v_pk_add_f32 v[226:227], v[180:181], v[164:165] neg_lo:[0,1] neg_hi:[0,1]
	v_pk_fma_f32 v[196:197], v[100:101], v[224:225], v[164:165]
	v_pk_fma_f32 v[196:197], v[116:117], v[226:227], v[196:197]
	v_pk_add_f32 v[224:225], v[150:151], v[166:167] neg_lo:[0,1] neg_hi:[0,1]
	v_pk_add_f32 v[226:227], v[182:183], v[166:167] neg_lo:[0,1] neg_hi:[0,1]
	v_pk_fma_f32 v[198:199], v[102:103], v[224:225], v[166:167]
	v_pk_fma_f32 v[198:199], v[118:119], v[226:227], v[198:199]
	v_pk_add_f32 v[224:225], v[152:153], v[168:169] neg_lo:[0,1] neg_hi:[0,1]
	v_pk_add_f32 v[226:227], v[184:185], v[168:169] neg_lo:[0,1] neg_hi:[0,1]
	v_pk_fma_f32 v[200:201], v[104:105], v[224:225], v[168:169]
	v_pk_fma_f32 v[200:201], v[120:121], v[226:227], v[200:201]
	v_pk_add_f32 v[224:225], v[154:155], v[170:171] neg_lo:[0,1] neg_hi:[0,1]
	v_pk_add_f32 v[226:227], v[186:187], v[170:171] neg_lo:[0,1] neg_hi:[0,1]
	v_pk_fma_f32 v[202:203], v[106:107], v[224:225], v[170:171]
	v_pk_fma_f32 v[202:203], v[122:123], v[226:227], v[202:203]
	v_pk_add_f32 v[224:225], v[156:157], v[172:173] neg_lo:[0,1] neg_hi:[0,1]
	v_pk_add_f32 v[226:227], v[188:189], v[172:173] neg_lo:[0,1] neg_hi:[0,1]
	v_pk_fma_f32 v[204:205], v[108:109], v[224:225], v[172:173]
	v_pk_fma_f32 v[204:205], v[124:125], v[226:227], v[204:205]
	v_pk_add_f32 v[224:225], v[158:159], v[174:175] neg_lo:[0,1] neg_hi:[0,1]
	v_pk_add_f32 v[226:227], v[190:191], v[174:175] neg_lo:[0,1] neg_hi:[0,1]
	v_pk_fma_f32 v[206:207], v[110:111], v[224:225], v[174:175]
	v_pk_fma_f32 v[206:207], v[126:127], v[226:227], v[206:207]
	v_pk_mul_f32 v[208:209], v[192:193], v[128:129]
	v_pk_mul_f32 v[210:211], v[194:195], v[130:131]
	v_pk_mul_f32 v[212:213], v[196:197], v[132:133]
	v_pk_mul_f32 v[214:215], v[198:199], v[134:135]
	v_pk_mul_f32 v[216:217], v[200:201], v[136:137]
	v_pk_mul_f32 v[218:219], v[202:203], v[138:139]
	v_pk_mul_f32 v[220:221], v[204:205], v[140:141]
	v_pk_mul_f32 v[222:223], v[206:207], v[142:143]
	v_mul_f32_e32 v224, v208, v208
	v_fmac_f32_e32 v224, v209, v209
	v_fmac_f32_e32 v224, v210, v210
	v_fmac_f32_e32 v224, v211, v211
	v_fmac_f32_e32 v224, v212, v212
	v_fmac_f32_e32 v224, v213, v213
	v_fmac_f32_e32 v224, v214, v214
	v_fmac_f32_e32 v224, v215, v215
	v_fmac_f32_e32 v224, v216, v216
	v_fmac_f32_e32 v224, v217, v217
	v_fmac_f32_e32 v224, v218, v218
	v_fmac_f32_e32 v224, v219, v219
	v_fmac_f32_e32 v224, v220, v220
	v_fmac_f32_e32 v224, v221, v221
	v_fmac_f32_e32 v224, v222, v222
	v_fmac_f32_e32 v224, v223, v223
	s_nop 1
	v_add_f32_dpp v224, v224, v224 quad_perm:[1,0,3,2] row_mask:0xf bank_mask:0xf
	s_nop 1
	v_add_f32_dpp v224, v224, v224 quad_perm:[2,3,0,1] row_mask:0xf bank_mask:0xf
	v_sqrt_f32_e32 v224, v224
	s_nop 0
	v_max_f32_e32 v224, 0x2b8cbccc, v224
	v_rcp_f32_e32 v224, v224
	s_nop 0
	v_xor_b32_e32 v224, 0x80000000, v224
	v_mov_b32_e32 v225, v224
	v_cvt_pk_bf16_f32 v144, v192, v193
	v_cvt_pk_bf16_f32 v145, v194, v195
	v_cvt_pk_bf16_f32 v146, v196, v197
	v_cvt_pk_bf16_f32 v147, v198, v199
	v_cvt_pk_bf16_f32 v148, v200, v201
	v_cvt_pk_bf16_f32 v149, v202, v203
	v_cvt_pk_bf16_f32 v150, v204, v205
	v_cvt_pk_bf16_f32 v151, v206, v207
	v_pk_mul_f32 v[208:209], v[208:209], v[224:225]
	v_pk_mul_f32 v[210:211], v[210:211], v[224:225]
	v_pk_mul_f32 v[212:213], v[212:213], v[224:225]
	v_pk_mul_f32 v[214:215], v[214:215], v[224:225]
	v_pk_mul_f32 v[216:217], v[216:217], v[224:225]
	v_pk_mul_f32 v[218:219], v[218:219], v[224:225]
	v_pk_mul_f32 v[220:221], v[220:221], v[224:225]
	v_pk_mul_f32 v[222:223], v[222:223], v[224:225]
	buffer_store_dwordx4 v[208:211], v234, s[68:71], s72 offen offset:0
	buffer_store_dwordx4 v[212:215], v234, s[68:71], s72 offen offset:16
	buffer_store_dwordx4 v[216:219], v234, s[68:71], s72 offen offset:32
	buffer_store_dwordx4 v[220:223], v234, s[68:71], s72 offen offset:48
	buffer_store_dwordx4 v[144:147], v236, s[68:71], s73 offen offset:0
	buffer_store_dwordx4 v[148:151], v236, s[68:71], s73 offen offset:16
	s_add_u32 s72, s72, 0x1000
	s_add_u32 s73, s73, 0x800
	s_add_u32 s74, s74, 0x200
	s_add_u32 s75, s75, 0x40
	s_waitcnt vmcnt(28)
; __device__ __forceinline__ void prep_phase(const Params& p) {
;     ...
;             float mpk[16], mnk[16], kkc[16]; ld16f(p.mu_prev + 1024 + c, mpk); ld16f(p.mu_next + 1024 + c, mnk); ld16f(p.k_k + c, kkc);
;             const u16* zc = ZS + (size_t)t0 * 3328 + 1024 + c;
;             Z16 kp = tt0 > 0 ? ldz(zc - 3328) : zz(), kc = ldz(zc);
; #pragma unroll 2
;             for (int i = 0; i < 16; ++i) {
;                 const bool hn = (tt0 + i) < SEQ - 1; const Z16 kn = hn ? ldz(zc + (size_t)(i + 1) * 3328) : zz();
;                 float k[16], kk[16]; mix16(kp, kc, kn, mpk, mnk, k);
;                 float s2 = 0.f;
; #pragma unroll
;                 for (int q = 0; q < 16; ++q) { kk[q] = k[q] * kkc[q]; s2 += kk[q] * kk[q]; }
;                 s2 += __shfl_xor(s2, 1); s2 += __shfl_xor(s2, 2);
;                 const float inv = -1.0f / fmaxf(sqrtf(s2), 1e-12f);
;                 const size_t o = (size_t)(t0 + i) * RW + c;
; #pragma unroll
;                 for (int j4 = 0; j4 < 4; ++j4) *(f32x4*)(A + o + j4 * 4) = (f32x4){kk[j4 * 4] * inv, kk[j4 * 4 + 1] * inv, kk[j4 * 4 + 2] * inv, kk[j4 * 4 + 3] * inv};
;                 st16bf(Kb + o, k);
;                 kp = kc; kc = kn;
;             }
	v_lshlrev_b32_e32 v144, 16, v36
	v_and_b32_e32 v145, 0xffff0000, v36
	v_lshlrev_b32_e32 v146, 16, v37
	v_and_b32_e32 v147, 0xffff0000, v37
	v_lshlrev_b32_e32 v148, 16, v38
	v_and_b32_e32 v149, 0xffff0000, v38
	v_lshlrev_b32_e32 v150, 16, v39
	v_and_b32_e32 v151, 0xffff0000, v39
	v_lshlrev_b32_e32 v152, 16, v40
	v_and_b32_e32 v153, 0xffff0000, v40
	v_lshlrev_b32_e32 v154, 16, v41
	v_and_b32_e32 v155, 0xffff0000, v41
	v_lshlrev_b32_e32 v156, 16, v42
	v_and_b32_e32 v157, 0xffff0000, v42
	v_lshlrev_b32_e32 v158, 16, v43
	v_and_b32_e32 v159, 0xffff0000, v43
	v_lshlrev_b32_e32 v160, 16, v48
	v_and_b32_e32 v161, 0xffff0000, v48
	v_lshlrev_b32_e32 v162, 16, v49
	v_and_b32_e32 v163, 0xffff0000, v49
	v_lshlrev_b32_e32 v164, 16, v50
	v_and_b32_e32 v165, 0xffff0000, v50
	v_lshlrev_b32_e32 v166, 16, v51
	v_and_b32_e32 v167, 0xffff0000, v51
	v_lshlrev_b32_e32 v168, 16, v52
	v_and_b32_e32 v169, 0xffff0000, v52
	v_lshlrev_b32_e32 v170, 16, v53
	v_and_b32_e32 v171, 0xffff0000, v53
	v_lshlrev_b32_e32 v172, 16, v54
	v_and_b32_e32 v173, 0xffff0000, v54
	v_lshlrev_b32_e32 v174, 16, v55
	v_and_b32_e32 v175, 0xffff0000, v55
	v_lshlrev_b32_e32 v176, 16, v60
	v_and_b32_e32 v177, 0xffff0000, v60
	v_lshlrev_b32_e32 v178, 16, v61
	v_and_b32_e32 v179, 0xffff0000, v61
	v_lshlrev_b32_e32 v180, 16, v62
	v_and_b32_e32 v181, 0xffff0000, v62
	v_lshlrev_b32_e32 v182, 16, v63
	v_and_b32_e32 v183, 0xffff0000, v63
	v_lshlrev_b32_e32 v184, 16, v64
	v_and_b32_e32 v185, 0xffff0000, v64
	v_lshlrev_b32_e32 v186, 16, v65
	v_and_b32_e32 v187, 0xffff0000, v65
	v_lshlrev_b32_e32 v188, 16, v66
	v_and_b32_e32 v189, 0xffff0000, v66
	v_lshlrev_b32_e32 v190, 16, v67
	v_and_b32_e32 v191, 0xffff0000, v67
	buffer_load_dwordx4 v[36:39], v232, s[64:67], 0 offen offset:2048
	buffer_load_dwordx4 v[40:43], v232, s[64:67], 0 offen offset:2064
	v_add_u32_e32 v232, 6656, v232
	v_pk_add_f32 v[224:225], v[144:145], v[160:161] neg_lo:[0,1] neg_hi:[0,1]
	v_pk_add_f32 v[226:227], v[176:177], v[160:161] neg_lo:[0,1] neg_hi:[0,1]
	v_pk_fma_f32 v[192:193], v[96:97], v[224:225], v[160:161]
	v_pk_fma_f32 v[192:193], v[112:113], v[226:227], v[192:193]
	v_pk_add_f32 v[224:225], v[146:147], v[162:163] neg_lo:[0,1] neg_hi:[0,1]
	v_pk_add_f32 v[226:227], v[178:179], v[162:163] neg_lo:[0,1] neg_hi:[0,1]
	v_pk_fma_f32 v[194:195], v[98:99], v[224:225], v[162:163]
	v_pk_fma_f32 v[194:195], v[114:115], v[226:227], v[194:195]
	v_pk_add_f32 v[224:225], v[148:149], v[164:165] neg_lo:[0,1] neg_hi:[0,1]
	v_pk_add_f32 v[226:227], v[180:181], v[164:165] neg_lo:[0,1] neg_hi:[0,1]
	v_pk_fma_f32 v[196:197], v[100:101], v[224:225], v[164:165]
	v_pk_fma_f32 v[196:197], v[116:117], v[226:227], v[196:197]
	v_pk_add_f32 v[224:225], v[150:151], v[166:167] neg_lo:[0,1] neg_hi:[0,1]
	v_pk_add_f32 v[226:227], v[182:183], v[166:167] neg_lo:[0,1] neg_hi:[0,1]
	v_pk_fma_f32 v[198:199], v[102:103], v[224:225], v[166:167]
	v_pk_fma_f32 v[198:199], v[118:119], v[226:227], v[198:199]
	v_pk_add_f32 v[224:225], v[152:153], v[168:169] neg_lo:[0,1] neg_hi:[0,1]
	v_pk_add_f32 v[226:227], v[184:185], v[168:169] neg_lo:[0,1] neg_hi:[0,1]
	v_pk_fma_f32 v[200:201], v[104:105], v[224:225], v[168:169]
	v_pk_fma_f32 v[200:201], v[120:121], v[226:227], v[200:201]
	v_pk_add_f32 v[224:225], v[154:155], v[170:171] neg_lo:[0,1] neg_hi:[0,1]
	v_pk_add_f32 v[226:227], v[186:187], v[170:171] neg_lo:[0,1] neg_hi:[0,1]
	v_pk_fma_f32 v[202:203], v[106:107], v[224:225], v[170:171]
	v_pk_fma_f32 v[202:203], v[122:123], v[226:227], v[202:203]
	v_pk_add_f32 v[224:225], v[156:157], v[172:173] neg_lo:[0,1] neg_hi:[0,1]
	v_pk_add_f32 v[226:227], v[188:189], v[172:173] neg_lo:[0,1] neg_hi:[0,1]
	v_pk_fma_f32 v[204:205], v[108:109], v[224:225], v[172:173]
	v_pk_fma_f32 v[204:205], v[124:125], v[226:227], v[204:205]
	v_pk_add_f32 v[224:225], v[158:159], v[174:175] neg_lo:[0,1] neg_hi:[0,1]
	v_pk_add_f32 v[226:227], v[190:191], v[174:175] neg_lo:[0,1] neg_hi:[0,1]
	v_pk_fma_f32 v[206:207], v[110:111], v[224:225], v[174:175]
	v_pk_fma_f32 v[206:207], v[126:127], v[226:227], v[206:207]
	v_pk_mul_f32 v[208:209], v[192:193], v[128:129]
	v_pk_mul_f32 v[210:211], v[194:195], v[130:131]
	v_pk_mul_f32 v[212:213], v[196:197], v[132:133]
	v_pk_mul_f32 v[214:215], v[198:199], v[134:135]
	v_pk_mul_f32 v[216:217], v[200:201], v[136:137]
	v_pk_mul_f32 v[218:219], v[202:203], v[138:139]
	v_pk_mul_f32 v[220:221], v[204:205], v[140:141]
	v_pk_mul_f32 v[222:223], v[206:207], v[142:143]
	v_mul_f32_e32 v224, v208, v208
	v_fmac_f32_e32 v224, v209, v209
	v_fmac_f32_e32 v224, v210, v210
	v_fmac_f32_e32 v224, v211, v211
	v_fmac_f32_e32 v224, v212, v212
	v_fmac_f32_e32 v224, v213, v213
	v_fmac_f32_e32 v224, v214, v214
	v_fmac_f32_e32 v224, v215, v215
	v_fmac_f32_e32 v224, v216, v216
	v_fmac_f32_e32 v224, v217, v217
	v_fmac_f32_e32 v224, v218, v218
	v_fmac_f32_e32 v224, v219, v219
	v_fmac_f32_e32 v224, v220, v220
	v_fmac_f32_e32 v224, v221, v221
	v_fmac_f32_e32 v224, v222, v222
	v_fmac_f32_e32 v224, v223, v223
	s_nop 1
	v_add_f32_dpp v224, v224, v224 quad_perm:[1,0,3,2] row_mask:0xf bank_mask:0xf
	s_nop 1
	v_add_f32_dpp v224, v224, v224 quad_perm:[2,3,0,1] row_mask:0xf bank_mask:0xf
	v_sqrt_f32_e32 v224, v224
	s_nop 0
	v_max_f32_e32 v224, 0x2b8cbccc, v224
	v_rcp_f32_e32 v224, v224
	s_nop 0
	v_xor_b32_e32 v224, 0x80000000, v224
	v_mov_b32_e32 v225, v224
	v_cvt_pk_bf16_f32 v144, v192, v193
	v_cvt_pk_bf16_f32 v145, v194, v195
	v_cvt_pk_bf16_f32 v146, v196, v197
	v_cvt_pk_bf16_f32 v147, v198, v199
	v_cvt_pk_bf16_f32 v148, v200, v201
	v_cvt_pk_bf16_f32 v149, v202, v203
	v_cvt_pk_bf16_f32 v150, v204, v205
	v_cvt_pk_bf16_f32 v151, v206, v207
	v_pk_mul_f32 v[208:209], v[208:209], v[224:225]
	v_pk_mul_f32 v[210:211], v[210:211], v[224:225]
	v_pk_mul_f32 v[212:213], v[212:213], v[224:225]
	v_pk_mul_f32 v[214:215], v[214:215], v[224:225]
	v_pk_mul_f32 v[216:217], v[216:217], v[224:225]
	v_pk_mul_f32 v[218:219], v[218:219], v[224:225]
	v_pk_mul_f32 v[220:221], v[220:221], v[224:225]
	v_pk_mul_f32 v[222:223], v[222:223], v[224:225]
	buffer_store_dwordx4 v[208:211], v234, s[68:71], s72 offen offset:0
	buffer_store_dwordx4 v[212:215], v234, s[68:71], s72 offen offset:16
	buffer_store_dwordx4 v[216:219], v234, s[68:71], s72 offen offset:32
	buffer_store_dwordx4 v[220:223], v234, s[68:71], s72 offen offset:48
	buffer_store_dwordx4 v[144:147], v236, s[68:71], s73 offen offset:0
	buffer_store_dwordx4 v[148:151], v236, s[68:71], s73 offen offset:16
	s_add_u32 s72, s72, 0x1000
	s_add_u32 s73, s73, 0x800
	s_add_u32 s74, s74, 0x200
	s_add_u32 s75, s75, 0x40
	s_waitcnt vmcnt(34)
; __device__ __forceinline__ void prep_phase(const Params& p) {
;     ...
;             float mpk[16], mnk[16], kkc[16]; ld16f(p.mu_prev + 1024 + c, mpk); ld16f(p.mu_next + 1024 + c, mnk); ld16f(p.k_k + c, kkc);
;             const u16* zc = ZS + (size_t)t0 * 3328 + 1024 + c;
;             Z16 kp = tt0 > 0 ? ldz(zc - 3328) : zz(), kc = ldz(zc);
; #pragma unroll 2
;             for (int i = 0; i < 16; ++i) {
;                 const bool hn = (tt0 + i) < SEQ - 1; const Z16 kn = hn ? ldz(zc + (size_t)(i + 1) * 3328) : zz();
;                 float k[16], kk[16]; mix16(kp, kc, kn, mpk, mnk, k);
;                 float s2 = 0.f;
; #pragma unroll
;                 for (int q = 0; q < 16; ++q) { kk[q] = k[q] * kkc[q]; s2 += kk[q] * kk[q]; }
;                 s2 += __shfl_xor(s2, 1); s2 += __shfl_xor(s2, 2);
;                 const float inv = -1.0f / fmaxf(sqrtf(s2), 1e-12f);
;                 const size_t o = (size_t)(t0 + i) * RW + c;
; #pragma unroll
;                 for (int j4 = 0; j4 < 4; ++j4) *(f32x4*)(A + o + j4 * 4) = (f32x4){kk[j4 * 4] * inv, kk[j4 * 4 + 1] * inv, kk[j4 * 4 + 2] * inv, kk[j4 * 4 + 3] * inv};
;                 st16bf(Kb + o, k);
;                 kp = kc; kc = kn;
;             }
	v_lshlrev_b32_e32 v144, 16, v48
	v_and_b32_e32 v145, 0xffff0000, v48
	v_lshlrev_b32_e32 v146, 16, v49
	v_and_b32_e32 v147, 0xffff0000, v49
	v_lshlrev_b32_e32 v148, 16, v50
	v_and_b32_e32 v149, 0xffff0000, v50
	v_lshlrev_b32_e32 v150, 16, v51
	v_and_b32_e32 v151, 0xffff0000, v51
	v_lshlrev_b32_e32 v152, 16, v52
	v_and_b32_e32 v153, 0xffff0000, v52
	v_lshlrev_b32_e32 v154, 16, v53
	v_and_b32_e32 v155, 0xffff0000, v53
	v_lshlrev_b32_e32 v156, 16, v54
	v_and_b32_e32 v157, 0xffff0000, v54
	v_lshlrev_b32_e32 v158, 16, v55
	v_and_b32_e32 v159, 0xffff0000, v55
	v_lshlrev_b32_e32 v160, 16, v60
	v_and_b32_e32 v161, 0xffff0000, v60
	v_lshlrev_b32_e32 v162, 16, v61
	v_and_b32_e32 v163, 0xffff0000, v61
	v_lshlrev_b32_e32 v164, 16, v62
	v_and_b32_e32 v165, 0xffff0000, v62
	v_lshlrev_b32_e32 v166, 16, v63
	v_and_b32_e32 v167, 0xffff0000, v63
	v_lshlrev_b32_e32 v168, 16, v64
	v_and_b32_e32 v169, 0xffff0000, v64
	v_lshlrev_b32_e32 v170, 16, v65
	v_and_b32_e32 v171, 0xffff0000, v65
	v_lshlrev_b32_e32 v172, 16, v66
	v_and_b32_e32 v173, 0xffff0000, v66
	v_lshlrev_b32_e32 v174, 16, v67
	v_and_b32_e32 v175, 0xffff0000, v67
	v_lshlrev_b32_e32 v176, 16, v72
	v_and_b32_e32 v177, 0xffff0000, v72
	v_lshlrev_b32_e32 v178, 16, v73
	v_and_b32_e32 v179, 0xffff0000, v73
	v_lshlrev_b32_e32 v180, 16, v74
	v_and_b32_e32 v181, 0xffff0000, v74
	v_lshlrev_b32_e32 v182, 16, v75
	v_and_b32_e32 v183, 0xffff0000, v75
	v_lshlrev_b32_e32 v184, 16, v76
	v_and_b32_e32 v185, 0xffff0000, v76
	v_lshlrev_b32_e32 v186, 16, v77
	v_and_b32_e32 v187, 0xffff0000, v77
	v_lshlrev_b32_e32 v188, 16, v78
	v_and_b32_e32 v189, 0xffff0000, v78
	v_lshlrev_b32_e32 v190, 16, v79
	v_and_b32_e32 v191, 0xffff0000, v79
	buffer_load_dwordx4 v[48:51], v232, s[64:67], 0 offen offset:2048
	buffer_load_dwordx4 v[52:55], v232, s[64:67], 0 offen offset:2064
	v_add_u32_e32 v232, 6656, v232
	v_pk_add_f32 v[224:225], v[144:145], v[160:161] neg_lo:[0,1] neg_hi:[0,1]
	v_pk_add_f32 v[226:227], v[176:177], v[160:161] neg_lo:[0,1] neg_hi:[0,1]
	v_pk_fma_f32 v[192:193], v[96:97], v[224:225], v[160:161]
	v_pk_fma_f32 v[192:193], v[112:113], v[226:227], v[192:193]
	v_pk_add_f32 v[224:225], v[146:147], v[162:163] neg_lo:[0,1] neg_hi:[0,1]
	v_pk_add_f32 v[226:227], v[178:179], v[162:163] neg_lo:[0,1] neg_hi:[0,1]
	v_pk_fma_f32 v[194:195], v[98:99], v[224:225], v[162:163]
	v_pk_fma_f32 v[194:195], v[114:115], v[226:227], v[194:195]
	v_pk_add_f32 v[224:225], v[148:149], v[164:165] neg_lo:[0,1] neg_hi:[0,1]
	v_pk_add_f32 v[226:227], v[180:181], v[164:165] neg_lo:[0,1] neg_hi:[0,1]
	v_pk_fma_f32 v[196:197], v[100:101], v[224:225], v[164:165]
	v_pk_fma_f32 v[196:197], v[116:117], v[226:227], v[196:197]
	v_pk_add_f32 v[224:225], v[150:151], v[166:167] neg_lo:[0,1] neg_hi:[0,1]
	v_pk_add_f32 v[226:227], v[182:183], v[166:167] neg_lo:[0,1] neg_hi:[0,1]
	v_pk_fma_f32 v[198:199], v[102:103], v[224:225], v[166:167]
	v_pk_fma_f32 v[198:199], v[118:119], v[226:227], v[198:199]
	v_pk_add_f32 v[224:225], v[152:153], v[168:169] neg_lo:[0,1] neg_hi:[0,1]
	v_pk_add_f32 v[226:227], v[184:185], v[168:169] neg_lo:[0,1] neg_hi:[0,1]
	v_pk_fma_f32 v[200:201], v[104:105], v[224:225], v[168:169]
	v_pk_fma_f32 v[200:201], v[120:121], v[226:227], v[200:201]
	v_pk_add_f32 v[224:225], v[154:155], v[170:171] neg_lo:[0,1] neg_hi:[0,1]
	v_pk_add_f32 v[226:227], v[186:187], v[170:171] neg_lo:[0,1] neg_hi:[0,1]
	v_pk_fma_f32 v[202:203], v[106:107], v[224:225], v[170:171]
	v_pk_fma_f32 v[202:203], v[122:123], v[226:227], v[202:203]
	v_pk_add_f32 v[224:225], v[156:157], v[172:173] neg_lo:[0,1] neg_hi:[0,1]
	v_pk_add_f32 v[226:227], v[188:189], v[172:173] neg_lo:[0,1] neg_hi:[0,1]
	v_pk_fma_f32 v[204:205], v[108:109], v[224:225], v[172:173]
	v_pk_fma_f32 v[204:205], v[124:125], v[226:227], v[204:205]
	v_pk_add_f32 v[224:225], v[158:159], v[174:175] neg_lo:[0,1] neg_hi:[0,1]
	v_pk_add_f32 v[226:227], v[190:191], v[174:175] neg_lo:[0,1] neg_hi:[0,1]
	v_pk_fma_f32 v[206:207], v[110:111], v[224:225], v[174:175]
	v_pk_fma_f32 v[206:207], v[126:127], v[226:227], v[206:207]
	v_pk_mul_f32 v[208:209], v[192:193], v[128:129]
	v_pk_mul_f32 v[210:211], v[194:195], v[130:131]
	v_pk_mul_f32 v[212:213], v[196:197], v[132:133]
	v_pk_mul_f32 v[214:215], v[198:199], v[134:135]
	v_pk_mul_f32 v[216:217], v[200:201], v[136:137]
	v_pk_mul_f32 v[218:219], v[202:203], v[138:139]
	v_pk_mul_f32 v[220:221], v[204:205], v[140:141]
	v_pk_mul_f32 v[222:223], v[206:207], v[142:143]
	v_mul_f32_e32 v224, v208, v208
	v_fmac_f32_e32 v224, v209, v209
	v_fmac_f32_e32 v224, v210, v210
	v_fmac_f32_e32 v224, v211, v211
	v_fmac_f32_e32 v224, v212, v212
	v_fmac_f32_e32 v224, v213, v213
	v_fmac_f32_e32 v224, v214, v214
	v_fmac_f32_e32 v224, v215, v215
	v_fmac_f32_e32 v224, v216, v216
	v_fmac_f32_e32 v224, v217, v217
	v_fmac_f32_e32 v224, v218, v218
	v_fmac_f32_e32 v224, v219, v219
	v_fmac_f32_e32 v224, v220, v220
	v_fmac_f32_e32 v224, v221, v221
	v_fmac_f32_e32 v224, v222, v222
	v_fmac_f32_e32 v224, v223, v223
	s_nop 1
	v_add_f32_dpp v224, v224, v224 quad_perm:[1,0,3,2] row_mask:0xf bank_mask:0xf
	s_nop 1
	v_add_f32_dpp v224, v224, v224 quad_perm:[2,3,0,1] row_mask:0xf bank_mask:0xf
	v_sqrt_f32_e32 v224, v224
	s_nop 0
	v_max_f32_e32 v224, 0x2b8cbccc, v224
	v_rcp_f32_e32 v224, v224
	s_nop 0
	v_xor_b32_e32 v224, 0x80000000, v224
	v_mov_b32_e32 v225, v224
	v_cvt_pk_bf16_f32 v144, v192, v193
	v_cvt_pk_bf16_f32 v145, v194, v195
	v_cvt_pk_bf16_f32 v146, v196, v197
	v_cvt_pk_bf16_f32 v147, v198, v199
	v_cvt_pk_bf16_f32 v148, v200, v201
	v_cvt_pk_bf16_f32 v149, v202, v203
	v_cvt_pk_bf16_f32 v150, v204, v205
	v_cvt_pk_bf16_f32 v151, v206, v207
	v_pk_mul_f32 v[208:209], v[208:209], v[224:225]
	v_pk_mul_f32 v[210:211], v[210:211], v[224:225]
	v_pk_mul_f32 v[212:213], v[212:213], v[224:225]
	v_pk_mul_f32 v[214:215], v[214:215], v[224:225]
	v_pk_mul_f32 v[216:217], v[216:217], v[224:225]
	v_pk_mul_f32 v[218:219], v[218:219], v[224:225]
	v_pk_mul_f32 v[220:221], v[220:221], v[224:225]
	v_pk_mul_f32 v[222:223], v[222:223], v[224:225]
	buffer_store_dwordx4 v[208:211], v234, s[68:71], s72 offen offset:0
	buffer_store_dwordx4 v[212:215], v234, s[68:71], s72 offen offset:16
	buffer_store_dwordx4 v[216:219], v234, s[68:71], s72 offen offset:32
	buffer_store_dwordx4 v[220:223], v234, s[68:71], s72 offen offset:48
	buffer_store_dwordx4 v[144:147], v236, s[68:71], s73 offen offset:0
	buffer_store_dwordx4 v[148:151], v236, s[68:71], s73 offen offset:16
	s_add_u32 s72, s72, 0x1000
	s_add_u32 s73, s73, 0x800
	s_add_u32 s74, s74, 0x200
	s_add_u32 s75, s75, 0x40
	s_waitcnt vmcnt(40)
; __device__ __forceinline__ void prep_phase(const Params& p) {
;     ...
;             float mpk[16], mnk[16], kkc[16]; ld16f(p.mu_prev + 1024 + c, mpk); ld16f(p.mu_next + 1024 + c, mnk); ld16f(p.k_k + c, kkc);
;             const u16* zc = ZS + (size_t)t0 * 3328 + 1024 + c;
;             Z16 kp = tt0 > 0 ? ldz(zc - 3328) : zz(), kc = ldz(zc);
; #pragma unroll 2
;             for (int i = 0; i < 16; ++i) {
;                 const bool hn = (tt0 + i) < SEQ - 1; const Z16 kn = hn ? ldz(zc + (size_t)(i + 1) * 3328) : zz();
;                 float k[16], kk[16]; mix16(kp, kc, kn, mpk, mnk, k);
;                 float s2 = 0.f;
; #pragma unroll
;                 for (int q = 0; q < 16; ++q) { kk[q] = k[q] * kkc[q]; s2 += kk[q] * kk[q]; }
;                 s2 += __shfl_xor(s2, 1); s2 += __shfl_xor(s2, 2);
;                 const float inv = -1.0f / fmaxf(sqrtf(s2), 1e-12f);
;                 const size_t o = (size_t)(t0 + i) * RW + c;
; #pragma unroll
;                 for (int j4 = 0; j4 < 4; ++j4) *(f32x4*)(A + o + j4 * 4) = (f32x4){kk[j4 * 4] * inv, kk[j4 * 4 + 1] * inv, kk[j4 * 4 + 2] * inv, kk[j4 * 4 + 3] * inv};
;                 st16bf(Kb + o, k);
;                 kp = kc; kc = kn;
;             }
	v_lshlrev_b32_e32 v144, 16, v60
	v_and_b32_e32 v145, 0xffff0000, v60
	v_lshlrev_b32_e32 v146, 16, v61
	v_and_b32_e32 v147, 0xffff0000, v61
	v_lshlrev_b32_e32 v148, 16, v62
	v_and_b32_e32 v149, 0xffff0000, v62
	v_lshlrev_b32_e32 v150, 16, v63
	v_and_b32_e32 v151, 0xffff0000, v63
	v_lshlrev_b32_e32 v152, 16, v64
	v_and_b32_e32 v153, 0xffff0000, v64
	v_lshlrev_b32_e32 v154, 16, v65
	v_and_b32_e32 v155, 0xffff0000, v65
	v_lshlrev_b32_e32 v156, 16, v66
	v_and_b32_e32 v157, 0xffff0000, v66
	v_lshlrev_b32_e32 v158, 16, v67
	v_and_b32_e32 v159, 0xffff0000, v67
	v_lshlrev_b32_e32 v160, 16, v72
	v_and_b32_e32 v161, 0xffff0000, v72
	v_lshlrev_b32_e32 v162, 16, v73
	v_and_b32_e32 v163, 0xffff0000, v73
	v_lshlrev_b32_e32 v164, 16, v74
	v_and_b32_e32 v165, 0xffff0000, v74
	v_lshlrev_b32_e32 v166, 16, v75
	v_and_b32_e32 v167, 0xffff0000, v75
	v_lshlrev_b32_e32 v168, 16, v76
	v_and_b32_e32 v169, 0xffff0000, v76
	v_lshlrev_b32_e32 v170, 16, v77
	v_and_b32_e32 v171, 0xffff0000, v77
	v_lshlrev_b32_e32 v172, 16, v78
	v_and_b32_e32 v173, 0xffff0000, v78
	v_lshlrev_b32_e32 v174, 16, v79
	v_and_b32_e32 v175, 0xffff0000, v79
	v_lshlrev_b32_e32 v176, 16, v84
	v_and_b32_e32 v177, 0xffff0000, v84
	v_lshlrev_b32_e32 v178, 16, v85
	v_and_b32_e32 v179, 0xffff0000, v85
	v_lshlrev_b32_e32 v180, 16, v86
	v_and_b32_e32 v181, 0xffff0000, v86
	v_lshlrev_b32_e32 v182, 16, v87
	v_and_b32_e32 v183, 0xffff0000, v87
	v_lshlrev_b32_e32 v184, 16, v88
	v_and_b32_e32 v185, 0xffff0000, v88
	v_lshlrev_b32_e32 v186, 16, v89
	v_and_b32_e32 v187, 0xffff0000, v89
	v_lshlrev_b32_e32 v188, 16, v90
	v_and_b32_e32 v189, 0xffff0000, v90
	v_lshlrev_b32_e32 v190, 16, v91
	v_and_b32_e32 v191, 0xffff0000, v91
	buffer_load_dwordx4 v[60:63], v232, s[64:67], 0 offen offset:2048
	buffer_load_dwordx4 v[64:67], v232, s[64:67], 0 offen offset:2064
	v_add_u32_e32 v232, 6656, v232
	v_pk_add_f32 v[224:225], v[144:145], v[160:161] neg_lo:[0,1] neg_hi:[0,1]
	v_pk_add_f32 v[226:227], v[176:177], v[160:161] neg_lo:[0,1] neg_hi:[0,1]
	v_pk_fma_f32 v[192:193], v[96:97], v[224:225], v[160:161]
	v_pk_fma_f32 v[192:193], v[112:113], v[226:227], v[192:193]
	v_pk_add_f32 v[224:225], v[146:147], v[162:163] neg_lo:[0,1] neg_hi:[0,1]
	v_pk_add_f32 v[226:227], v[178:179], v[162:163] neg_lo:[0,1] neg_hi:[0,1]
	v_pk_fma_f32 v[194:195], v[98:99], v[224:225], v[162:163]
	v_pk_fma_f32 v[194:195], v[114:115], v[226:227], v[194:195]
	v_pk_add_f32 v[224:225], v[148:149], v[164:165] neg_lo:[0,1] neg_hi:[0,1]
	v_pk_add_f32 v[226:227], v[180:181], v[164:165] neg_lo:[0,1] neg_hi:[0,1]
	v_pk_fma_f32 v[196:197], v[100:101], v[224:225], v[164:165]
	v_pk_fma_f32 v[196:197], v[116:117], v[226:227], v[196:197]
	v_pk_add_f32 v[224:225], v[150:151], v[166:167] neg_lo:[0,1] neg_hi:[0,1]
	v_pk_add_f32 v[226:227], v[182:183], v[166:167] neg_lo:[0,1] neg_hi:[0,1]
	v_pk_fma_f32 v[198:199], v[102:103], v[224:225], v[166:167]
	v_pk_fma_f32 v[198:199], v[118:119], v[226:227], v[198:199]
	v_pk_add_f32 v[224:225], v[152:153], v[168:169] neg_lo:[0,1] neg_hi:[0,1]
	v_pk_add_f32 v[226:227], v[184:185], v[168:169] neg_lo:[0,1] neg_hi:[0,1]
	v_pk_fma_f32 v[200:201], v[104:105], v[224:225], v[168:169]
	v_pk_fma_f32 v[200:201], v[120:121], v[226:227], v[200:201]
	v_pk_add_f32 v[224:225], v[154:155], v[170:171] neg_lo:[0,1] neg_hi:[0,1]
	v_pk_add_f32 v[226:227], v[186:187], v[170:171] neg_lo:[0,1] neg_hi:[0,1]
	v_pk_fma_f32 v[202:203], v[106:107], v[224:225], v[170:171]
	v_pk_fma_f32 v[202:203], v[122:123], v[226:227], v[202:203]
	v_pk_add_f32 v[224:225], v[156:157], v[172:173] neg_lo:[0,1] neg_hi:[0,1]
	v_pk_add_f32 v[226:227], v[188:189], v[172:173] neg_lo:[0,1] neg_hi:[0,1]
	v_pk_fma_f32 v[204:205], v[108:109], v[224:225], v[172:173]
	v_pk_fma_f32 v[204:205], v[124:125], v[226:227], v[204:205]
	v_pk_add_f32 v[224:225], v[158:159], v[174:175] neg_lo:[0,1] neg_hi:[0,1]
	v_pk_add_f32 v[226:227], v[190:191], v[174:175] neg_lo:[0,1] neg_hi:[0,1]
	v_pk_fma_f32 v[206:207], v[110:111], v[224:225], v[174:175]
	v_pk_fma_f32 v[206:207], v[126:127], v[226:227], v[206:207]
	v_pk_mul_f32 v[208:209], v[192:193], v[128:129]
	v_pk_mul_f32 v[210:211], v[194:195], v[130:131]
	v_pk_mul_f32 v[212:213], v[196:197], v[132:133]
	v_pk_mul_f32 v[214:215], v[198:199], v[134:135]
	v_pk_mul_f32 v[216:217], v[200:201], v[136:137]
	v_pk_mul_f32 v[218:219], v[202:203], v[138:139]
	v_pk_mul_f32 v[220:221], v[204:205], v[140:141]
	v_pk_mul_f32 v[222:223], v[206:207], v[142:143]
	v_mul_f32_e32 v224, v208, v208
	v_fmac_f32_e32 v224, v209, v209
	v_fmac_f32_e32 v224, v210, v210
	v_fmac_f32_e32 v224, v211, v211
	v_fmac_f32_e32 v224, v212, v212
	v_fmac_f32_e32 v224, v213, v213
	v_fmac_f32_e32 v224, v214, v214
	v_fmac_f32_e32 v224, v215, v215
	v_fmac_f32_e32 v224, v216, v216
	v_fmac_f32_e32 v224, v217, v217
	v_fmac_f32_e32 v224, v218, v218
	v_fmac_f32_e32 v224, v219, v219
	v_fmac_f32_e32 v224, v220, v220
	v_fmac_f32_e32 v224, v221, v221
	v_fmac_f32_e32 v224, v222, v222
	v_fmac_f32_e32 v224, v223, v223
	s_nop 1
	v_add_f32_dpp v224, v224, v224 quad_perm:[1,0,3,2] row_mask:0xf bank_mask:0xf
	s_nop 1
	v_add_f32_dpp v224, v224, v224 quad_perm:[2,3,0,1] row_mask:0xf bank_mask:0xf
	v_sqrt_f32_e32 v224, v224
	s_nop 0
	v_max_f32_e32 v224, 0x2b8cbccc, v224
	v_rcp_f32_e32 v224, v224
	s_nop 0
	v_xor_b32_e32 v224, 0x80000000, v224
	v_mov_b32_e32 v225, v224
	v_cvt_pk_bf16_f32 v144, v192, v193
	v_cvt_pk_bf16_f32 v145, v194, v195
	v_cvt_pk_bf16_f32 v146, v196, v197
	v_cvt_pk_bf16_f32 v147, v198, v199
	v_cvt_pk_bf16_f32 v148, v200, v201
	v_cvt_pk_bf16_f32 v149, v202, v203
	v_cvt_pk_bf16_f32 v150, v204, v205
	v_cvt_pk_bf16_f32 v151, v206, v207
	v_pk_mul_f32 v[208:209], v[208:209], v[224:225]
	v_pk_mul_f32 v[210:211], v[210:211], v[224:225]
	v_pk_mul_f32 v[212:213], v[212:213], v[224:225]
	v_pk_mul_f32 v[214:215], v[214:215], v[224:225]
	v_pk_mul_f32 v[216:217], v[216:217], v[224:225]
	v_pk_mul_f32 v[218:219], v[218:219], v[224:225]
	v_pk_mul_f32 v[220:221], v[220:221], v[224:225]
	v_pk_mul_f32 v[222:223], v[222:223], v[224:225]
	buffer_store_dwordx4 v[208:211], v234, s[68:71], s72 offen offset:0
	buffer_store_dwordx4 v[212:215], v234, s[68:71], s72 offen offset:16
	buffer_store_dwordx4 v[216:219], v234, s[68:71], s72 offen offset:32
	buffer_store_dwordx4 v[220:223], v234, s[68:71], s72 offen offset:48
	buffer_store_dwordx4 v[144:147], v236, s[68:71], s73 offen offset:0
	buffer_store_dwordx4 v[148:151], v236, s[68:71], s73 offen offset:16
	s_add_u32 s72, s72, 0x1000
	s_add_u32 s73, s73, 0x800
	s_add_u32 s74, s74, 0x200
	s_add_u32 s75, s75, 0x40
	s_waitcnt vmcnt(46)
; __device__ __forceinline__ void prep_phase(const Params& p) {
;     ...
;             float mpk[16], mnk[16], kkc[16]; ld16f(p.mu_prev + 1024 + c, mpk); ld16f(p.mu_next + 1024 + c, mnk); ld16f(p.k_k + c, kkc);
;             const u16* zc = ZS + (size_t)t0 * 3328 + 1024 + c;
;             Z16 kp = tt0 > 0 ? ldz(zc - 3328) : zz(), kc = ldz(zc);
; #pragma unroll 2
;             for (int i = 0; i < 16; ++i) {
;                 const bool hn = (tt0 + i) < SEQ - 1; const Z16 kn = hn ? ldz(zc + (size_t)(i + 1) * 3328) : zz();
;                 float k[16], kk[16]; mix16(kp, kc, kn, mpk, mnk, k);
;                 float s2 = 0.f;
; #pragma unroll
;                 for (int q = 0; q < 16; ++q) { kk[q] = k[q] * kkc[q]; s2 += kk[q] * kk[q]; }
;                 s2 += __shfl_xor(s2, 1); s2 += __shfl_xor(s2, 2);
;                 const float inv = -1.0f / fmaxf(sqrtf(s2), 1e-12f);
;                 const size_t o = (size_t)(t0 + i) * RW + c;
; #pragma unroll
;                 for (int j4 = 0; j4 < 4; ++j4) *(f32x4*)(A + o + j4 * 4) = (f32x4){kk[j4 * 4] * inv, kk[j4 * 4 + 1] * inv, kk[j4 * 4 + 2] * inv, kk[j4 * 4 + 3] * inv};
;                 st16bf(Kb + o, k);
;                 kp = kc; kc = kn;
;             }
	v_lshlrev_b32_e32 v144, 16, v72
	v_and_b32_e32 v145, 0xffff0000, v72
	v_lshlrev_b32_e32 v146, 16, v73
	v_and_b32_e32 v147, 0xffff0000, v73
	v_lshlrev_b32_e32 v148, 16, v74
	v_and_b32_e32 v149, 0xffff0000, v74
	v_lshlrev_b32_e32 v150, 16, v75
	v_and_b32_e32 v151, 0xffff0000, v75
	v_lshlrev_b32_e32 v152, 16, v76
	v_and_b32_e32 v153, 0xffff0000, v76
	v_lshlrev_b32_e32 v154, 16, v77
	v_and_b32_e32 v155, 0xffff0000, v77
	v_lshlrev_b32_e32 v156, 16, v78
	v_and_b32_e32 v157, 0xffff0000, v78
	v_lshlrev_b32_e32 v158, 16, v79
	v_and_b32_e32 v159, 0xffff0000, v79
	v_lshlrev_b32_e32 v160, 16, v84
	v_and_b32_e32 v161, 0xffff0000, v84
	v_lshlrev_b32_e32 v162, 16, v85
	v_and_b32_e32 v163, 0xffff0000, v85
	v_lshlrev_b32_e32 v164, 16, v86
	v_and_b32_e32 v165, 0xffff0000, v86
	v_lshlrev_b32_e32 v166, 16, v87
	v_and_b32_e32 v167, 0xffff0000, v87
	v_lshlrev_b32_e32 v168, 16, v88
	v_and_b32_e32 v169, 0xffff0000, v88
	v_lshlrev_b32_e32 v170, 16, v89
	v_and_b32_e32 v171, 0xffff0000, v89
	v_lshlrev_b32_e32 v172, 16, v90
	v_and_b32_e32 v173, 0xffff0000, v90
	v_lshlrev_b32_e32 v174, 16, v91
	v_and_b32_e32 v175, 0xffff0000, v91
	v_lshlrev_b32_e32 v176, 16, v0
	v_and_b32_e32 v177, 0xffff0000, v0
	v_lshlrev_b32_e32 v178, 16, v1
	v_and_b32_e32 v179, 0xffff0000, v1
	v_lshlrev_b32_e32 v180, 16, v2
	v_and_b32_e32 v181, 0xffff0000, v2
	v_lshlrev_b32_e32 v182, 16, v3
	v_and_b32_e32 v183, 0xffff0000, v3
	v_lshlrev_b32_e32 v184, 16, v4
	v_and_b32_e32 v185, 0xffff0000, v4
	v_lshlrev_b32_e32 v186, 16, v5
	v_and_b32_e32 v187, 0xffff0000, v5
	v_lshlrev_b32_e32 v188, 16, v6
	v_and_b32_e32 v189, 0xffff0000, v6
	v_lshlrev_b32_e32 v190, 16, v7
	v_and_b32_e32 v191, 0xffff0000, v7
	buffer_load_dwordx4 v[72:75], v232, s[64:67], 0 offen offset:2048
	buffer_load_dwordx4 v[76:79], v232, s[64:67], 0 offen offset:2064
	v_add_u32_e32 v232, 6656, v232
	v_pk_add_f32 v[224:225], v[144:145], v[160:161] neg_lo:[0,1] neg_hi:[0,1]
	v_pk_add_f32 v[226:227], v[176:177], v[160:161] neg_lo:[0,1] neg_hi:[0,1]
	v_pk_fma_f32 v[192:193], v[96:97], v[224:225], v[160:161]
	v_pk_fma_f32 v[192:193], v[112:113], v[226:227], v[192:193]
	v_pk_add_f32 v[224:225], v[146:147], v[162:163] neg_lo:[0,1] neg_hi:[0,1]
	v_pk_add_f32 v[226:227], v[178:179], v[162:163] neg_lo:[0,1] neg_hi:[0,1]
	v_pk_fma_f32 v[194:195], v[98:99], v[224:225], v[162:163]
	v_pk_fma_f32 v[194:195], v[114:115], v[226:227], v[194:195]
	v_pk_add_f32 v[224:225], v[148:149], v[164:165] neg_lo:[0,1] neg_hi:[0,1]
	v_pk_add_f32 v[226:227], v[180:181], v[164:165] neg_lo:[0,1] neg_hi:[0,1]
	v_pk_fma_f32 v[196:197], v[100:101], v[224:225], v[164:165]
	v_pk_fma_f32 v[196:197], v[116:117], v[226:227], v[196:197]
	v_pk_add_f32 v[224:225], v[150:151], v[166:167] neg_lo:[0,1] neg_hi:[0,1]
	v_pk_add_f32 v[226:227], v[182:183], v[166:167] neg_lo:[0,1] neg_hi:[0,1]
	v_pk_fma_f32 v[198:199], v[102:103], v[224:225], v[166:167]
	v_pk_fma_f32 v[198:199], v[118:119], v[226:227], v[198:199]
	v_pk_add_f32 v[224:225], v[152:153], v[168:169] neg_lo:[0,1] neg_hi:[0,1]
	v_pk_add_f32 v[226:227], v[184:185], v[168:169] neg_lo:[0,1] neg_hi:[0,1]
	v_pk_fma_f32 v[200:201], v[104:105], v[224:225], v[168:169]
	v_pk_fma_f32 v[200:201], v[120:121], v[226:227], v[200:201]
	v_pk_add_f32 v[224:225], v[154:155], v[170:171] neg_lo:[0,1] neg_hi:[0,1]
	v_pk_add_f32 v[226:227], v[186:187], v[170:171] neg_lo:[0,1] neg_hi:[0,1]
	v_pk_fma_f32 v[202:203], v[106:107], v[224:225], v[170:171]
	v_pk_fma_f32 v[202:203], v[122:123], v[226:227], v[202:203]
	v_pk_add_f32 v[224:225], v[156:157], v[172:173] neg_lo:[0,1] neg_hi:[0,1]
	v_pk_add_f32 v[226:227], v[188:189], v[172:173] neg_lo:[0,1] neg_hi:[0,1]
	v_pk_fma_f32 v[204:205], v[108:109], v[224:225], v[172:173]
	v_pk_fma_f32 v[204:205], v[124:125], v[226:227], v[204:205]
	v_pk_add_f32 v[224:225], v[158:159], v[174:175] neg_lo:[0,1] neg_hi:[0,1]
	v_pk_add_f32 v[226:227], v[190:191], v[174:175] neg_lo:[0,1] neg_hi:[0,1]
	v_pk_fma_f32 v[206:207], v[110:111], v[224:225], v[174:175]
	v_pk_fma_f32 v[206:207], v[126:127], v[226:227], v[206:207]
	v_pk_mul_f32 v[208:209], v[192:193], v[128:129]
	v_pk_mul_f32 v[210:211], v[194:195], v[130:131]
	v_pk_mul_f32 v[212:213], v[196:197], v[132:133]
	v_pk_mul_f32 v[214:215], v[198:199], v[134:135]
	v_pk_mul_f32 v[216:217], v[200:201], v[136:137]
	v_pk_mul_f32 v[218:219], v[202:203], v[138:139]
	v_pk_mul_f32 v[220:221], v[204:205], v[140:141]
	v_pk_mul_f32 v[222:223], v[206:207], v[142:143]
	v_mul_f32_e32 v224, v208, v208
	v_fmac_f32_e32 v224, v209, v209
	v_fmac_f32_e32 v224, v210, v210
	v_fmac_f32_e32 v224, v211, v211
	v_fmac_f32_e32 v224, v212, v212
	v_fmac_f32_e32 v224, v213, v213
	v_fmac_f32_e32 v224, v214, v214
	v_fmac_f32_e32 v224, v215, v215
	v_fmac_f32_e32 v224, v216, v216
	v_fmac_f32_e32 v224, v217, v217
	v_fmac_f32_e32 v224, v218, v218
	v_fmac_f32_e32 v224, v219, v219
	v_fmac_f32_e32 v224, v220, v220
	v_fmac_f32_e32 v224, v221, v221
	v_fmac_f32_e32 v224, v222, v222
	v_fmac_f32_e32 v224, v223, v223
	s_nop 1
	v_add_f32_dpp v224, v224, v224 quad_perm:[1,0,3,2] row_mask:0xf bank_mask:0xf
	s_nop 1
	v_add_f32_dpp v224, v224, v224 quad_perm:[2,3,0,1] row_mask:0xf bank_mask:0xf
	v_sqrt_f32_e32 v224, v224
	s_nop 0
	v_max_f32_e32 v224, 0x2b8cbccc, v224
	v_rcp_f32_e32 v224, v224
	s_nop 0
	v_xor_b32_e32 v224, 0x80000000, v224
	v_mov_b32_e32 v225, v224
	v_cvt_pk_bf16_f32 v144, v192, v193
	v_cvt_pk_bf16_f32 v145, v194, v195
	v_cvt_pk_bf16_f32 v146, v196, v197
	v_cvt_pk_bf16_f32 v147, v198, v199
	v_cvt_pk_bf16_f32 v148, v200, v201
	v_cvt_pk_bf16_f32 v149, v202, v203
	v_cvt_pk_bf16_f32 v150, v204, v205
	v_cvt_pk_bf16_f32 v151, v206, v207
	v_pk_mul_f32 v[208:209], v[208:209], v[224:225]
	v_pk_mul_f32 v[210:211], v[210:211], v[224:225]
	v_pk_mul_f32 v[212:213], v[212:213], v[224:225]
	v_pk_mul_f32 v[214:215], v[214:215], v[224:225]
	v_pk_mul_f32 v[216:217], v[216:217], v[224:225]
	v_pk_mul_f32 v[218:219], v[218:219], v[224:225]
	v_pk_mul_f32 v[220:221], v[220:221], v[224:225]
	v_pk_mul_f32 v[222:223], v[222:223], v[224:225]
	buffer_store_dwordx4 v[208:211], v234, s[68:71], s72 offen offset:0
	buffer_store_dwordx4 v[212:215], v234, s[68:71], s72 offen offset:16
	buffer_store_dwordx4 v[216:219], v234, s[68:71], s72 offen offset:32
	buffer_store_dwordx4 v[220:223], v234, s[68:71], s72 offen offset:48
	buffer_store_dwordx4 v[144:147], v236, s[68:71], s73 offen offset:0
	buffer_store_dwordx4 v[148:151], v236, s[68:71], s73 offen offset:16
	s_add_u32 s72, s72, 0x1000
	s_add_u32 s73, s73, 0x800
	s_add_u32 s74, s74, 0x200
	s_add_u32 s75, s75, 0x40
	s_waitcnt vmcnt(46)
; __device__ __forceinline__ void prep_phase(const Params& p) {
;     ...
;             float mpk[16], mnk[16], kkc[16]; ld16f(p.mu_prev + 1024 + c, mpk); ld16f(p.mu_next + 1024 + c, mnk); ld16f(p.k_k + c, kkc);
;             const u16* zc = ZS + (size_t)t0 * 3328 + 1024 + c;
;             Z16 kp = tt0 > 0 ? ldz(zc - 3328) : zz(), kc = ldz(zc);
; #pragma unroll 2
;             for (int i = 0; i < 16; ++i) {
;                 const bool hn = (tt0 + i) < SEQ - 1; const Z16 kn = hn ? ldz(zc + (size_t)(i + 1) * 3328) : zz();
;                 float k[16], kk[16]; mix16(kp, kc, kn, mpk, mnk, k);
;                 float s2 = 0.f;
; #pragma unroll
;                 for (int q = 0; q < 16; ++q) { kk[q] = k[q] * kkc[q]; s2 += kk[q] * kk[q]; }
;                 s2 += __shfl_xor(s2, 1); s2 += __shfl_xor(s2, 2);
;                 const float inv = -1.0f / fmaxf(sqrtf(s2), 1e-12f);
;                 const size_t o = (size_t)(t0 + i) * RW + c;
; #pragma unroll
;                 for (int j4 = 0; j4 < 4; ++j4) *(f32x4*)(A + o + j4 * 4) = (f32x4){kk[j4 * 4] * inv, kk[j4 * 4 + 1] * inv, kk[j4 * 4 + 2] * inv, kk[j4 * 4 + 3] * inv};
;                 st16bf(Kb + o, k);
;                 kp = kc; kc = kn;
;             }
	v_lshlrev_b32_e32 v144, 16, v84
	v_and_b32_e32 v145, 0xffff0000, v84
	v_lshlrev_b32_e32 v146, 16, v85
	v_and_b32_e32 v147, 0xffff0000, v85
	v_lshlrev_b32_e32 v148, 16, v86
	v_and_b32_e32 v149, 0xffff0000, v86
	v_lshlrev_b32_e32 v150, 16, v87
	v_and_b32_e32 v151, 0xffff0000, v87
	v_lshlrev_b32_e32 v152, 16, v88
	v_and_b32_e32 v153, 0xffff0000, v88
	v_lshlrev_b32_e32 v154, 16, v89
	v_and_b32_e32 v155, 0xffff0000, v89
	v_lshlrev_b32_e32 v156, 16, v90
	v_and_b32_e32 v157, 0xffff0000, v90
	v_lshlrev_b32_e32 v158, 16, v91
	v_and_b32_e32 v159, 0xffff0000, v91
	v_lshlrev_b32_e32 v160, 16, v0
	v_and_b32_e32 v161, 0xffff0000, v0
	v_lshlrev_b32_e32 v162, 16, v1
	v_and_b32_e32 v163, 0xffff0000, v1
	v_lshlrev_b32_e32 v164, 16, v2
	v_and_b32_e32 v165, 0xffff0000, v2
	v_lshlrev_b32_e32 v166, 16, v3
	v_and_b32_e32 v167, 0xffff0000, v3
	v_lshlrev_b32_e32 v168, 16, v4
	v_and_b32_e32 v169, 0xffff0000, v4
	v_lshlrev_b32_e32 v170, 16, v5
	v_and_b32_e32 v171, 0xffff0000, v5
	v_lshlrev_b32_e32 v172, 16, v6
	v_and_b32_e32 v173, 0xffff0000, v6
	v_lshlrev_b32_e32 v174, 16, v7
	v_and_b32_e32 v175, 0xffff0000, v7
	v_lshlrev_b32_e32 v176, 16, v12
	v_and_b32_e32 v177, 0xffff0000, v12
	v_lshlrev_b32_e32 v178, 16, v13
	v_and_b32_e32 v179, 0xffff0000, v13
	v_lshlrev_b32_e32 v180, 16, v14
	v_and_b32_e32 v181, 0xffff0000, v14
	v_lshlrev_b32_e32 v182, 16, v15
	v_and_b32_e32 v183, 0xffff0000, v15
	v_lshlrev_b32_e32 v184, 16, v16
	v_and_b32_e32 v185, 0xffff0000, v16
	v_lshlrev_b32_e32 v186, 16, v17
	v_and_b32_e32 v187, 0xffff0000, v17
	v_lshlrev_b32_e32 v188, 16, v18
	v_and_b32_e32 v189, 0xffff0000, v18
	v_lshlrev_b32_e32 v190, 16, v19
	v_and_b32_e32 v191, 0xffff0000, v19
	buffer_load_dwordx4 v[84:87], v232, s[64:67], 0 offen offset:2048
	buffer_load_dwordx4 v[88:91], v232, s[64:67], 0 offen offset:2064
	v_add_u32_e32 v232, 6656, v232
	v_pk_add_f32 v[224:225], v[144:145], v[160:161] neg_lo:[0,1] neg_hi:[0,1]
	v_pk_add_f32 v[226:227], v[176:177], v[160:161] neg_lo:[0,1] neg_hi:[0,1]
	v_pk_fma_f32 v[192:193], v[96:97], v[224:225], v[160:161]
	v_pk_fma_f32 v[192:193], v[112:113], v[226:227], v[192:193]
	v_pk_add_f32 v[224:225], v[146:147], v[162:163] neg_lo:[0,1] neg_hi:[0,1]
	v_pk_add_f32 v[226:227], v[178:179], v[162:163] neg_lo:[0,1] neg_hi:[0,1]
	v_pk_fma_f32 v[194:195], v[98:99], v[224:225], v[162:163]
	v_pk_fma_f32 v[194:195], v[114:115], v[226:227], v[194:195]
	v_pk_add_f32 v[224:225], v[148:149], v[164:165] neg_lo:[0,1] neg_hi:[0,1]
	v_pk_add_f32 v[226:227], v[180:181], v[164:165] neg_lo:[0,1] neg_hi:[0,1]
	v_pk_fma_f32 v[196:197], v[100:101], v[224:225], v[164:165]
	v_pk_fma_f32 v[196:197], v[116:117], v[226:227], v[196:197]
	v_pk_add_f32 v[224:225], v[150:151], v[166:167] neg_lo:[0,1] neg_hi:[0,1]
	v_pk_add_f32 v[226:227], v[182:183], v[166:167] neg_lo:[0,1] neg_hi:[0,1]
	v_pk_fma_f32 v[198:199], v[102:103], v[224:225], v[166:167]
	v_pk_fma_f32 v[198:199], v[118:119], v[226:227], v[198:199]
	v_pk_add_f32 v[224:225], v[152:153], v[168:169] neg_lo:[0,1] neg_hi:[0,1]
	v_pk_add_f32 v[226:227], v[184:185], v[168:169] neg_lo:[0,1] neg_hi:[0,1]
	v_pk_fma_f32 v[200:201], v[104:105], v[224:225], v[168:169]
	v_pk_fma_f32 v[200:201], v[120:121], v[226:227], v[200:201]
	v_pk_add_f32 v[224:225], v[154:155], v[170:171] neg_lo:[0,1] neg_hi:[0,1]
	v_pk_add_f32 v[226:227], v[186:187], v[170:171] neg_lo:[0,1] neg_hi:[0,1]
	v_pk_fma_f32 v[202:203], v[106:107], v[224:225], v[170:171]
	v_pk_fma_f32 v[202:203], v[122:123], v[226:227], v[202:203]
	v_pk_add_f32 v[224:225], v[156:157], v[172:173] neg_lo:[0,1] neg_hi:[0,1]
	v_pk_add_f32 v[226:227], v[188:189], v[172:173] neg_lo:[0,1] neg_hi:[0,1]
	v_pk_fma_f32 v[204:205], v[108:109], v[224:225], v[172:173]
	v_pk_fma_f32 v[204:205], v[124:125], v[226:227], v[204:205]
	v_pk_add_f32 v[224:225], v[158:159], v[174:175] neg_lo:[0,1] neg_hi:[0,1]
	v_pk_add_f32 v[226:227], v[190:191], v[174:175] neg_lo:[0,1] neg_hi:[0,1]
	v_pk_fma_f32 v[206:207], v[110:111], v[224:225], v[174:175]
	v_pk_fma_f32 v[206:207], v[126:127], v[226:227], v[206:207]
	v_pk_mul_f32 v[208:209], v[192:193], v[128:129]
	v_pk_mul_f32 v[210:211], v[194:195], v[130:131]
	v_pk_mul_f32 v[212:213], v[196:197], v[132:133]
	v_pk_mul_f32 v[214:215], v[198:199], v[134:135]
	v_pk_mul_f32 v[216:217], v[200:201], v[136:137]
	v_pk_mul_f32 v[218:219], v[202:203], v[138:139]
	v_pk_mul_f32 v[220:221], v[204:205], v[140:141]
	v_pk_mul_f32 v[222:223], v[206:207], v[142:143]
	v_mul_f32_e32 v224, v208, v208
	v_fmac_f32_e32 v224, v209, v209
	v_fmac_f32_e32 v224, v210, v210
	v_fmac_f32_e32 v224, v211, v211
	v_fmac_f32_e32 v224, v212, v212
	v_fmac_f32_e32 v224, v213, v213
	v_fmac_f32_e32 v224, v214, v214
	v_fmac_f32_e32 v224, v215, v215
	v_fmac_f32_e32 v224, v216, v216
	v_fmac_f32_e32 v224, v217, v217
	v_fmac_f32_e32 v224, v218, v218
	v_fmac_f32_e32 v224, v219, v219
	v_fmac_f32_e32 v224, v220, v220
	v_fmac_f32_e32 v224, v221, v221
	v_fmac_f32_e32 v224, v222, v222
	v_fmac_f32_e32 v224, v223, v223
	s_nop 1
	v_add_f32_dpp v224, v224, v224 quad_perm:[1,0,3,2] row_mask:0xf bank_mask:0xf
	s_nop 1
	v_add_f32_dpp v224, v224, v224 quad_perm:[2,3,0,1] row_mask:0xf bank_mask:0xf
	v_sqrt_f32_e32 v224, v224
	s_nop 0
	v_max_f32_e32 v224, 0x2b8cbccc, v224
	v_rcp_f32_e32 v224, v224
	s_nop 0
	v_xor_b32_e32 v224, 0x80000000, v224
	v_mov_b32_e32 v225, v224
	v_cvt_pk_bf16_f32 v144, v192, v193
	v_cvt_pk_bf16_f32 v145, v194, v195
	v_cvt_pk_bf16_f32 v146, v196, v197
	v_cvt_pk_bf16_f32 v147, v198, v199
	v_cvt_pk_bf16_f32 v148, v200, v201
	v_cvt_pk_bf16_f32 v149, v202, v203
	v_cvt_pk_bf16_f32 v150, v204, v205
	v_cvt_pk_bf16_f32 v151, v206, v207
	v_pk_mul_f32 v[208:209], v[208:209], v[224:225]
	v_pk_mul_f32 v[210:211], v[210:211], v[224:225]
	v_pk_mul_f32 v[212:213], v[212:213], v[224:225]
	v_pk_mul_f32 v[214:215], v[214:215], v[224:225]
	v_pk_mul_f32 v[216:217], v[216:217], v[224:225]
	v_pk_mul_f32 v[218:219], v[218:219], v[224:225]
	v_pk_mul_f32 v[220:221], v[220:221], v[224:225]
	v_pk_mul_f32 v[222:223], v[222:223], v[224:225]
	buffer_store_dwordx4 v[208:211], v234, s[68:71], s72 offen offset:0
	buffer_store_dwordx4 v[212:215], v234, s[68:71], s72 offen offset:16
	buffer_store_dwordx4 v[216:219], v234, s[68:71], s72 offen offset:32
	buffer_store_dwordx4 v[220:223], v234, s[68:71], s72 offen offset:48
	buffer_store_dwordx4 v[144:147], v236, s[68:71], s73 offen offset:0
	buffer_store_dwordx4 v[148:151], v236, s[68:71], s73 offen offset:16
	s_add_u32 s72, s72, 0x1000
	s_add_u32 s73, s73, 0x800
	s_add_u32 s74, s74, 0x200
	s_add_u32 s75, s75, 0x40
	s_waitcnt vmcnt(46)
; __device__ __forceinline__ void prep_phase(const Params& p) {
;     ...
;             float mpk[16], mnk[16], kkc[16]; ld16f(p.mu_prev + 1024 + c, mpk); ld16f(p.mu_next + 1024 + c, mnk); ld16f(p.k_k + c, kkc);
;             const u16* zc = ZS + (size_t)t0 * 3328 + 1024 + c;
;             Z16 kp = tt0 > 0 ? ldz(zc - 3328) : zz(), kc = ldz(zc);
; #pragma unroll 2
;             for (int i = 0; i < 16; ++i) {
;                 const bool hn = (tt0 + i) < SEQ - 1; const Z16 kn = hn ? ldz(zc + (size_t)(i + 1) * 3328) : zz();
;                 float k[16], kk[16]; mix16(kp, kc, kn, mpk, mnk, k);
;                 float s2 = 0.f;
; #pragma unroll
;                 for (int q = 0; q < 16; ++q) { kk[q] = k[q] * kkc[q]; s2 += kk[q] * kk[q]; }
;                 s2 += __shfl_xor(s2, 1); s2 += __shfl_xor(s2, 2);
;                 const float inv = -1.0f / fmaxf(sqrtf(s2), 1e-12f);
;                 const size_t o = (size_t)(t0 + i) * RW + c;
; #pragma unroll
;                 for (int j4 = 0; j4 < 4; ++j4) *(f32x4*)(A + o + j4 * 4) = (f32x4){kk[j4 * 4] * inv, kk[j4 * 4 + 1] * inv, kk[j4 * 4 + 2] * inv, kk[j4 * 4 + 3] * inv};
;                 st16bf(Kb + o, k);
;                 kp = kc; kc = kn;
;             }
	v_lshlrev_b32_e32 v144, 16, v0
	v_and_b32_e32 v145, 0xffff0000, v0
	v_lshlrev_b32_e32 v146, 16, v1
	v_and_b32_e32 v147, 0xffff0000, v1
	v_lshlrev_b32_e32 v148, 16, v2
	v_and_b32_e32 v149, 0xffff0000, v2
	v_lshlrev_b32_e32 v150, 16, v3
	v_and_b32_e32 v151, 0xffff0000, v3
	v_lshlrev_b32_e32 v152, 16, v4
	v_and_b32_e32 v153, 0xffff0000, v4
	v_lshlrev_b32_e32 v154, 16, v5
	v_and_b32_e32 v155, 0xffff0000, v5
	v_lshlrev_b32_e32 v156, 16, v6
	v_and_b32_e32 v157, 0xffff0000, v6
	v_lshlrev_b32_e32 v158, 16, v7
	v_and_b32_e32 v159, 0xffff0000, v7
	v_lshlrev_b32_e32 v160, 16, v12
	v_and_b32_e32 v161, 0xffff0000, v12
	v_lshlrev_b32_e32 v162, 16, v13
	v_and_b32_e32 v163, 0xffff0000, v13
	v_lshlrev_b32_e32 v164, 16, v14
	v_and_b32_e32 v165, 0xffff0000, v14
	v_lshlrev_b32_e32 v166, 16, v15
	v_and_b32_e32 v167, 0xffff0000, v15
	v_lshlrev_b32_e32 v168, 16, v16
	v_and_b32_e32 v169, 0xffff0000, v16
	v_lshlrev_b32_e32 v170, 16, v17
	v_and_b32_e32 v171, 0xffff0000, v17
	v_lshlrev_b32_e32 v172, 16, v18
	v_and_b32_e32 v173, 0xffff0000, v18
	v_lshlrev_b32_e32 v174, 16, v19
	v_and_b32_e32 v175, 0xffff0000, v19
	v_lshlrev_b32_e32 v176, 16, v24
	v_and_b32_e32 v177, 0xffff0000, v24
	v_lshlrev_b32_e32 v178, 16, v25
	v_and_b32_e32 v179, 0xffff0000, v25
	v_lshlrev_b32_e32 v180, 16, v26
	v_and_b32_e32 v181, 0xffff0000, v26
	v_lshlrev_b32_e32 v182, 16, v27
	v_and_b32_e32 v183, 0xffff0000, v27
	v_lshlrev_b32_e32 v184, 16, v28
	v_and_b32_e32 v185, 0xffff0000, v28
	v_lshlrev_b32_e32 v186, 16, v29
	v_and_b32_e32 v187, 0xffff0000, v29
	v_lshlrev_b32_e32 v188, 16, v30
	v_and_b32_e32 v189, 0xffff0000, v30
	v_lshlrev_b32_e32 v190, 16, v31
	v_and_b32_e32 v191, 0xffff0000, v31
	buffer_load_dwordx4 v[0:3], v232, s[64:67], 0 offen offset:2048
	buffer_load_dwordx4 v[4:7], v232, s[64:67], 0 offen offset:2064
	v_add_u32_e32 v232, 6656, v232
	v_pk_add_f32 v[224:225], v[144:145], v[160:161] neg_lo:[0,1] neg_hi:[0,1]
	v_pk_add_f32 v[226:227], v[176:177], v[160:161] neg_lo:[0,1] neg_hi:[0,1]
	v_pk_fma_f32 v[192:193], v[96:97], v[224:225], v[160:161]
	v_pk_fma_f32 v[192:193], v[112:113], v[226:227], v[192:193]
	v_pk_add_f32 v[224:225], v[146:147], v[162:163] neg_lo:[0,1] neg_hi:[0,1]
	v_pk_add_f32 v[226:227], v[178:179], v[162:163] neg_lo:[0,1] neg_hi:[0,1]
	v_pk_fma_f32 v[194:195], v[98:99], v[224:225], v[162:163]
	v_pk_fma_f32 v[194:195], v[114:115], v[226:227], v[194:195]
	v_pk_add_f32 v[224:225], v[148:149], v[164:165] neg_lo:[0,1] neg_hi:[0,1]
	v_pk_add_f32 v[226:227], v[180:181], v[164:165] neg_lo:[0,1] neg_hi:[0,1]
	v_pk_fma_f32 v[196:197], v[100:101], v[224:225], v[164:165]
	v_pk_fma_f32 v[196:197], v[116:117], v[226:227], v[196:197]
	v_pk_add_f32 v[224:225], v[150:151], v[166:167] neg_lo:[0,1] neg_hi:[0,1]
	v_pk_add_f32 v[226:227], v[182:183], v[166:167] neg_lo:[0,1] neg_hi:[0,1]
	v_pk_fma_f32 v[198:199], v[102:103], v[224:225], v[166:167]
	v_pk_fma_f32 v[198:199], v[118:119], v[226:227], v[198:199]
	v_pk_add_f32 v[224:225], v[152:153], v[168:169] neg_lo:[0,1] neg_hi:[0,1]
	v_pk_add_f32 v[226:227], v[184:185], v[168:169] neg_lo:[0,1] neg_hi:[0,1]
	v_pk_fma_f32 v[200:201], v[104:105], v[224:225], v[168:169]
	v_pk_fma_f32 v[200:201], v[120:121], v[226:227], v[200:201]
	v_pk_add_f32 v[224:225], v[154:155], v[170:171] neg_lo:[0,1] neg_hi:[0,1]
	v_pk_add_f32 v[226:227], v[186:187], v[170:171] neg_lo:[0,1] neg_hi:[0,1]
	v_pk_fma_f32 v[202:203], v[106:107], v[224:225], v[170:171]
	v_pk_fma_f32 v[202:203], v[122:123], v[226:227], v[202:203]
	v_pk_add_f32 v[224:225], v[156:157], v[172:173] neg_lo:[0,1] neg_hi:[0,1]
	v_pk_add_f32 v[226:227], v[188:189], v[172:173] neg_lo:[0,1] neg_hi:[0,1]
	v_pk_fma_f32 v[204:205], v[108:109], v[224:225], v[172:173]
	v_pk_fma_f32 v[204:205], v[124:125], v[226:227], v[204:205]
	v_pk_add_f32 v[224:225], v[158:159], v[174:175] neg_lo:[0,1] neg_hi:[0,1]
	v_pk_add_f32 v[226:227], v[190:191], v[174:175] neg_lo:[0,1] neg_hi:[0,1]
	v_pk_fma_f32 v[206:207], v[110:111], v[224:225], v[174:175]
	v_pk_fma_f32 v[206:207], v[126:127], v[226:227], v[206:207]
	v_pk_mul_f32 v[208:209], v[192:193], v[128:129]
	v_pk_mul_f32 v[210:211], v[194:195], v[130:131]
	v_pk_mul_f32 v[212:213], v[196:197], v[132:133]
	v_pk_mul_f32 v[214:215], v[198:199], v[134:135]
	v_pk_mul_f32 v[216:217], v[200:201], v[136:137]
	v_pk_mul_f32 v[218:219], v[202:203], v[138:139]
	v_pk_mul_f32 v[220:221], v[204:205], v[140:141]
	v_pk_mul_f32 v[222:223], v[206:207], v[142:143]
	v_mul_f32_e32 v224, v208, v208
	v_fmac_f32_e32 v224, v209, v209
	v_fmac_f32_e32 v224, v210, v210
	v_fmac_f32_e32 v224, v211, v211
	v_fmac_f32_e32 v224, v212, v212
	v_fmac_f32_e32 v224, v213, v213
	v_fmac_f32_e32 v224, v214, v214
	v_fmac_f32_e32 v224, v215, v215
	v_fmac_f32_e32 v224, v216, v216
	v_fmac_f32_e32 v224, v217, v217
	v_fmac_f32_e32 v224, v218, v218
	v_fmac_f32_e32 v224, v219, v219
	v_fmac_f32_e32 v224, v220, v220
	v_fmac_f32_e32 v224, v221, v221
	v_fmac_f32_e32 v224, v222, v222
	v_fmac_f32_e32 v224, v223, v223
	s_nop 1
	v_add_f32_dpp v224, v224, v224 quad_perm:[1,0,3,2] row_mask:0xf bank_mask:0xf
	s_nop 1
	v_add_f32_dpp v224, v224, v224 quad_perm:[2,3,0,1] row_mask:0xf bank_mask:0xf
	v_sqrt_f32_e32 v224, v224
	s_nop 0
	v_max_f32_e32 v224, 0x2b8cbccc, v224
	v_rcp_f32_e32 v224, v224
	s_nop 0
	v_xor_b32_e32 v224, 0x80000000, v224
	v_mov_b32_e32 v225, v224
	v_cvt_pk_bf16_f32 v144, v192, v193
	v_cvt_pk_bf16_f32 v145, v194, v195
	v_cvt_pk_bf16_f32 v146, v196, v197
	v_cvt_pk_bf16_f32 v147, v198, v199
	v_cvt_pk_bf16_f32 v148, v200, v201
	v_cvt_pk_bf16_f32 v149, v202, v203
	v_cvt_pk_bf16_f32 v150, v204, v205
	v_cvt_pk_bf16_f32 v151, v206, v207
	v_pk_mul_f32 v[208:209], v[208:209], v[224:225]
	v_pk_mul_f32 v[210:211], v[210:211], v[224:225]
	v_pk_mul_f32 v[212:213], v[212:213], v[224:225]
	v_pk_mul_f32 v[214:215], v[214:215], v[224:225]
	v_pk_mul_f32 v[216:217], v[216:217], v[224:225]
	v_pk_mul_f32 v[218:219], v[218:219], v[224:225]
	v_pk_mul_f32 v[220:221], v[220:221], v[224:225]
	v_pk_mul_f32 v[222:223], v[222:223], v[224:225]
	buffer_store_dwordx4 v[208:211], v234, s[68:71], s72 offen offset:0
	buffer_store_dwordx4 v[212:215], v234, s[68:71], s72 offen offset:16
	buffer_store_dwordx4 v[216:219], v234, s[68:71], s72 offen offset:32
	buffer_store_dwordx4 v[220:223], v234, s[68:71], s72 offen offset:48
	buffer_store_dwordx4 v[144:147], v236, s[68:71], s73 offen offset:0
	buffer_store_dwordx4 v[148:151], v236, s[68:71], s73 offen offset:16
	s_add_u32 s72, s72, 0x1000
	s_add_u32 s73, s73, 0x800
	s_add_u32 s74, s74, 0x200
	s_add_u32 s75, s75, 0x40
	s_waitcnt vmcnt(46)
; __device__ __forceinline__ void prep_phase(const Params& p) {
;     ...
;             float mpk[16], mnk[16], kkc[16]; ld16f(p.mu_prev + 1024 + c, mpk); ld16f(p.mu_next + 1024 + c, mnk); ld16f(p.k_k + c, kkc);
;             const u16* zc = ZS + (size_t)t0 * 3328 + 1024 + c;
;             Z16 kp = tt0 > 0 ? ldz(zc - 3328) : zz(), kc = ldz(zc);
; #pragma unroll 2
;             for (int i = 0; i < 16; ++i) {
;                 const bool hn = (tt0 + i) < SEQ - 1; const Z16 kn = hn ? ldz(zc + (size_t)(i + 1) * 3328) : zz();
;                 float k[16], kk[16]; mix16(kp, kc, kn, mpk, mnk, k);
;                 float s2 = 0.f;
; #pragma unroll
;                 for (int q = 0; q < 16; ++q) { kk[q] = k[q] * kkc[q]; s2 += kk[q] * kk[q]; }
;                 s2 += __shfl_xor(s2, 1); s2 += __shfl_xor(s2, 2);
;                 const float inv = -1.0f / fmaxf(sqrtf(s2), 1e-12f);
;                 const size_t o = (size_t)(t0 + i) * RW + c;
; #pragma unroll
;                 for (int j4 = 0; j4 < 4; ++j4) *(f32x4*)(A + o + j4 * 4) = (f32x4){kk[j4 * 4] * inv, kk[j4 * 4 + 1] * inv, kk[j4 * 4 + 2] * inv, kk[j4 * 4 + 3] * inv};
;                 st16bf(Kb + o, k);
;                 kp = kc; kc = kn;
;             }
	v_lshlrev_b32_e32 v144, 16, v12
	v_and_b32_e32 v145, 0xffff0000, v12
	v_lshlrev_b32_e32 v146, 16, v13
	v_and_b32_e32 v147, 0xffff0000, v13
	v_lshlrev_b32_e32 v148, 16, v14
	v_and_b32_e32 v149, 0xffff0000, v14
	v_lshlrev_b32_e32 v150, 16, v15
	v_and_b32_e32 v151, 0xffff0000, v15
	v_lshlrev_b32_e32 v152, 16, v16
	v_and_b32_e32 v153, 0xffff0000, v16
	v_lshlrev_b32_e32 v154, 16, v17
	v_and_b32_e32 v155, 0xffff0000, v17
	v_lshlrev_b32_e32 v156, 16, v18
	v_and_b32_e32 v157, 0xffff0000, v18
	v_lshlrev_b32_e32 v158, 16, v19
	v_and_b32_e32 v159, 0xffff0000, v19
	v_lshlrev_b32_e32 v160, 16, v24
	v_and_b32_e32 v161, 0xffff0000, v24
	v_lshlrev_b32_e32 v162, 16, v25
	v_and_b32_e32 v163, 0xffff0000, v25
	v_lshlrev_b32_e32 v164, 16, v26
	v_and_b32_e32 v165, 0xffff0000, v26
	v_lshlrev_b32_e32 v166, 16, v27
	v_and_b32_e32 v167, 0xffff0000, v27
	v_lshlrev_b32_e32 v168, 16, v28
	v_and_b32_e32 v169, 0xffff0000, v28
	v_lshlrev_b32_e32 v170, 16, v29
	v_and_b32_e32 v171, 0xffff0000, v29
	v_lshlrev_b32_e32 v172, 16, v30
	v_and_b32_e32 v173, 0xffff0000, v30
	v_lshlrev_b32_e32 v174, 16, v31
	v_and_b32_e32 v175, 0xffff0000, v31
	v_lshlrev_b32_e32 v176, 16, v36
	v_and_b32_e32 v177, 0xffff0000, v36
	v_lshlrev_b32_e32 v178, 16, v37
	v_and_b32_e32 v179, 0xffff0000, v37
	v_lshlrev_b32_e32 v180, 16, v38
	v_and_b32_e32 v181, 0xffff0000, v38
	v_lshlrev_b32_e32 v182, 16, v39
	v_and_b32_e32 v183, 0xffff0000, v39
	v_lshlrev_b32_e32 v184, 16, v40
	v_and_b32_e32 v185, 0xffff0000, v40
	v_lshlrev_b32_e32 v186, 16, v41
	v_and_b32_e32 v187, 0xffff0000, v41
	v_lshlrev_b32_e32 v188, 16, v42
	v_and_b32_e32 v189, 0xffff0000, v42
	v_lshlrev_b32_e32 v190, 16, v43
	v_and_b32_e32 v191, 0xffff0000, v43
	buffer_load_dwordx4 v[12:15], v232, s[64:67], 0 offen offset:2048
	buffer_load_dwordx4 v[16:19], v232, s[64:67], 0 offen offset:2064
	v_add_u32_e32 v232, 6656, v232
	v_pk_add_f32 v[224:225], v[144:145], v[160:161] neg_lo:[0,1] neg_hi:[0,1]
	v_pk_add_f32 v[226:227], v[176:177], v[160:161] neg_lo:[0,1] neg_hi:[0,1]
	v_pk_fma_f32 v[192:193], v[96:97], v[224:225], v[160:161]
	v_pk_fma_f32 v[192:193], v[112:113], v[226:227], v[192:193]
	v_pk_add_f32 v[224:225], v[146:147], v[162:163] neg_lo:[0,1] neg_hi:[0,1]
	v_pk_add_f32 v[226:227], v[178:179], v[162:163] neg_lo:[0,1] neg_hi:[0,1]
	v_pk_fma_f32 v[194:195], v[98:99], v[224:225], v[162:163]
	v_pk_fma_f32 v[194:195], v[114:115], v[226:227], v[194:195]
	v_pk_add_f32 v[224:225], v[148:149], v[164:165] neg_lo:[0,1] neg_hi:[0,1]
	v_pk_add_f32 v[226:227], v[180:181], v[164:165] neg_lo:[0,1] neg_hi:[0,1]
	v_pk_fma_f32 v[196:197], v[100:101], v[224:225], v[164:165]
	v_pk_fma_f32 v[196:197], v[116:117], v[226:227], v[196:197]
	v_pk_add_f32 v[224:225], v[150:151], v[166:167] neg_lo:[0,1] neg_hi:[0,1]
	v_pk_add_f32 v[226:227], v[182:183], v[166:167] neg_lo:[0,1] neg_hi:[0,1]
	v_pk_fma_f32 v[198:199], v[102:103], v[224:225], v[166:167]
	v_pk_fma_f32 v[198:199], v[118:119], v[226:227], v[198:199]
	v_pk_add_f32 v[224:225], v[152:153], v[168:169] neg_lo:[0,1] neg_hi:[0,1]
	v_pk_add_f32 v[226:227], v[184:185], v[168:169] neg_lo:[0,1] neg_hi:[0,1]
	v_pk_fma_f32 v[200:201], v[104:105], v[224:225], v[168:169]
	v_pk_fma_f32 v[200:201], v[120:121], v[226:227], v[200:201]
	v_pk_add_f32 v[224:225], v[154:155], v[170:171] neg_lo:[0,1] neg_hi:[0,1]
	v_pk_add_f32 v[226:227], v[186:187], v[170:171] neg_lo:[0,1] neg_hi:[0,1]
	v_pk_fma_f32 v[202:203], v[106:107], v[224:225], v[170:171]
	v_pk_fma_f32 v[202:203], v[122:123], v[226:227], v[202:203]
	v_pk_add_f32 v[224:225], v[156:157], v[172:173] neg_lo:[0,1] neg_hi:[0,1]
	v_pk_add_f32 v[226:227], v[188:189], v[172:173] neg_lo:[0,1] neg_hi:[0,1]
	v_pk_fma_f32 v[204:205], v[108:109], v[224:225], v[172:173]
	v_pk_fma_f32 v[204:205], v[124:125], v[226:227], v[204:205]
	v_pk_add_f32 v[224:225], v[158:159], v[174:175] neg_lo:[0,1] neg_hi:[0,1]
	v_pk_add_f32 v[226:227], v[190:191], v[174:175] neg_lo:[0,1] neg_hi:[0,1]
	v_pk_fma_f32 v[206:207], v[110:111], v[224:225], v[174:175]
	v_pk_fma_f32 v[206:207], v[126:127], v[226:227], v[206:207]
	v_pk_mul_f32 v[208:209], v[192:193], v[128:129]
	v_pk_mul_f32 v[210:211], v[194:195], v[130:131]
	v_pk_mul_f32 v[212:213], v[196:197], v[132:133]
	v_pk_mul_f32 v[214:215], v[198:199], v[134:135]
	v_pk_mul_f32 v[216:217], v[200:201], v[136:137]
	v_pk_mul_f32 v[218:219], v[202:203], v[138:139]
	v_pk_mul_f32 v[220:221], v[204:205], v[140:141]
	v_pk_mul_f32 v[222:223], v[206:207], v[142:143]
	v_mul_f32_e32 v224, v208, v208
	v_fmac_f32_e32 v224, v209, v209
	v_fmac_f32_e32 v224, v210, v210
	v_fmac_f32_e32 v224, v211, v211
	v_fmac_f32_e32 v224, v212, v212
	v_fmac_f32_e32 v224, v213, v213
	v_fmac_f32_e32 v224, v214, v214
	v_fmac_f32_e32 v224, v215, v215
	v_fmac_f32_e32 v224, v216, v216
	v_fmac_f32_e32 v224, v217, v217
	v_fmac_f32_e32 v224, v218, v218
	v_fmac_f32_e32 v224, v219, v219
	v_fmac_f32_e32 v224, v220, v220
	v_fmac_f32_e32 v224, v221, v221
	v_fmac_f32_e32 v224, v222, v222
	v_fmac_f32_e32 v224, v223, v223
	s_nop 1
	v_add_f32_dpp v224, v224, v224 quad_perm:[1,0,3,2] row_mask:0xf bank_mask:0xf
	s_nop 1
	v_add_f32_dpp v224, v224, v224 quad_perm:[2,3,0,1] row_mask:0xf bank_mask:0xf
	v_sqrt_f32_e32 v224, v224
	s_nop 0
	v_max_f32_e32 v224, 0x2b8cbccc, v224
	v_rcp_f32_e32 v224, v224
	s_nop 0
	v_xor_b32_e32 v224, 0x80000000, v224
	v_mov_b32_e32 v225, v224
	v_cvt_pk_bf16_f32 v144, v192, v193
	v_cvt_pk_bf16_f32 v145, v194, v195
	v_cvt_pk_bf16_f32 v146, v196, v197
	v_cvt_pk_bf16_f32 v147, v198, v199
	v_cvt_pk_bf16_f32 v148, v200, v201
	v_cvt_pk_bf16_f32 v149, v202, v203
	v_cvt_pk_bf16_f32 v150, v204, v205
	v_cvt_pk_bf16_f32 v151, v206, v207
	v_pk_mul_f32 v[208:209], v[208:209], v[224:225]
	v_pk_mul_f32 v[210:211], v[210:211], v[224:225]
	v_pk_mul_f32 v[212:213], v[212:213], v[224:225]
	v_pk_mul_f32 v[214:215], v[214:215], v[224:225]
	v_pk_mul_f32 v[216:217], v[216:217], v[224:225]
	v_pk_mul_f32 v[218:219], v[218:219], v[224:225]
	v_pk_mul_f32 v[220:221], v[220:221], v[224:225]
	v_pk_mul_f32 v[222:223], v[222:223], v[224:225]
	buffer_store_dwordx4 v[208:211], v234, s[68:71], s72 offen offset:0
	buffer_store_dwordx4 v[212:215], v234, s[68:71], s72 offen offset:16
	buffer_store_dwordx4 v[216:219], v234, s[68:71], s72 offen offset:32
	buffer_store_dwordx4 v[220:223], v234, s[68:71], s72 offen offset:48
	buffer_store_dwordx4 v[144:147], v236, s[68:71], s73 offen offset:0
	buffer_store_dwordx4 v[148:151], v236, s[68:71], s73 offen offset:16
	s_add_u32 s72, s72, 0x1000
	s_add_u32 s73, s73, 0x800
	s_add_u32 s74, s74, 0x200
	s_add_u32 s75, s75, 0x40
	s_waitcnt vmcnt(46)
; __device__ __forceinline__ void mix16(const Z16& zp, const Z16& zc, const Z16& zn, const float* mp, const float* mn, float* o) {
;     float p_[16], c_[16], n_[16]; unz(zp, p_); unz(zc, c_); unz(zn, n_);
; #pragma unroll
;     for (int q = 0; q < 16; ++q) o[q] = c_[q] + mp[q] * (p_[q] - c_[q]) + mn[q] * (n_[q] - c_[q]);
; __device__ __forceinline__ void prep_phase(const Params& p) {
;     ...
;                 float k[16], kk[16]; mix16(kp, kc, kn, mpk, mnk, k);
;                 float s2 = 0.f;
; #pragma unroll
;                 for (int q = 0; q < 16; ++q) { kk[q] = k[q] * kkc[q]; s2 += kk[q] * kk[q]; }
;                 s2 += __shfl_xor(s2, 1); s2 += __shfl_xor(s2, 2);
;                 const float inv = -1.0f / fmaxf(sqrtf(s2), 1e-12f);
;                 const size_t o = (size_t)(t0 + i) * RW + c;
; #pragma unroll
;                 for (int j4 = 0; j4 < 4; ++j4) *(f32x4*)(A + o + j4 * 4) = (f32x4){kk[j4 * 4] * inv, kk[j4 * 4 + 1] * inv, kk[j4 * 4 + 2] * inv, kk[j4 * 4 + 3] * inv};
;                 st16bf(Kb + o, k);
;                 kp = kc; kc = kn;
	v_lshlrev_b32_e32 v144, 16, v24
	v_and_b32_e32 v145, 0xffff0000, v24
	v_lshlrev_b32_e32 v146, 16, v25
	v_and_b32_e32 v147, 0xffff0000, v25
	v_lshlrev_b32_e32 v148, 16, v26
	v_and_b32_e32 v149, 0xffff0000, v26
	v_lshlrev_b32_e32 v150, 16, v27
	v_and_b32_e32 v151, 0xffff0000, v27
	v_lshlrev_b32_e32 v152, 16, v28
	v_and_b32_e32 v153, 0xffff0000, v28
	v_lshlrev_b32_e32 v154, 16, v29
	v_and_b32_e32 v155, 0xffff0000, v29
	v_lshlrev_b32_e32 v156, 16, v30
	v_and_b32_e32 v157, 0xffff0000, v30
	v_lshlrev_b32_e32 v158, 16, v31
	v_and_b32_e32 v159, 0xffff0000, v31
	v_lshlrev_b32_e32 v160, 16, v36
	v_and_b32_e32 v161, 0xffff0000, v36
	v_lshlrev_b32_e32 v162, 16, v37
	v_and_b32_e32 v163, 0xffff0000, v37
	v_lshlrev_b32_e32 v164, 16, v38
	v_and_b32_e32 v165, 0xffff0000, v38
	v_lshlrev_b32_e32 v166, 16, v39
	v_and_b32_e32 v167, 0xffff0000, v39
	v_lshlrev_b32_e32 v168, 16, v40
	v_and_b32_e32 v169, 0xffff0000, v40
	v_lshlrev_b32_e32 v170, 16, v41
	v_and_b32_e32 v171, 0xffff0000, v41
	v_lshlrev_b32_e32 v172, 16, v42
	v_and_b32_e32 v173, 0xffff0000, v42
	v_lshlrev_b32_e32 v174, 16, v43
	v_and_b32_e32 v175, 0xffff0000, v43
	v_lshlrev_b32_e32 v176, 16, v48
	v_and_b32_e32 v177, 0xffff0000, v48
	v_lshlrev_b32_e32 v178, 16, v49
	v_and_b32_e32 v179, 0xffff0000, v49
	v_lshlrev_b32_e32 v180, 16, v50
	v_and_b32_e32 v181, 0xffff0000, v50
	v_lshlrev_b32_e32 v182, 16, v51
	v_and_b32_e32 v183, 0xffff0000, v51
	v_lshlrev_b32_e32 v184, 16, v52
	v_and_b32_e32 v185, 0xffff0000, v52
	v_lshlrev_b32_e32 v186, 16, v53
	v_and_b32_e32 v187, 0xffff0000, v53
	v_lshlrev_b32_e32 v188, 16, v54
	v_and_b32_e32 v189, 0xffff0000, v54
	v_lshlrev_b32_e32 v190, 16, v55
	v_and_b32_e32 v191, 0xffff0000, v55
	v_pk_add_f32 v[224:225], v[144:145], v[160:161] neg_lo:[0,1] neg_hi:[0,1]
	v_pk_add_f32 v[226:227], v[176:177], v[160:161] neg_lo:[0,1] neg_hi:[0,1]
	v_pk_fma_f32 v[192:193], v[96:97], v[224:225], v[160:161]
	v_pk_fma_f32 v[192:193], v[112:113], v[226:227], v[192:193]
	v_pk_add_f32 v[224:225], v[146:147], v[162:163] neg_lo:[0,1] neg_hi:[0,1]
	v_pk_add_f32 v[226:227], v[178:179], v[162:163] neg_lo:[0,1] neg_hi:[0,1]
	v_pk_fma_f32 v[194:195], v[98:99], v[224:225], v[162:163]
	v_pk_fma_f32 v[194:195], v[114:115], v[226:227], v[194:195]
	v_pk_add_f32 v[224:225], v[148:149], v[164:165] neg_lo:[0,1] neg_hi:[0,1]
	v_pk_add_f32 v[226:227], v[180:181], v[164:165] neg_lo:[0,1] neg_hi:[0,1]
	v_pk_fma_f32 v[196:197], v[100:101], v[224:225], v[164:165]
	v_pk_fma_f32 v[196:197], v[116:117], v[226:227], v[196:197]
	v_pk_add_f32 v[224:225], v[150:151], v[166:167] neg_lo:[0,1] neg_hi:[0,1]
	v_pk_add_f32 v[226:227], v[182:183], v[166:167] neg_lo:[0,1] neg_hi:[0,1]
	v_pk_fma_f32 v[198:199], v[102:103], v[224:225], v[166:167]
	v_pk_fma_f32 v[198:199], v[118:119], v[226:227], v[198:199]
	v_pk_add_f32 v[224:225], v[152:153], v[168:169] neg_lo:[0,1] neg_hi:[0,1]
	v_pk_add_f32 v[226:227], v[184:185], v[168:169] neg_lo:[0,1] neg_hi:[0,1]
	v_pk_fma_f32 v[200:201], v[104:105], v[224:225], v[168:169]
	v_pk_fma_f32 v[200:201], v[120:121], v[226:227], v[200:201]
	v_pk_add_f32 v[224:225], v[154:155], v[170:171] neg_lo:[0,1] neg_hi:[0,1]
	v_pk_add_f32 v[226:227], v[186:187], v[170:171] neg_lo:[0,1] neg_hi:[0,1]
	v_pk_fma_f32 v[202:203], v[106:107], v[224:225], v[170:171]
	v_pk_fma_f32 v[202:203], v[122:123], v[226:227], v[202:203]
	v_pk_add_f32 v[224:225], v[156:157], v[172:173] neg_lo:[0,1] neg_hi:[0,1]
	v_pk_add_f32 v[226:227], v[188:189], v[172:173] neg_lo:[0,1] neg_hi:[0,1]
	v_pk_fma_f32 v[204:205], v[108:109], v[224:225], v[172:173]
	v_pk_fma_f32 v[204:205], v[124:125], v[226:227], v[204:205]
	v_pk_add_f32 v[224:225], v[158:159], v[174:175] neg_lo:[0,1] neg_hi:[0,1]
	v_pk_add_f32 v[226:227], v[190:191], v[174:175] neg_lo:[0,1] neg_hi:[0,1]
	v_pk_fma_f32 v[206:207], v[110:111], v[224:225], v[174:175]
	v_pk_fma_f32 v[206:207], v[126:127], v[226:227], v[206:207]
	v_pk_mul_f32 v[208:209], v[192:193], v[128:129]
	v_pk_mul_f32 v[210:211], v[194:195], v[130:131]
	v_pk_mul_f32 v[212:213], v[196:197], v[132:133]
	v_pk_mul_f32 v[214:215], v[198:199], v[134:135]
	v_pk_mul_f32 v[216:217], v[200:201], v[136:137]
	v_pk_mul_f32 v[218:219], v[202:203], v[138:139]
	v_pk_mul_f32 v[220:221], v[204:205], v[140:141]
	v_pk_mul_f32 v[222:223], v[206:207], v[142:143]
	v_mul_f32_e32 v224, v208, v208
	v_fmac_f32_e32 v224, v209, v209
	v_fmac_f32_e32 v224, v210, v210
	v_fmac_f32_e32 v224, v211, v211
	v_fmac_f32_e32 v224, v212, v212
	v_fmac_f32_e32 v224, v213, v213
	v_fmac_f32_e32 v224, v214, v214
	v_fmac_f32_e32 v224, v215, v215
	v_fmac_f32_e32 v224, v216, v216
	v_fmac_f32_e32 v224, v217, v217
	v_fmac_f32_e32 v224, v218, v218
	v_fmac_f32_e32 v224, v219, v219
	v_fmac_f32_e32 v224, v220, v220
	v_fmac_f32_e32 v224, v221, v221
	v_fmac_f32_e32 v224, v222, v222
	v_fmac_f32_e32 v224, v223, v223
	s_nop 1
	v_add_f32_dpp v224, v224, v224 quad_perm:[1,0,3,2] row_mask:0xf bank_mask:0xf
	s_nop 1
	v_add_f32_dpp v224, v224, v224 quad_perm:[2,3,0,1] row_mask:0xf bank_mask:0xf
	v_sqrt_f32_e32 v224, v224
	s_nop 0
	v_max_f32_e32 v224, 0x2b8cbccc, v224
	v_rcp_f32_e32 v224, v224
	s_nop 0
	v_xor_b32_e32 v224, 0x80000000, v224
	v_mov_b32_e32 v225, v224
	v_cvt_pk_bf16_f32 v144, v192, v193
	v_cvt_pk_bf16_f32 v145, v194, v195
	v_cvt_pk_bf16_f32 v146, v196, v197
	v_cvt_pk_bf16_f32 v147, v198, v199
	v_cvt_pk_bf16_f32 v148, v200, v201
	v_cvt_pk_bf16_f32 v149, v202, v203
	v_cvt_pk_bf16_f32 v150, v204, v205
	v_cvt_pk_bf16_f32 v151, v206, v207
	v_pk_mul_f32 v[208:209], v[208:209], v[224:225]
	v_pk_mul_f32 v[210:211], v[210:211], v[224:225]
	v_pk_mul_f32 v[212:213], v[212:213], v[224:225]
	v_pk_mul_f32 v[214:215], v[214:215], v[224:225]
	v_pk_mul_f32 v[216:217], v[216:217], v[224:225]
	v_pk_mul_f32 v[218:219], v[218:219], v[224:225]
	v_pk_mul_f32 v[220:221], v[220:221], v[224:225]
	v_pk_mul_f32 v[222:223], v[222:223], v[224:225]
	buffer_store_dwordx4 v[208:211], v234, s[68:71], s72 offen offset:0
	buffer_store_dwordx4 v[212:215], v234, s[68:71], s72 offen offset:16
	buffer_store_dwordx4 v[216:219], v234, s[68:71], s72 offen offset:32
	buffer_store_dwordx4 v[220:223], v234, s[68:71], s72 offen offset:48
	buffer_store_dwordx4 v[144:147], v236, s[68:71], s73 offen offset:0
	buffer_store_dwordx4 v[148:151], v236, s[68:71], s73 offen offset:16
	s_add_u32 s72, s72, 0x1000
	s_add_u32 s73, s73, 0x800
	s_add_u32 s74, s74, 0x200
	s_add_u32 s75, s75, 0x40
	s_waitcnt vmcnt(44)
; __device__ __forceinline__ void mix16(const Z16& zp, const Z16& zc, const Z16& zn, const float* mp, const float* mn, float* o) {
;     float p_[16], c_[16], n_[16]; unz(zp, p_); unz(zc, c_); unz(zn, n_);
; #pragma unroll
;     for (int q = 0; q < 16; ++q) o[q] = c_[q] + mp[q] * (p_[q] - c_[q]) + mn[q] * (n_[q] - c_[q]);
; __device__ __forceinline__ void prep_phase(const Params& p) {
;     ...
;                 float k[16], kk[16]; mix16(kp, kc, kn, mpk, mnk, k);
;                 float s2 = 0.f;
; #pragma unroll
;                 for (int q = 0; q < 16; ++q) { kk[q] = k[q] * kkc[q]; s2 += kk[q] * kk[q]; }
;                 s2 += __shfl_xor(s2, 1); s2 += __shfl_xor(s2, 2);
;                 const float inv = -1.0f / fmaxf(sqrtf(s2), 1e-12f);
;                 const size_t o = (size_t)(t0 + i) * RW + c;
; #pragma unroll
;                 for (int j4 = 0; j4 < 4; ++j4) *(f32x4*)(A + o + j4 * 4) = (f32x4){kk[j4 * 4] * inv, kk[j4 * 4 + 1] * inv, kk[j4 * 4 + 2] * inv, kk[j4 * 4 + 3] * inv};
;                 st16bf(Kb + o, k);
;                 kp = kc; kc = kn;
	v_lshlrev_b32_e32 v144, 16, v36
	v_and_b32_e32 v145, 0xffff0000, v36
	v_lshlrev_b32_e32 v146, 16, v37
	v_and_b32_e32 v147, 0xffff0000, v37
	v_lshlrev_b32_e32 v148, 16, v38
	v_and_b32_e32 v149, 0xffff0000, v38
	v_lshlrev_b32_e32 v150, 16, v39
	v_and_b32_e32 v151, 0xffff0000, v39
	v_lshlrev_b32_e32 v152, 16, v40
	v_and_b32_e32 v153, 0xffff0000, v40
	v_lshlrev_b32_e32 v154, 16, v41
	v_and_b32_e32 v155, 0xffff0000, v41
	v_lshlrev_b32_e32 v156, 16, v42
	v_and_b32_e32 v157, 0xffff0000, v42
	v_lshlrev_b32_e32 v158, 16, v43
	v_and_b32_e32 v159, 0xffff0000, v43
	v_lshlrev_b32_e32 v160, 16, v48
	v_and_b32_e32 v161, 0xffff0000, v48
	v_lshlrev_b32_e32 v162, 16, v49
	v_and_b32_e32 v163, 0xffff0000, v49
	v_lshlrev_b32_e32 v164, 16, v50
	v_and_b32_e32 v165, 0xffff0000, v50
	v_lshlrev_b32_e32 v166, 16, v51
	v_and_b32_e32 v167, 0xffff0000, v51
	v_lshlrev_b32_e32 v168, 16, v52
	v_and_b32_e32 v169, 0xffff0000, v52
	v_lshlrev_b32_e32 v170, 16, v53
	v_and_b32_e32 v171, 0xffff0000, v53
	v_lshlrev_b32_e32 v172, 16, v54
	v_and_b32_e32 v173, 0xffff0000, v54
	v_lshlrev_b32_e32 v174, 16, v55
	v_and_b32_e32 v175, 0xffff0000, v55
	v_lshlrev_b32_e32 v176, 16, v60
	v_and_b32_e32 v177, 0xffff0000, v60
	v_lshlrev_b32_e32 v178, 16, v61
	v_and_b32_e32 v179, 0xffff0000, v61
	v_lshlrev_b32_e32 v180, 16, v62
	v_and_b32_e32 v181, 0xffff0000, v62
	v_lshlrev_b32_e32 v182, 16, v63
	v_and_b32_e32 v183, 0xffff0000, v63
	v_lshlrev_b32_e32 v184, 16, v64
	v_and_b32_e32 v185, 0xffff0000, v64
	v_lshlrev_b32_e32 v186, 16, v65
	v_and_b32_e32 v187, 0xffff0000, v65
	v_lshlrev_b32_e32 v188, 16, v66
	v_and_b32_e32 v189, 0xffff0000, v66
	v_lshlrev_b32_e32 v190, 16, v67
	v_and_b32_e32 v191, 0xffff0000, v67
	v_pk_add_f32 v[224:225], v[144:145], v[160:161] neg_lo:[0,1] neg_hi:[0,1]
	v_pk_add_f32 v[226:227], v[176:177], v[160:161] neg_lo:[0,1] neg_hi:[0,1]
	v_pk_fma_f32 v[192:193], v[96:97], v[224:225], v[160:161]
	v_pk_fma_f32 v[192:193], v[112:113], v[226:227], v[192:193]
	v_pk_add_f32 v[224:225], v[146:147], v[162:163] neg_lo:[0,1] neg_hi:[0,1]
	v_pk_add_f32 v[226:227], v[178:179], v[162:163] neg_lo:[0,1] neg_hi:[0,1]
	v_pk_fma_f32 v[194:195], v[98:99], v[224:225], v[162:163]
	v_pk_fma_f32 v[194:195], v[114:115], v[226:227], v[194:195]
	v_pk_add_f32 v[224:225], v[148:149], v[164:165] neg_lo:[0,1] neg_hi:[0,1]
	v_pk_add_f32 v[226:227], v[180:181], v[164:165] neg_lo:[0,1] neg_hi:[0,1]
	v_pk_fma_f32 v[196:197], v[100:101], v[224:225], v[164:165]
	v_pk_fma_f32 v[196:197], v[116:117], v[226:227], v[196:197]
	v_pk_add_f32 v[224:225], v[150:151], v[166:167] neg_lo:[0,1] neg_hi:[0,1]
	v_pk_add_f32 v[226:227], v[182:183], v[166:167] neg_lo:[0,1] neg_hi:[0,1]
	v_pk_fma_f32 v[198:199], v[102:103], v[224:225], v[166:167]
	v_pk_fma_f32 v[198:199], v[118:119], v[226:227], v[198:199]
	v_pk_add_f32 v[224:225], v[152:153], v[168:169] neg_lo:[0,1] neg_hi:[0,1]
	v_pk_add_f32 v[226:227], v[184:185], v[168:169] neg_lo:[0,1] neg_hi:[0,1]
	v_pk_fma_f32 v[200:201], v[104:105], v[224:225], v[168:169]
	v_pk_fma_f32 v[200:201], v[120:121], v[226:227], v[200:201]
	v_pk_add_f32 v[224:225], v[154:155], v[170:171] neg_lo:[0,1] neg_hi:[0,1]
	v_pk_add_f32 v[226:227], v[186:187], v[170:171] neg_lo:[0,1] neg_hi:[0,1]
	v_pk_fma_f32 v[202:203], v[106:107], v[224:225], v[170:171]
	v_pk_fma_f32 v[202:203], v[122:123], v[226:227], v[202:203]
	v_pk_add_f32 v[224:225], v[156:157], v[172:173] neg_lo:[0,1] neg_hi:[0,1]
	v_pk_add_f32 v[226:227], v[188:189], v[172:173] neg_lo:[0,1] neg_hi:[0,1]
	v_pk_fma_f32 v[204:205], v[108:109], v[224:225], v[172:173]
	v_pk_fma_f32 v[204:205], v[124:125], v[226:227], v[204:205]
	v_pk_add_f32 v[224:225], v[158:159], v[174:175] neg_lo:[0,1] neg_hi:[0,1]
	v_pk_add_f32 v[226:227], v[190:191], v[174:175] neg_lo:[0,1] neg_hi:[0,1]
	v_pk_fma_f32 v[206:207], v[110:111], v[224:225], v[174:175]
	v_pk_fma_f32 v[206:207], v[126:127], v[226:227], v[206:207]
	v_pk_mul_f32 v[208:209], v[192:193], v[128:129]
	v_pk_mul_f32 v[210:211], v[194:195], v[130:131]
	v_pk_mul_f32 v[212:213], v[196:197], v[132:133]
	v_pk_mul_f32 v[214:215], v[198:199], v[134:135]
	v_pk_mul_f32 v[216:217], v[200:201], v[136:137]
	v_pk_mul_f32 v[218:219], v[202:203], v[138:139]
	v_pk_mul_f32 v[220:221], v[204:205], v[140:141]
	v_pk_mul_f32 v[222:223], v[206:207], v[142:143]
	v_mul_f32_e32 v224, v208, v208
	v_fmac_f32_e32 v224, v209, v209
	v_fmac_f32_e32 v224, v210, v210
	v_fmac_f32_e32 v224, v211, v211
	v_fmac_f32_e32 v224, v212, v212
	v_fmac_f32_e32 v224, v213, v213
	v_fmac_f32_e32 v224, v214, v214
	v_fmac_f32_e32 v224, v215, v215
	v_fmac_f32_e32 v224, v216, v216
	v_fmac_f32_e32 v224, v217, v217
	v_fmac_f32_e32 v224, v218, v218
	v_fmac_f32_e32 v224, v219, v219
	v_fmac_f32_e32 v224, v220, v220
	v_fmac_f32_e32 v224, v221, v221
	v_fmac_f32_e32 v224, v222, v222
	v_fmac_f32_e32 v224, v223, v223
	s_nop 1
	v_add_f32_dpp v224, v224, v224 quad_perm:[1,0,3,2] row_mask:0xf bank_mask:0xf
	s_nop 1
	v_add_f32_dpp v224, v224, v224 quad_perm:[2,3,0,1] row_mask:0xf bank_mask:0xf
	v_sqrt_f32_e32 v224, v224
	s_nop 0
	v_max_f32_e32 v224, 0x2b8cbccc, v224
	v_rcp_f32_e32 v224, v224
	s_nop 0
	v_xor_b32_e32 v224, 0x80000000, v224
	v_mov_b32_e32 v225, v224
	v_cvt_pk_bf16_f32 v144, v192, v193
	v_cvt_pk_bf16_f32 v145, v194, v195
	v_cvt_pk_bf16_f32 v146, v196, v197
	v_cvt_pk_bf16_f32 v147, v198, v199
	v_cvt_pk_bf16_f32 v148, v200, v201
	v_cvt_pk_bf16_f32 v149, v202, v203
	v_cvt_pk_bf16_f32 v150, v204, v205
	v_cvt_pk_bf16_f32 v151, v206, v207
	v_pk_mul_f32 v[208:209], v[208:209], v[224:225]
	v_pk_mul_f32 v[210:211], v[210:211], v[224:225]
	v_pk_mul_f32 v[212:213], v[212:213], v[224:225]
	v_pk_mul_f32 v[214:215], v[214:215], v[224:225]
	v_pk_mul_f32 v[216:217], v[216:217], v[224:225]
	v_pk_mul_f32 v[218:219], v[218:219], v[224:225]
	v_pk_mul_f32 v[220:221], v[220:221], v[224:225]
	v_pk_mul_f32 v[222:223], v[222:223], v[224:225]
	buffer_store_dwordx4 v[208:211], v234, s[68:71], s72 offen offset:0
	buffer_store_dwordx4 v[212:215], v234, s[68:71], s72 offen offset:16
	buffer_store_dwordx4 v[216:219], v234, s[68:71], s72 offen offset:32
	buffer_store_dwordx4 v[220:223], v234, s[68:71], s72 offen offset:48
	buffer_store_dwordx4 v[144:147], v236, s[68:71], s73 offen offset:0
	buffer_store_dwordx4 v[148:151], v236, s[68:71], s73 offen offset:16
	s_add_u32 s72, s72, 0x1000
	s_add_u32 s73, s73, 0x800
	s_add_u32 s74, s74, 0x200
	s_add_u32 s75, s75, 0x40
	s_waitcnt vmcnt(42)
; __device__ __forceinline__ void mix16(const Z16& zp, const Z16& zc, const Z16& zn, const float* mp, const float* mn, float* o) {
;     float p_[16], c_[16], n_[16]; unz(zp, p_); unz(zc, c_); unz(zn, n_);
; #pragma unroll
;     for (int q = 0; q < 16; ++q) o[q] = c_[q] + mp[q] * (p_[q] - c_[q]) + mn[q] * (n_[q] - c_[q]);
; __device__ __forceinline__ void prep_phase(const Params& p) {
;     ...
;                 float k[16], kk[16]; mix16(kp, kc, kn, mpk, mnk, k);
;                 float s2 = 0.f;
; #pragma unroll
;                 for (int q = 0; q < 16; ++q) { kk[q] = k[q] * kkc[q]; s2 += kk[q] * kk[q]; }
;                 s2 += __shfl_xor(s2, 1); s2 += __shfl_xor(s2, 2);
;                 const float inv = -1.0f / fmaxf(sqrtf(s2), 1e-12f);
;                 const size_t o = (size_t)(t0 + i) * RW + c;
; #pragma unroll
;                 for (int j4 = 0; j4 < 4; ++j4) *(f32x4*)(A + o + j4 * 4) = (f32x4){kk[j4 * 4] * inv, kk[j4 * 4 + 1] * inv, kk[j4 * 4 + 2] * inv, kk[j4 * 4 + 3] * inv};
;                 st16bf(Kb + o, k);
;                 kp = kc; kc = kn;
	v_lshlrev_b32_e32 v144, 16, v48
	v_and_b32_e32 v145, 0xffff0000, v48
	v_lshlrev_b32_e32 v146, 16, v49
	v_and_b32_e32 v147, 0xffff0000, v49
	v_lshlrev_b32_e32 v148, 16, v50
	v_and_b32_e32 v149, 0xffff0000, v50
	v_lshlrev_b32_e32 v150, 16, v51
	v_and_b32_e32 v151, 0xffff0000, v51
	v_lshlrev_b32_e32 v152, 16, v52
	v_and_b32_e32 v153, 0xffff0000, v52
	v_lshlrev_b32_e32 v154, 16, v53
	v_and_b32_e32 v155, 0xffff0000, v53
	v_lshlrev_b32_e32 v156, 16, v54
	v_and_b32_e32 v157, 0xffff0000, v54
	v_lshlrev_b32_e32 v158, 16, v55
	v_and_b32_e32 v159, 0xffff0000, v55
	v_lshlrev_b32_e32 v160, 16, v60
	v_and_b32_e32 v161, 0xffff0000, v60
	v_lshlrev_b32_e32 v162, 16, v61
	v_and_b32_e32 v163, 0xffff0000, v61
	v_lshlrev_b32_e32 v164, 16, v62
	v_and_b32_e32 v165, 0xffff0000, v62
	v_lshlrev_b32_e32 v166, 16, v63
	v_and_b32_e32 v167, 0xffff0000, v63
	v_lshlrev_b32_e32 v168, 16, v64
	v_and_b32_e32 v169, 0xffff0000, v64
	v_lshlrev_b32_e32 v170, 16, v65
	v_and_b32_e32 v171, 0xffff0000, v65
	v_lshlrev_b32_e32 v172, 16, v66
	v_and_b32_e32 v173, 0xffff0000, v66
	v_lshlrev_b32_e32 v174, 16, v67
	v_and_b32_e32 v175, 0xffff0000, v67
	v_lshlrev_b32_e32 v176, 16, v72
	v_and_b32_e32 v177, 0xffff0000, v72
	v_lshlrev_b32_e32 v178, 16, v73
	v_and_b32_e32 v179, 0xffff0000, v73
	v_lshlrev_b32_e32 v180, 16, v74
	v_and_b32_e32 v181, 0xffff0000, v74
	v_lshlrev_b32_e32 v182, 16, v75
	v_and_b32_e32 v183, 0xffff0000, v75
	v_lshlrev_b32_e32 v184, 16, v76
	v_and_b32_e32 v185, 0xffff0000, v76
	v_lshlrev_b32_e32 v186, 16, v77
	v_and_b32_e32 v187, 0xffff0000, v77
	v_lshlrev_b32_e32 v188, 16, v78
	v_and_b32_e32 v189, 0xffff0000, v78
	v_lshlrev_b32_e32 v190, 16, v79
	v_and_b32_e32 v191, 0xffff0000, v79
	v_pk_add_f32 v[224:225], v[144:145], v[160:161] neg_lo:[0,1] neg_hi:[0,1]
	v_pk_add_f32 v[226:227], v[176:177], v[160:161] neg_lo:[0,1] neg_hi:[0,1]
	v_pk_fma_f32 v[192:193], v[96:97], v[224:225], v[160:161]
	v_pk_fma_f32 v[192:193], v[112:113], v[226:227], v[192:193]
	v_pk_add_f32 v[224:225], v[146:147], v[162:163] neg_lo:[0,1] neg_hi:[0,1]
	v_pk_add_f32 v[226:227], v[178:179], v[162:163] neg_lo:[0,1] neg_hi:[0,1]
	v_pk_fma_f32 v[194:195], v[98:99], v[224:225], v[162:163]
	v_pk_fma_f32 v[194:195], v[114:115], v[226:227], v[194:195]
	v_pk_add_f32 v[224:225], v[148:149], v[164:165] neg_lo:[0,1] neg_hi:[0,1]
	v_pk_add_f32 v[226:227], v[180:181], v[164:165] neg_lo:[0,1] neg_hi:[0,1]
	v_pk_fma_f32 v[196:197], v[100:101], v[224:225], v[164:165]
	v_pk_fma_f32 v[196:197], v[116:117], v[226:227], v[196:197]
	v_pk_add_f32 v[224:225], v[150:151], v[166:167] neg_lo:[0,1] neg_hi:[0,1]
	v_pk_add_f32 v[226:227], v[182:183], v[166:167] neg_lo:[0,1] neg_hi:[0,1]
	v_pk_fma_f32 v[198:199], v[102:103], v[224:225], v[166:167]
	v_pk_fma_f32 v[198:199], v[118:119], v[226:227], v[198:199]
	v_pk_add_f32 v[224:225], v[152:153], v[168:169] neg_lo:[0,1] neg_hi:[0,1]
	v_pk_add_f32 v[226:227], v[184:185], v[168:169] neg_lo:[0,1] neg_hi:[0,1]
	v_pk_fma_f32 v[200:201], v[104:105], v[224:225], v[168:169]
	v_pk_fma_f32 v[200:201], v[120:121], v[226:227], v[200:201]
	v_pk_add_f32 v[224:225], v[154:155], v[170:171] neg_lo:[0,1] neg_hi:[0,1]
	v_pk_add_f32 v[226:227], v[186:187], v[170:171] neg_lo:[0,1] neg_hi:[0,1]
	v_pk_fma_f32 v[202:203], v[106:107], v[224:225], v[170:171]
	v_pk_fma_f32 v[202:203], v[122:123], v[226:227], v[202:203]
	v_pk_add_f32 v[224:225], v[156:157], v[172:173] neg_lo:[0,1] neg_hi:[0,1]
	v_pk_add_f32 v[226:227], v[188:189], v[172:173] neg_lo:[0,1] neg_hi:[0,1]
	v_pk_fma_f32 v[204:205], v[108:109], v[224:225], v[172:173]
	v_pk_fma_f32 v[204:205], v[124:125], v[226:227], v[204:205]
	v_pk_add_f32 v[224:225], v[158:159], v[174:175] neg_lo:[0,1] neg_hi:[0,1]
	v_pk_add_f32 v[226:227], v[190:191], v[174:175] neg_lo:[0,1] neg_hi:[0,1]
	v_pk_fma_f32 v[206:207], v[110:111], v[224:225], v[174:175]
	v_pk_fma_f32 v[206:207], v[126:127], v[226:227], v[206:207]
	v_pk_mul_f32 v[208:209], v[192:193], v[128:129]
	v_pk_mul_f32 v[210:211], v[194:195], v[130:131]
	v_pk_mul_f32 v[212:213], v[196:197], v[132:133]
	v_pk_mul_f32 v[214:215], v[198:199], v[134:135]
	v_pk_mul_f32 v[216:217], v[200:201], v[136:137]
	v_pk_mul_f32 v[218:219], v[202:203], v[138:139]
	v_pk_mul_f32 v[220:221], v[204:205], v[140:141]
	v_pk_mul_f32 v[222:223], v[206:207], v[142:143]
	v_mul_f32_e32 v224, v208, v208
	v_fmac_f32_e32 v224, v209, v209
	v_fmac_f32_e32 v224, v210, v210
	v_fmac_f32_e32 v224, v211, v211
	v_fmac_f32_e32 v224, v212, v212
	v_fmac_f32_e32 v224, v213, v213
	v_fmac_f32_e32 v224, v214, v214
	v_fmac_f32_e32 v224, v215, v215
	v_fmac_f32_e32 v224, v216, v216
	v_fmac_f32_e32 v224, v217, v217
	v_fmac_f32_e32 v224, v218, v218
	v_fmac_f32_e32 v224, v219, v219
	v_fmac_f32_e32 v224, v220, v220
	v_fmac_f32_e32 v224, v221, v221
	v_fmac_f32_e32 v224, v222, v222
	v_fmac_f32_e32 v224, v223, v223
	s_nop 1
	v_add_f32_dpp v224, v224, v224 quad_perm:[1,0,3,2] row_mask:0xf bank_mask:0xf
	s_nop 1
	v_add_f32_dpp v224, v224, v224 quad_perm:[2,3,0,1] row_mask:0xf bank_mask:0xf
	v_sqrt_f32_e32 v224, v224
	s_nop 0
	v_max_f32_e32 v224, 0x2b8cbccc, v224
	v_rcp_f32_e32 v224, v224
	s_nop 0
	v_xor_b32_e32 v224, 0x80000000, v224
	v_mov_b32_e32 v225, v224
	v_cvt_pk_bf16_f32 v144, v192, v193
	v_cvt_pk_bf16_f32 v145, v194, v195
	v_cvt_pk_bf16_f32 v146, v196, v197
	v_cvt_pk_bf16_f32 v147, v198, v199
	v_cvt_pk_bf16_f32 v148, v200, v201
	v_cvt_pk_bf16_f32 v149, v202, v203
	v_cvt_pk_bf16_f32 v150, v204, v205
	v_cvt_pk_bf16_f32 v151, v206, v207
	v_pk_mul_f32 v[208:209], v[208:209], v[224:225]
	v_pk_mul_f32 v[210:211], v[210:211], v[224:225]
	v_pk_mul_f32 v[212:213], v[212:213], v[224:225]
	v_pk_mul_f32 v[214:215], v[214:215], v[224:225]
	v_pk_mul_f32 v[216:217], v[216:217], v[224:225]
	v_pk_mul_f32 v[218:219], v[218:219], v[224:225]
	v_pk_mul_f32 v[220:221], v[220:221], v[224:225]
	v_pk_mul_f32 v[222:223], v[222:223], v[224:225]
	buffer_store_dwordx4 v[208:211], v234, s[68:71], s72 offen offset:0
	buffer_store_dwordx4 v[212:215], v234, s[68:71], s72 offen offset:16
	buffer_store_dwordx4 v[216:219], v234, s[68:71], s72 offen offset:32
	buffer_store_dwordx4 v[220:223], v234, s[68:71], s72 offen offset:48
	buffer_store_dwordx4 v[144:147], v236, s[68:71], s73 offen offset:0
	buffer_store_dwordx4 v[148:151], v236, s[68:71], s73 offen offset:16
	s_add_u32 s72, s72, 0x1000
	s_add_u32 s73, s73, 0x800
	s_add_u32 s74, s74, 0x200
	s_add_u32 s75, s75, 0x40
	s_waitcnt vmcnt(40)
; __device__ __forceinline__ void mix16(const Z16& zp, const Z16& zc, const Z16& zn, const float* mp, const float* mn, float* o) {
;     float p_[16], c_[16], n_[16]; unz(zp, p_); unz(zc, c_); unz(zn, n_);
; #pragma unroll
;     for (int q = 0; q < 16; ++q) o[q] = c_[q] + mp[q] * (p_[q] - c_[q]) + mn[q] * (n_[q] - c_[q]);
; __device__ __forceinline__ void prep_phase(const Params& p) {
;     ...
;                 float k[16], kk[16]; mix16(kp, kc, kn, mpk, mnk, k);
;                 float s2 = 0.f;
; #pragma unroll
;                 for (int q = 0; q < 16; ++q) { kk[q] = k[q] * kkc[q]; s2 += kk[q] * kk[q]; }
;                 s2 += __shfl_xor(s2, 1); s2 += __shfl_xor(s2, 2);
;                 const float inv = -1.0f / fmaxf(sqrtf(s2), 1e-12f);
;                 const size_t o = (size_t)(t0 + i) * RW + c;
; #pragma unroll
;                 for (int j4 = 0; j4 < 4; ++j4) *(f32x4*)(A + o + j4 * 4) = (f32x4){kk[j4 * 4] * inv, kk[j4 * 4 + 1] * inv, kk[j4 * 4 + 2] * inv, kk[j4 * 4 + 3] * inv};
;                 st16bf(Kb + o, k);
;                 kp = kc; kc = kn;
	v_lshlrev_b32_e32 v144, 16, v60
	v_and_b32_e32 v145, 0xffff0000, v60
	v_lshlrev_b32_e32 v146, 16, v61
	v_and_b32_e32 v147, 0xffff0000, v61
	v_lshlrev_b32_e32 v148, 16, v62
	v_and_b32_e32 v149, 0xffff0000, v62
	v_lshlrev_b32_e32 v150, 16, v63
	v_and_b32_e32 v151, 0xffff0000, v63
	v_lshlrev_b32_e32 v152, 16, v64
	v_and_b32_e32 v153, 0xffff0000, v64
	v_lshlrev_b32_e32 v154, 16, v65
	v_and_b32_e32 v155, 0xffff0000, v65
	v_lshlrev_b32_e32 v156, 16, v66
	v_and_b32_e32 v157, 0xffff0000, v66
	v_lshlrev_b32_e32 v158, 16, v67
	v_and_b32_e32 v159, 0xffff0000, v67
	v_lshlrev_b32_e32 v160, 16, v72
	v_and_b32_e32 v161, 0xffff0000, v72
	v_lshlrev_b32_e32 v162, 16, v73
	v_and_b32_e32 v163, 0xffff0000, v73
	v_lshlrev_b32_e32 v164, 16, v74
	v_and_b32_e32 v165, 0xffff0000, v74
	v_lshlrev_b32_e32 v166, 16, v75
	v_and_b32_e32 v167, 0xffff0000, v75
	v_lshlrev_b32_e32 v168, 16, v76
	v_and_b32_e32 v169, 0xffff0000, v76
	v_lshlrev_b32_e32 v170, 16, v77
	v_and_b32_e32 v171, 0xffff0000, v77
	v_lshlrev_b32_e32 v172, 16, v78
	v_and_b32_e32 v173, 0xffff0000, v78
	v_lshlrev_b32_e32 v174, 16, v79
	v_and_b32_e32 v175, 0xffff0000, v79
	v_lshlrev_b32_e32 v176, 16, v84
	v_and_b32_e32 v177, 0xffff0000, v84
	v_lshlrev_b32_e32 v178, 16, v85
	v_and_b32_e32 v179, 0xffff0000, v85
	v_lshlrev_b32_e32 v180, 16, v86
	v_and_b32_e32 v181, 0xffff0000, v86
	v_lshlrev_b32_e32 v182, 16, v87
	v_and_b32_e32 v183, 0xffff0000, v87
	v_lshlrev_b32_e32 v184, 16, v88
	v_and_b32_e32 v185, 0xffff0000, v88
	v_lshlrev_b32_e32 v186, 16, v89
	v_and_b32_e32 v187, 0xffff0000, v89
	v_lshlrev_b32_e32 v188, 16, v90
	v_and_b32_e32 v189, 0xffff0000, v90
	v_lshlrev_b32_e32 v190, 16, v91
	v_and_b32_e32 v191, 0xffff0000, v91
	v_pk_add_f32 v[224:225], v[144:145], v[160:161] neg_lo:[0,1] neg_hi:[0,1]
	v_pk_add_f32 v[226:227], v[176:177], v[160:161] neg_lo:[0,1] neg_hi:[0,1]
	v_pk_fma_f32 v[192:193], v[96:97], v[224:225], v[160:161]
	v_pk_fma_f32 v[192:193], v[112:113], v[226:227], v[192:193]
	v_pk_add_f32 v[224:225], v[146:147], v[162:163] neg_lo:[0,1] neg_hi:[0,1]
	v_pk_add_f32 v[226:227], v[178:179], v[162:163] neg_lo:[0,1] neg_hi:[0,1]
	v_pk_fma_f32 v[194:195], v[98:99], v[224:225], v[162:163]
	v_pk_fma_f32 v[194:195], v[114:115], v[226:227], v[194:195]
	v_pk_add_f32 v[224:225], v[148:149], v[164:165] neg_lo:[0,1] neg_hi:[0,1]
	v_pk_add_f32 v[226:227], v[180:181], v[164:165] neg_lo:[0,1] neg_hi:[0,1]
	v_pk_fma_f32 v[196:197], v[100:101], v[224:225], v[164:165]
	v_pk_fma_f32 v[196:197], v[116:117], v[226:227], v[196:197]
	v_pk_add_f32 v[224:225], v[150:151], v[166:167] neg_lo:[0,1] neg_hi:[0,1]
	v_pk_add_f32 v[226:227], v[182:183], v[166:167] neg_lo:[0,1] neg_hi:[0,1]
	v_pk_fma_f32 v[198:199], v[102:103], v[224:225], v[166:167]
	v_pk_fma_f32 v[198:199], v[118:119], v[226:227], v[198:199]
	v_pk_add_f32 v[224:225], v[152:153], v[168:169] neg_lo:[0,1] neg_hi:[0,1]
	v_pk_add_f32 v[226:227], v[184:185], v[168:169] neg_lo:[0,1] neg_hi:[0,1]
	v_pk_fma_f32 v[200:201], v[104:105], v[224:225], v[168:169]
	v_pk_fma_f32 v[200:201], v[120:121], v[226:227], v[200:201]
	v_pk_add_f32 v[224:225], v[154:155], v[170:171] neg_lo:[0,1] neg_hi:[0,1]
	v_pk_add_f32 v[226:227], v[186:187], v[170:171] neg_lo:[0,1] neg_hi:[0,1]
	v_pk_fma_f32 v[202:203], v[106:107], v[224:225], v[170:171]
	v_pk_fma_f32 v[202:203], v[122:123], v[226:227], v[202:203]
	v_pk_add_f32 v[224:225], v[156:157], v[172:173] neg_lo:[0,1] neg_hi:[0,1]
	v_pk_add_f32 v[226:227], v[188:189], v[172:173] neg_lo:[0,1] neg_hi:[0,1]
	v_pk_fma_f32 v[204:205], v[108:109], v[224:225], v[172:173]
	v_pk_fma_f32 v[204:205], v[124:125], v[226:227], v[204:205]
	v_pk_add_f32 v[224:225], v[158:159], v[174:175] neg_lo:[0,1] neg_hi:[0,1]
	v_pk_add_f32 v[226:227], v[190:191], v[174:175] neg_lo:[0,1] neg_hi:[0,1]
	v_pk_fma_f32 v[206:207], v[110:111], v[224:225], v[174:175]
	v_pk_fma_f32 v[206:207], v[126:127], v[226:227], v[206:207]
	v_pk_mul_f32 v[208:209], v[192:193], v[128:129]
	v_pk_mul_f32 v[210:211], v[194:195], v[130:131]
	v_pk_mul_f32 v[212:213], v[196:197], v[132:133]
	v_pk_mul_f32 v[214:215], v[198:199], v[134:135]
	v_pk_mul_f32 v[216:217], v[200:201], v[136:137]
	v_pk_mul_f32 v[218:219], v[202:203], v[138:139]
	v_pk_mul_f32 v[220:221], v[204:205], v[140:141]
	v_pk_mul_f32 v[222:223], v[206:207], v[142:143]
	v_mul_f32_e32 v224, v208, v208
	v_fmac_f32_e32 v224, v209, v209
	v_fmac_f32_e32 v224, v210, v210
	v_fmac_f32_e32 v224, v211, v211
	v_fmac_f32_e32 v224, v212, v212
	v_fmac_f32_e32 v224, v213, v213
	v_fmac_f32_e32 v224, v214, v214
	v_fmac_f32_e32 v224, v215, v215
	v_fmac_f32_e32 v224, v216, v216
	v_fmac_f32_e32 v224, v217, v217
	v_fmac_f32_e32 v224, v218, v218
	v_fmac_f32_e32 v224, v219, v219
	v_fmac_f32_e32 v224, v220, v220
	v_fmac_f32_e32 v224, v221, v221
	v_fmac_f32_e32 v224, v222, v222
	v_fmac_f32_e32 v224, v223, v223
	s_nop 1
	v_add_f32_dpp v224, v224, v224 quad_perm:[1,0,3,2] row_mask:0xf bank_mask:0xf
	s_nop 1
	v_add_f32_dpp v224, v224, v224 quad_perm:[2,3,0,1] row_mask:0xf bank_mask:0xf
	v_sqrt_f32_e32 v224, v224
	s_nop 0
	v_max_f32_e32 v224, 0x2b8cbccc, v224
	v_rcp_f32_e32 v224, v224
	s_nop 0
	v_xor_b32_e32 v224, 0x80000000, v224
	v_mov_b32_e32 v225, v224
	v_cvt_pk_bf16_f32 v144, v192, v193
	v_cvt_pk_bf16_f32 v145, v194, v195
	v_cvt_pk_bf16_f32 v146, v196, v197
	v_cvt_pk_bf16_f32 v147, v198, v199
	v_cvt_pk_bf16_f32 v148, v200, v201
	v_cvt_pk_bf16_f32 v149, v202, v203
	v_cvt_pk_bf16_f32 v150, v204, v205
	v_cvt_pk_bf16_f32 v151, v206, v207
	v_pk_mul_f32 v[208:209], v[208:209], v[224:225]
	v_pk_mul_f32 v[210:211], v[210:211], v[224:225]
	v_pk_mul_f32 v[212:213], v[212:213], v[224:225]
	v_pk_mul_f32 v[214:215], v[214:215], v[224:225]
	v_pk_mul_f32 v[216:217], v[216:217], v[224:225]
	v_pk_mul_f32 v[218:219], v[218:219], v[224:225]
	v_pk_mul_f32 v[220:221], v[220:221], v[224:225]
	v_pk_mul_f32 v[222:223], v[222:223], v[224:225]
	buffer_store_dwordx4 v[208:211], v234, s[68:71], s72 offen offset:0
	buffer_store_dwordx4 v[212:215], v234, s[68:71], s72 offen offset:16
	buffer_store_dwordx4 v[216:219], v234, s[68:71], s72 offen offset:32
	buffer_store_dwordx4 v[220:223], v234, s[68:71], s72 offen offset:48
	buffer_store_dwordx4 v[144:147], v236, s[68:71], s73 offen offset:0
	buffer_store_dwordx4 v[148:151], v236, s[68:71], s73 offen offset:16
	s_add_u32 s72, s72, 0x1000
	s_add_u32 s73, s73, 0x800
	s_add_u32 s74, s74, 0x200
	s_add_u32 s75, s75, 0x40
	s_waitcnt vmcnt(38)
; __device__ __forceinline__ void mix16(const Z16& zp, const Z16& zc, const Z16& zn, const float* mp, const float* mn, float* o) {
;     float p_[16], c_[16], n_[16]; unz(zp, p_); unz(zc, c_); unz(zn, n_);
; #pragma unroll
;     for (int q = 0; q < 16; ++q) o[q] = c_[q] + mp[q] * (p_[q] - c_[q]) + mn[q] * (n_[q] - c_[q]);
; __device__ __forceinline__ void prep_phase(const Params& p) {
;     ...
;                 float k[16], kk[16]; mix16(kp, kc, kn, mpk, mnk, k);
;                 float s2 = 0.f;
; #pragma unroll
;                 for (int q = 0; q < 16; ++q) { kk[q] = k[q] * kkc[q]; s2 += kk[q] * kk[q]; }
;                 s2 += __shfl_xor(s2, 1); s2 += __shfl_xor(s2, 2);
;                 const float inv = -1.0f / fmaxf(sqrtf(s2), 1e-12f);
;                 const size_t o = (size_t)(t0 + i) * RW + c;
; #pragma unroll
;                 for (int j4 = 0; j4 < 4; ++j4) *(f32x4*)(A + o + j4 * 4) = (f32x4){kk[j4 * 4] * inv, kk[j4 * 4 + 1] * inv, kk[j4 * 4 + 2] * inv, kk[j4 * 4 + 3] * inv};
;                 st16bf(Kb + o, k);
;                 kp = kc; kc = kn;
	v_lshlrev_b32_e32 v144, 16, v72
	v_and_b32_e32 v145, 0xffff0000, v72
	v_lshlrev_b32_e32 v146, 16, v73
	v_and_b32_e32 v147, 0xffff0000, v73
	v_lshlrev_b32_e32 v148, 16, v74
	v_and_b32_e32 v149, 0xffff0000, v74
	v_lshlrev_b32_e32 v150, 16, v75
	v_and_b32_e32 v151, 0xffff0000, v75
	v_lshlrev_b32_e32 v152, 16, v76
	v_and_b32_e32 v153, 0xffff0000, v76
	v_lshlrev_b32_e32 v154, 16, v77
	v_and_b32_e32 v155, 0xffff0000, v77
	v_lshlrev_b32_e32 v156, 16, v78
	v_and_b32_e32 v157, 0xffff0000, v78
	v_lshlrev_b32_e32 v158, 16, v79
	v_and_b32_e32 v159, 0xffff0000, v79
	v_lshlrev_b32_e32 v160, 16, v84
	v_and_b32_e32 v161, 0xffff0000, v84
	v_lshlrev_b32_e32 v162, 16, v85
	v_and_b32_e32 v163, 0xffff0000, v85
	v_lshlrev_b32_e32 v164, 16, v86
	v_and_b32_e32 v165, 0xffff0000, v86
	v_lshlrev_b32_e32 v166, 16, v87
	v_and_b32_e32 v167, 0xffff0000, v87
	v_lshlrev_b32_e32 v168, 16, v88
	v_and_b32_e32 v169, 0xffff0000, v88
	v_lshlrev_b32_e32 v170, 16, v89
	v_and_b32_e32 v171, 0xffff0000, v89
	v_lshlrev_b32_e32 v172, 16, v90
	v_and_b32_e32 v173, 0xffff0000, v90
	v_lshlrev_b32_e32 v174, 16, v91
	v_and_b32_e32 v175, 0xffff0000, v91
	v_lshlrev_b32_e32 v176, 16, v0
	v_and_b32_e32 v177, 0xffff0000, v0
	v_lshlrev_b32_e32 v178, 16, v1
	v_and_b32_e32 v179, 0xffff0000, v1
	v_lshlrev_b32_e32 v180, 16, v2
	v_and_b32_e32 v181, 0xffff0000, v2
	v_lshlrev_b32_e32 v182, 16, v3
	v_and_b32_e32 v183, 0xffff0000, v3
	v_lshlrev_b32_e32 v184, 16, v4
	v_and_b32_e32 v185, 0xffff0000, v4
	v_lshlrev_b32_e32 v186, 16, v5
	v_and_b32_e32 v187, 0xffff0000, v5
	v_lshlrev_b32_e32 v188, 16, v6
	v_and_b32_e32 v189, 0xffff0000, v6
	v_lshlrev_b32_e32 v190, 16, v7
	v_and_b32_e32 v191, 0xffff0000, v7
	v_pk_add_f32 v[224:225], v[144:145], v[160:161] neg_lo:[0,1] neg_hi:[0,1]
	v_pk_add_f32 v[226:227], v[176:177], v[160:161] neg_lo:[0,1] neg_hi:[0,1]
	v_pk_fma_f32 v[192:193], v[96:97], v[224:225], v[160:161]
	v_pk_fma_f32 v[192:193], v[112:113], v[226:227], v[192:193]
	v_pk_add_f32 v[224:225], v[146:147], v[162:163] neg_lo:[0,1] neg_hi:[0,1]
	v_pk_add_f32 v[226:227], v[178:179], v[162:163] neg_lo:[0,1] neg_hi:[0,1]
	v_pk_fma_f32 v[194:195], v[98:99], v[224:225], v[162:163]
	v_pk_fma_f32 v[194:195], v[114:115], v[226:227], v[194:195]
	v_pk_add_f32 v[224:225], v[148:149], v[164:165] neg_lo:[0,1] neg_hi:[0,1]
	v_pk_add_f32 v[226:227], v[180:181], v[164:165] neg_lo:[0,1] neg_hi:[0,1]
	v_pk_fma_f32 v[196:197], v[100:101], v[224:225], v[164:165]
	v_pk_fma_f32 v[196:197], v[116:117], v[226:227], v[196:197]
	v_pk_add_f32 v[224:225], v[150:151], v[166:167] neg_lo:[0,1] neg_hi:[0,1]
	v_pk_add_f32 v[226:227], v[182:183], v[166:167] neg_lo:[0,1] neg_hi:[0,1]
	v_pk_fma_f32 v[198:199], v[102:103], v[224:225], v[166:167]
	v_pk_fma_f32 v[198:199], v[118:119], v[226:227], v[198:199]
	v_pk_add_f32 v[224:225], v[152:153], v[168:169] neg_lo:[0,1] neg_hi:[0,1]
	v_pk_add_f32 v[226:227], v[184:185], v[168:169] neg_lo:[0,1] neg_hi:[0,1]
	v_pk_fma_f32 v[200:201], v[104:105], v[224:225], v[168:169]
	v_pk_fma_f32 v[200:201], v[120:121], v[226:227], v[200:201]
	v_pk_add_f32 v[224:225], v[154:155], v[170:171] neg_lo:[0,1] neg_hi:[0,1]
	v_pk_add_f32 v[226:227], v[186:187], v[170:171] neg_lo:[0,1] neg_hi:[0,1]
	v_pk_fma_f32 v[202:203], v[106:107], v[224:225], v[170:171]
	v_pk_fma_f32 v[202:203], v[122:123], v[226:227], v[202:203]
	v_pk_add_f32 v[224:225], v[156:157], v[172:173] neg_lo:[0,1] neg_hi:[0,1]
	v_pk_add_f32 v[226:227], v[188:189], v[172:173] neg_lo:[0,1] neg_hi:[0,1]
	v_pk_fma_f32 v[204:205], v[108:109], v[224:225], v[172:173]
	v_pk_fma_f32 v[204:205], v[124:125], v[226:227], v[204:205]
	v_pk_add_f32 v[224:225], v[158:159], v[174:175] neg_lo:[0,1] neg_hi:[0,1]
	v_pk_add_f32 v[226:227], v[190:191], v[174:175] neg_lo:[0,1] neg_hi:[0,1]
	v_pk_fma_f32 v[206:207], v[110:111], v[224:225], v[174:175]
	v_pk_fma_f32 v[206:207], v[126:127], v[226:227], v[206:207]
	v_pk_mul_f32 v[208:209], v[192:193], v[128:129]
	v_pk_mul_f32 v[210:211], v[194:195], v[130:131]
	v_pk_mul_f32 v[212:213], v[196:197], v[132:133]
	v_pk_mul_f32 v[214:215], v[198:199], v[134:135]
	v_pk_mul_f32 v[216:217], v[200:201], v[136:137]
	v_pk_mul_f32 v[218:219], v[202:203], v[138:139]
	v_pk_mul_f32 v[220:221], v[204:205], v[140:141]
	v_pk_mul_f32 v[222:223], v[206:207], v[142:143]
	v_mul_f32_e32 v224, v208, v208
	v_fmac_f32_e32 v224, v209, v209
	v_fmac_f32_e32 v224, v210, v210
	v_fmac_f32_e32 v224, v211, v211
	v_fmac_f32_e32 v224, v212, v212
	v_fmac_f32_e32 v224, v213, v213
	v_fmac_f32_e32 v224, v214, v214
	v_fmac_f32_e32 v224, v215, v215
	v_fmac_f32_e32 v224, v216, v216
	v_fmac_f32_e32 v224, v217, v217
	v_fmac_f32_e32 v224, v218, v218
	v_fmac_f32_e32 v224, v219, v219
	v_fmac_f32_e32 v224, v220, v220
	v_fmac_f32_e32 v224, v221, v221
	v_fmac_f32_e32 v224, v222, v222
	v_fmac_f32_e32 v224, v223, v223
	s_nop 1
	v_add_f32_dpp v224, v224, v224 quad_perm:[1,0,3,2] row_mask:0xf bank_mask:0xf
	s_nop 1
	v_add_f32_dpp v224, v224, v224 quad_perm:[2,3,0,1] row_mask:0xf bank_mask:0xf
	v_sqrt_f32_e32 v224, v224
	s_nop 0
	v_max_f32_e32 v224, 0x2b8cbccc, v224
	v_rcp_f32_e32 v224, v224
	s_nop 0
	v_xor_b32_e32 v224, 0x80000000, v224
	v_mov_b32_e32 v225, v224
	v_cvt_pk_bf16_f32 v144, v192, v193
	v_cvt_pk_bf16_f32 v145, v194, v195
	v_cvt_pk_bf16_f32 v146, v196, v197
	v_cvt_pk_bf16_f32 v147, v198, v199
	v_cvt_pk_bf16_f32 v148, v200, v201
	v_cvt_pk_bf16_f32 v149, v202, v203
	v_cvt_pk_bf16_f32 v150, v204, v205
	v_cvt_pk_bf16_f32 v151, v206, v207
	v_pk_mul_f32 v[208:209], v[208:209], v[224:225]
	v_pk_mul_f32 v[210:211], v[210:211], v[224:225]
	v_pk_mul_f32 v[212:213], v[212:213], v[224:225]
	v_pk_mul_f32 v[214:215], v[214:215], v[224:225]
	v_pk_mul_f32 v[216:217], v[216:217], v[224:225]
	v_pk_mul_f32 v[218:219], v[218:219], v[224:225]
	v_pk_mul_f32 v[220:221], v[220:221], v[224:225]
	v_pk_mul_f32 v[222:223], v[222:223], v[224:225]
	buffer_store_dwordx4 v[208:211], v234, s[68:71], s72 offen offset:0
	buffer_store_dwordx4 v[212:215], v234, s[68:71], s72 offen offset:16
	buffer_store_dwordx4 v[216:219], v234, s[68:71], s72 offen offset:32
	buffer_store_dwordx4 v[220:223], v234, s[68:71], s72 offen offset:48
	buffer_store_dwordx4 v[144:147], v236, s[68:71], s73 offen offset:0
	buffer_store_dwordx4 v[148:151], v236, s[68:71], s73 offen offset:16
	s_add_u32 s72, s72, 0x1000
	s_add_u32 s73, s73, 0x800
	s_add_u32 s74, s74, 0x200
	s_add_u32 s75, s75, 0x40
	s_waitcnt vmcnt(36)
; __device__ __forceinline__ void mix16(const Z16& zp, const Z16& zc, const Z16& zn, const float* mp, const float* mn, float* o) {
;     float p_[16], c_[16], n_[16]; unz(zp, p_); unz(zc, c_); unz(zn, n_);
; #pragma unroll
;     for (int q = 0; q < 16; ++q) o[q] = c_[q] + mp[q] * (p_[q] - c_[q]) + mn[q] * (n_[q] - c_[q]);
; __device__ __forceinline__ void prep_phase(const Params& p) {
;     ...
;                 float k[16], kk[16]; mix16(kp, kc, kn, mpk, mnk, k);
;                 float s2 = 0.f;
; #pragma unroll
;                 for (int q = 0; q < 16; ++q) { kk[q] = k[q] * kkc[q]; s2 += kk[q] * kk[q]; }
;                 s2 += __shfl_xor(s2, 1); s2 += __shfl_xor(s2, 2);
;                 const float inv = -1.0f / fmaxf(sqrtf(s2), 1e-12f);
;                 const size_t o = (size_t)(t0 + i) * RW + c;
; #pragma unroll
;                 for (int j4 = 0; j4 < 4; ++j4) *(f32x4*)(A + o + j4 * 4) = (f32x4){kk[j4 * 4] * inv, kk[j4 * 4 + 1] * inv, kk[j4 * 4 + 2] * inv, kk[j4 * 4 + 3] * inv};
;                 st16bf(Kb + o, k);
;                 kp = kc; kc = kn;
;             }
	v_lshlrev_b32_e32 v144, 16, v84
	v_and_b32_e32 v145, 0xffff0000, v84
	v_lshlrev_b32_e32 v146, 16, v85
	v_and_b32_e32 v147, 0xffff0000, v85
	v_lshlrev_b32_e32 v148, 16, v86
	v_and_b32_e32 v149, 0xffff0000, v86
	v_lshlrev_b32_e32 v150, 16, v87
	v_and_b32_e32 v151, 0xffff0000, v87
	v_lshlrev_b32_e32 v152, 16, v88
	v_and_b32_e32 v153, 0xffff0000, v88
	v_lshlrev_b32_e32 v154, 16, v89
	v_and_b32_e32 v155, 0xffff0000, v89
	v_lshlrev_b32_e32 v156, 16, v90
	v_and_b32_e32 v157, 0xffff0000, v90
	v_lshlrev_b32_e32 v158, 16, v91
	v_and_b32_e32 v159, 0xffff0000, v91
	v_lshlrev_b32_e32 v160, 16, v0
	v_and_b32_e32 v161, 0xffff0000, v0
	v_lshlrev_b32_e32 v162, 16, v1
	v_and_b32_e32 v163, 0xffff0000, v1
	v_lshlrev_b32_e32 v164, 16, v2
	v_and_b32_e32 v165, 0xffff0000, v2
	v_lshlrev_b32_e32 v166, 16, v3
	v_and_b32_e32 v167, 0xffff0000, v3
	v_lshlrev_b32_e32 v168, 16, v4
	v_and_b32_e32 v169, 0xffff0000, v4
	v_lshlrev_b32_e32 v170, 16, v5
	v_and_b32_e32 v171, 0xffff0000, v5
	v_lshlrev_b32_e32 v172, 16, v6
	v_and_b32_e32 v173, 0xffff0000, v6
	v_lshlrev_b32_e32 v174, 16, v7
	v_and_b32_e32 v175, 0xffff0000, v7
	v_lshlrev_b32_e32 v176, 16, v12
	v_and_b32_e32 v177, 0xffff0000, v12
	v_lshlrev_b32_e32 v178, 16, v13
	v_and_b32_e32 v179, 0xffff0000, v13
	v_lshlrev_b32_e32 v180, 16, v14
	v_and_b32_e32 v181, 0xffff0000, v14
	v_lshlrev_b32_e32 v182, 16, v15
	v_and_b32_e32 v183, 0xffff0000, v15
	v_lshlrev_b32_e32 v184, 16, v16
	v_and_b32_e32 v185, 0xffff0000, v16
	v_lshlrev_b32_e32 v186, 16, v17
	v_and_b32_e32 v187, 0xffff0000, v17
	v_lshlrev_b32_e32 v188, 16, v18
	v_and_b32_e32 v189, 0xffff0000, v18
	v_lshlrev_b32_e32 v190, 16, v19
	v_and_b32_e32 v191, 0xffff0000, v19
	v_pk_add_f32 v[224:225], v[144:145], v[160:161] neg_lo:[0,1] neg_hi:[0,1]
	v_pk_add_f32 v[226:227], v[176:177], v[160:161] neg_lo:[0,1] neg_hi:[0,1]
	v_pk_fma_f32 v[192:193], v[96:97], v[224:225], v[160:161]
	v_pk_fma_f32 v[192:193], v[112:113], v[226:227], v[192:193]
	v_pk_add_f32 v[224:225], v[146:147], v[162:163] neg_lo:[0,1] neg_hi:[0,1]
	v_pk_add_f32 v[226:227], v[178:179], v[162:163] neg_lo:[0,1] neg_hi:[0,1]
	v_pk_fma_f32 v[194:195], v[98:99], v[224:225], v[162:163]
	v_pk_fma_f32 v[194:195], v[114:115], v[226:227], v[194:195]
	v_pk_add_f32 v[224:225], v[148:149], v[164:165] neg_lo:[0,1] neg_hi:[0,1]
	v_pk_add_f32 v[226:227], v[180:181], v[164:165] neg_lo:[0,1] neg_hi:[0,1]
	v_pk_fma_f32 v[196:197], v[100:101], v[224:225], v[164:165]
	v_pk_fma_f32 v[196:197], v[116:117], v[226:227], v[196:197]
	v_pk_add_f32 v[224:225], v[150:151], v[166:167] neg_lo:[0,1] neg_hi:[0,1]
	v_pk_add_f32 v[226:227], v[182:183], v[166:167] neg_lo:[0,1] neg_hi:[0,1]
	v_pk_fma_f32 v[198:199], v[102:103], v[224:225], v[166:167]
	v_pk_fma_f32 v[198:199], v[118:119], v[226:227], v[198:199]
	v_pk_add_f32 v[224:225], v[152:153], v[168:169] neg_lo:[0,1] neg_hi:[0,1]
	v_pk_add_f32 v[226:227], v[184:185], v[168:169] neg_lo:[0,1] neg_hi:[0,1]
	v_pk_fma_f32 v[200:201], v[104:105], v[224:225], v[168:169]
	v_pk_fma_f32 v[200:201], v[120:121], v[226:227], v[200:201]
	v_pk_add_f32 v[224:225], v[154:155], v[170:171] neg_lo:[0,1] neg_hi:[0,1]
	v_pk_add_f32 v[226:227], v[186:187], v[170:171] neg_lo:[0,1] neg_hi:[0,1]
	v_pk_fma_f32 v[202:203], v[106:107], v[224:225], v[170:171]
	v_pk_fma_f32 v[202:203], v[122:123], v[226:227], v[202:203]
	v_pk_add_f32 v[224:225], v[156:157], v[172:173] neg_lo:[0,1] neg_hi:[0,1]
	v_pk_add_f32 v[226:227], v[188:189], v[172:173] neg_lo:[0,1] neg_hi:[0,1]
	v_pk_fma_f32 v[204:205], v[108:109], v[224:225], v[172:173]
	v_pk_fma_f32 v[204:205], v[124:125], v[226:227], v[204:205]
	v_pk_add_f32 v[224:225], v[158:159], v[174:175] neg_lo:[0,1] neg_hi:[0,1]
	v_pk_add_f32 v[226:227], v[190:191], v[174:175] neg_lo:[0,1] neg_hi:[0,1]
	v_pk_fma_f32 v[206:207], v[110:111], v[224:225], v[174:175]
	v_pk_fma_f32 v[206:207], v[126:127], v[226:227], v[206:207]
	v_pk_mul_f32 v[208:209], v[192:193], v[128:129]
	v_pk_mul_f32 v[210:211], v[194:195], v[130:131]
	v_pk_mul_f32 v[212:213], v[196:197], v[132:133]
	v_pk_mul_f32 v[214:215], v[198:199], v[134:135]
	v_pk_mul_f32 v[216:217], v[200:201], v[136:137]
	v_pk_mul_f32 v[218:219], v[202:203], v[138:139]
	v_pk_mul_f32 v[220:221], v[204:205], v[140:141]
	v_pk_mul_f32 v[222:223], v[206:207], v[142:143]
	v_mul_f32_e32 v224, v208, v208
	v_fmac_f32_e32 v224, v209, v209
	v_fmac_f32_e32 v224, v210, v210
	v_fmac_f32_e32 v224, v211, v211
	v_fmac_f32_e32 v224, v212, v212
	v_fmac_f32_e32 v224, v213, v213
	v_fmac_f32_e32 v224, v214, v214
	v_fmac_f32_e32 v224, v215, v215
	v_fmac_f32_e32 v224, v216, v216
	v_fmac_f32_e32 v224, v217, v217
	v_fmac_f32_e32 v224, v218, v218
	v_fmac_f32_e32 v224, v219, v219
	v_fmac_f32_e32 v224, v220, v220
	v_fmac_f32_e32 v224, v221, v221
	v_fmac_f32_e32 v224, v222, v222
	v_fmac_f32_e32 v224, v223, v223
	s_nop 1
	v_add_f32_dpp v224, v224, v224 quad_perm:[1,0,3,2] row_mask:0xf bank_mask:0xf
	s_nop 1
	v_add_f32_dpp v224, v224, v224 quad_perm:[2,3,0,1] row_mask:0xf bank_mask:0xf
	v_sqrt_f32_e32 v224, v224
	s_nop 0
	v_max_f32_e32 v224, 0x2b8cbccc, v224
	v_rcp_f32_e32 v224, v224
	s_nop 0
	v_xor_b32_e32 v224, 0x80000000, v224
	v_mov_b32_e32 v225, v224
	v_cvt_pk_bf16_f32 v144, v192, v193
	v_cvt_pk_bf16_f32 v145, v194, v195
	v_cvt_pk_bf16_f32 v146, v196, v197
	v_cvt_pk_bf16_f32 v147, v198, v199
	v_cvt_pk_bf16_f32 v148, v200, v201
	v_cvt_pk_bf16_f32 v149, v202, v203
	v_cvt_pk_bf16_f32 v150, v204, v205
	v_cvt_pk_bf16_f32 v151, v206, v207
	v_pk_mul_f32 v[208:209], v[208:209], v[224:225]
	v_pk_mul_f32 v[210:211], v[210:211], v[224:225]
	v_pk_mul_f32 v[212:213], v[212:213], v[224:225]
	v_pk_mul_f32 v[214:215], v[214:215], v[224:225]
	v_pk_mul_f32 v[216:217], v[216:217], v[224:225]
	v_pk_mul_f32 v[218:219], v[218:219], v[224:225]
	v_pk_mul_f32 v[220:221], v[220:221], v[224:225]
	v_pk_mul_f32 v[222:223], v[222:223], v[224:225]
	buffer_store_dwordx4 v[208:211], v234, s[68:71], s72 offen offset:0
	buffer_store_dwordx4 v[212:215], v234, s[68:71], s72 offen offset:16
	buffer_store_dwordx4 v[216:219], v234, s[68:71], s72 offen offset:32
	buffer_store_dwordx4 v[220:223], v234, s[68:71], s72 offen offset:48
	buffer_store_dwordx4 v[144:147], v236, s[68:71], s73 offen offset:0
	buffer_store_dwordx4 v[148:151], v236, s[68:71], s73 offen offset:16
	s_waitcnt vmcnt(0)
; __device__ __forceinline__ void mix16(const Z16& zp, const Z16& zc, const Z16& zn, const float* mp, const float* mn, float* o) {
;     float p_[16], c_[16], n_[16]; unz(zp, p_); unz(zc, c_); unz(zn, n_);
; #pragma unroll
;     for (int q = 0; q < 16; ++q) o[q] = c_[q] + mp[q] * (p_[q] - c_[q]) + mn[q] * (n_[q] - c_[q]);
; __device__ __forceinline__ void prep_phase(const Params& p) {
;     ...
;             float mpr[16], mnr[16], rkc[16]; ld16f(p.mu_prev + c, mpr); ld16f(p.mu_next + c, mnr); ld16f(p.r_k + c, rkc);
;             const u16* zc = ZS + (size_t)t0 * 3328 + c;
;             Z16 rp = tt0 > 0 ? ldz(zc - 3328) : zz(), rc = ldz(zc);
; #pragma unroll 2
;             for (int i = 0; i < 16; ++i) {
;                 const bool hn = (tt0 + i) < SEQ - 1; const Z16 rn = hn ? ldz(zc + (size_t)(i + 1) * 3328) : zz();
;                 const size_t o = (size_t)(t0 + i) * RW + c;
;                 float r[16], k[16]; mix16(rp, rc, rn, mpr, mnr, r); unz(ldz(Kb + o), k);
	v_lshl_add_u32 v232, v240, 5, s5
	v_lshlrev_b32_e32 v224, 6, v240
	global_load_dwordx4 v[96:99], v224, s[20:21] offset:0
	global_load_dwordx4 v[100:103], v224, s[20:21] offset:16
	global_load_dwordx4 v[104:107], v224, s[20:21] offset:32
	global_load_dwordx4 v[108:111], v224, s[20:21] offset:48
	global_load_dwordx4 v[112:115], v224, s[22:23] offset:0
	global_load_dwordx4 v[116:119], v224, s[22:23] offset:16
	global_load_dwordx4 v[120:123], v224, s[22:23] offset:32
	global_load_dwordx4 v[124:127], v224, s[22:23] offset:48
	global_load_dwordx4 v[128:131], v224, s[44:45] offset:0
	global_load_dwordx4 v[132:135], v224, s[44:45] offset:16
	global_load_dwordx4 v[136:139], v224, s[44:45] offset:32
	global_load_dwordx4 v[140:143], v224, s[44:45] offset:48
	buffer_load_dwordx4 v[0:3], v232, s[64:67], 0 offen
	buffer_load_dwordx4 v[4:7], v232, s[64:67], 0 offen offset:16
	v_add_u32_e32 v232, 6656, v232
	buffer_load_dwordx4 v[12:15], v232, s[64:67], 0 offen
	buffer_load_dwordx4 v[16:19], v232, s[64:67], 0 offen offset:16
	v_add_u32_e32 v232, 6656, v232
	buffer_load_dwordx4 v[24:27], v232, s[64:67], 0 offen
	buffer_load_dwordx4 v[28:31], v232, s[64:67], 0 offen offset:16
	v_add_u32_e32 v232, 6656, v232
	buffer_load_dwordx4 v[36:39], v232, s[64:67], 0 offen
	buffer_load_dwordx4 v[40:43], v232, s[64:67], 0 offen offset:16
	v_add_u32_e32 v232, 6656, v232
	buffer_load_dwordx4 v[48:51], v232, s[64:67], 0 offen
	buffer_load_dwordx4 v[52:55], v232, s[64:67], 0 offen offset:16
	v_add_u32_e32 v232, 6656, v232
	buffer_load_dwordx4 v[60:63], v232, s[64:67], 0 offen
	buffer_load_dwordx4 v[64:67], v232, s[64:67], 0 offen offset:16
	v_add_u32_e32 v232, 6656, v232
	buffer_load_dwordx4 v[72:75], v232, s[64:67], 0 offen
	buffer_load_dwordx4 v[76:79], v232, s[64:67], 0 offen offset:16
	v_add_u32_e32 v232, 6656, v232
	buffer_load_dwordx4 v[84:87], v232, s[64:67], 0 offen
	buffer_load_dwordx4 v[88:91], v232, s[64:67], 0 offen offset:16
	v_add_u32_e32 v232, 6656, v232
	s_lshl_b32 s76, s0, 11
	buffer_load_dwordx4 v[208:211], v236, s[68:71], s76 offen
	buffer_load_dwordx4 v[212:215], v236, s[68:71], s76 offen offset:16
	s_lshl_b32 s72, s0, 12
	s_lshl_b32 s73, s0, 11
	s_lshl_b32 s74, s0, 9
	s_lshl_b32 s75, s0, 6
	s_waitcnt vmcnt(12)
	v_lshlrev_b32_e32 v144, 16, v0
	v_and_b32_e32 v145, 0xffff0000, v0
	v_lshlrev_b32_e32 v146, 16, v1
	v_and_b32_e32 v147, 0xffff0000, v1
	v_lshlrev_b32_e32 v148, 16, v2
	v_and_b32_e32 v149, 0xffff0000, v2
	v_lshlrev_b32_e32 v150, 16, v3
	v_and_b32_e32 v151, 0xffff0000, v3
	v_lshlrev_b32_e32 v152, 16, v4
	v_and_b32_e32 v153, 0xffff0000, v4
	v_lshlrev_b32_e32 v154, 16, v5
	v_and_b32_e32 v155, 0xffff0000, v5
	v_lshlrev_b32_e32 v156, 16, v6
	v_and_b32_e32 v157, 0xffff0000, v6
	v_lshlrev_b32_e32 v158, 16, v7
	v_and_b32_e32 v159, 0xffff0000, v7
	v_lshlrev_b32_e32 v160, 16, v12
	v_and_b32_e32 v161, 0xffff0000, v12
	v_lshlrev_b32_e32 v162, 16, v13
	v_and_b32_e32 v163, 0xffff0000, v13
	v_lshlrev_b32_e32 v164, 16, v14
	v_and_b32_e32 v165, 0xffff0000, v14
	v_lshlrev_b32_e32 v166, 16, v15
	v_and_b32_e32 v167, 0xffff0000, v15
	v_lshlrev_b32_e32 v168, 16, v16
	v_and_b32_e32 v169, 0xffff0000, v16
	v_lshlrev_b32_e32 v170, 16, v17
	v_and_b32_e32 v171, 0xffff0000, v17
	v_lshlrev_b32_e32 v172, 16, v18
	v_and_b32_e32 v173, 0xffff0000, v18
	v_lshlrev_b32_e32 v174, 16, v19
	v_and_b32_e32 v175, 0xffff0000, v19
	v_lshlrev_b32_e32 v176, 16, v24
	v_and_b32_e32 v177, 0xffff0000, v24
	v_lshlrev_b32_e32 v178, 16, v25
	v_and_b32_e32 v179, 0xffff0000, v25
	v_lshlrev_b32_e32 v180, 16, v26
	v_and_b32_e32 v181, 0xffff0000, v26
	v_lshlrev_b32_e32 v182, 16, v27
	v_and_b32_e32 v183, 0xffff0000, v27
	v_lshlrev_b32_e32 v184, 16, v28
	v_and_b32_e32 v185, 0xffff0000, v28
	v_lshlrev_b32_e32 v186, 16, v29
	v_and_b32_e32 v187, 0xffff0000, v29
	v_lshlrev_b32_e32 v188, 16, v30
	v_and_b32_e32 v189, 0xffff0000, v30
	v_lshlrev_b32_e32 v190, 16, v31
	v_and_b32_e32 v191, 0xffff0000, v31
	buffer_load_dwordx4 v[0:3], v232, s[64:67], 0 offen
	buffer_load_dwordx4 v[4:7], v232, s[64:67], 0 offen offset:16
	v_add_u32_e32 v232, 6656, v232
	v_pk_add_f32 v[224:225], v[144:145], v[160:161] neg_lo:[0,1] neg_hi:[0,1]
	v_pk_add_f32 v[226:227], v[176:177], v[160:161] neg_lo:[0,1] neg_hi:[0,1]
	v_pk_fma_f32 v[192:193], v[96:97], v[224:225], v[160:161]
	v_pk_fma_f32 v[192:193], v[112:113], v[226:227], v[192:193]
	v_pk_add_f32 v[224:225], v[146:147], v[162:163] neg_lo:[0,1] neg_hi:[0,1]
	v_pk_add_f32 v[226:227], v[178:179], v[162:163] neg_lo:[0,1] neg_hi:[0,1]
	v_pk_fma_f32 v[194:195], v[98:99], v[224:225], v[162:163]
	v_pk_fma_f32 v[194:195], v[114:115], v[226:227], v[194:195]
	v_pk_add_f32 v[224:225], v[148:149], v[164:165] neg_lo:[0,1] neg_hi:[0,1]
	v_pk_add_f32 v[226:227], v[180:181], v[164:165] neg_lo:[0,1] neg_hi:[0,1]
	v_pk_fma_f32 v[196:197], v[100:101], v[224:225], v[164:165]
	v_pk_fma_f32 v[196:197], v[116:117], v[226:227], v[196:197]
	v_pk_add_f32 v[224:225], v[150:151], v[166:167] neg_lo:[0,1] neg_hi:[0,1]
	v_pk_add_f32 v[226:227], v[182:183], v[166:167] neg_lo:[0,1] neg_hi:[0,1]
	v_pk_fma_f32 v[198:199], v[102:103], v[224:225], v[166:167]
	v_pk_fma_f32 v[198:199], v[118:119], v[226:227], v[198:199]
	v_pk_add_f32 v[224:225], v[152:153], v[168:169] neg_lo:[0,1] neg_hi:[0,1]
	v_pk_add_f32 v[226:227], v[184:185], v[168:169] neg_lo:[0,1] neg_hi:[0,1]
	v_pk_fma_f32 v[200:201], v[104:105], v[224:225], v[168:169]
	v_pk_fma_f32 v[200:201], v[120:121], v[226:227], v[200:201]
	v_pk_add_f32 v[224:225], v[154:155], v[170:171] neg_lo:[0,1] neg_hi:[0,1]
	v_pk_add_f32 v[226:227], v[186:187], v[170:171] neg_lo:[0,1] neg_hi:[0,1]
	v_pk_fma_f32 v[202:203], v[106:107], v[224:225], v[170:171]
	v_pk_fma_f32 v[202:203], v[122:123], v[226:227], v[202:203]
	v_pk_add_f32 v[224:225], v[156:157], v[172:173] neg_lo:[0,1] neg_hi:[0,1]
	v_pk_add_f32 v[226:227], v[188:189], v[172:173] neg_lo:[0,1] neg_hi:[0,1]
	v_pk_fma_f32 v[204:205], v[108:109], v[224:225], v[172:173]
	v_pk_fma_f32 v[204:205], v[124:125], v[226:227], v[204:205]
	v_pk_add_f32 v[224:225], v[158:159], v[174:175] neg_lo:[0,1] neg_hi:[0,1]
	v_pk_add_f32 v[226:227], v[190:191], v[174:175] neg_lo:[0,1] neg_hi:[0,1]
	v_pk_fma_f32 v[206:207], v[110:111], v[224:225], v[174:175]
	v_pk_fma_f32 v[206:207], v[126:127], v[226:227], v[206:207]
	s_add_u32 s76, s76, 0x800
	buffer_load_dwordx4 v[216:219], v236, s[68:71], s76 offen
	buffer_load_dwordx4 v[220:223], v236, s[68:71], s76 offen offset:16
	buffer_store_dwordx4 v[192:195], v235, s[68:71], s72 offen offset:0
	buffer_store_dwordx4 v[196:199], v235, s[68:71], s72 offen offset:16
	buffer_store_dwordx4 v[200:203], v235, s[68:71], s72 offen offset:32
	buffer_store_dwordx4 v[204:207], v235, s[68:71], s72 offen offset:48
	s_waitcnt vmcnt(8)
; __device__ __forceinline__ void mix16(const Z16& zp, const Z16& zc, const Z16& zn, const float* mp, const float* mn, float* o) {
;     float p_[16], c_[16], n_[16]; unz(zp, p_); unz(zc, c_); unz(zn, n_);
; #pragma unroll
;     for (int q = 0; q < 16; ++q) o[q] = c_[q] + mp[q] * (p_[q] - c_[q]) + mn[q] * (n_[q] - c_[q]);
; __device__ __forceinline__ void prep_phase(const Params& p) {
;     ...
;                 const bool hn = (tt0 + i) < SEQ - 1; const Z16 rn = hn ? ldz(zc + (size_t)(i + 1) * 3328) : zz();
;                 const size_t o = (size_t)(t0 + i) * RW + c;
;                 float r[16], k[16]; mix16(rp, rc, rn, mpr, mnr, r); unz(ldz(Kb + o), k);
;                 float bs = 0.f;
; #pragma unroll
;                 for (int q = 0; q < 16; ++q) bs += r[q] * k[q] * rkc[q];
;                 bs += __shfl_xor(bs, 1); bs += __shfl_xor(bs, 2);
; #pragma unroll
;                 for (int j4 = 0; j4 < 4; ++j4) *(f32x4*)(R + o + j4 * 4) = (f32x4){r[j4 * 4], r[j4 * 4 + 1], r[j4 * 4 + 2], r[j4 * 4 + 3]};
;                 if ((lane & 3) == 0) BON[(size_t)(t0 + i) * 16 + (lane >> 2)] = bs;
;                 rp = rc; rc = rn;
	v_lshlrev_b32_e32 v144, 16, v208
	v_and_b32_e32 v145, 0xffff0000, v208
	v_lshlrev_b32_e32 v146, 16, v209
	v_and_b32_e32 v147, 0xffff0000, v209
	v_lshlrev_b32_e32 v148, 16, v210
	v_and_b32_e32 v149, 0xffff0000, v210
	v_lshlrev_b32_e32 v150, 16, v211
	v_and_b32_e32 v151, 0xffff0000, v211
	v_lshlrev_b32_e32 v152, 16, v212
	v_and_b32_e32 v153, 0xffff0000, v212
	v_lshlrev_b32_e32 v154, 16, v213
	v_and_b32_e32 v155, 0xffff0000, v213
	v_lshlrev_b32_e32 v156, 16, v214
	v_and_b32_e32 v157, 0xffff0000, v214
	v_lshlrev_b32_e32 v158, 16, v215
	v_and_b32_e32 v159, 0xffff0000, v215
	v_pk_mul_f32 v[144:145], v[192:193], v[144:145]
	v_pk_mul_f32 v[146:147], v[194:195], v[146:147]
	v_pk_mul_f32 v[148:149], v[196:197], v[148:149]
	v_pk_mul_f32 v[150:151], v[198:199], v[150:151]
	v_pk_mul_f32 v[152:153], v[200:201], v[152:153]
	v_pk_mul_f32 v[154:155], v[202:203], v[154:155]
	v_pk_mul_f32 v[156:157], v[204:205], v[156:157]
	v_pk_mul_f32 v[158:159], v[206:207], v[158:159]
	v_mul_f32_e32 v224, v144, v128
	v_fmac_f32_e32 v224, v145, v129
	v_fmac_f32_e32 v224, v146, v130
	v_fmac_f32_e32 v224, v147, v131
	v_fmac_f32_e32 v224, v148, v132
	v_fmac_f32_e32 v224, v149, v133
	v_fmac_f32_e32 v224, v150, v134
	v_fmac_f32_e32 v224, v151, v135
	v_fmac_f32_e32 v224, v152, v136
	v_fmac_f32_e32 v224, v153, v137
	v_fmac_f32_e32 v224, v154, v138
	v_fmac_f32_e32 v224, v155, v139
	v_fmac_f32_e32 v224, v156, v140
	v_fmac_f32_e32 v224, v157, v141
	v_fmac_f32_e32 v224, v158, v142
	v_fmac_f32_e32 v224, v159, v143
	s_nop 1
	v_add_f32_dpp v224, v224, v224 quad_perm:[1,0,3,2] row_mask:0xf bank_mask:0xf
	s_nop 1
	v_add_f32_dpp v224, v224, v224 quad_perm:[2,3,0,1] row_mask:0xf bank_mask:0xf
	buffer_store_dword v224, v239, s[68:71], s75 offen
	s_add_u32 s72, s72, 0x1000
	s_add_u32 s73, s73, 0x800
	s_add_u32 s74, s74, 0x200
	s_add_u32 s75, s75, 0x40
	s_waitcnt vmcnt(19)
	v_lshlrev_b32_e32 v144, 16, v12
	v_and_b32_e32 v145, 0xffff0000, v12
	v_lshlrev_b32_e32 v146, 16, v13
	v_and_b32_e32 v147, 0xffff0000, v13
	v_lshlrev_b32_e32 v148, 16, v14
	v_and_b32_e32 v149, 0xffff0000, v14
	v_lshlrev_b32_e32 v150, 16, v15
	v_and_b32_e32 v151, 0xffff0000, v15
	v_lshlrev_b32_e32 v152, 16, v16
	v_and_b32_e32 v153, 0xffff0000, v16
	v_lshlrev_b32_e32 v154, 16, v17
	v_and_b32_e32 v155, 0xffff0000, v17
	v_lshlrev_b32_e32 v156, 16, v18
	v_and_b32_e32 v157, 0xffff0000, v18
	v_lshlrev_b32_e32 v158, 16, v19
	v_and_b32_e32 v159, 0xffff0000, v19
	v_lshlrev_b32_e32 v160, 16, v24
	v_and_b32_e32 v161, 0xffff0000, v24
	v_lshlrev_b32_e32 v162, 16, v25
	v_and_b32_e32 v163, 0xffff0000, v25
	v_lshlrev_b32_e32 v164, 16, v26
	v_and_b32_e32 v165, 0xffff0000, v26
	v_lshlrev_b32_e32 v166, 16, v27
	v_and_b32_e32 v167, 0xffff0000, v27
	v_lshlrev_b32_e32 v168, 16, v28
	v_and_b32_e32 v169, 0xffff0000, v28
	v_lshlrev_b32_e32 v170, 16, v29
	v_and_b32_e32 v171, 0xffff0000, v29
	v_lshlrev_b32_e32 v172, 16, v30
	v_and_b32_e32 v173, 0xffff0000, v30
	v_lshlrev_b32_e32 v174, 16, v31
	v_and_b32_e32 v175, 0xffff0000, v31
	v_lshlrev_b32_e32 v176, 16, v36
	v_and_b32_e32 v177, 0xffff0000, v36
	v_lshlrev_b32_e32 v178, 16, v37
	v_and_b32_e32 v179, 0xffff0000, v37
	v_lshlrev_b32_e32 v180, 16, v38
	v_and_b32_e32 v181, 0xffff0000, v38
	v_lshlrev_b32_e32 v182, 16, v39
	v_and_b32_e32 v183, 0xffff0000, v39
	v_lshlrev_b32_e32 v184, 16, v40
	v_and_b32_e32 v185, 0xffff0000, v40
	v_lshlrev_b32_e32 v186, 16, v41
	v_and_b32_e32 v187, 0xffff0000, v41
	v_lshlrev_b32_e32 v188, 16, v42
	v_and_b32_e32 v189, 0xffff0000, v42
	v_lshlrev_b32_e32 v190, 16, v43
	v_and_b32_e32 v191, 0xffff0000, v43
	buffer_load_dwordx4 v[12:15], v232, s[64:67], 0 offen
	buffer_load_dwordx4 v[16:19], v232, s[64:67], 0 offen offset:16
	v_add_u32_e32 v232, 6656, v232
	v_pk_add_f32 v[224:225], v[144:145], v[160:161] neg_lo:[0,1] neg_hi:[0,1]
	v_pk_add_f32 v[226:227], v[176:177], v[160:161] neg_lo:[0,1] neg_hi:[0,1]
	v_pk_fma_f32 v[192:193], v[96:97], v[224:225], v[160:161]
	v_pk_fma_f32 v[192:193], v[112:113], v[226:227], v[192:193]
	v_pk_add_f32 v[224:225], v[146:147], v[162:163] neg_lo:[0,1] neg_hi:[0,1]
	v_pk_add_f32 v[226:227], v[178:179], v[162:163] neg_lo:[0,1] neg_hi:[0,1]
	v_pk_fma_f32 v[194:195], v[98:99], v[224:225], v[162:163]
	v_pk_fma_f32 v[194:195], v[114:115], v[226:227], v[194:195]
	v_pk_add_f32 v[224:225], v[148:149], v[164:165] neg_lo:[0,1] neg_hi:[0,1]
	v_pk_add_f32 v[226:227], v[180:181], v[164:165] neg_lo:[0,1] neg_hi:[0,1]
	v_pk_fma_f32 v[196:197], v[100:101], v[224:225], v[164:165]
	v_pk_fma_f32 v[196:197], v[116:117], v[226:227], v[196:197]
	v_pk_add_f32 v[224:225], v[150:151], v[166:167] neg_lo:[0,1] neg_hi:[0,1]
	v_pk_add_f32 v[226:227], v[182:183], v[166:167] neg_lo:[0,1] neg_hi:[0,1]
	v_pk_fma_f32 v[198:199], v[102:103], v[224:225], v[166:167]
	v_pk_fma_f32 v[198:199], v[118:119], v[226:227], v[198:199]
	v_pk_add_f32 v[224:225], v[152:153], v[168:169] neg_lo:[0,1] neg_hi:[0,1]
	v_pk_add_f32 v[226:227], v[184:185], v[168:169] neg_lo:[0,1] neg_hi:[0,1]
	v_pk_fma_f32 v[200:201], v[104:105], v[224:225], v[168:169]
	v_pk_fma_f32 v[200:201], v[120:121], v[226:227], v[200:201]
	v_pk_add_f32 v[224:225], v[154:155], v[170:171] neg_lo:[0,1] neg_hi:[0,1]
	v_pk_add_f32 v[226:227], v[186:187], v[170:171] neg_lo:[0,1] neg_hi:[0,1]
	v_pk_fma_f32 v[202:203], v[106:107], v[224:225], v[170:171]
	v_pk_fma_f32 v[202:203], v[122:123], v[226:227], v[202:203]
	v_pk_add_f32 v[224:225], v[156:157], v[172:173] neg_lo:[0,1] neg_hi:[0,1]
	v_pk_add_f32 v[226:227], v[188:189], v[172:173] neg_lo:[0,1] neg_hi:[0,1]
	v_pk_fma_f32 v[204:205], v[108:109], v[224:225], v[172:173]
	v_pk_fma_f32 v[204:205], v[124:125], v[226:227], v[204:205]
	v_pk_add_f32 v[224:225], v[158:159], v[174:175] neg_lo:[0,1] neg_hi:[0,1]
	v_pk_add_f32 v[226:227], v[190:191], v[174:175] neg_lo:[0,1] neg_hi:[0,1]
	v_pk_fma_f32 v[206:207], v[110:111], v[224:225], v[174:175]
	v_pk_fma_f32 v[206:207], v[126:127], v[226:227], v[206:207]
	s_add_u32 s76, s76, 0x800
	buffer_load_dwordx4 v[208:211], v236, s[68:71], s76 offen
	buffer_load_dwordx4 v[212:215], v236, s[68:71], s76 offen offset:16
	buffer_store_dwordx4 v[192:195], v235, s[68:71], s72 offen offset:0
	buffer_store_dwordx4 v[196:199], v235, s[68:71], s72 offen offset:16
	buffer_store_dwordx4 v[200:203], v235, s[68:71], s72 offen offset:32
	buffer_store_dwordx4 v[204:207], v235, s[68:71], s72 offen offset:48
	s_waitcnt vmcnt(13)
; __device__ __forceinline__ void mix16(const Z16& zp, const Z16& zc, const Z16& zn, const float* mp, const float* mn, float* o) {
;     float p_[16], c_[16], n_[16]; unz(zp, p_); unz(zc, c_); unz(zn, n_);
; #pragma unroll
;     for (int q = 0; q < 16; ++q) o[q] = c_[q] + mp[q] * (p_[q] - c_[q]) + mn[q] * (n_[q] - c_[q]);
; __device__ __forceinline__ void prep_phase(const Params& p) {
;     ...
;                 const bool hn = (tt0 + i) < SEQ - 1; const Z16 rn = hn ? ldz(zc + (size_t)(i + 1) * 3328) : zz();
;                 const size_t o = (size_t)(t0 + i) * RW + c;
;                 float r[16], k[16]; mix16(rp, rc, rn, mpr, mnr, r); unz(ldz(Kb + o), k);
;                 float bs = 0.f;
; #pragma unroll
;                 for (int q = 0; q < 16; ++q) bs += r[q] * k[q] * rkc[q];
;                 bs += __shfl_xor(bs, 1); bs += __shfl_xor(bs, 2);
; #pragma unroll
;                 for (int j4 = 0; j4 < 4; ++j4) *(f32x4*)(R + o + j4 * 4) = (f32x4){r[j4 * 4], r[j4 * 4 + 1], r[j4 * 4 + 2], r[j4 * 4 + 3]};
;                 if ((lane & 3) == 0) BON[(size_t)(t0 + i) * 16 + (lane >> 2)] = bs;
;                 rp = rc; rc = rn;
	v_lshlrev_b32_e32 v144, 16, v216
	v_and_b32_e32 v145, 0xffff0000, v216
	v_lshlrev_b32_e32 v146, 16, v217
	v_and_b32_e32 v147, 0xffff0000, v217
	v_lshlrev_b32_e32 v148, 16, v218
	v_and_b32_e32 v149, 0xffff0000, v218
	v_lshlrev_b32_e32 v150, 16, v219
	v_and_b32_e32 v151, 0xffff0000, v219
	v_lshlrev_b32_e32 v152, 16, v220
	v_and_b32_e32 v153, 0xffff0000, v220
	v_lshlrev_b32_e32 v154, 16, v221
	v_and_b32_e32 v155, 0xffff0000, v221
	v_lshlrev_b32_e32 v156, 16, v222
	v_and_b32_e32 v157, 0xffff0000, v222
	v_lshlrev_b32_e32 v158, 16, v223
	v_and_b32_e32 v159, 0xffff0000, v223
	v_pk_mul_f32 v[144:145], v[192:193], v[144:145]
	v_pk_mul_f32 v[146:147], v[194:195], v[146:147]
	v_pk_mul_f32 v[148:149], v[196:197], v[148:149]
	v_pk_mul_f32 v[150:151], v[198:199], v[150:151]
	v_pk_mul_f32 v[152:153], v[200:201], v[152:153]
	v_pk_mul_f32 v[154:155], v[202:203], v[154:155]
	v_pk_mul_f32 v[156:157], v[204:205], v[156:157]
	v_pk_mul_f32 v[158:159], v[206:207], v[158:159]
	v_mul_f32_e32 v224, v144, v128
	v_fmac_f32_e32 v224, v145, v129
	v_fmac_f32_e32 v224, v146, v130
	v_fmac_f32_e32 v224, v147, v131
	v_fmac_f32_e32 v224, v148, v132
	v_fmac_f32_e32 v224, v149, v133
	v_fmac_f32_e32 v224, v150, v134
	v_fmac_f32_e32 v224, v151, v135
	v_fmac_f32_e32 v224, v152, v136
	v_fmac_f32_e32 v224, v153, v137
	v_fmac_f32_e32 v224, v154, v138
	v_fmac_f32_e32 v224, v155, v139
	v_fmac_f32_e32 v224, v156, v140
	v_fmac_f32_e32 v224, v157, v141
	v_fmac_f32_e32 v224, v158, v142
	v_fmac_f32_e32 v224, v159, v143
	s_nop 1
	v_add_f32_dpp v224, v224, v224 quad_perm:[1,0,3,2] row_mask:0xf bank_mask:0xf
	s_nop 1
	v_add_f32_dpp v224, v224, v224 quad_perm:[2,3,0,1] row_mask:0xf bank_mask:0xf
	buffer_store_dword v224, v239, s[68:71], s75 offen
	s_add_u32 s72, s72, 0x1000
	s_add_u32 s73, s73, 0x800
	s_add_u32 s74, s74, 0x200
	s_add_u32 s75, s75, 0x40
	s_waitcnt vmcnt(26)
	v_lshlrev_b32_e32 v144, 16, v24
	v_and_b32_e32 v145, 0xffff0000, v24
	v_lshlrev_b32_e32 v146, 16, v25
	v_and_b32_e32 v147, 0xffff0000, v25
	v_lshlrev_b32_e32 v148, 16, v26
	v_and_b32_e32 v149, 0xffff0000, v26
	v_lshlrev_b32_e32 v150, 16, v27
	v_and_b32_e32 v151, 0xffff0000, v27
	v_lshlrev_b32_e32 v152, 16, v28
	v_and_b32_e32 v153, 0xffff0000, v28
	v_lshlrev_b32_e32 v154, 16, v29
	v_and_b32_e32 v155, 0xffff0000, v29
	v_lshlrev_b32_e32 v156, 16, v30
	v_and_b32_e32 v157, 0xffff0000, v30
	v_lshlrev_b32_e32 v158, 16, v31
	v_and_b32_e32 v159, 0xffff0000, v31
	v_lshlrev_b32_e32 v160, 16, v36
	v_and_b32_e32 v161, 0xffff0000, v36
	v_lshlrev_b32_e32 v162, 16, v37
	v_and_b32_e32 v163, 0xffff0000, v37
	v_lshlrev_b32_e32 v164, 16, v38
	v_and_b32_e32 v165, 0xffff0000, v38
	v_lshlrev_b32_e32 v166, 16, v39
	v_and_b32_e32 v167, 0xffff0000, v39
	v_lshlrev_b32_e32 v168, 16, v40
	v_and_b32_e32 v169, 0xffff0000, v40
	v_lshlrev_b32_e32 v170, 16, v41
	v_and_b32_e32 v171, 0xffff0000, v41
	v_lshlrev_b32_e32 v172, 16, v42
	v_and_b32_e32 v173, 0xffff0000, v42
	v_lshlrev_b32_e32 v174, 16, v43
	v_and_b32_e32 v175, 0xffff0000, v43
	v_lshlrev_b32_e32 v176, 16, v48
	v_and_b32_e32 v177, 0xffff0000, v48
	v_lshlrev_b32_e32 v178, 16, v49
	v_and_b32_e32 v179, 0xffff0000, v49
	v_lshlrev_b32_e32 v180, 16, v50
	v_and_b32_e32 v181, 0xffff0000, v50
	v_lshlrev_b32_e32 v182, 16, v51
	v_and_b32_e32 v183, 0xffff0000, v51
	v_lshlrev_b32_e32 v184, 16, v52
	v_and_b32_e32 v185, 0xffff0000, v52
	v_lshlrev_b32_e32 v186, 16, v53
	v_and_b32_e32 v187, 0xffff0000, v53
	v_lshlrev_b32_e32 v188, 16, v54
	v_and_b32_e32 v189, 0xffff0000, v54
	v_lshlrev_b32_e32 v190, 16, v55
	v_and_b32_e32 v191, 0xffff0000, v55
	buffer_load_dwordx4 v[24:27], v232, s[64:67], 0 offen
	buffer_load_dwordx4 v[28:31], v232, s[64:67], 0 offen offset:16
	v_add_u32_e32 v232, 6656, v232
	v_pk_add_f32 v[224:225], v[144:145], v[160:161] neg_lo:[0,1] neg_hi:[0,1]
	v_pk_add_f32 v[226:227], v[176:177], v[160:161] neg_lo:[0,1] neg_hi:[0,1]
	v_pk_fma_f32 v[192:193], v[96:97], v[224:225], v[160:161]
	v_pk_fma_f32 v[192:193], v[112:113], v[226:227], v[192:193]
	v_pk_add_f32 v[224:225], v[146:147], v[162:163] neg_lo:[0,1] neg_hi:[0,1]
	v_pk_add_f32 v[226:227], v[178:179], v[162:163] neg_lo:[0,1] neg_hi:[0,1]
	v_pk_fma_f32 v[194:195], v[98:99], v[224:225], v[162:163]
	v_pk_fma_f32 v[194:195], v[114:115], v[226:227], v[194:195]
	v_pk_add_f32 v[224:225], v[148:149], v[164:165] neg_lo:[0,1] neg_hi:[0,1]
	v_pk_add_f32 v[226:227], v[180:181], v[164:165] neg_lo:[0,1] neg_hi:[0,1]
	v_pk_fma_f32 v[196:197], v[100:101], v[224:225], v[164:165]
	v_pk_fma_f32 v[196:197], v[116:117], v[226:227], v[196:197]
	v_pk_add_f32 v[224:225], v[150:151], v[166:167] neg_lo:[0,1] neg_hi:[0,1]
	v_pk_add_f32 v[226:227], v[182:183], v[166:167] neg_lo:[0,1] neg_hi:[0,1]
	v_pk_fma_f32 v[198:199], v[102:103], v[224:225], v[166:167]
	v_pk_fma_f32 v[198:199], v[118:119], v[226:227], v[198:199]
	v_pk_add_f32 v[224:225], v[152:153], v[168:169] neg_lo:[0,1] neg_hi:[0,1]
	v_pk_add_f32 v[226:227], v[184:185], v[168:169] neg_lo:[0,1] neg_hi:[0,1]
	v_pk_fma_f32 v[200:201], v[104:105], v[224:225], v[168:169]
	v_pk_fma_f32 v[200:201], v[120:121], v[226:227], v[200:201]
	v_pk_add_f32 v[224:225], v[154:155], v[170:171] neg_lo:[0,1] neg_hi:[0,1]
	v_pk_add_f32 v[226:227], v[186:187], v[170:171] neg_lo:[0,1] neg_hi:[0,1]
	v_pk_fma_f32 v[202:203], v[106:107], v[224:225], v[170:171]
	v_pk_fma_f32 v[202:203], v[122:123], v[226:227], v[202:203]
	v_pk_add_f32 v[224:225], v[156:157], v[172:173] neg_lo:[0,1] neg_hi:[0,1]
	v_pk_add_f32 v[226:227], v[188:189], v[172:173] neg_lo:[0,1] neg_hi:[0,1]
	v_pk_fma_f32 v[204:205], v[108:109], v[224:225], v[172:173]
	v_pk_fma_f32 v[204:205], v[124:125], v[226:227], v[204:205]
	v_pk_add_f32 v[224:225], v[158:159], v[174:175] neg_lo:[0,1] neg_hi:[0,1]
	v_pk_add_f32 v[226:227], v[190:191], v[174:175] neg_lo:[0,1] neg_hi:[0,1]
	v_pk_fma_f32 v[206:207], v[110:111], v[224:225], v[174:175]
	v_pk_fma_f32 v[206:207], v[126:127], v[226:227], v[206:207]
	s_add_u32 s76, s76, 0x800
	buffer_load_dwordx4 v[216:219], v236, s[68:71], s76 offen
	buffer_load_dwordx4 v[220:223], v236, s[68:71], s76 offen offset:16
	buffer_store_dwordx4 v[192:195], v235, s[68:71], s72 offen offset:0
	buffer_store_dwordx4 v[196:199], v235, s[68:71], s72 offen offset:16
	buffer_store_dwordx4 v[200:203], v235, s[68:71], s72 offen offset:32
	buffer_store_dwordx4 v[204:207], v235, s[68:71], s72 offen offset:48
	s_waitcnt vmcnt(13)
; __device__ __forceinline__ void mix16(const Z16& zp, const Z16& zc, const Z16& zn, const float* mp, const float* mn, float* o) {
;     float p_[16], c_[16], n_[16]; unz(zp, p_); unz(zc, c_); unz(zn, n_);
; #pragma unroll
;     for (int q = 0; q < 16; ++q) o[q] = c_[q] + mp[q] * (p_[q] - c_[q]) + mn[q] * (n_[q] - c_[q]);
; __device__ __forceinline__ void prep_phase(const Params& p) {
;     ...
;                 const bool hn = (tt0 + i) < SEQ - 1; const Z16 rn = hn ? ldz(zc + (size_t)(i + 1) * 3328) : zz();
;                 const size_t o = (size_t)(t0 + i) * RW + c;
;                 float r[16], k[16]; mix16(rp, rc, rn, mpr, mnr, r); unz(ldz(Kb + o), k);
;                 float bs = 0.f;
; #pragma unroll
;                 for (int q = 0; q < 16; ++q) bs += r[q] * k[q] * rkc[q];
;                 bs += __shfl_xor(bs, 1); bs += __shfl_xor(bs, 2);
; #pragma unroll
;                 for (int j4 = 0; j4 < 4; ++j4) *(f32x4*)(R + o + j4 * 4) = (f32x4){r[j4 * 4], r[j4 * 4 + 1], r[j4 * 4 + 2], r[j4 * 4 + 3]};
;                 if ((lane & 3) == 0) BON[(size_t)(t0 + i) * 16 + (lane >> 2)] = bs;
;                 rp = rc; rc = rn;
	v_lshlrev_b32_e32 v144, 16, v208
	v_and_b32_e32 v145, 0xffff0000, v208
	v_lshlrev_b32_e32 v146, 16, v209
	v_and_b32_e32 v147, 0xffff0000, v209
	v_lshlrev_b32_e32 v148, 16, v210
	v_and_b32_e32 v149, 0xffff0000, v210
	v_lshlrev_b32_e32 v150, 16, v211
	v_and_b32_e32 v151, 0xffff0000, v211
	v_lshlrev_b32_e32 v152, 16, v212
	v_and_b32_e32 v153, 0xffff0000, v212
	v_lshlrev_b32_e32 v154, 16, v213
	v_and_b32_e32 v155, 0xffff0000, v213
	v_lshlrev_b32_e32 v156, 16, v214
	v_and_b32_e32 v157, 0xffff0000, v214
	v_lshlrev_b32_e32 v158, 16, v215
	v_and_b32_e32 v159, 0xffff0000, v215
	v_pk_mul_f32 v[144:145], v[192:193], v[144:145]
	v_pk_mul_f32 v[146:147], v[194:195], v[146:147]
	v_pk_mul_f32 v[148:149], v[196:197], v[148:149]
	v_pk_mul_f32 v[150:151], v[198:199], v[150:151]
	v_pk_mul_f32 v[152:153], v[200:201], v[152:153]
	v_pk_mul_f32 v[154:155], v[202:203], v[154:155]
	v_pk_mul_f32 v[156:157], v[204:205], v[156:157]
	v_pk_mul_f32 v[158:159], v[206:207], v[158:159]
	v_mul_f32_e32 v224, v144, v128
	v_fmac_f32_e32 v224, v145, v129
	v_fmac_f32_e32 v224, v146, v130
	v_fmac_f32_e32 v224, v147, v131
	v_fmac_f32_e32 v224, v148, v132
	v_fmac_f32_e32 v224, v149, v133
	v_fmac_f32_e32 v224, v150, v134
	v_fmac_f32_e32 v224, v151, v135
	v_fmac_f32_e32 v224, v152, v136
	v_fmac_f32_e32 v224, v153, v137
	v_fmac_f32_e32 v224, v154, v138
	v_fmac_f32_e32 v224, v155, v139
	v_fmac_f32_e32 v224, v156, v140
	v_fmac_f32_e32 v224, v157, v141
	v_fmac_f32_e32 v224, v158, v142
	v_fmac_f32_e32 v224, v159, v143
	s_nop 1
	v_add_f32_dpp v224, v224, v224 quad_perm:[1,0,3,2] row_mask:0xf bank_mask:0xf
	s_nop 1
	v_add_f32_dpp v224, v224, v224 quad_perm:[2,3,0,1] row_mask:0xf bank_mask:0xf
	buffer_store_dword v224, v239, s[68:71], s75 offen
	s_add_u32 s72, s72, 0x1000
	s_add_u32 s73, s73, 0x800
	s_add_u32 s74, s74, 0x200
	s_add_u32 s75, s75, 0x40
	s_waitcnt vmcnt(33)
	v_lshlrev_b32_e32 v144, 16, v36
	v_and_b32_e32 v145, 0xffff0000, v36
	v_lshlrev_b32_e32 v146, 16, v37
	v_and_b32_e32 v147, 0xffff0000, v37
	v_lshlrev_b32_e32 v148, 16, v38
	v_and_b32_e32 v149, 0xffff0000, v38
	v_lshlrev_b32_e32 v150, 16, v39
	v_and_b32_e32 v151, 0xffff0000, v39
	v_lshlrev_b32_e32 v152, 16, v40
	v_and_b32_e32 v153, 0xffff0000, v40
	v_lshlrev_b32_e32 v154, 16, v41
	v_and_b32_e32 v155, 0xffff0000, v41
	v_lshlrev_b32_e32 v156, 16, v42
	v_and_b32_e32 v157, 0xffff0000, v42
	v_lshlrev_b32_e32 v158, 16, v43
	v_and_b32_e32 v159, 0xffff0000, v43
	v_lshlrev_b32_e32 v160, 16, v48
	v_and_b32_e32 v161, 0xffff0000, v48
	v_lshlrev_b32_e32 v162, 16, v49
	v_and_b32_e32 v163, 0xffff0000, v49
	v_lshlrev_b32_e32 v164, 16, v50
	v_and_b32_e32 v165, 0xffff0000, v50
	v_lshlrev_b32_e32 v166, 16, v51
	v_and_b32_e32 v167, 0xffff0000, v51
	v_lshlrev_b32_e32 v168, 16, v52
	v_and_b32_e32 v169, 0xffff0000, v52
	v_lshlrev_b32_e32 v170, 16, v53
	v_and_b32_e32 v171, 0xffff0000, v53
	v_lshlrev_b32_e32 v172, 16, v54
	v_and_b32_e32 v173, 0xffff0000, v54
	v_lshlrev_b32_e32 v174, 16, v55
	v_and_b32_e32 v175, 0xffff0000, v55
	v_lshlrev_b32_e32 v176, 16, v60
	v_and_b32_e32 v177, 0xffff0000, v60
	v_lshlrev_b32_e32 v178, 16, v61
	v_and_b32_e32 v179, 0xffff0000, v61
	v_lshlrev_b32_e32 v180, 16, v62
	v_and_b32_e32 v181, 0xffff0000, v62
	v_lshlrev_b32_e32 v182, 16, v63
	v_and_b32_e32 v183, 0xffff0000, v63
	v_lshlrev_b32_e32 v184, 16, v64
	v_and_b32_e32 v185, 0xffff0000, v64
	v_lshlrev_b32_e32 v186, 16, v65
	v_and_b32_e32 v187, 0xffff0000, v65
	v_lshlrev_b32_e32 v188, 16, v66
	v_and_b32_e32 v189, 0xffff0000, v66
	v_lshlrev_b32_e32 v190, 16, v67
	v_and_b32_e32 v191, 0xffff0000, v67
	buffer_load_dwordx4 v[36:39], v232, s[64:67], 0 offen
	buffer_load_dwordx4 v[40:43], v232, s[64:67], 0 offen offset:16
	v_add_u32_e32 v232, 6656, v232
	v_pk_add_f32 v[224:225], v[144:145], v[160:161] neg_lo:[0,1] neg_hi:[0,1]
	v_pk_add_f32 v[226:227], v[176:177], v[160:161] neg_lo:[0,1] neg_hi:[0,1]
	v_pk_fma_f32 v[192:193], v[96:97], v[224:225], v[160:161]
	v_pk_fma_f32 v[192:193], v[112:113], v[226:227], v[192:193]
	v_pk_add_f32 v[224:225], v[146:147], v[162:163] neg_lo:[0,1] neg_hi:[0,1]
	v_pk_add_f32 v[226:227], v[178:179], v[162:163] neg_lo:[0,1] neg_hi:[0,1]
	v_pk_fma_f32 v[194:195], v[98:99], v[224:225], v[162:163]
	v_pk_fma_f32 v[194:195], v[114:115], v[226:227], v[194:195]
	v_pk_add_f32 v[224:225], v[148:149], v[164:165] neg_lo:[0,1] neg_hi:[0,1]
	v_pk_add_f32 v[226:227], v[180:181], v[164:165] neg_lo:[0,1] neg_hi:[0,1]
	v_pk_fma_f32 v[196:197], v[100:101], v[224:225], v[164:165]
	v_pk_fma_f32 v[196:197], v[116:117], v[226:227], v[196:197]
	v_pk_add_f32 v[224:225], v[150:151], v[166:167] neg_lo:[0,1] neg_hi:[0,1]
	v_pk_add_f32 v[226:227], v[182:183], v[166:167] neg_lo:[0,1] neg_hi:[0,1]
	v_pk_fma_f32 v[198:199], v[102:103], v[224:225], v[166:167]
	v_pk_fma_f32 v[198:199], v[118:119], v[226:227], v[198:199]
	v_pk_add_f32 v[224:225], v[152:153], v[168:169] neg_lo:[0,1] neg_hi:[0,1]
	v_pk_add_f32 v[226:227], v[184:185], v[168:169] neg_lo:[0,1] neg_hi:[0,1]
	v_pk_fma_f32 v[200:201], v[104:105], v[224:225], v[168:169]
	v_pk_fma_f32 v[200:201], v[120:121], v[226:227], v[200:201]
	v_pk_add_f32 v[224:225], v[154:155], v[170:171] neg_lo:[0,1] neg_hi:[0,1]
	v_pk_add_f32 v[226:227], v[186:187], v[170:171] neg_lo:[0,1] neg_hi:[0,1]
	v_pk_fma_f32 v[202:203], v[106:107], v[224:225], v[170:171]
	v_pk_fma_f32 v[202:203], v[122:123], v[226:227], v[202:203]
	v_pk_add_f32 v[224:225], v[156:157], v[172:173] neg_lo:[0,1] neg_hi:[0,1]
	v_pk_add_f32 v[226:227], v[188:189], v[172:173] neg_lo:[0,1] neg_hi:[0,1]
	v_pk_fma_f32 v[204:205], v[108:109], v[224:225], v[172:173]
	v_pk_fma_f32 v[204:205], v[124:125], v[226:227], v[204:205]
	v_pk_add_f32 v[224:225], v[158:159], v[174:175] neg_lo:[0,1] neg_hi:[0,1]
	v_pk_add_f32 v[226:227], v[190:191], v[174:175] neg_lo:[0,1] neg_hi:[0,1]
	v_pk_fma_f32 v[206:207], v[110:111], v[224:225], v[174:175]
	v_pk_fma_f32 v[206:207], v[126:127], v[226:227], v[206:207]
	s_add_u32 s76, s76, 0x800
	buffer_load_dwordx4 v[208:211], v236, s[68:71], s76 offen
	buffer_load_dwordx4 v[212:215], v236, s[68:71], s76 offen offset:16
	buffer_store_dwordx4 v[192:195], v235, s[68:71], s72 offen offset:0
	buffer_store_dwordx4 v[196:199], v235, s[68:71], s72 offen offset:16
	buffer_store_dwordx4 v[200:203], v235, s[68:71], s72 offen offset:32
	buffer_store_dwordx4 v[204:207], v235, s[68:71], s72 offen offset:48
	s_waitcnt vmcnt(13)
; __device__ __forceinline__ void mix16(const Z16& zp, const Z16& zc, const Z16& zn, const float* mp, const float* mn, float* o) {
;     float p_[16], c_[16], n_[16]; unz(zp, p_); unz(zc, c_); unz(zn, n_);
; #pragma unroll
;     for (int q = 0; q < 16; ++q) o[q] = c_[q] + mp[q] * (p_[q] - c_[q]) + mn[q] * (n_[q] - c_[q]);
; __device__ __forceinline__ void prep_phase(const Params& p) {
;     ...
;                 const bool hn = (tt0 + i) < SEQ - 1; const Z16 rn = hn ? ldz(zc + (size_t)(i + 1) * 3328) : zz();
;                 const size_t o = (size_t)(t0 + i) * RW + c;
;                 float r[16], k[16]; mix16(rp, rc, rn, mpr, mnr, r); unz(ldz(Kb + o), k);
;                 float bs = 0.f;
; #pragma unroll
;                 for (int q = 0; q < 16; ++q) bs += r[q] * k[q] * rkc[q];
;                 bs += __shfl_xor(bs, 1); bs += __shfl_xor(bs, 2);
; #pragma unroll
;                 for (int j4 = 0; j4 < 4; ++j4) *(f32x4*)(R + o + j4 * 4) = (f32x4){r[j4 * 4], r[j4 * 4 + 1], r[j4 * 4 + 2], r[j4 * 4 + 3]};
;                 if ((lane & 3) == 0) BON[(size_t)(t0 + i) * 16 + (lane >> 2)] = bs;
;                 rp = rc; rc = rn;
	v_lshlrev_b32_e32 v144, 16, v216
	v_and_b32_e32 v145, 0xffff0000, v216
	v_lshlrev_b32_e32 v146, 16, v217
	v_and_b32_e32 v147, 0xffff0000, v217
	v_lshlrev_b32_e32 v148, 16, v218
	v_and_b32_e32 v149, 0xffff0000, v218
	v_lshlrev_b32_e32 v150, 16, v219
	v_and_b32_e32 v151, 0xffff0000, v219
	v_lshlrev_b32_e32 v152, 16, v220
	v_and_b32_e32 v153, 0xffff0000, v220
	v_lshlrev_b32_e32 v154, 16, v221
	v_and_b32_e32 v155, 0xffff0000, v221
	v_lshlrev_b32_e32 v156, 16, v222
	v_and_b32_e32 v157, 0xffff0000, v222
	v_lshlrev_b32_e32 v158, 16, v223
	v_and_b32_e32 v159, 0xffff0000, v223
	v_pk_mul_f32 v[144:145], v[192:193], v[144:145]
	v_pk_mul_f32 v[146:147], v[194:195], v[146:147]
	v_pk_mul_f32 v[148:149], v[196:197], v[148:149]
	v_pk_mul_f32 v[150:151], v[198:199], v[150:151]
	v_pk_mul_f32 v[152:153], v[200:201], v[152:153]
	v_pk_mul_f32 v[154:155], v[202:203], v[154:155]
	v_pk_mul_f32 v[156:157], v[204:205], v[156:157]
	v_pk_mul_f32 v[158:159], v[206:207], v[158:159]
	v_mul_f32_e32 v224, v144, v128
	v_fmac_f32_e32 v224, v145, v129
	v_fmac_f32_e32 v224, v146, v130
	v_fmac_f32_e32 v224, v147, v131
	v_fmac_f32_e32 v224, v148, v132
	v_fmac_f32_e32 v224, v149, v133
	v_fmac_f32_e32 v224, v150, v134
	v_fmac_f32_e32 v224, v151, v135
	v_fmac_f32_e32 v224, v152, v136
	v_fmac_f32_e32 v224, v153, v137
	v_fmac_f32_e32 v224, v154, v138
	v_fmac_f32_e32 v224, v155, v139
	v_fmac_f32_e32 v224, v156, v140
	v_fmac_f32_e32 v224, v157, v141
	v_fmac_f32_e32 v224, v158, v142
	v_fmac_f32_e32 v224, v159, v143
	s_nop 1
	v_add_f32_dpp v224, v224, v224 quad_perm:[1,0,3,2] row_mask:0xf bank_mask:0xf
	s_nop 1
	v_add_f32_dpp v224, v224, v224 quad_perm:[2,3,0,1] row_mask:0xf bank_mask:0xf
	buffer_store_dword v224, v239, s[68:71], s75 offen
	s_add_u32 s72, s72, 0x1000
	s_add_u32 s73, s73, 0x800
	s_add_u32 s74, s74, 0x200
	s_add_u32 s75, s75, 0x40
	s_waitcnt vmcnt(40)
	v_lshlrev_b32_e32 v144, 16, v48
	v_and_b32_e32 v145, 0xffff0000, v48
	v_lshlrev_b32_e32 v146, 16, v49
	v_and_b32_e32 v147, 0xffff0000, v49
	v_lshlrev_b32_e32 v148, 16, v50
	v_and_b32_e32 v149, 0xffff0000, v50
	v_lshlrev_b32_e32 v150, 16, v51
	v_and_b32_e32 v151, 0xffff0000, v51
	v_lshlrev_b32_e32 v152, 16, v52
	v_and_b32_e32 v153, 0xffff0000, v52
	v_lshlrev_b32_e32 v154, 16, v53
	v_and_b32_e32 v155, 0xffff0000, v53
	v_lshlrev_b32_e32 v156, 16, v54
	v_and_b32_e32 v157, 0xffff0000, v54
	v_lshlrev_b32_e32 v158, 16, v55
	v_and_b32_e32 v159, 0xffff0000, v55
	v_lshlrev_b32_e32 v160, 16, v60
	v_and_b32_e32 v161, 0xffff0000, v60
	v_lshlrev_b32_e32 v162, 16, v61
	v_and_b32_e32 v163, 0xffff0000, v61
	v_lshlrev_b32_e32 v164, 16, v62
	v_and_b32_e32 v165, 0xffff0000, v62
	v_lshlrev_b32_e32 v166, 16, v63
	v_and_b32_e32 v167, 0xffff0000, v63
	v_lshlrev_b32_e32 v168, 16, v64
	v_and_b32_e32 v169, 0xffff0000, v64
	v_lshlrev_b32_e32 v170, 16, v65
	v_and_b32_e32 v171, 0xffff0000, v65
	v_lshlrev_b32_e32 v172, 16, v66
	v_and_b32_e32 v173, 0xffff0000, v66
	v_lshlrev_b32_e32 v174, 16, v67
	v_and_b32_e32 v175, 0xffff0000, v67
	v_lshlrev_b32_e32 v176, 16, v72
	v_and_b32_e32 v177, 0xffff0000, v72
	v_lshlrev_b32_e32 v178, 16, v73
	v_and_b32_e32 v179, 0xffff0000, v73
	v_lshlrev_b32_e32 v180, 16, v74
	v_and_b32_e32 v181, 0xffff0000, v74
	v_lshlrev_b32_e32 v182, 16, v75
	v_and_b32_e32 v183, 0xffff0000, v75
	v_lshlrev_b32_e32 v184, 16, v76
	v_and_b32_e32 v185, 0xffff0000, v76
	v_lshlrev_b32_e32 v186, 16, v77
	v_and_b32_e32 v187, 0xffff0000, v77
	v_lshlrev_b32_e32 v188, 16, v78
	v_and_b32_e32 v189, 0xffff0000, v78
	v_lshlrev_b32_e32 v190, 16, v79
	v_and_b32_e32 v191, 0xffff0000, v79
	buffer_load_dwordx4 v[48:51], v232, s[64:67], 0 offen
	buffer_load_dwordx4 v[52:55], v232, s[64:67], 0 offen offset:16
	v_add_u32_e32 v232, 6656, v232
	v_pk_add_f32 v[224:225], v[144:145], v[160:161] neg_lo:[0,1] neg_hi:[0,1]
	v_pk_add_f32 v[226:227], v[176:177], v[160:161] neg_lo:[0,1] neg_hi:[0,1]
	v_pk_fma_f32 v[192:193], v[96:97], v[224:225], v[160:161]
	v_pk_fma_f32 v[192:193], v[112:113], v[226:227], v[192:193]
	v_pk_add_f32 v[224:225], v[146:147], v[162:163] neg_lo:[0,1] neg_hi:[0,1]
	v_pk_add_f32 v[226:227], v[178:179], v[162:163] neg_lo:[0,1] neg_hi:[0,1]
	v_pk_fma_f32 v[194:195], v[98:99], v[224:225], v[162:163]
	v_pk_fma_f32 v[194:195], v[114:115], v[226:227], v[194:195]
	v_pk_add_f32 v[224:225], v[148:149], v[164:165] neg_lo:[0,1] neg_hi:[0,1]
	v_pk_add_f32 v[226:227], v[180:181], v[164:165] neg_lo:[0,1] neg_hi:[0,1]
	v_pk_fma_f32 v[196:197], v[100:101], v[224:225], v[164:165]
	v_pk_fma_f32 v[196:197], v[116:117], v[226:227], v[196:197]
	v_pk_add_f32 v[224:225], v[150:151], v[166:167] neg_lo:[0,1] neg_hi:[0,1]
	v_pk_add_f32 v[226:227], v[182:183], v[166:167] neg_lo:[0,1] neg_hi:[0,1]
	v_pk_fma_f32 v[198:199], v[102:103], v[224:225], v[166:167]
	v_pk_fma_f32 v[198:199], v[118:119], v[226:227], v[198:199]
	v_pk_add_f32 v[224:225], v[152:153], v[168:169] neg_lo:[0,1] neg_hi:[0,1]
	v_pk_add_f32 v[226:227], v[184:185], v[168:169] neg_lo:[0,1] neg_hi:[0,1]
	v_pk_fma_f32 v[200:201], v[104:105], v[224:225], v[168:169]
	v_pk_fma_f32 v[200:201], v[120:121], v[226:227], v[200:201]
	v_pk_add_f32 v[224:225], v[154:155], v[170:171] neg_lo:[0,1] neg_hi:[0,1]
	v_pk_add_f32 v[226:227], v[186:187], v[170:171] neg_lo:[0,1] neg_hi:[0,1]
	v_pk_fma_f32 v[202:203], v[106:107], v[224:225], v[170:171]
	v_pk_fma_f32 v[202:203], v[122:123], v[226:227], v[202:203]
	v_pk_add_f32 v[224:225], v[156:157], v[172:173] neg_lo:[0,1] neg_hi:[0,1]
	v_pk_add_f32 v[226:227], v[188:189], v[172:173] neg_lo:[0,1] neg_hi:[0,1]
	v_pk_fma_f32 v[204:205], v[108:109], v[224:225], v[172:173]
	v_pk_fma_f32 v[204:205], v[124:125], v[226:227], v[204:205]
	v_pk_add_f32 v[224:225], v[158:159], v[174:175] neg_lo:[0,1] neg_hi:[0,1]
	v_pk_add_f32 v[226:227], v[190:191], v[174:175] neg_lo:[0,1] neg_hi:[0,1]
	v_pk_fma_f32 v[206:207], v[110:111], v[224:225], v[174:175]
	v_pk_fma_f32 v[206:207], v[126:127], v[226:227], v[206:207]
	s_add_u32 s76, s76, 0x800
	buffer_load_dwordx4 v[216:219], v236, s[68:71], s76 offen
	buffer_load_dwordx4 v[220:223], v236, s[68:71], s76 offen offset:16
	buffer_store_dwordx4 v[192:195], v235, s[68:71], s72 offen offset:0
	buffer_store_dwordx4 v[196:199], v235, s[68:71], s72 offen offset:16
	buffer_store_dwordx4 v[200:203], v235, s[68:71], s72 offen offset:32
	buffer_store_dwordx4 v[204:207], v235, s[68:71], s72 offen offset:48
	s_waitcnt vmcnt(13)
; __device__ __forceinline__ void mix16(const Z16& zp, const Z16& zc, const Z16& zn, const float* mp, const float* mn, float* o) {
;     float p_[16], c_[16], n_[16]; unz(zp, p_); unz(zc, c_); unz(zn, n_);
; #pragma unroll
;     for (int q = 0; q < 16; ++q) o[q] = c_[q] + mp[q] * (p_[q] - c_[q]) + mn[q] * (n_[q] - c_[q]);
; __device__ __forceinline__ void prep_phase(const Params& p) {
;     ...
;                 const bool hn = (tt0 + i) < SEQ - 1; const Z16 rn = hn ? ldz(zc + (size_t)(i + 1) * 3328) : zz();
;                 const size_t o = (size_t)(t0 + i) * RW + c;
;                 float r[16], k[16]; mix16(rp, rc, rn, mpr, mnr, r); unz(ldz(Kb + o), k);
;                 float bs = 0.f;
; #pragma unroll
;                 for (int q = 0; q < 16; ++q) bs += r[q] * k[q] * rkc[q];
;                 bs += __shfl_xor(bs, 1); bs += __shfl_xor(bs, 2);
; #pragma unroll
;                 for (int j4 = 0; j4 < 4; ++j4) *(f32x4*)(R + o + j4 * 4) = (f32x4){r[j4 * 4], r[j4 * 4 + 1], r[j4 * 4 + 2], r[j4 * 4 + 3]};
;                 if ((lane & 3) == 0) BON[(size_t)(t0 + i) * 16 + (lane >> 2)] = bs;
;                 rp = rc; rc = rn;
	v_lshlrev_b32_e32 v144, 16, v208
	v_and_b32_e32 v145, 0xffff0000, v208
	v_lshlrev_b32_e32 v146, 16, v209
	v_and_b32_e32 v147, 0xffff0000, v209
	v_lshlrev_b32_e32 v148, 16, v210
	v_and_b32_e32 v149, 0xffff0000, v210
	v_lshlrev_b32_e32 v150, 16, v211
	v_and_b32_e32 v151, 0xffff0000, v211
	v_lshlrev_b32_e32 v152, 16, v212
	v_and_b32_e32 v153, 0xffff0000, v212
	v_lshlrev_b32_e32 v154, 16, v213
	v_and_b32_e32 v155, 0xffff0000, v213
	v_lshlrev_b32_e32 v156, 16, v214
	v_and_b32_e32 v157, 0xffff0000, v214
	v_lshlrev_b32_e32 v158, 16, v215
	v_and_b32_e32 v159, 0xffff0000, v215
	v_pk_mul_f32 v[144:145], v[192:193], v[144:145]
	v_pk_mul_f32 v[146:147], v[194:195], v[146:147]
	v_pk_mul_f32 v[148:149], v[196:197], v[148:149]
	v_pk_mul_f32 v[150:151], v[198:199], v[150:151]
	v_pk_mul_f32 v[152:153], v[200:201], v[152:153]
	v_pk_mul_f32 v[154:155], v[202:203], v[154:155]
	v_pk_mul_f32 v[156:157], v[204:205], v[156:157]
	v_pk_mul_f32 v[158:159], v[206:207], v[158:159]
	v_mul_f32_e32 v224, v144, v128
	v_fmac_f32_e32 v224, v145, v129
	v_fmac_f32_e32 v224, v146, v130
	v_fmac_f32_e32 v224, v147, v131
	v_fmac_f32_e32 v224, v148, v132
	v_fmac_f32_e32 v224, v149, v133
	v_fmac_f32_e32 v224, v150, v134
	v_fmac_f32_e32 v224, v151, v135
	v_fmac_f32_e32 v224, v152, v136
	v_fmac_f32_e32 v224, v153, v137
	v_fmac_f32_e32 v224, v154, v138
	v_fmac_f32_e32 v224, v155, v139
	v_fmac_f32_e32 v224, v156, v140
	v_fmac_f32_e32 v224, v157, v141
	v_fmac_f32_e32 v224, v158, v142
	v_fmac_f32_e32 v224, v159, v143
	s_nop 1
	v_add_f32_dpp v224, v224, v224 quad_perm:[1,0,3,2] row_mask:0xf bank_mask:0xf
	s_nop 1
	v_add_f32_dpp v224, v224, v224 quad_perm:[2,3,0,1] row_mask:0xf bank_mask:0xf
	buffer_store_dword v224, v239, s[68:71], s75 offen
	s_add_u32 s72, s72, 0x1000
	s_add_u32 s73, s73, 0x800
	s_add_u32 s74, s74, 0x200
	s_add_u32 s75, s75, 0x40
	s_waitcnt vmcnt(47)
	v_lshlrev_b32_e32 v144, 16, v60
	v_and_b32_e32 v145, 0xffff0000, v60
	v_lshlrev_b32_e32 v146, 16, v61
	v_and_b32_e32 v147, 0xffff0000, v61
	v_lshlrev_b32_e32 v148, 16, v62
	v_and_b32_e32 v149, 0xffff0000, v62
	v_lshlrev_b32_e32 v150, 16, v63
	v_and_b32_e32 v151, 0xffff0000, v63
	v_lshlrev_b32_e32 v152, 16, v64
	v_and_b32_e32 v153, 0xffff0000, v64
	v_lshlrev_b32_e32 v154, 16, v65
	v_and_b32_e32 v155, 0xffff0000, v65
	v_lshlrev_b32_e32 v156, 16, v66
	v_and_b32_e32 v157, 0xffff0000, v66
	v_lshlrev_b32_e32 v158, 16, v67
	v_and_b32_e32 v159, 0xffff0000, v67
	v_lshlrev_b32_e32 v160, 16, v72
	v_and_b32_e32 v161, 0xffff0000, v72
	v_lshlrev_b32_e32 v162, 16, v73
	v_and_b32_e32 v163, 0xffff0000, v73
	v_lshlrev_b32_e32 v164, 16, v74
	v_and_b32_e32 v165, 0xffff0000, v74
	v_lshlrev_b32_e32 v166, 16, v75
	v_and_b32_e32 v167, 0xffff0000, v75
	v_lshlrev_b32_e32 v168, 16, v76
	v_and_b32_e32 v169, 0xffff0000, v76
	v_lshlrev_b32_e32 v170, 16, v77
	v_and_b32_e32 v171, 0xffff0000, v77
	v_lshlrev_b32_e32 v172, 16, v78
	v_and_b32_e32 v173, 0xffff0000, v78
	v_lshlrev_b32_e32 v174, 16, v79
	v_and_b32_e32 v175, 0xffff0000, v79
	v_lshlrev_b32_e32 v176, 16, v84
	v_and_b32_e32 v177, 0xffff0000, v84
	v_lshlrev_b32_e32 v178, 16, v85
	v_and_b32_e32 v179, 0xffff0000, v85
	v_lshlrev_b32_e32 v180, 16, v86
	v_and_b32_e32 v181, 0xffff0000, v86
	v_lshlrev_b32_e32 v182, 16, v87
	v_and_b32_e32 v183, 0xffff0000, v87
	v_lshlrev_b32_e32 v184, 16, v88
	v_and_b32_e32 v185, 0xffff0000, v88
	v_lshlrev_b32_e32 v186, 16, v89
	v_and_b32_e32 v187, 0xffff0000, v89
	v_lshlrev_b32_e32 v188, 16, v90
	v_and_b32_e32 v189, 0xffff0000, v90
	v_lshlrev_b32_e32 v190, 16, v91
	v_and_b32_e32 v191, 0xffff0000, v91
	buffer_load_dwordx4 v[60:63], v232, s[64:67], 0 offen
	buffer_load_dwordx4 v[64:67], v232, s[64:67], 0 offen offset:16
	v_add_u32_e32 v232, 6656, v232
	v_pk_add_f32 v[224:225], v[144:145], v[160:161] neg_lo:[0,1] neg_hi:[0,1]
	v_pk_add_f32 v[226:227], v[176:177], v[160:161] neg_lo:[0,1] neg_hi:[0,1]
	v_pk_fma_f32 v[192:193], v[96:97], v[224:225], v[160:161]
	v_pk_fma_f32 v[192:193], v[112:113], v[226:227], v[192:193]
	v_pk_add_f32 v[224:225], v[146:147], v[162:163] neg_lo:[0,1] neg_hi:[0,1]
	v_pk_add_f32 v[226:227], v[178:179], v[162:163] neg_lo:[0,1] neg_hi:[0,1]
	v_pk_fma_f32 v[194:195], v[98:99], v[224:225], v[162:163]
	v_pk_fma_f32 v[194:195], v[114:115], v[226:227], v[194:195]
	v_pk_add_f32 v[224:225], v[148:149], v[164:165] neg_lo:[0,1] neg_hi:[0,1]
	v_pk_add_f32 v[226:227], v[180:181], v[164:165] neg_lo:[0,1] neg_hi:[0,1]
	v_pk_fma_f32 v[196:197], v[100:101], v[224:225], v[164:165]
	v_pk_fma_f32 v[196:197], v[116:117], v[226:227], v[196:197]
	v_pk_add_f32 v[224:225], v[150:151], v[166:167] neg_lo:[0,1] neg_hi:[0,1]
	v_pk_add_f32 v[226:227], v[182:183], v[166:167] neg_lo:[0,1] neg_hi:[0,1]
	v_pk_fma_f32 v[198:199], v[102:103], v[224:225], v[166:167]
	v_pk_fma_f32 v[198:199], v[118:119], v[226:227], v[198:199]
	v_pk_add_f32 v[224:225], v[152:153], v[168:169] neg_lo:[0,1] neg_hi:[0,1]
	v_pk_add_f32 v[226:227], v[184:185], v[168:169] neg_lo:[0,1] neg_hi:[0,1]
	v_pk_fma_f32 v[200:201], v[104:105], v[224:225], v[168:169]
	v_pk_fma_f32 v[200:201], v[120:121], v[226:227], v[200:201]
	v_pk_add_f32 v[224:225], v[154:155], v[170:171] neg_lo:[0,1] neg_hi:[0,1]
	v_pk_add_f32 v[226:227], v[186:187], v[170:171] neg_lo:[0,1] neg_hi:[0,1]
	v_pk_fma_f32 v[202:203], v[106:107], v[224:225], v[170:171]
	v_pk_fma_f32 v[202:203], v[122:123], v[226:227], v[202:203]
	v_pk_add_f32 v[224:225], v[156:157], v[172:173] neg_lo:[0,1] neg_hi:[0,1]
	v_pk_add_f32 v[226:227], v[188:189], v[172:173] neg_lo:[0,1] neg_hi:[0,1]
	v_pk_fma_f32 v[204:205], v[108:109], v[224:225], v[172:173]
	v_pk_fma_f32 v[204:205], v[124:125], v[226:227], v[204:205]
	v_pk_add_f32 v[224:225], v[158:159], v[174:175] neg_lo:[0,1] neg_hi:[0,1]
	v_pk_add_f32 v[226:227], v[190:191], v[174:175] neg_lo:[0,1] neg_hi:[0,1]
	v_pk_fma_f32 v[206:207], v[110:111], v[224:225], v[174:175]
	v_pk_fma_f32 v[206:207], v[126:127], v[226:227], v[206:207]
	s_add_u32 s76, s76, 0x800
	buffer_load_dwordx4 v[208:211], v236, s[68:71], s76 offen
	buffer_load_dwordx4 v[212:215], v236, s[68:71], s76 offen offset:16
	buffer_store_dwordx4 v[192:195], v235, s[68:71], s72 offen offset:0
	buffer_store_dwordx4 v[196:199], v235, s[68:71], s72 offen offset:16
	buffer_store_dwordx4 v[200:203], v235, s[68:71], s72 offen offset:32
	buffer_store_dwordx4 v[204:207], v235, s[68:71], s72 offen offset:48
	s_waitcnt vmcnt(13)
; __device__ __forceinline__ void mix16(const Z16& zp, const Z16& zc, const Z16& zn, const float* mp, const float* mn, float* o) {
;     float p_[16], c_[16], n_[16]; unz(zp, p_); unz(zc, c_); unz(zn, n_);
; #pragma unroll
;     for (int q = 0; q < 16; ++q) o[q] = c_[q] + mp[q] * (p_[q] - c_[q]) + mn[q] * (n_[q] - c_[q]);
; __device__ __forceinline__ void prep_phase(const Params& p) {
;     ...
;                 const bool hn = (tt0 + i) < SEQ - 1; const Z16 rn = hn ? ldz(zc + (size_t)(i + 1) * 3328) : zz();
;                 const size_t o = (size_t)(t0 + i) * RW + c;
;                 float r[16], k[16]; mix16(rp, rc, rn, mpr, mnr, r); unz(ldz(Kb + o), k);
;                 float bs = 0.f;
; #pragma unroll
;                 for (int q = 0; q < 16; ++q) bs += r[q] * k[q] * rkc[q];
;                 bs += __shfl_xor(bs, 1); bs += __shfl_xor(bs, 2);
; #pragma unroll
;                 for (int j4 = 0; j4 < 4; ++j4) *(f32x4*)(R + o + j4 * 4) = (f32x4){r[j4 * 4], r[j4 * 4 + 1], r[j4 * 4 + 2], r[j4 * 4 + 3]};
;                 if ((lane & 3) == 0) BON[(size_t)(t0 + i) * 16 + (lane >> 2)] = bs;
;                 rp = rc; rc = rn;
	v_lshlrev_b32_e32 v144, 16, v216
	v_and_b32_e32 v145, 0xffff0000, v216
	v_lshlrev_b32_e32 v146, 16, v217
	v_and_b32_e32 v147, 0xffff0000, v217
	v_lshlrev_b32_e32 v148, 16, v218
	v_and_b32_e32 v149, 0xffff0000, v218
	v_lshlrev_b32_e32 v150, 16, v219
	v_and_b32_e32 v151, 0xffff0000, v219
	v_lshlrev_b32_e32 v152, 16, v220
	v_and_b32_e32 v153, 0xffff0000, v220
	v_lshlrev_b32_e32 v154, 16, v221
	v_and_b32_e32 v155, 0xffff0000, v221
	v_lshlrev_b32_e32 v156, 16, v222
	v_and_b32_e32 v157, 0xffff0000, v222
	v_lshlrev_b32_e32 v158, 16, v223
	v_and_b32_e32 v159, 0xffff0000, v223
	v_pk_mul_f32 v[144:145], v[192:193], v[144:145]
	v_pk_mul_f32 v[146:147], v[194:195], v[146:147]
	v_pk_mul_f32 v[148:149], v[196:197], v[148:149]
	v_pk_mul_f32 v[150:151], v[198:199], v[150:151]
	v_pk_mul_f32 v[152:153], v[200:201], v[152:153]
	v_pk_mul_f32 v[154:155], v[202:203], v[154:155]
	v_pk_mul_f32 v[156:157], v[204:205], v[156:157]
	v_pk_mul_f32 v[158:159], v[206:207], v[158:159]
	v_mul_f32_e32 v224, v144, v128
	v_fmac_f32_e32 v224, v145, v129
	v_fmac_f32_e32 v224, v146, v130
	v_fmac_f32_e32 v224, v147, v131
	v_fmac_f32_e32 v224, v148, v132
	v_fmac_f32_e32 v224, v149, v133
	v_fmac_f32_e32 v224, v150, v134
	v_fmac_f32_e32 v224, v151, v135
	v_fmac_f32_e32 v224, v152, v136
	v_fmac_f32_e32 v224, v153, v137
	v_fmac_f32_e32 v224, v154, v138
	v_fmac_f32_e32 v224, v155, v139
	v_fmac_f32_e32 v224, v156, v140
	v_fmac_f32_e32 v224, v157, v141
	v_fmac_f32_e32 v224, v158, v142
	v_fmac_f32_e32 v224, v159, v143
	s_nop 1
	v_add_f32_dpp v224, v224, v224 quad_perm:[1,0,3,2] row_mask:0xf bank_mask:0xf
	s_nop 1
	v_add_f32_dpp v224, v224, v224 quad_perm:[2,3,0,1] row_mask:0xf bank_mask:0xf
	buffer_store_dword v224, v239, s[68:71], s75 offen
	s_add_u32 s72, s72, 0x1000
	s_add_u32 s73, s73, 0x800
	s_add_u32 s74, s74, 0x200
	s_add_u32 s75, s75, 0x40
	s_waitcnt vmcnt(52)
	v_lshlrev_b32_e32 v144, 16, v72
	v_and_b32_e32 v145, 0xffff0000, v72
	v_lshlrev_b32_e32 v146, 16, v73
	v_and_b32_e32 v147, 0xffff0000, v73
	v_lshlrev_b32_e32 v148, 16, v74
	v_and_b32_e32 v149, 0xffff0000, v74
	v_lshlrev_b32_e32 v150, 16, v75
	v_and_b32_e32 v151, 0xffff0000, v75
	v_lshlrev_b32_e32 v152, 16, v76
	v_and_b32_e32 v153, 0xffff0000, v76
	v_lshlrev_b32_e32 v154, 16, v77
	v_and_b32_e32 v155, 0xffff0000, v77
	v_lshlrev_b32_e32 v156, 16, v78
	v_and_b32_e32 v157, 0xffff0000, v78
	v_lshlrev_b32_e32 v158, 16, v79
	v_and_b32_e32 v159, 0xffff0000, v79
	v_lshlrev_b32_e32 v160, 16, v84
	v_and_b32_e32 v161, 0xffff0000, v84
	v_lshlrev_b32_e32 v162, 16, v85
	v_and_b32_e32 v163, 0xffff0000, v85
	v_lshlrev_b32_e32 v164, 16, v86
	v_and_b32_e32 v165, 0xffff0000, v86
	v_lshlrev_b32_e32 v166, 16, v87
	v_and_b32_e32 v167, 0xffff0000, v87
	v_lshlrev_b32_e32 v168, 16, v88
	v_and_b32_e32 v169, 0xffff0000, v88
	v_lshlrev_b32_e32 v170, 16, v89
	v_and_b32_e32 v171, 0xffff0000, v89
	v_lshlrev_b32_e32 v172, 16, v90
	v_and_b32_e32 v173, 0xffff0000, v90
	v_lshlrev_b32_e32 v174, 16, v91
	v_and_b32_e32 v175, 0xffff0000, v91
	v_lshlrev_b32_e32 v176, 16, v0
	v_and_b32_e32 v177, 0xffff0000, v0
	v_lshlrev_b32_e32 v178, 16, v1
	v_and_b32_e32 v179, 0xffff0000, v1
	v_lshlrev_b32_e32 v180, 16, v2
	v_and_b32_e32 v181, 0xffff0000, v2
	v_lshlrev_b32_e32 v182, 16, v3
	v_and_b32_e32 v183, 0xffff0000, v3
	v_lshlrev_b32_e32 v184, 16, v4
	v_and_b32_e32 v185, 0xffff0000, v4
	v_lshlrev_b32_e32 v186, 16, v5
	v_and_b32_e32 v187, 0xffff0000, v5
	v_lshlrev_b32_e32 v188, 16, v6
	v_and_b32_e32 v189, 0xffff0000, v6
	v_lshlrev_b32_e32 v190, 16, v7
	v_and_b32_e32 v191, 0xffff0000, v7
	buffer_load_dwordx4 v[72:75], v232, s[64:67], 0 offen
	buffer_load_dwordx4 v[76:79], v232, s[64:67], 0 offen offset:16
	v_add_u32_e32 v232, 6656, v232
	v_pk_add_f32 v[224:225], v[144:145], v[160:161] neg_lo:[0,1] neg_hi:[0,1]
	v_pk_add_f32 v[226:227], v[176:177], v[160:161] neg_lo:[0,1] neg_hi:[0,1]
	v_pk_fma_f32 v[192:193], v[96:97], v[224:225], v[160:161]
	v_pk_fma_f32 v[192:193], v[112:113], v[226:227], v[192:193]
	v_pk_add_f32 v[224:225], v[146:147], v[162:163] neg_lo:[0,1] neg_hi:[0,1]
	v_pk_add_f32 v[226:227], v[178:179], v[162:163] neg_lo:[0,1] neg_hi:[0,1]
	v_pk_fma_f32 v[194:195], v[98:99], v[224:225], v[162:163]
	v_pk_fma_f32 v[194:195], v[114:115], v[226:227], v[194:195]
	v_pk_add_f32 v[224:225], v[148:149], v[164:165] neg_lo:[0,1] neg_hi:[0,1]
	v_pk_add_f32 v[226:227], v[180:181], v[164:165] neg_lo:[0,1] neg_hi:[0,1]
	v_pk_fma_f32 v[196:197], v[100:101], v[224:225], v[164:165]
	v_pk_fma_f32 v[196:197], v[116:117], v[226:227], v[196:197]
	v_pk_add_f32 v[224:225], v[150:151], v[166:167] neg_lo:[0,1] neg_hi:[0,1]
	v_pk_add_f32 v[226:227], v[182:183], v[166:167] neg_lo:[0,1] neg_hi:[0,1]
	v_pk_fma_f32 v[198:199], v[102:103], v[224:225], v[166:167]
	v_pk_fma_f32 v[198:199], v[118:119], v[226:227], v[198:199]
	v_pk_add_f32 v[224:225], v[152:153], v[168:169] neg_lo:[0,1] neg_hi:[0,1]
	v_pk_add_f32 v[226:227], v[184:185], v[168:169] neg_lo:[0,1] neg_hi:[0,1]
	v_pk_fma_f32 v[200:201], v[104:105], v[224:225], v[168:169]
	v_pk_fma_f32 v[200:201], v[120:121], v[226:227], v[200:201]
	v_pk_add_f32 v[224:225], v[154:155], v[170:171] neg_lo:[0,1] neg_hi:[0,1]
	v_pk_add_f32 v[226:227], v[186:187], v[170:171] neg_lo:[0,1] neg_hi:[0,1]
	v_pk_fma_f32 v[202:203], v[106:107], v[224:225], v[170:171]
	v_pk_fma_f32 v[202:203], v[122:123], v[226:227], v[202:203]
	v_pk_add_f32 v[224:225], v[156:157], v[172:173] neg_lo:[0,1] neg_hi:[0,1]
	v_pk_add_f32 v[226:227], v[188:189], v[172:173] neg_lo:[0,1] neg_hi:[0,1]
	v_pk_fma_f32 v[204:205], v[108:109], v[224:225], v[172:173]
	v_pk_fma_f32 v[204:205], v[124:125], v[226:227], v[204:205]
	v_pk_add_f32 v[224:225], v[158:159], v[174:175] neg_lo:[0,1] neg_hi:[0,1]
	v_pk_add_f32 v[226:227], v[190:191], v[174:175] neg_lo:[0,1] neg_hi:[0,1]
	v_pk_fma_f32 v[206:207], v[110:111], v[224:225], v[174:175]
	v_pk_fma_f32 v[206:207], v[126:127], v[226:227], v[206:207]
	s_add_u32 s76, s76, 0x800
	buffer_load_dwordx4 v[216:219], v236, s[68:71], s76 offen
	buffer_load_dwordx4 v[220:223], v236, s[68:71], s76 offen offset:16
	buffer_store_dwordx4 v[192:195], v235, s[68:71], s72 offen offset:0
	buffer_store_dwordx4 v[196:199], v235, s[68:71], s72 offen offset:16
	buffer_store_dwordx4 v[200:203], v235, s[68:71], s72 offen offset:32
	buffer_store_dwordx4 v[204:207], v235, s[68:71], s72 offen offset:48
	s_waitcnt vmcnt(13)
; __device__ __forceinline__ void mix16(const Z16& zp, const Z16& zc, const Z16& zn, const float* mp, const float* mn, float* o) {
;     float p_[16], c_[16], n_[16]; unz(zp, p_); unz(zc, c_); unz(zn, n_);
; #pragma unroll
;     for (int q = 0; q < 16; ++q) o[q] = c_[q] + mp[q] * (p_[q] - c_[q]) + mn[q] * (n_[q] - c_[q]);
; __device__ __forceinline__ void prep_phase(const Params& p) {
;     ...
;                 const bool hn = (tt0 + i) < SEQ - 1; const Z16 rn = hn ? ldz(zc + (size_t)(i + 1) * 3328) : zz();
;                 const size_t o = (size_t)(t0 + i) * RW + c;
;                 float r[16], k[16]; mix16(rp, rc, rn, mpr, mnr, r); unz(ldz(Kb + o), k);
;                 float bs = 0.f;
; #pragma unroll
;                 for (int q = 0; q < 16; ++q) bs += r[q] * k[q] * rkc[q];
;                 bs += __shfl_xor(bs, 1); bs += __shfl_xor(bs, 2);
; #pragma unroll
;                 for (int j4 = 0; j4 < 4; ++j4) *(f32x4*)(R + o + j4 * 4) = (f32x4){r[j4 * 4], r[j4 * 4 + 1], r[j4 * 4 + 2], r[j4 * 4 + 3]};
;                 if ((lane & 3) == 0) BON[(size_t)(t0 + i) * 16 + (lane >> 2)] = bs;
;                 rp = rc; rc = rn;
	v_lshlrev_b32_e32 v144, 16, v208
	v_and_b32_e32 v145, 0xffff0000, v208
	v_lshlrev_b32_e32 v146, 16, v209
	v_and_b32_e32 v147, 0xffff0000, v209
	v_lshlrev_b32_e32 v148, 16, v210
	v_and_b32_e32 v149, 0xffff0000, v210
	v_lshlrev_b32_e32 v150, 16, v211
	v_and_b32_e32 v151, 0xffff0000, v211
	v_lshlrev_b32_e32 v152, 16, v212
	v_and_b32_e32 v153, 0xffff0000, v212
	v_lshlrev_b32_e32 v154, 16, v213
	v_and_b32_e32 v155, 0xffff0000, v213
	v_lshlrev_b32_e32 v156, 16, v214
	v_and_b32_e32 v157, 0xffff0000, v214
	v_lshlrev_b32_e32 v158, 16, v215
	v_and_b32_e32 v159, 0xffff0000, v215
	v_pk_mul_f32 v[144:145], v[192:193], v[144:145]
	v_pk_mul_f32 v[146:147], v[194:195], v[146:147]
	v_pk_mul_f32 v[148:149], v[196:197], v[148:149]
	v_pk_mul_f32 v[150:151], v[198:199], v[150:151]
	v_pk_mul_f32 v[152:153], v[200:201], v[152:153]
	v_pk_mul_f32 v[154:155], v[202:203], v[154:155]
	v_pk_mul_f32 v[156:157], v[204:205], v[156:157]
	v_pk_mul_f32 v[158:159], v[206:207], v[158:159]
	v_mul_f32_e32 v224, v144, v128
	v_fmac_f32_e32 v224, v145, v129
	v_fmac_f32_e32 v224, v146, v130
	v_fmac_f32_e32 v224, v147, v131
	v_fmac_f32_e32 v224, v148, v132
	v_fmac_f32_e32 v224, v149, v133
	v_fmac_f32_e32 v224, v150, v134
	v_fmac_f32_e32 v224, v151, v135
	v_fmac_f32_e32 v224, v152, v136
	v_fmac_f32_e32 v224, v153, v137
	v_fmac_f32_e32 v224, v154, v138
	v_fmac_f32_e32 v224, v155, v139
	v_fmac_f32_e32 v224, v156, v140
	v_fmac_f32_e32 v224, v157, v141
	v_fmac_f32_e32 v224, v158, v142
	v_fmac_f32_e32 v224, v159, v143
	s_nop 1
	v_add_f32_dpp v224, v224, v224 quad_perm:[1,0,3,2] row_mask:0xf bank_mask:0xf
	s_nop 1
	v_add_f32_dpp v224, v224, v224 quad_perm:[2,3,0,1] row_mask:0xf bank_mask:0xf
	buffer_store_dword v224, v239, s[68:71], s75 offen
	s_add_u32 s72, s72, 0x1000
	s_add_u32 s73, s73, 0x800
	s_add_u32 s74, s74, 0x200
	s_add_u32 s75, s75, 0x40
	s_waitcnt vmcnt(52)
	v_lshlrev_b32_e32 v144, 16, v84
	v_and_b32_e32 v145, 0xffff0000, v84
	v_lshlrev_b32_e32 v146, 16, v85
	v_and_b32_e32 v147, 0xffff0000, v85
	v_lshlrev_b32_e32 v148, 16, v86
	v_and_b32_e32 v149, 0xffff0000, v86
	v_lshlrev_b32_e32 v150, 16, v87
	v_and_b32_e32 v151, 0xffff0000, v87
	v_lshlrev_b32_e32 v152, 16, v88
	v_and_b32_e32 v153, 0xffff0000, v88
	v_lshlrev_b32_e32 v154, 16, v89
	v_and_b32_e32 v155, 0xffff0000, v89
	v_lshlrev_b32_e32 v156, 16, v90
	v_and_b32_e32 v157, 0xffff0000, v90
	v_lshlrev_b32_e32 v158, 16, v91
	v_and_b32_e32 v159, 0xffff0000, v91
	v_lshlrev_b32_e32 v160, 16, v0
	v_and_b32_e32 v161, 0xffff0000, v0
	v_lshlrev_b32_e32 v162, 16, v1
	v_and_b32_e32 v163, 0xffff0000, v1
	v_lshlrev_b32_e32 v164, 16, v2
	v_and_b32_e32 v165, 0xffff0000, v2
	v_lshlrev_b32_e32 v166, 16, v3
	v_and_b32_e32 v167, 0xffff0000, v3
	v_lshlrev_b32_e32 v168, 16, v4
	v_and_b32_e32 v169, 0xffff0000, v4
	v_lshlrev_b32_e32 v170, 16, v5
	v_and_b32_e32 v171, 0xffff0000, v5
	v_lshlrev_b32_e32 v172, 16, v6
	v_and_b32_e32 v173, 0xffff0000, v6
	v_lshlrev_b32_e32 v174, 16, v7
	v_and_b32_e32 v175, 0xffff0000, v7
	v_lshlrev_b32_e32 v176, 16, v12
	v_and_b32_e32 v177, 0xffff0000, v12
	v_lshlrev_b32_e32 v178, 16, v13
	v_and_b32_e32 v179, 0xffff0000, v13
	v_lshlrev_b32_e32 v180, 16, v14
	v_and_b32_e32 v181, 0xffff0000, v14
	v_lshlrev_b32_e32 v182, 16, v15
	v_and_b32_e32 v183, 0xffff0000, v15
	v_lshlrev_b32_e32 v184, 16, v16
	v_and_b32_e32 v185, 0xffff0000, v16
	v_lshlrev_b32_e32 v186, 16, v17
	v_and_b32_e32 v187, 0xffff0000, v17
	v_lshlrev_b32_e32 v188, 16, v18
	v_and_b32_e32 v189, 0xffff0000, v18
	v_lshlrev_b32_e32 v190, 16, v19
	v_and_b32_e32 v191, 0xffff0000, v19
	buffer_load_dwordx4 v[84:87], v232, s[64:67], 0 offen
	buffer_load_dwordx4 v[88:91], v232, s[64:67], 0 offen offset:16
	v_add_u32_e32 v232, 6656, v232
	v_pk_add_f32 v[224:225], v[144:145], v[160:161] neg_lo:[0,1] neg_hi:[0,1]
	v_pk_add_f32 v[226:227], v[176:177], v[160:161] neg_lo:[0,1] neg_hi:[0,1]
	v_pk_fma_f32 v[192:193], v[96:97], v[224:225], v[160:161]
	v_pk_fma_f32 v[192:193], v[112:113], v[226:227], v[192:193]
	v_pk_add_f32 v[224:225], v[146:147], v[162:163] neg_lo:[0,1] neg_hi:[0,1]
	v_pk_add_f32 v[226:227], v[178:179], v[162:163] neg_lo:[0,1] neg_hi:[0,1]
	v_pk_fma_f32 v[194:195], v[98:99], v[224:225], v[162:163]
	v_pk_fma_f32 v[194:195], v[114:115], v[226:227], v[194:195]
	v_pk_add_f32 v[224:225], v[148:149], v[164:165] neg_lo:[0,1] neg_hi:[0,1]
	v_pk_add_f32 v[226:227], v[180:181], v[164:165] neg_lo:[0,1] neg_hi:[0,1]
	v_pk_fma_f32 v[196:197], v[100:101], v[224:225], v[164:165]
	v_pk_fma_f32 v[196:197], v[116:117], v[226:227], v[196:197]
	v_pk_add_f32 v[224:225], v[150:151], v[166:167] neg_lo:[0,1] neg_hi:[0,1]
	v_pk_add_f32 v[226:227], v[182:183], v[166:167] neg_lo:[0,1] neg_hi:[0,1]
	v_pk_fma_f32 v[198:199], v[102:103], v[224:225], v[166:167]
	v_pk_fma_f32 v[198:199], v[118:119], v[226:227], v[198:199]
	v_pk_add_f32 v[224:225], v[152:153], v[168:169] neg_lo:[0,1] neg_hi:[0,1]
	v_pk_add_f32 v[226:227], v[184:185], v[168:169] neg_lo:[0,1] neg_hi:[0,1]
	v_pk_fma_f32 v[200:201], v[104:105], v[224:225], v[168:169]
	v_pk_fma_f32 v[200:201], v[120:121], v[226:227], v[200:201]
	v_pk_add_f32 v[224:225], v[154:155], v[170:171] neg_lo:[0,1] neg_hi:[0,1]
	v_pk_add_f32 v[226:227], v[186:187], v[170:171] neg_lo:[0,1] neg_hi:[0,1]
	v_pk_fma_f32 v[202:203], v[106:107], v[224:225], v[170:171]
	v_pk_fma_f32 v[202:203], v[122:123], v[226:227], v[202:203]
	v_pk_add_f32 v[224:225], v[156:157], v[172:173] neg_lo:[0,1] neg_hi:[0,1]
	v_pk_add_f32 v[226:227], v[188:189], v[172:173] neg_lo:[0,1] neg_hi:[0,1]
	v_pk_fma_f32 v[204:205], v[108:109], v[224:225], v[172:173]
	v_pk_fma_f32 v[204:205], v[124:125], v[226:227], v[204:205]
	v_pk_add_f32 v[224:225], v[158:159], v[174:175] neg_lo:[0,1] neg_hi:[0,1]
	v_pk_add_f32 v[226:227], v[190:191], v[174:175] neg_lo:[0,1] neg_hi:[0,1]
	v_pk_fma_f32 v[206:207], v[110:111], v[224:225], v[174:175]
	v_pk_fma_f32 v[206:207], v[126:127], v[226:227], v[206:207]
	s_add_u32 s76, s76, 0x800
	buffer_load_dwordx4 v[208:211], v236, s[68:71], s76 offen
	buffer_load_dwordx4 v[212:215], v236, s[68:71], s76 offen offset:16
	buffer_store_dwordx4 v[192:195], v235, s[68:71], s72 offen offset:0
	buffer_store_dwordx4 v[196:199], v235, s[68:71], s72 offen offset:16
	buffer_store_dwordx4 v[200:203], v235, s[68:71], s72 offen offset:32
	buffer_store_dwordx4 v[204:207], v235, s[68:71], s72 offen offset:48
	s_waitcnt vmcnt(13)
; __device__ __forceinline__ void mix16(const Z16& zp, const Z16& zc, const Z16& zn, const float* mp, const float* mn, float* o) {
;     float p_[16], c_[16], n_[16]; unz(zp, p_); unz(zc, c_); unz(zn, n_);
; #pragma unroll
;     for (int q = 0; q < 16; ++q) o[q] = c_[q] + mp[q] * (p_[q] - c_[q]) + mn[q] * (n_[q] - c_[q]);
; __device__ __forceinline__ void prep_phase(const Params& p) {
;     ...
;                 const bool hn = (tt0 + i) < SEQ - 1; const Z16 rn = hn ? ldz(zc + (size_t)(i + 1) * 3328) : zz();
;                 const size_t o = (size_t)(t0 + i) * RW + c;
;                 float r[16], k[16]; mix16(rp, rc, rn, mpr, mnr, r); unz(ldz(Kb + o), k);
;                 float bs = 0.f;
; #pragma unroll
;                 for (int q = 0; q < 16; ++q) bs += r[q] * k[q] * rkc[q];
;                 bs += __shfl_xor(bs, 1); bs += __shfl_xor(bs, 2);
; #pragma unroll
;                 for (int j4 = 0; j4 < 4; ++j4) *(f32x4*)(R + o + j4 * 4) = (f32x4){r[j4 * 4], r[j4 * 4 + 1], r[j4 * 4 + 2], r[j4 * 4 + 3]};
;                 if ((lane & 3) == 0) BON[(size_t)(t0 + i) * 16 + (lane >> 2)] = bs;
;                 rp = rc; rc = rn;
	v_lshlrev_b32_e32 v144, 16, v216
	v_and_b32_e32 v145, 0xffff0000, v216
	v_lshlrev_b32_e32 v146, 16, v217
	v_and_b32_e32 v147, 0xffff0000, v217
	v_lshlrev_b32_e32 v148, 16, v218
	v_and_b32_e32 v149, 0xffff0000, v218
	v_lshlrev_b32_e32 v150, 16, v219
	v_and_b32_e32 v151, 0xffff0000, v219
	v_lshlrev_b32_e32 v152, 16, v220
	v_and_b32_e32 v153, 0xffff0000, v220
	v_lshlrev_b32_e32 v154, 16, v221
	v_and_b32_e32 v155, 0xffff0000, v221
	v_lshlrev_b32_e32 v156, 16, v222
	v_and_b32_e32 v157, 0xffff0000, v222
	v_lshlrev_b32_e32 v158, 16, v223
	v_and_b32_e32 v159, 0xffff0000, v223
	v_pk_mul_f32 v[144:145], v[192:193], v[144:145]
	v_pk_mul_f32 v[146:147], v[194:195], v[146:147]
	v_pk_mul_f32 v[148:149], v[196:197], v[148:149]
	v_pk_mul_f32 v[150:151], v[198:199], v[150:151]
	v_pk_mul_f32 v[152:153], v[200:201], v[152:153]
	v_pk_mul_f32 v[154:155], v[202:203], v[154:155]
	v_pk_mul_f32 v[156:157], v[204:205], v[156:157]
	v_pk_mul_f32 v[158:159], v[206:207], v[158:159]
	v_mul_f32_e32 v224, v144, v128
	v_fmac_f32_e32 v224, v145, v129
	v_fmac_f32_e32 v224, v146, v130
	v_fmac_f32_e32 v224, v147, v131
	v_fmac_f32_e32 v224, v148, v132
	v_fmac_f32_e32 v224, v149, v133
	v_fmac_f32_e32 v224, v150, v134
	v_fmac_f32_e32 v224, v151, v135
	v_fmac_f32_e32 v224, v152, v136
	v_fmac_f32_e32 v224, v153, v137
	v_fmac_f32_e32 v224, v154, v138
	v_fmac_f32_e32 v224, v155, v139
	v_fmac_f32_e32 v224, v156, v140
	v_fmac_f32_e32 v224, v157, v141
	v_fmac_f32_e32 v224, v158, v142
	v_fmac_f32_e32 v224, v159, v143
	s_nop 1
	v_add_f32_dpp v224, v224, v224 quad_perm:[1,0,3,2] row_mask:0xf bank_mask:0xf
	s_nop 1
	v_add_f32_dpp v224, v224, v224 quad_perm:[2,3,0,1] row_mask:0xf bank_mask:0xf
	buffer_store_dword v224, v239, s[68:71], s75 offen
	s_add_u32 s72, s72, 0x1000
	s_add_u32 s73, s73, 0x800
	s_add_u32 s74, s74, 0x200
	s_add_u32 s75, s75, 0x40
	s_waitcnt vmcnt(52)
	v_lshlrev_b32_e32 v144, 16, v0
	v_and_b32_e32 v145, 0xffff0000, v0
	v_lshlrev_b32_e32 v146, 16, v1
	v_and_b32_e32 v147, 0xffff0000, v1
	v_lshlrev_b32_e32 v148, 16, v2
	v_and_b32_e32 v149, 0xffff0000, v2
	v_lshlrev_b32_e32 v150, 16, v3
	v_and_b32_e32 v151, 0xffff0000, v3
	v_lshlrev_b32_e32 v152, 16, v4
	v_and_b32_e32 v153, 0xffff0000, v4
	v_lshlrev_b32_e32 v154, 16, v5
	v_and_b32_e32 v155, 0xffff0000, v5
	v_lshlrev_b32_e32 v156, 16, v6
	v_and_b32_e32 v157, 0xffff0000, v6
	v_lshlrev_b32_e32 v158, 16, v7
	v_and_b32_e32 v159, 0xffff0000, v7
	v_lshlrev_b32_e32 v160, 16, v12
	v_and_b32_e32 v161, 0xffff0000, v12
	v_lshlrev_b32_e32 v162, 16, v13
	v_and_b32_e32 v163, 0xffff0000, v13
	v_lshlrev_b32_e32 v164, 16, v14
	v_and_b32_e32 v165, 0xffff0000, v14
	v_lshlrev_b32_e32 v166, 16, v15
	v_and_b32_e32 v167, 0xffff0000, v15
	v_lshlrev_b32_e32 v168, 16, v16
	v_and_b32_e32 v169, 0xffff0000, v16
	v_lshlrev_b32_e32 v170, 16, v17
	v_and_b32_e32 v171, 0xffff0000, v17
	v_lshlrev_b32_e32 v172, 16, v18
	v_and_b32_e32 v173, 0xffff0000, v18
	v_lshlrev_b32_e32 v174, 16, v19
	v_and_b32_e32 v175, 0xffff0000, v19
	v_lshlrev_b32_e32 v176, 16, v24
	v_and_b32_e32 v177, 0xffff0000, v24
	v_lshlrev_b32_e32 v178, 16, v25
	v_and_b32_e32 v179, 0xffff0000, v25
	v_lshlrev_b32_e32 v180, 16, v26
	v_and_b32_e32 v181, 0xffff0000, v26
	v_lshlrev_b32_e32 v182, 16, v27
	v_and_b32_e32 v183, 0xffff0000, v27
	v_lshlrev_b32_e32 v184, 16, v28
	v_and_b32_e32 v185, 0xffff0000, v28
	v_lshlrev_b32_e32 v186, 16, v29
	v_and_b32_e32 v187, 0xffff0000, v29
	v_lshlrev_b32_e32 v188, 16, v30
	v_and_b32_e32 v189, 0xffff0000, v30
	v_lshlrev_b32_e32 v190, 16, v31
	v_and_b32_e32 v191, 0xffff0000, v31
	buffer_load_dwordx4 v[0:3], v232, s[64:67], 0 offen
	buffer_load_dwordx4 v[4:7], v232, s[64:67], 0 offen offset:16
	v_add_u32_e32 v232, 6656, v232
	v_pk_add_f32 v[224:225], v[144:145], v[160:161] neg_lo:[0,1] neg_hi:[0,1]
	v_pk_add_f32 v[226:227], v[176:177], v[160:161] neg_lo:[0,1] neg_hi:[0,1]
	v_pk_fma_f32 v[192:193], v[96:97], v[224:225], v[160:161]
	v_pk_fma_f32 v[192:193], v[112:113], v[226:227], v[192:193]
	v_pk_add_f32 v[224:225], v[146:147], v[162:163] neg_lo:[0,1] neg_hi:[0,1]
	v_pk_add_f32 v[226:227], v[178:179], v[162:163] neg_lo:[0,1] neg_hi:[0,1]
	v_pk_fma_f32 v[194:195], v[98:99], v[224:225], v[162:163]
	v_pk_fma_f32 v[194:195], v[114:115], v[226:227], v[194:195]
	v_pk_add_f32 v[224:225], v[148:149], v[164:165] neg_lo:[0,1] neg_hi:[0,1]
	v_pk_add_f32 v[226:227], v[180:181], v[164:165] neg_lo:[0,1] neg_hi:[0,1]
	v_pk_fma_f32 v[196:197], v[100:101], v[224:225], v[164:165]
	v_pk_fma_f32 v[196:197], v[116:117], v[226:227], v[196:197]
	v_pk_add_f32 v[224:225], v[150:151], v[166:167] neg_lo:[0,1] neg_hi:[0,1]
	v_pk_add_f32 v[226:227], v[182:183], v[166:167] neg_lo:[0,1] neg_hi:[0,1]
	v_pk_fma_f32 v[198:199], v[102:103], v[224:225], v[166:167]
	v_pk_fma_f32 v[198:199], v[118:119], v[226:227], v[198:199]
	v_pk_add_f32 v[224:225], v[152:153], v[168:169] neg_lo:[0,1] neg_hi:[0,1]
	v_pk_add_f32 v[226:227], v[184:185], v[168:169] neg_lo:[0,1] neg_hi:[0,1]
	v_pk_fma_f32 v[200:201], v[104:105], v[224:225], v[168:169]
	v_pk_fma_f32 v[200:201], v[120:121], v[226:227], v[200:201]
	v_pk_add_f32 v[224:225], v[154:155], v[170:171] neg_lo:[0,1] neg_hi:[0,1]
	v_pk_add_f32 v[226:227], v[186:187], v[170:171] neg_lo:[0,1] neg_hi:[0,1]
	v_pk_fma_f32 v[202:203], v[106:107], v[224:225], v[170:171]
	v_pk_fma_f32 v[202:203], v[122:123], v[226:227], v[202:203]
	v_pk_add_f32 v[224:225], v[156:157], v[172:173] neg_lo:[0,1] neg_hi:[0,1]
	v_pk_add_f32 v[226:227], v[188:189], v[172:173] neg_lo:[0,1] neg_hi:[0,1]
	v_pk_fma_f32 v[204:205], v[108:109], v[224:225], v[172:173]
	v_pk_fma_f32 v[204:205], v[124:125], v[226:227], v[204:205]
	v_pk_add_f32 v[224:225], v[158:159], v[174:175] neg_lo:[0,1] neg_hi:[0,1]
	v_pk_add_f32 v[226:227], v[190:191], v[174:175] neg_lo:[0,1] neg_hi:[0,1]
	v_pk_fma_f32 v[206:207], v[110:111], v[224:225], v[174:175]
	v_pk_fma_f32 v[206:207], v[126:127], v[226:227], v[206:207]
	s_add_u32 s76, s76, 0x800
	buffer_load_dwordx4 v[216:219], v236, s[68:71], s76 offen
	buffer_load_dwordx4 v[220:223], v236, s[68:71], s76 offen offset:16
	buffer_store_dwordx4 v[192:195], v235, s[68:71], s72 offen offset:0
	buffer_store_dwordx4 v[196:199], v235, s[68:71], s72 offen offset:16
	buffer_store_dwordx4 v[200:203], v235, s[68:71], s72 offen offset:32
	buffer_store_dwordx4 v[204:207], v235, s[68:71], s72 offen offset:48
	s_waitcnt vmcnt(13)
; __device__ __forceinline__ void mix16(const Z16& zp, const Z16& zc, const Z16& zn, const float* mp, const float* mn, float* o) {
;     float p_[16], c_[16], n_[16]; unz(zp, p_); unz(zc, c_); unz(zn, n_);
; #pragma unroll
;     for (int q = 0; q < 16; ++q) o[q] = c_[q] + mp[q] * (p_[q] - c_[q]) + mn[q] * (n_[q] - c_[q]);
; __device__ __forceinline__ void prep_phase(const Params& p) {
;     ...
;                 const bool hn = (tt0 + i) < SEQ - 1; const Z16 rn = hn ? ldz(zc + (size_t)(i + 1) * 3328) : zz();
;                 const size_t o = (size_t)(t0 + i) * RW + c;
;                 float r[16], k[16]; mix16(rp, rc, rn, mpr, mnr, r); unz(ldz(Kb + o), k);
;                 float bs = 0.f;
; #pragma unroll
;                 for (int q = 0; q < 16; ++q) bs += r[q] * k[q] * rkc[q];
;                 bs += __shfl_xor(bs, 1); bs += __shfl_xor(bs, 2);
; #pragma unroll
;                 for (int j4 = 0; j4 < 4; ++j4) *(f32x4*)(R + o + j4 * 4) = (f32x4){r[j4 * 4], r[j4 * 4 + 1], r[j4 * 4 + 2], r[j4 * 4 + 3]};
;                 if ((lane & 3) == 0) BON[(size_t)(t0 + i) * 16 + (lane >> 2)] = bs;
;                 rp = rc; rc = rn;
	v_lshlrev_b32_e32 v144, 16, v208
	v_and_b32_e32 v145, 0xffff0000, v208
	v_lshlrev_b32_e32 v146, 16, v209
	v_and_b32_e32 v147, 0xffff0000, v209
	v_lshlrev_b32_e32 v148, 16, v210
	v_and_b32_e32 v149, 0xffff0000, v210
	v_lshlrev_b32_e32 v150, 16, v211
	v_and_b32_e32 v151, 0xffff0000, v211
	v_lshlrev_b32_e32 v152, 16, v212
	v_and_b32_e32 v153, 0xffff0000, v212
	v_lshlrev_b32_e32 v154, 16, v213
	v_and_b32_e32 v155, 0xffff0000, v213
	v_lshlrev_b32_e32 v156, 16, v214
	v_and_b32_e32 v157, 0xffff0000, v214
	v_lshlrev_b32_e32 v158, 16, v215
	v_and_b32_e32 v159, 0xffff0000, v215
	v_pk_mul_f32 v[144:145], v[192:193], v[144:145]
	v_pk_mul_f32 v[146:147], v[194:195], v[146:147]
	v_pk_mul_f32 v[148:149], v[196:197], v[148:149]
	v_pk_mul_f32 v[150:151], v[198:199], v[150:151]
	v_pk_mul_f32 v[152:153], v[200:201], v[152:153]
	v_pk_mul_f32 v[154:155], v[202:203], v[154:155]
	v_pk_mul_f32 v[156:157], v[204:205], v[156:157]
	v_pk_mul_f32 v[158:159], v[206:207], v[158:159]
	v_mul_f32_e32 v224, v144, v128
	v_fmac_f32_e32 v224, v145, v129
	v_fmac_f32_e32 v224, v146, v130
	v_fmac_f32_e32 v224, v147, v131
	v_fmac_f32_e32 v224, v148, v132
	v_fmac_f32_e32 v224, v149, v133
	v_fmac_f32_e32 v224, v150, v134
	v_fmac_f32_e32 v224, v151, v135
	v_fmac_f32_e32 v224, v152, v136
	v_fmac_f32_e32 v224, v153, v137
	v_fmac_f32_e32 v224, v154, v138
	v_fmac_f32_e32 v224, v155, v139
	v_fmac_f32_e32 v224, v156, v140
	v_fmac_f32_e32 v224, v157, v141
	v_fmac_f32_e32 v224, v158, v142
	v_fmac_f32_e32 v224, v159, v143
	s_nop 1
	v_add_f32_dpp v224, v224, v224 quad_perm:[1,0,3,2] row_mask:0xf bank_mask:0xf
	s_nop 1
	v_add_f32_dpp v224, v224, v224 quad_perm:[2,3,0,1] row_mask:0xf bank_mask:0xf
	buffer_store_dword v224, v239, s[68:71], s75 offen
	s_add_u32 s72, s72, 0x1000
	s_add_u32 s73, s73, 0x800
	s_add_u32 s74, s74, 0x200
	s_add_u32 s75, s75, 0x40
	s_waitcnt vmcnt(52)
	v_lshlrev_b32_e32 v144, 16, v12
	v_and_b32_e32 v145, 0xffff0000, v12
	v_lshlrev_b32_e32 v146, 16, v13
	v_and_b32_e32 v147, 0xffff0000, v13
	v_lshlrev_b32_e32 v148, 16, v14
	v_and_b32_e32 v149, 0xffff0000, v14
	v_lshlrev_b32_e32 v150, 16, v15
	v_and_b32_e32 v151, 0xffff0000, v15
	v_lshlrev_b32_e32 v152, 16, v16
	v_and_b32_e32 v153, 0xffff0000, v16
	v_lshlrev_b32_e32 v154, 16, v17
	v_and_b32_e32 v155, 0xffff0000, v17
	v_lshlrev_b32_e32 v156, 16, v18
	v_and_b32_e32 v157, 0xffff0000, v18
	v_lshlrev_b32_e32 v158, 16, v19
	v_and_b32_e32 v159, 0xffff0000, v19
	v_lshlrev_b32_e32 v160, 16, v24
	v_and_b32_e32 v161, 0xffff0000, v24
	v_lshlrev_b32_e32 v162, 16, v25
	v_and_b32_e32 v163, 0xffff0000, v25
	v_lshlrev_b32_e32 v164, 16, v26
	v_and_b32_e32 v165, 0xffff0000, v26
	v_lshlrev_b32_e32 v166, 16, v27
	v_and_b32_e32 v167, 0xffff0000, v27
	v_lshlrev_b32_e32 v168, 16, v28
	v_and_b32_e32 v169, 0xffff0000, v28
	v_lshlrev_b32_e32 v170, 16, v29
	v_and_b32_e32 v171, 0xffff0000, v29
	v_lshlrev_b32_e32 v172, 16, v30
	v_and_b32_e32 v173, 0xffff0000, v30
	v_lshlrev_b32_e32 v174, 16, v31
	v_and_b32_e32 v175, 0xffff0000, v31
	v_lshlrev_b32_e32 v176, 16, v36
	v_and_b32_e32 v177, 0xffff0000, v36
	v_lshlrev_b32_e32 v178, 16, v37
	v_and_b32_e32 v179, 0xffff0000, v37
	v_lshlrev_b32_e32 v180, 16, v38
	v_and_b32_e32 v181, 0xffff0000, v38
	v_lshlrev_b32_e32 v182, 16, v39
	v_and_b32_e32 v183, 0xffff0000, v39
	v_lshlrev_b32_e32 v184, 16, v40
	v_and_b32_e32 v185, 0xffff0000, v40
	v_lshlrev_b32_e32 v186, 16, v41
	v_and_b32_e32 v187, 0xffff0000, v41
	v_lshlrev_b32_e32 v188, 16, v42
	v_and_b32_e32 v189, 0xffff0000, v42
	v_lshlrev_b32_e32 v190, 16, v43
	v_and_b32_e32 v191, 0xffff0000, v43
	buffer_load_dwordx4 v[12:15], v232, s[64:67], 0 offen
	buffer_load_dwordx4 v[16:19], v232, s[64:67], 0 offen offset:16
	v_add_u32_e32 v232, 6656, v232
	v_pk_add_f32 v[224:225], v[144:145], v[160:161] neg_lo:[0,1] neg_hi:[0,1]
	v_pk_add_f32 v[226:227], v[176:177], v[160:161] neg_lo:[0,1] neg_hi:[0,1]
	v_pk_fma_f32 v[192:193], v[96:97], v[224:225], v[160:161]
	v_pk_fma_f32 v[192:193], v[112:113], v[226:227], v[192:193]
	v_pk_add_f32 v[224:225], v[146:147], v[162:163] neg_lo:[0,1] neg_hi:[0,1]
	v_pk_add_f32 v[226:227], v[178:179], v[162:163] neg_lo:[0,1] neg_hi:[0,1]
	v_pk_fma_f32 v[194:195], v[98:99], v[224:225], v[162:163]
	v_pk_fma_f32 v[194:195], v[114:115], v[226:227], v[194:195]
	v_pk_add_f32 v[224:225], v[148:149], v[164:165] neg_lo:[0,1] neg_hi:[0,1]
	v_pk_add_f32 v[226:227], v[180:181], v[164:165] neg_lo:[0,1] neg_hi:[0,1]
	v_pk_fma_f32 v[196:197], v[100:101], v[224:225], v[164:165]
	v_pk_fma_f32 v[196:197], v[116:117], v[226:227], v[196:197]
	v_pk_add_f32 v[224:225], v[150:151], v[166:167] neg_lo:[0,1] neg_hi:[0,1]
	v_pk_add_f32 v[226:227], v[182:183], v[166:167] neg_lo:[0,1] neg_hi:[0,1]
	v_pk_fma_f32 v[198:199], v[102:103], v[224:225], v[166:167]
	v_pk_fma_f32 v[198:199], v[118:119], v[226:227], v[198:199]
	v_pk_add_f32 v[224:225], v[152:153], v[168:169] neg_lo:[0,1] neg_hi:[0,1]
	v_pk_add_f32 v[226:227], v[184:185], v[168:169] neg_lo:[0,1] neg_hi:[0,1]
	v_pk_fma_f32 v[200:201], v[104:105], v[224:225], v[168:169]
	v_pk_fma_f32 v[200:201], v[120:121], v[226:227], v[200:201]
	v_pk_add_f32 v[224:225], v[154:155], v[170:171] neg_lo:[0,1] neg_hi:[0,1]
	v_pk_add_f32 v[226:227], v[186:187], v[170:171] neg_lo:[0,1] neg_hi:[0,1]
	v_pk_fma_f32 v[202:203], v[106:107], v[224:225], v[170:171]
	v_pk_fma_f32 v[202:203], v[122:123], v[226:227], v[202:203]
	v_pk_add_f32 v[224:225], v[156:157], v[172:173] neg_lo:[0,1] neg_hi:[0,1]
	v_pk_add_f32 v[226:227], v[188:189], v[172:173] neg_lo:[0,1] neg_hi:[0,1]
	v_pk_fma_f32 v[204:205], v[108:109], v[224:225], v[172:173]
	v_pk_fma_f32 v[204:205], v[124:125], v[226:227], v[204:205]
	v_pk_add_f32 v[224:225], v[158:159], v[174:175] neg_lo:[0,1] neg_hi:[0,1]
	v_pk_add_f32 v[226:227], v[190:191], v[174:175] neg_lo:[0,1] neg_hi:[0,1]
	v_pk_fma_f32 v[206:207], v[110:111], v[224:225], v[174:175]
	v_pk_fma_f32 v[206:207], v[126:127], v[226:227], v[206:207]
	s_add_u32 s76, s76, 0x800
	buffer_load_dwordx4 v[208:211], v236, s[68:71], s76 offen
	buffer_load_dwordx4 v[212:215], v236, s[68:71], s76 offen offset:16
	buffer_store_dwordx4 v[192:195], v235, s[68:71], s72 offen offset:0
	buffer_store_dwordx4 v[196:199], v235, s[68:71], s72 offen offset:16
	buffer_store_dwordx4 v[200:203], v235, s[68:71], s72 offen offset:32
	buffer_store_dwordx4 v[204:207], v235, s[68:71], s72 offen offset:48
	s_waitcnt vmcnt(13)
; __device__ __forceinline__ void mix16(const Z16& zp, const Z16& zc, const Z16& zn, const float* mp, const float* mn, float* o) {
;     float p_[16], c_[16], n_[16]; unz(zp, p_); unz(zc, c_); unz(zn, n_);
; #pragma unroll
;     for (int q = 0; q < 16; ++q) o[q] = c_[q] + mp[q] * (p_[q] - c_[q]) + mn[q] * (n_[q] - c_[q]);
; __device__ __forceinline__ void prep_phase(const Params& p) {
;     ...
;                 const bool hn = (tt0 + i) < SEQ - 1; const Z16 rn = hn ? ldz(zc + (size_t)(i + 1) * 3328) : zz();
;                 const size_t o = (size_t)(t0 + i) * RW + c;
;                 float r[16], k[16]; mix16(rp, rc, rn, mpr, mnr, r); unz(ldz(Kb + o), k);
;                 float bs = 0.f;
; #pragma unroll
;                 for (int q = 0; q < 16; ++q) bs += r[q] * k[q] * rkc[q];
;                 bs += __shfl_xor(bs, 1); bs += __shfl_xor(bs, 2);
; #pragma unroll
;                 for (int j4 = 0; j4 < 4; ++j4) *(f32x4*)(R + o + j4 * 4) = (f32x4){r[j4 * 4], r[j4 * 4 + 1], r[j4 * 4 + 2], r[j4 * 4 + 3]};
;                 if ((lane & 3) == 0) BON[(size_t)(t0 + i) * 16 + (lane >> 2)] = bs;
;                 rp = rc; rc = rn;
	v_lshlrev_b32_e32 v144, 16, v216
	v_and_b32_e32 v145, 0xffff0000, v216
	v_lshlrev_b32_e32 v146, 16, v217
	v_and_b32_e32 v147, 0xffff0000, v217
	v_lshlrev_b32_e32 v148, 16, v218
	v_and_b32_e32 v149, 0xffff0000, v218
	v_lshlrev_b32_e32 v150, 16, v219
	v_and_b32_e32 v151, 0xffff0000, v219
	v_lshlrev_b32_e32 v152, 16, v220
	v_and_b32_e32 v153, 0xffff0000, v220
	v_lshlrev_b32_e32 v154, 16, v221
	v_and_b32_e32 v155, 0xffff0000, v221
	v_lshlrev_b32_e32 v156, 16, v222
	v_and_b32_e32 v157, 0xffff0000, v222
	v_lshlrev_b32_e32 v158, 16, v223
	v_and_b32_e32 v159, 0xffff0000, v223
	v_pk_mul_f32 v[144:145], v[192:193], v[144:145]
	v_pk_mul_f32 v[146:147], v[194:195], v[146:147]
	v_pk_mul_f32 v[148:149], v[196:197], v[148:149]
	v_pk_mul_f32 v[150:151], v[198:199], v[150:151]
	v_pk_mul_f32 v[152:153], v[200:201], v[152:153]
	v_pk_mul_f32 v[154:155], v[202:203], v[154:155]
	v_pk_mul_f32 v[156:157], v[204:205], v[156:157]
	v_pk_mul_f32 v[158:159], v[206:207], v[158:159]
	v_mul_f32_e32 v224, v144, v128
	v_fmac_f32_e32 v224, v145, v129
	v_fmac_f32_e32 v224, v146, v130
	v_fmac_f32_e32 v224, v147, v131
	v_fmac_f32_e32 v224, v148, v132
	v_fmac_f32_e32 v224, v149, v133
	v_fmac_f32_e32 v224, v150, v134
	v_fmac_f32_e32 v224, v151, v135
	v_fmac_f32_e32 v224, v152, v136
	v_fmac_f32_e32 v224, v153, v137
	v_fmac_f32_e32 v224, v154, v138
	v_fmac_f32_e32 v224, v155, v139
	v_fmac_f32_e32 v224, v156, v140
	v_fmac_f32_e32 v224, v157, v141
	v_fmac_f32_e32 v224, v158, v142
	v_fmac_f32_e32 v224, v159, v143
	s_nop 1
	v_add_f32_dpp v224, v224, v224 quad_perm:[1,0,3,2] row_mask:0xf bank_mask:0xf
	s_nop 1
	v_add_f32_dpp v224, v224, v224 quad_perm:[2,3,0,1] row_mask:0xf bank_mask:0xf
	buffer_store_dword v224, v239, s[68:71], s75 offen
	s_add_u32 s72, s72, 0x1000
	s_add_u32 s73, s73, 0x800
	s_add_u32 s74, s74, 0x200
	s_add_u32 s75, s75, 0x40
	s_waitcnt vmcnt(52)
	v_lshlrev_b32_e32 v144, 16, v24
	v_and_b32_e32 v145, 0xffff0000, v24
	v_lshlrev_b32_e32 v146, 16, v25
	v_and_b32_e32 v147, 0xffff0000, v25
	v_lshlrev_b32_e32 v148, 16, v26
	v_and_b32_e32 v149, 0xffff0000, v26
	v_lshlrev_b32_e32 v150, 16, v27
	v_and_b32_e32 v151, 0xffff0000, v27
	v_lshlrev_b32_e32 v152, 16, v28
	v_and_b32_e32 v153, 0xffff0000, v28
	v_lshlrev_b32_e32 v154, 16, v29
	v_and_b32_e32 v155, 0xffff0000, v29
	v_lshlrev_b32_e32 v156, 16, v30
	v_and_b32_e32 v157, 0xffff0000, v30
	v_lshlrev_b32_e32 v158, 16, v31
	v_and_b32_e32 v159, 0xffff0000, v31
	v_lshlrev_b32_e32 v160, 16, v36
	v_and_b32_e32 v161, 0xffff0000, v36
	v_lshlrev_b32_e32 v162, 16, v37
	v_and_b32_e32 v163, 0xffff0000, v37
	v_lshlrev_b32_e32 v164, 16, v38
	v_and_b32_e32 v165, 0xffff0000, v38
	v_lshlrev_b32_e32 v166, 16, v39
	v_and_b32_e32 v167, 0xffff0000, v39
	v_lshlrev_b32_e32 v168, 16, v40
	v_and_b32_e32 v169, 0xffff0000, v40
	v_lshlrev_b32_e32 v170, 16, v41
	v_and_b32_e32 v171, 0xffff0000, v41
	v_lshlrev_b32_e32 v172, 16, v42
	v_and_b32_e32 v173, 0xffff0000, v42
	v_lshlrev_b32_e32 v174, 16, v43
	v_and_b32_e32 v175, 0xffff0000, v43
	v_lshlrev_b32_e32 v176, 16, v48
	v_and_b32_e32 v177, 0xffff0000, v48
	v_lshlrev_b32_e32 v178, 16, v49
	v_and_b32_e32 v179, 0xffff0000, v49
	v_lshlrev_b32_e32 v180, 16, v50
	v_and_b32_e32 v181, 0xffff0000, v50
	v_lshlrev_b32_e32 v182, 16, v51
	v_and_b32_e32 v183, 0xffff0000, v51
	v_lshlrev_b32_e32 v184, 16, v52
	v_and_b32_e32 v185, 0xffff0000, v52
	v_lshlrev_b32_e32 v186, 16, v53
	v_and_b32_e32 v187, 0xffff0000, v53
	v_lshlrev_b32_e32 v188, 16, v54
	v_and_b32_e32 v189, 0xffff0000, v54
	v_lshlrev_b32_e32 v190, 16, v55
	v_and_b32_e32 v191, 0xffff0000, v55
	v_pk_add_f32 v[224:225], v[144:145], v[160:161] neg_lo:[0,1] neg_hi:[0,1]
	v_pk_add_f32 v[226:227], v[176:177], v[160:161] neg_lo:[0,1] neg_hi:[0,1]
	v_pk_fma_f32 v[192:193], v[96:97], v[224:225], v[160:161]
	v_pk_fma_f32 v[192:193], v[112:113], v[226:227], v[192:193]
	v_pk_add_f32 v[224:225], v[146:147], v[162:163] neg_lo:[0,1] neg_hi:[0,1]
	v_pk_add_f32 v[226:227], v[178:179], v[162:163] neg_lo:[0,1] neg_hi:[0,1]
	v_pk_fma_f32 v[194:195], v[98:99], v[224:225], v[162:163]
	v_pk_fma_f32 v[194:195], v[114:115], v[226:227], v[194:195]
	v_pk_add_f32 v[224:225], v[148:149], v[164:165] neg_lo:[0,1] neg_hi:[0,1]
	v_pk_add_f32 v[226:227], v[180:181], v[164:165] neg_lo:[0,1] neg_hi:[0,1]
	v_pk_fma_f32 v[196:197], v[100:101], v[224:225], v[164:165]
	v_pk_fma_f32 v[196:197], v[116:117], v[226:227], v[196:197]
	v_pk_add_f32 v[224:225], v[150:151], v[166:167] neg_lo:[0,1] neg_hi:[0,1]
	v_pk_add_f32 v[226:227], v[182:183], v[166:167] neg_lo:[0,1] neg_hi:[0,1]
	v_pk_fma_f32 v[198:199], v[102:103], v[224:225], v[166:167]
	v_pk_fma_f32 v[198:199], v[118:119], v[226:227], v[198:199]
	v_pk_add_f32 v[224:225], v[152:153], v[168:169] neg_lo:[0,1] neg_hi:[0,1]
	v_pk_add_f32 v[226:227], v[184:185], v[168:169] neg_lo:[0,1] neg_hi:[0,1]
	v_pk_fma_f32 v[200:201], v[104:105], v[224:225], v[168:169]
	v_pk_fma_f32 v[200:201], v[120:121], v[226:227], v[200:201]
	v_pk_add_f32 v[224:225], v[154:155], v[170:171] neg_lo:[0,1] neg_hi:[0,1]
	v_pk_add_f32 v[226:227], v[186:187], v[170:171] neg_lo:[0,1] neg_hi:[0,1]
	v_pk_fma_f32 v[202:203], v[106:107], v[224:225], v[170:171]
	v_pk_fma_f32 v[202:203], v[122:123], v[226:227], v[202:203]
	v_pk_add_f32 v[224:225], v[156:157], v[172:173] neg_lo:[0,1] neg_hi:[0,1]
	v_pk_add_f32 v[226:227], v[188:189], v[172:173] neg_lo:[0,1] neg_hi:[0,1]
	v_pk_fma_f32 v[204:205], v[108:109], v[224:225], v[172:173]
	v_pk_fma_f32 v[204:205], v[124:125], v[226:227], v[204:205]
	v_pk_add_f32 v[224:225], v[158:159], v[174:175] neg_lo:[0,1] neg_hi:[0,1]
	v_pk_add_f32 v[226:227], v[190:191], v[174:175] neg_lo:[0,1] neg_hi:[0,1]
	v_pk_fma_f32 v[206:207], v[110:111], v[224:225], v[174:175]
	v_pk_fma_f32 v[206:207], v[126:127], v[226:227], v[206:207]
	s_add_u32 s76, s76, 0x800
	buffer_load_dwordx4 v[216:219], v236, s[68:71], s76 offen
	buffer_load_dwordx4 v[220:223], v236, s[68:71], s76 offen offset:16
	buffer_store_dwordx4 v[192:195], v235, s[68:71], s72 offen offset:0
	buffer_store_dwordx4 v[196:199], v235, s[68:71], s72 offen offset:16
	buffer_store_dwordx4 v[200:203], v235, s[68:71], s72 offen offset:32
	buffer_store_dwordx4 v[204:207], v235, s[68:71], s72 offen offset:48
	s_waitcnt vmcnt(11)
; __device__ __forceinline__ void mix16(const Z16& zp, const Z16& zc, const Z16& zn, const float* mp, const float* mn, float* o) {
;     float p_[16], c_[16], n_[16]; unz(zp, p_); unz(zc, c_); unz(zn, n_);
; #pragma unroll
;     for (int q = 0; q < 16; ++q) o[q] = c_[q] + mp[q] * (p_[q] - c_[q]) + mn[q] * (n_[q] - c_[q]);
; __device__ __forceinline__ void prep_phase(const Params& p) {
;     ...
;                 const bool hn = (tt0 + i) < SEQ - 1; const Z16 rn = hn ? ldz(zc + (size_t)(i + 1) * 3328) : zz();
;                 const size_t o = (size_t)(t0 + i) * RW + c;
;                 float r[16], k[16]; mix16(rp, rc, rn, mpr, mnr, r); unz(ldz(Kb + o), k);
;                 float bs = 0.f;
; #pragma unroll
;                 for (int q = 0; q < 16; ++q) bs += r[q] * k[q] * rkc[q];
;                 bs += __shfl_xor(bs, 1); bs += __shfl_xor(bs, 2);
; #pragma unroll
;                 for (int j4 = 0; j4 < 4; ++j4) *(f32x4*)(R + o + j4 * 4) = (f32x4){r[j4 * 4], r[j4 * 4 + 1], r[j4 * 4 + 2], r[j4 * 4 + 3]};
;                 if ((lane & 3) == 0) BON[(size_t)(t0 + i) * 16 + (lane >> 2)] = bs;
;                 rp = rc; rc = rn;
	v_lshlrev_b32_e32 v144, 16, v208
	v_and_b32_e32 v145, 0xffff0000, v208
	v_lshlrev_b32_e32 v146, 16, v209
	v_and_b32_e32 v147, 0xffff0000, v209
	v_lshlrev_b32_e32 v148, 16, v210
	v_and_b32_e32 v149, 0xffff0000, v210
	v_lshlrev_b32_e32 v150, 16, v211
	v_and_b32_e32 v151, 0xffff0000, v211
	v_lshlrev_b32_e32 v152, 16, v212
	v_and_b32_e32 v153, 0xffff0000, v212
	v_lshlrev_b32_e32 v154, 16, v213
	v_and_b32_e32 v155, 0xffff0000, v213
	v_lshlrev_b32_e32 v156, 16, v214
	v_and_b32_e32 v157, 0xffff0000, v214
	v_lshlrev_b32_e32 v158, 16, v215
	v_and_b32_e32 v159, 0xffff0000, v215
	v_pk_mul_f32 v[144:145], v[192:193], v[144:145]
	v_pk_mul_f32 v[146:147], v[194:195], v[146:147]
	v_pk_mul_f32 v[148:149], v[196:197], v[148:149]
	v_pk_mul_f32 v[150:151], v[198:199], v[150:151]
	v_pk_mul_f32 v[152:153], v[200:201], v[152:153]
	v_pk_mul_f32 v[154:155], v[202:203], v[154:155]
	v_pk_mul_f32 v[156:157], v[204:205], v[156:157]
	v_pk_mul_f32 v[158:159], v[206:207], v[158:159]
	v_mul_f32_e32 v224, v144, v128
	v_fmac_f32_e32 v224, v145, v129
	v_fmac_f32_e32 v224, v146, v130
	v_fmac_f32_e32 v224, v147, v131
	v_fmac_f32_e32 v224, v148, v132
	v_fmac_f32_e32 v224, v149, v133
	v_fmac_f32_e32 v224, v150, v134
	v_fmac_f32_e32 v224, v151, v135
	v_fmac_f32_e32 v224, v152, v136
	v_fmac_f32_e32 v224, v153, v137
	v_fmac_f32_e32 v224, v154, v138
	v_fmac_f32_e32 v224, v155, v139
	v_fmac_f32_e32 v224, v156, v140
	v_fmac_f32_e32 v224, v157, v141
	v_fmac_f32_e32 v224, v158, v142
	v_fmac_f32_e32 v224, v159, v143
	s_nop 1
	v_add_f32_dpp v224, v224, v224 quad_perm:[1,0,3,2] row_mask:0xf bank_mask:0xf
	s_nop 1
	v_add_f32_dpp v224, v224, v224 quad_perm:[2,3,0,1] row_mask:0xf bank_mask:0xf
	buffer_store_dword v224, v239, s[68:71], s75 offen
	s_add_u32 s72, s72, 0x1000
	s_add_u32 s73, s73, 0x800
	s_add_u32 s74, s74, 0x200
	s_add_u32 s75, s75, 0x40
	s_waitcnt vmcnt(50)
	v_lshlrev_b32_e32 v144, 16, v36
	v_and_b32_e32 v145, 0xffff0000, v36
	v_lshlrev_b32_e32 v146, 16, v37
	v_and_b32_e32 v147, 0xffff0000, v37
	v_lshlrev_b32_e32 v148, 16, v38
	v_and_b32_e32 v149, 0xffff0000, v38
	v_lshlrev_b32_e32 v150, 16, v39
	v_and_b32_e32 v151, 0xffff0000, v39
	v_lshlrev_b32_e32 v152, 16, v40
	v_and_b32_e32 v153, 0xffff0000, v40
	v_lshlrev_b32_e32 v154, 16, v41
	v_and_b32_e32 v155, 0xffff0000, v41
	v_lshlrev_b32_e32 v156, 16, v42
	v_and_b32_e32 v157, 0xffff0000, v42
	v_lshlrev_b32_e32 v158, 16, v43
	v_and_b32_e32 v159, 0xffff0000, v43
	v_lshlrev_b32_e32 v160, 16, v48
	v_and_b32_e32 v161, 0xffff0000, v48
	v_lshlrev_b32_e32 v162, 16, v49
	v_and_b32_e32 v163, 0xffff0000, v49
	v_lshlrev_b32_e32 v164, 16, v50
	v_and_b32_e32 v165, 0xffff0000, v50
	v_lshlrev_b32_e32 v166, 16, v51
	v_and_b32_e32 v167, 0xffff0000, v51
	v_lshlrev_b32_e32 v168, 16, v52
	v_and_b32_e32 v169, 0xffff0000, v52
	v_lshlrev_b32_e32 v170, 16, v53
	v_and_b32_e32 v171, 0xffff0000, v53
	v_lshlrev_b32_e32 v172, 16, v54
	v_and_b32_e32 v173, 0xffff0000, v54
	v_lshlrev_b32_e32 v174, 16, v55
	v_and_b32_e32 v175, 0xffff0000, v55
	v_lshlrev_b32_e32 v176, 16, v60
	v_and_b32_e32 v177, 0xffff0000, v60
	v_lshlrev_b32_e32 v178, 16, v61
	v_and_b32_e32 v179, 0xffff0000, v61
	v_lshlrev_b32_e32 v180, 16, v62
	v_and_b32_e32 v181, 0xffff0000, v62
	v_lshlrev_b32_e32 v182, 16, v63
	v_and_b32_e32 v183, 0xffff0000, v63
	v_lshlrev_b32_e32 v184, 16, v64
	v_and_b32_e32 v185, 0xffff0000, v64
	v_lshlrev_b32_e32 v186, 16, v65
	v_and_b32_e32 v187, 0xffff0000, v65
	v_lshlrev_b32_e32 v188, 16, v66
	v_and_b32_e32 v189, 0xffff0000, v66
	v_lshlrev_b32_e32 v190, 16, v67
	v_and_b32_e32 v191, 0xffff0000, v67
	v_pk_add_f32 v[224:225], v[144:145], v[160:161] neg_lo:[0,1] neg_hi:[0,1]
	v_pk_add_f32 v[226:227], v[176:177], v[160:161] neg_lo:[0,1] neg_hi:[0,1]
	v_pk_fma_f32 v[192:193], v[96:97], v[224:225], v[160:161]
	v_pk_fma_f32 v[192:193], v[112:113], v[226:227], v[192:193]
	v_pk_add_f32 v[224:225], v[146:147], v[162:163] neg_lo:[0,1] neg_hi:[0,1]
	v_pk_add_f32 v[226:227], v[178:179], v[162:163] neg_lo:[0,1] neg_hi:[0,1]
	v_pk_fma_f32 v[194:195], v[98:99], v[224:225], v[162:163]
	v_pk_fma_f32 v[194:195], v[114:115], v[226:227], v[194:195]
	v_pk_add_f32 v[224:225], v[148:149], v[164:165] neg_lo:[0,1] neg_hi:[0,1]
	v_pk_add_f32 v[226:227], v[180:181], v[164:165] neg_lo:[0,1] neg_hi:[0,1]
	v_pk_fma_f32 v[196:197], v[100:101], v[224:225], v[164:165]
	v_pk_fma_f32 v[196:197], v[116:117], v[226:227], v[196:197]
	v_pk_add_f32 v[224:225], v[150:151], v[166:167] neg_lo:[0,1] neg_hi:[0,1]
	v_pk_add_f32 v[226:227], v[182:183], v[166:167] neg_lo:[0,1] neg_hi:[0,1]
	v_pk_fma_f32 v[198:199], v[102:103], v[224:225], v[166:167]
	v_pk_fma_f32 v[198:199], v[118:119], v[226:227], v[198:199]
	v_pk_add_f32 v[224:225], v[152:153], v[168:169] neg_lo:[0,1] neg_hi:[0,1]
	v_pk_add_f32 v[226:227], v[184:185], v[168:169] neg_lo:[0,1] neg_hi:[0,1]
	v_pk_fma_f32 v[200:201], v[104:105], v[224:225], v[168:169]
	v_pk_fma_f32 v[200:201], v[120:121], v[226:227], v[200:201]
	v_pk_add_f32 v[224:225], v[154:155], v[170:171] neg_lo:[0,1] neg_hi:[0,1]
	v_pk_add_f32 v[226:227], v[186:187], v[170:171] neg_lo:[0,1] neg_hi:[0,1]
	v_pk_fma_f32 v[202:203], v[106:107], v[224:225], v[170:171]
	v_pk_fma_f32 v[202:203], v[122:123], v[226:227], v[202:203]
	v_pk_add_f32 v[224:225], v[156:157], v[172:173] neg_lo:[0,1] neg_hi:[0,1]
	v_pk_add_f32 v[226:227], v[188:189], v[172:173] neg_lo:[0,1] neg_hi:[0,1]
	v_pk_fma_f32 v[204:205], v[108:109], v[224:225], v[172:173]
	v_pk_fma_f32 v[204:205], v[124:125], v[226:227], v[204:205]
	v_pk_add_f32 v[224:225], v[158:159], v[174:175] neg_lo:[0,1] neg_hi:[0,1]
	v_pk_add_f32 v[226:227], v[190:191], v[174:175] neg_lo:[0,1] neg_hi:[0,1]
	v_pk_fma_f32 v[206:207], v[110:111], v[224:225], v[174:175]
	v_pk_fma_f32 v[206:207], v[126:127], v[226:227], v[206:207]
	s_add_u32 s76, s76, 0x800
	buffer_load_dwordx4 v[208:211], v236, s[68:71], s76 offen
	buffer_load_dwordx4 v[212:215], v236, s[68:71], s76 offen offset:16
	buffer_store_dwordx4 v[192:195], v235, s[68:71], s72 offen offset:0
	buffer_store_dwordx4 v[196:199], v235, s[68:71], s72 offen offset:16
	buffer_store_dwordx4 v[200:203], v235, s[68:71], s72 offen offset:32
	buffer_store_dwordx4 v[204:207], v235, s[68:71], s72 offen offset:48
	s_waitcnt vmcnt(11)
; __device__ __forceinline__ void mix16(const Z16& zp, const Z16& zc, const Z16& zn, const float* mp, const float* mn, float* o) {
;     float p_[16], c_[16], n_[16]; unz(zp, p_); unz(zc, c_); unz(zn, n_);
; #pragma unroll
;     for (int q = 0; q < 16; ++q) o[q] = c_[q] + mp[q] * (p_[q] - c_[q]) + mn[q] * (n_[q] - c_[q]);
; __device__ __forceinline__ void prep_phase(const Params& p) {
;     ...
;                 const bool hn = (tt0 + i) < SEQ - 1; const Z16 rn = hn ? ldz(zc + (size_t)(i + 1) * 3328) : zz();
;                 const size_t o = (size_t)(t0 + i) * RW + c;
;                 float r[16], k[16]; mix16(rp, rc, rn, mpr, mnr, r); unz(ldz(Kb + o), k);
;                 float bs = 0.f;
; #pragma unroll
;                 for (int q = 0; q < 16; ++q) bs += r[q] * k[q] * rkc[q];
;                 bs += __shfl_xor(bs, 1); bs += __shfl_xor(bs, 2);
; #pragma unroll
;                 for (int j4 = 0; j4 < 4; ++j4) *(f32x4*)(R + o + j4 * 4) = (f32x4){r[j4 * 4], r[j4 * 4 + 1], r[j4 * 4 + 2], r[j4 * 4 + 3]};
;                 if ((lane & 3) == 0) BON[(size_t)(t0 + i) * 16 + (lane >> 2)] = bs;
;                 rp = rc; rc = rn;
	v_lshlrev_b32_e32 v144, 16, v216
	v_and_b32_e32 v145, 0xffff0000, v216
	v_lshlrev_b32_e32 v146, 16, v217
	v_and_b32_e32 v147, 0xffff0000, v217
	v_lshlrev_b32_e32 v148, 16, v218
	v_and_b32_e32 v149, 0xffff0000, v218
	v_lshlrev_b32_e32 v150, 16, v219
	v_and_b32_e32 v151, 0xffff0000, v219
	v_lshlrev_b32_e32 v152, 16, v220
	v_and_b32_e32 v153, 0xffff0000, v220
	v_lshlrev_b32_e32 v154, 16, v221
	v_and_b32_e32 v155, 0xffff0000, v221
	v_lshlrev_b32_e32 v156, 16, v222
	v_and_b32_e32 v157, 0xffff0000, v222
	v_lshlrev_b32_e32 v158, 16, v223
	v_and_b32_e32 v159, 0xffff0000, v223
	v_pk_mul_f32 v[144:145], v[192:193], v[144:145]
	v_pk_mul_f32 v[146:147], v[194:195], v[146:147]
	v_pk_mul_f32 v[148:149], v[196:197], v[148:149]
	v_pk_mul_f32 v[150:151], v[198:199], v[150:151]
	v_pk_mul_f32 v[152:153], v[200:201], v[152:153]
	v_pk_mul_f32 v[154:155], v[202:203], v[154:155]
	v_pk_mul_f32 v[156:157], v[204:205], v[156:157]
	v_pk_mul_f32 v[158:159], v[206:207], v[158:159]
	v_mul_f32_e32 v224, v144, v128
	v_fmac_f32_e32 v224, v145, v129
	v_fmac_f32_e32 v224, v146, v130
	v_fmac_f32_e32 v224, v147, v131
	v_fmac_f32_e32 v224, v148, v132
	v_fmac_f32_e32 v224, v149, v133
	v_fmac_f32_e32 v224, v150, v134
	v_fmac_f32_e32 v224, v151, v135
	v_fmac_f32_e32 v224, v152, v136
	v_fmac_f32_e32 v224, v153, v137
	v_fmac_f32_e32 v224, v154, v138
	v_fmac_f32_e32 v224, v155, v139
	v_fmac_f32_e32 v224, v156, v140
	v_fmac_f32_e32 v224, v157, v141
	v_fmac_f32_e32 v224, v158, v142
	v_fmac_f32_e32 v224, v159, v143
	s_nop 1
	v_add_f32_dpp v224, v224, v224 quad_perm:[1,0,3,2] row_mask:0xf bank_mask:0xf
	s_nop 1
	v_add_f32_dpp v224, v224, v224 quad_perm:[2,3,0,1] row_mask:0xf bank_mask:0xf
	buffer_store_dword v224, v239, s[68:71], s75 offen
	s_add_u32 s72, s72, 0x1000
	s_add_u32 s73, s73, 0x800
	s_add_u32 s74, s74, 0x200
	s_add_u32 s75, s75, 0x40
	s_waitcnt vmcnt(48)
	v_lshlrev_b32_e32 v144, 16, v48
	v_and_b32_e32 v145, 0xffff0000, v48
	v_lshlrev_b32_e32 v146, 16, v49
	v_and_b32_e32 v147, 0xffff0000, v49
	v_lshlrev_b32_e32 v148, 16, v50
	v_and_b32_e32 v149, 0xffff0000, v50
	v_lshlrev_b32_e32 v150, 16, v51
	v_and_b32_e32 v151, 0xffff0000, v51
	v_lshlrev_b32_e32 v152, 16, v52
	v_and_b32_e32 v153, 0xffff0000, v52
	v_lshlrev_b32_e32 v154, 16, v53
	v_and_b32_e32 v155, 0xffff0000, v53
	v_lshlrev_b32_e32 v156, 16, v54
	v_and_b32_e32 v157, 0xffff0000, v54
	v_lshlrev_b32_e32 v158, 16, v55
	v_and_b32_e32 v159, 0xffff0000, v55
	v_lshlrev_b32_e32 v160, 16, v60
	v_and_b32_e32 v161, 0xffff0000, v60
	v_lshlrev_b32_e32 v162, 16, v61
	v_and_b32_e32 v163, 0xffff0000, v61
	v_lshlrev_b32_e32 v164, 16, v62
	v_and_b32_e32 v165, 0xffff0000, v62
	v_lshlrev_b32_e32 v166, 16, v63
	v_and_b32_e32 v167, 0xffff0000, v63
	v_lshlrev_b32_e32 v168, 16, v64
	v_and_b32_e32 v169, 0xffff0000, v64
	v_lshlrev_b32_e32 v170, 16, v65
	v_and_b32_e32 v171, 0xffff0000, v65
	v_lshlrev_b32_e32 v172, 16, v66
	v_and_b32_e32 v173, 0xffff0000, v66
	v_lshlrev_b32_e32 v174, 16, v67
	v_and_b32_e32 v175, 0xffff0000, v67
	v_lshlrev_b32_e32 v176, 16, v72
	v_and_b32_e32 v177, 0xffff0000, v72
	v_lshlrev_b32_e32 v178, 16, v73
	v_and_b32_e32 v179, 0xffff0000, v73
	v_lshlrev_b32_e32 v180, 16, v74
	v_and_b32_e32 v181, 0xffff0000, v74
	v_lshlrev_b32_e32 v182, 16, v75
	v_and_b32_e32 v183, 0xffff0000, v75
	v_lshlrev_b32_e32 v184, 16, v76
	v_and_b32_e32 v185, 0xffff0000, v76
	v_lshlrev_b32_e32 v186, 16, v77
	v_and_b32_e32 v187, 0xffff0000, v77
	v_lshlrev_b32_e32 v188, 16, v78
	v_and_b32_e32 v189, 0xffff0000, v78
	v_lshlrev_b32_e32 v190, 16, v79
	v_and_b32_e32 v191, 0xffff0000, v79
	v_pk_add_f32 v[224:225], v[144:145], v[160:161] neg_lo:[0,1] neg_hi:[0,1]
	v_pk_add_f32 v[226:227], v[176:177], v[160:161] neg_lo:[0,1] neg_hi:[0,1]
	v_pk_fma_f32 v[192:193], v[96:97], v[224:225], v[160:161]
	v_pk_fma_f32 v[192:193], v[112:113], v[226:227], v[192:193]
	v_pk_add_f32 v[224:225], v[146:147], v[162:163] neg_lo:[0,1] neg_hi:[0,1]
	v_pk_add_f32 v[226:227], v[178:179], v[162:163] neg_lo:[0,1] neg_hi:[0,1]
	v_pk_fma_f32 v[194:195], v[98:99], v[224:225], v[162:163]
	v_pk_fma_f32 v[194:195], v[114:115], v[226:227], v[194:195]
	v_pk_add_f32 v[224:225], v[148:149], v[164:165] neg_lo:[0,1] neg_hi:[0,1]
	v_pk_add_f32 v[226:227], v[180:181], v[164:165] neg_lo:[0,1] neg_hi:[0,1]
	v_pk_fma_f32 v[196:197], v[100:101], v[224:225], v[164:165]
	v_pk_fma_f32 v[196:197], v[116:117], v[226:227], v[196:197]
	v_pk_add_f32 v[224:225], v[150:151], v[166:167] neg_lo:[0,1] neg_hi:[0,1]
	v_pk_add_f32 v[226:227], v[182:183], v[166:167] neg_lo:[0,1] neg_hi:[0,1]
	v_pk_fma_f32 v[198:199], v[102:103], v[224:225], v[166:167]
	v_pk_fma_f32 v[198:199], v[118:119], v[226:227], v[198:199]
	v_pk_add_f32 v[224:225], v[152:153], v[168:169] neg_lo:[0,1] neg_hi:[0,1]
	v_pk_add_f32 v[226:227], v[184:185], v[168:169] neg_lo:[0,1] neg_hi:[0,1]
	v_pk_fma_f32 v[200:201], v[104:105], v[224:225], v[168:169]
	v_pk_fma_f32 v[200:201], v[120:121], v[226:227], v[200:201]
	v_pk_add_f32 v[224:225], v[154:155], v[170:171] neg_lo:[0,1] neg_hi:[0,1]
	v_pk_add_f32 v[226:227], v[186:187], v[170:171] neg_lo:[0,1] neg_hi:[0,1]
	v_pk_fma_f32 v[202:203], v[106:107], v[224:225], v[170:171]
	v_pk_fma_f32 v[202:203], v[122:123], v[226:227], v[202:203]
	v_pk_add_f32 v[224:225], v[156:157], v[172:173] neg_lo:[0,1] neg_hi:[0,1]
	v_pk_add_f32 v[226:227], v[188:189], v[172:173] neg_lo:[0,1] neg_hi:[0,1]
	v_pk_fma_f32 v[204:205], v[108:109], v[224:225], v[172:173]
	v_pk_fma_f32 v[204:205], v[124:125], v[226:227], v[204:205]
	v_pk_add_f32 v[224:225], v[158:159], v[174:175] neg_lo:[0,1] neg_hi:[0,1]
	v_pk_add_f32 v[226:227], v[190:191], v[174:175] neg_lo:[0,1] neg_hi:[0,1]
	v_pk_fma_f32 v[206:207], v[110:111], v[224:225], v[174:175]
	v_pk_fma_f32 v[206:207], v[126:127], v[226:227], v[206:207]
	s_add_u32 s76, s76, 0x800
	buffer_load_dwordx4 v[216:219], v236, s[68:71], s76 offen
	buffer_load_dwordx4 v[220:223], v236, s[68:71], s76 offen offset:16
	buffer_store_dwordx4 v[192:195], v235, s[68:71], s72 offen offset:0
	buffer_store_dwordx4 v[196:199], v235, s[68:71], s72 offen offset:16
	buffer_store_dwordx4 v[200:203], v235, s[68:71], s72 offen offset:32
	buffer_store_dwordx4 v[204:207], v235, s[68:71], s72 offen offset:48
	s_waitcnt vmcnt(11)
; __device__ __forceinline__ void prep_phase(const Params& p) {
;     ...
;             for (int i = 0; i < 16; ++i) {
;                 const bool hn = (tt0 + i) < SEQ - 1; const Z16 rn = hn ? ldz(zc + (size_t)(i + 1) * 3328) : zz();
;                 const size_t o = (size_t)(t0 + i) * RW + c;
;                 float r[16], k[16]; mix16(rp, rc, rn, mpr, mnr, r); unz(ldz(Kb + o), k);
;                 float bs = 0.f;
; #pragma unroll
;                 for (int q = 0; q < 16; ++q) bs += r[q] * k[q] * rkc[q];
;                 bs += __shfl_xor(bs, 1); bs += __shfl_xor(bs, 2);
; #pragma unroll
;                 for (int j4 = 0; j4 < 4; ++j4) *(f32x4*)(R + o + j4 * 4) = (f32x4){r[j4 * 4], r[j4 * 4 + 1], r[j4 * 4 + 2], r[j4 * 4 + 3]};
;                 if ((lane & 3) == 0) BON[(size_t)(t0 + i) * 16 + (lane >> 2)] = bs;
;                 rp = rc; rc = rn;
	v_lshlrev_b32_e32 v144, 16, v208
	v_and_b32_e32 v145, 0xffff0000, v208
	v_lshlrev_b32_e32 v146, 16, v209
	v_and_b32_e32 v147, 0xffff0000, v209
	v_lshlrev_b32_e32 v148, 16, v210
	v_and_b32_e32 v149, 0xffff0000, v210
	v_lshlrev_b32_e32 v150, 16, v211
	v_and_b32_e32 v151, 0xffff0000, v211
	v_lshlrev_b32_e32 v152, 16, v212
	v_and_b32_e32 v153, 0xffff0000, v212
	v_lshlrev_b32_e32 v154, 16, v213
	v_and_b32_e32 v155, 0xffff0000, v213
	v_lshlrev_b32_e32 v156, 16, v214
	v_and_b32_e32 v157, 0xffff0000, v214
	v_lshlrev_b32_e32 v158, 16, v215
	v_and_b32_e32 v159, 0xffff0000, v215
	v_pk_mul_f32 v[144:145], v[192:193], v[144:145]
	v_pk_mul_f32 v[146:147], v[194:195], v[146:147]
	v_pk_mul_f32 v[148:149], v[196:197], v[148:149]
	v_pk_mul_f32 v[150:151], v[198:199], v[150:151]
	v_pk_mul_f32 v[152:153], v[200:201], v[152:153]
	v_pk_mul_f32 v[154:155], v[202:203], v[154:155]
	v_pk_mul_f32 v[156:157], v[204:205], v[156:157]
	v_pk_mul_f32 v[158:159], v[206:207], v[158:159]
	v_mul_f32_e32 v224, v144, v128
	v_fmac_f32_e32 v224, v145, v129
	v_fmac_f32_e32 v224, v146, v130
	v_fmac_f32_e32 v224, v147, v131
	v_fmac_f32_e32 v224, v148, v132
	v_fmac_f32_e32 v224, v149, v133
	v_fmac_f32_e32 v224, v150, v134
	v_fmac_f32_e32 v224, v151, v135
	v_fmac_f32_e32 v224, v152, v136
	v_fmac_f32_e32 v224, v153, v137
	v_fmac_f32_e32 v224, v154, v138
	v_fmac_f32_e32 v224, v155, v139
	v_fmac_f32_e32 v224, v156, v140
	v_fmac_f32_e32 v224, v157, v141
	v_fmac_f32_e32 v224, v158, v142
	v_fmac_f32_e32 v224, v159, v143
	s_nop 1
	v_add_f32_dpp v224, v224, v224 quad_perm:[1,0,3,2] row_mask:0xf bank_mask:0xf
	s_nop 1
	v_add_f32_dpp v224, v224, v224 quad_perm:[2,3,0,1] row_mask:0xf bank_mask:0xf
	buffer_store_dword v224, v239, s[68:71], s75 offen
	s_add_u32 s72, s72, 0x1000
	s_add_u32 s73, s73, 0x800
	s_add_u32 s74, s74, 0x200
	s_add_u32 s75, s75, 0x40
	s_waitcnt vmcnt(46)
	v_lshlrev_b32_e32 v144, 16, v60
	v_and_b32_e32 v145, 0xffff0000, v60
	v_lshlrev_b32_e32 v146, 16, v61
	v_and_b32_e32 v147, 0xffff0000, v61
	v_lshlrev_b32_e32 v148, 16, v62
	v_and_b32_e32 v149, 0xffff0000, v62
	v_lshlrev_b32_e32 v150, 16, v63
	v_and_b32_e32 v151, 0xffff0000, v63
	v_lshlrev_b32_e32 v152, 16, v64
	v_and_b32_e32 v153, 0xffff0000, v64
	v_lshlrev_b32_e32 v154, 16, v65
	v_and_b32_e32 v155, 0xffff0000, v65
	v_lshlrev_b32_e32 v156, 16, v66
	v_and_b32_e32 v157, 0xffff0000, v66
	v_lshlrev_b32_e32 v158, 16, v67
	v_and_b32_e32 v159, 0xffff0000, v67
	v_lshlrev_b32_e32 v160, 16, v72
	v_and_b32_e32 v161, 0xffff0000, v72
	v_lshlrev_b32_e32 v162, 16, v73
	v_and_b32_e32 v163, 0xffff0000, v73
	v_lshlrev_b32_e32 v164, 16, v74
	v_and_b32_e32 v165, 0xffff0000, v74
	v_lshlrev_b32_e32 v166, 16, v75
	v_and_b32_e32 v167, 0xffff0000, v75
	v_lshlrev_b32_e32 v168, 16, v76
	v_and_b32_e32 v169, 0xffff0000, v76
	v_lshlrev_b32_e32 v170, 16, v77
	v_and_b32_e32 v171, 0xffff0000, v77
	v_lshlrev_b32_e32 v172, 16, v78
	v_and_b32_e32 v173, 0xffff0000, v78
	v_lshlrev_b32_e32 v174, 16, v79
	v_and_b32_e32 v175, 0xffff0000, v79
	v_lshlrev_b32_e32 v176, 16, v84
	v_and_b32_e32 v177, 0xffff0000, v84
	v_lshlrev_b32_e32 v178, 16, v85
	v_and_b32_e32 v179, 0xffff0000, v85
	v_lshlrev_b32_e32 v180, 16, v86
	v_and_b32_e32 v181, 0xffff0000, v86
	v_lshlrev_b32_e32 v182, 16, v87
	v_and_b32_e32 v183, 0xffff0000, v87
	v_lshlrev_b32_e32 v184, 16, v88
	v_and_b32_e32 v185, 0xffff0000, v88
	v_lshlrev_b32_e32 v186, 16, v89
	v_and_b32_e32 v187, 0xffff0000, v89
	v_lshlrev_b32_e32 v188, 16, v90
	v_and_b32_e32 v189, 0xffff0000, v90
	v_lshlrev_b32_e32 v190, 16, v91
	v_and_b32_e32 v191, 0xffff0000, v91
	v_pk_add_f32 v[224:225], v[144:145], v[160:161] neg_lo:[0,1] neg_hi:[0,1]
	v_pk_add_f32 v[226:227], v[176:177], v[160:161] neg_lo:[0,1] neg_hi:[0,1]
	v_pk_fma_f32 v[192:193], v[96:97], v[224:225], v[160:161]
	v_pk_fma_f32 v[192:193], v[112:113], v[226:227], v[192:193]
	v_pk_add_f32 v[224:225], v[146:147], v[162:163] neg_lo:[0,1] neg_hi:[0,1]
	v_pk_add_f32 v[226:227], v[178:179], v[162:163] neg_lo:[0,1] neg_hi:[0,1]
	v_pk_fma_f32 v[194:195], v[98:99], v[224:225], v[162:163]
	v_pk_fma_f32 v[194:195], v[114:115], v[226:227], v[194:195]
	v_pk_add_f32 v[224:225], v[148:149], v[164:165] neg_lo:[0,1] neg_hi:[0,1]
	v_pk_add_f32 v[226:227], v[180:181], v[164:165] neg_lo:[0,1] neg_hi:[0,1]
	v_pk_fma_f32 v[196:197], v[100:101], v[224:225], v[164:165]
	v_pk_fma_f32 v[196:197], v[116:117], v[226:227], v[196:197]
	v_pk_add_f32 v[224:225], v[150:151], v[166:167] neg_lo:[0,1] neg_hi:[0,1]
	v_pk_add_f32 v[226:227], v[182:183], v[166:167] neg_lo:[0,1] neg_hi:[0,1]
	v_pk_fma_f32 v[198:199], v[102:103], v[224:225], v[166:167]
	v_pk_fma_f32 v[198:199], v[118:119], v[226:227], v[198:199]
	v_pk_add_f32 v[224:225], v[152:153], v[168:169] neg_lo:[0,1] neg_hi:[0,1]
	v_pk_add_f32 v[226:227], v[184:185], v[168:169] neg_lo:[0,1] neg_hi:[0,1]
	v_pk_fma_f32 v[200:201], v[104:105], v[224:225], v[168:169]
	v_pk_fma_f32 v[200:201], v[120:121], v[226:227], v[200:201]
	v_pk_add_f32 v[224:225], v[154:155], v[170:171] neg_lo:[0,1] neg_hi:[0,1]
	v_pk_add_f32 v[226:227], v[186:187], v[170:171] neg_lo:[0,1] neg_hi:[0,1]
	v_pk_fma_f32 v[202:203], v[106:107], v[224:225], v[170:171]
	v_pk_fma_f32 v[202:203], v[122:123], v[226:227], v[202:203]
	v_pk_add_f32 v[224:225], v[156:157], v[172:173] neg_lo:[0,1] neg_hi:[0,1]
	v_pk_add_f32 v[226:227], v[188:189], v[172:173] neg_lo:[0,1] neg_hi:[0,1]
	v_pk_fma_f32 v[204:205], v[108:109], v[224:225], v[172:173]
	v_pk_fma_f32 v[204:205], v[124:125], v[226:227], v[204:205]
	v_pk_add_f32 v[224:225], v[158:159], v[174:175] neg_lo:[0,1] neg_hi:[0,1]
	v_pk_add_f32 v[226:227], v[190:191], v[174:175] neg_lo:[0,1] neg_hi:[0,1]
	v_pk_fma_f32 v[206:207], v[110:111], v[224:225], v[174:175]
	v_pk_fma_f32 v[206:207], v[126:127], v[226:227], v[206:207]
	s_add_u32 s76, s76, 0x800
	buffer_load_dwordx4 v[208:211], v236, s[68:71], s76 offen
	buffer_load_dwordx4 v[212:215], v236, s[68:71], s76 offen offset:16
	buffer_store_dwordx4 v[192:195], v235, s[68:71], s72 offen offset:0
	buffer_store_dwordx4 v[196:199], v235, s[68:71], s72 offen offset:16
	buffer_store_dwordx4 v[200:203], v235, s[68:71], s72 offen offset:32
	buffer_store_dwordx4 v[204:207], v235, s[68:71], s72 offen offset:48
	s_waitcnt vmcnt(11)
; __device__ __forceinline__ void prep_phase(const Params& p) {
;     ...
;             for (int i = 0; i < 16; ++i) {
;                 const bool hn = (tt0 + i) < SEQ - 1; const Z16 rn = hn ? ldz(zc + (size_t)(i + 1) * 3328) : zz();
;                 const size_t o = (size_t)(t0 + i) * RW + c;
;                 float r[16], k[16]; mix16(rp, rc, rn, mpr, mnr, r); unz(ldz(Kb + o), k);
;                 float bs = 0.f;
; #pragma unroll
;                 for (int q = 0; q < 16; ++q) bs += r[q] * k[q] * rkc[q];
;                 bs += __shfl_xor(bs, 1); bs += __shfl_xor(bs, 2);
; #pragma unroll
;                 for (int j4 = 0; j4 < 4; ++j4) *(f32x4*)(R + o + j4 * 4) = (f32x4){r[j4 * 4], r[j4 * 4 + 1], r[j4 * 4 + 2], r[j4 * 4 + 3]};
;                 if ((lane & 3) == 0) BON[(size_t)(t0 + i) * 16 + (lane >> 2)] = bs;
;                 rp = rc; rc = rn;
	v_lshlrev_b32_e32 v144, 16, v216
	v_and_b32_e32 v145, 0xffff0000, v216
	v_lshlrev_b32_e32 v146, 16, v217
	v_and_b32_e32 v147, 0xffff0000, v217
	v_lshlrev_b32_e32 v148, 16, v218
	v_and_b32_e32 v149, 0xffff0000, v218
	v_lshlrev_b32_e32 v150, 16, v219
	v_and_b32_e32 v151, 0xffff0000, v219
	v_lshlrev_b32_e32 v152, 16, v220
	v_and_b32_e32 v153, 0xffff0000, v220
	v_lshlrev_b32_e32 v154, 16, v221
	v_and_b32_e32 v155, 0xffff0000, v221
	v_lshlrev_b32_e32 v156, 16, v222
	v_and_b32_e32 v157, 0xffff0000, v222
	v_lshlrev_b32_e32 v158, 16, v223
	v_and_b32_e32 v159, 0xffff0000, v223
	v_pk_mul_f32 v[144:145], v[192:193], v[144:145]
	v_pk_mul_f32 v[146:147], v[194:195], v[146:147]
	v_pk_mul_f32 v[148:149], v[196:197], v[148:149]
	v_pk_mul_f32 v[150:151], v[198:199], v[150:151]
	v_pk_mul_f32 v[152:153], v[200:201], v[152:153]
	v_pk_mul_f32 v[154:155], v[202:203], v[154:155]
	v_pk_mul_f32 v[156:157], v[204:205], v[156:157]
	v_pk_mul_f32 v[158:159], v[206:207], v[158:159]
	v_mul_f32_e32 v224, v144, v128
	v_fmac_f32_e32 v224, v145, v129
	v_fmac_f32_e32 v224, v146, v130
	v_fmac_f32_e32 v224, v147, v131
	v_fmac_f32_e32 v224, v148, v132
	v_fmac_f32_e32 v224, v149, v133
	v_fmac_f32_e32 v224, v150, v134
	v_fmac_f32_e32 v224, v151, v135
	v_fmac_f32_e32 v224, v152, v136
	v_fmac_f32_e32 v224, v153, v137
	v_fmac_f32_e32 v224, v154, v138
	v_fmac_f32_e32 v224, v155, v139
	v_fmac_f32_e32 v224, v156, v140
	v_fmac_f32_e32 v224, v157, v141
	v_fmac_f32_e32 v224, v158, v142
	v_fmac_f32_e32 v224, v159, v143
	s_nop 1
	v_add_f32_dpp v224, v224, v224 quad_perm:[1,0,3,2] row_mask:0xf bank_mask:0xf
	s_nop 1
	v_add_f32_dpp v224, v224, v224 quad_perm:[2,3,0,1] row_mask:0xf bank_mask:0xf
	buffer_store_dword v224, v239, s[68:71], s75 offen
	s_add_u32 s72, s72, 0x1000
	s_add_u32 s73, s73, 0x800
	s_add_u32 s74, s74, 0x200
	s_add_u32 s75, s75, 0x40
	s_waitcnt vmcnt(44)
	v_lshlrev_b32_e32 v144, 16, v72
	v_and_b32_e32 v145, 0xffff0000, v72
	v_lshlrev_b32_e32 v146, 16, v73
	v_and_b32_e32 v147, 0xffff0000, v73
	v_lshlrev_b32_e32 v148, 16, v74
	v_and_b32_e32 v149, 0xffff0000, v74
	v_lshlrev_b32_e32 v150, 16, v75
	v_and_b32_e32 v151, 0xffff0000, v75
	v_lshlrev_b32_e32 v152, 16, v76
	v_and_b32_e32 v153, 0xffff0000, v76
	v_lshlrev_b32_e32 v154, 16, v77
	v_and_b32_e32 v155, 0xffff0000, v77
	v_lshlrev_b32_e32 v156, 16, v78
	v_and_b32_e32 v157, 0xffff0000, v78
	v_lshlrev_b32_e32 v158, 16, v79
	v_and_b32_e32 v159, 0xffff0000, v79
	v_lshlrev_b32_e32 v160, 16, v84
	v_and_b32_e32 v161, 0xffff0000, v84
	v_lshlrev_b32_e32 v162, 16, v85
	v_and_b32_e32 v163, 0xffff0000, v85
	v_lshlrev_b32_e32 v164, 16, v86
	v_and_b32_e32 v165, 0xffff0000, v86
	v_lshlrev_b32_e32 v166, 16, v87
	v_and_b32_e32 v167, 0xffff0000, v87
	v_lshlrev_b32_e32 v168, 16, v88
	v_and_b32_e32 v169, 0xffff0000, v88
	v_lshlrev_b32_e32 v170, 16, v89
	v_and_b32_e32 v171, 0xffff0000, v89
	v_lshlrev_b32_e32 v172, 16, v90
	v_and_b32_e32 v173, 0xffff0000, v90
	v_lshlrev_b32_e32 v174, 16, v91
	v_and_b32_e32 v175, 0xffff0000, v91
	v_lshlrev_b32_e32 v176, 16, v0
	v_and_b32_e32 v177, 0xffff0000, v0
	v_lshlrev_b32_e32 v178, 16, v1
	v_and_b32_e32 v179, 0xffff0000, v1
	v_lshlrev_b32_e32 v180, 16, v2
	v_and_b32_e32 v181, 0xffff0000, v2
	v_lshlrev_b32_e32 v182, 16, v3
	v_and_b32_e32 v183, 0xffff0000, v3
	v_lshlrev_b32_e32 v184, 16, v4
	v_and_b32_e32 v185, 0xffff0000, v4
	v_lshlrev_b32_e32 v186, 16, v5
	v_and_b32_e32 v187, 0xffff0000, v5
	v_lshlrev_b32_e32 v188, 16, v6
	v_and_b32_e32 v189, 0xffff0000, v6
	v_lshlrev_b32_e32 v190, 16, v7
	v_and_b32_e32 v191, 0xffff0000, v7
	v_pk_add_f32 v[224:225], v[144:145], v[160:161] neg_lo:[0,1] neg_hi:[0,1]
	v_pk_add_f32 v[226:227], v[176:177], v[160:161] neg_lo:[0,1] neg_hi:[0,1]
	v_pk_fma_f32 v[192:193], v[96:97], v[224:225], v[160:161]
	v_pk_fma_f32 v[192:193], v[112:113], v[226:227], v[192:193]
	v_pk_add_f32 v[224:225], v[146:147], v[162:163] neg_lo:[0,1] neg_hi:[0,1]
	v_pk_add_f32 v[226:227], v[178:179], v[162:163] neg_lo:[0,1] neg_hi:[0,1]
	v_pk_fma_f32 v[194:195], v[98:99], v[224:225], v[162:163]
	v_pk_fma_f32 v[194:195], v[114:115], v[226:227], v[194:195]
	v_pk_add_f32 v[224:225], v[148:149], v[164:165] neg_lo:[0,1] neg_hi:[0,1]
	v_pk_add_f32 v[226:227], v[180:181], v[164:165] neg_lo:[0,1] neg_hi:[0,1]
	v_pk_fma_f32 v[196:197], v[100:101], v[224:225], v[164:165]
	v_pk_fma_f32 v[196:197], v[116:117], v[226:227], v[196:197]
	v_pk_add_f32 v[224:225], v[150:151], v[166:167] neg_lo:[0,1] neg_hi:[0,1]
	v_pk_add_f32 v[226:227], v[182:183], v[166:167] neg_lo:[0,1] neg_hi:[0,1]
	v_pk_fma_f32 v[198:199], v[102:103], v[224:225], v[166:167]
	v_pk_fma_f32 v[198:199], v[118:119], v[226:227], v[198:199]
	v_pk_add_f32 v[224:225], v[152:153], v[168:169] neg_lo:[0,1] neg_hi:[0,1]
	v_pk_add_f32 v[226:227], v[184:185], v[168:169] neg_lo:[0,1] neg_hi:[0,1]
	v_pk_fma_f32 v[200:201], v[104:105], v[224:225], v[168:169]
	v_pk_fma_f32 v[200:201], v[120:121], v[226:227], v[200:201]
	v_pk_add_f32 v[224:225], v[154:155], v[170:171] neg_lo:[0,1] neg_hi:[0,1]
	v_pk_add_f32 v[226:227], v[186:187], v[170:171] neg_lo:[0,1] neg_hi:[0,1]
	v_pk_fma_f32 v[202:203], v[106:107], v[224:225], v[170:171]
	v_pk_fma_f32 v[202:203], v[122:123], v[226:227], v[202:203]
	v_pk_add_f32 v[224:225], v[156:157], v[172:173] neg_lo:[0,1] neg_hi:[0,1]
	v_pk_add_f32 v[226:227], v[188:189], v[172:173] neg_lo:[0,1] neg_hi:[0,1]
	v_pk_fma_f32 v[204:205], v[108:109], v[224:225], v[172:173]
	v_pk_fma_f32 v[204:205], v[124:125], v[226:227], v[204:205]
	v_pk_add_f32 v[224:225], v[158:159], v[174:175] neg_lo:[0,1] neg_hi:[0,1]
	v_pk_add_f32 v[226:227], v[190:191], v[174:175] neg_lo:[0,1] neg_hi:[0,1]
	v_pk_fma_f32 v[206:207], v[110:111], v[224:225], v[174:175]
	v_pk_fma_f32 v[206:207], v[126:127], v[226:227], v[206:207]
	s_add_u32 s76, s76, 0x800
	buffer_load_dwordx4 v[216:219], v236, s[68:71], s76 offen
	buffer_load_dwordx4 v[220:223], v236, s[68:71], s76 offen offset:16
	buffer_store_dwordx4 v[192:195], v235, s[68:71], s72 offen offset:0
	buffer_store_dwordx4 v[196:199], v235, s[68:71], s72 offen offset:16
	buffer_store_dwordx4 v[200:203], v235, s[68:71], s72 offen offset:32
	buffer_store_dwordx4 v[204:207], v235, s[68:71], s72 offen offset:48
	s_waitcnt vmcnt(11)
; __device__ __forceinline__ void prep_phase(const Params& p) {
;     ...
;             for (int i = 0; i < 16; ++i) {
;                 const bool hn = (tt0 + i) < SEQ - 1; const Z16 rn = hn ? ldz(zc + (size_t)(i + 1) * 3328) : zz();
;                 const size_t o = (size_t)(t0 + i) * RW + c;
;                 float r[16], k[16]; mix16(rp, rc, rn, mpr, mnr, r); unz(ldz(Kb + o), k);
;                 float bs = 0.f;
; #pragma unroll
;                 for (int q = 0; q < 16; ++q) bs += r[q] * k[q] * rkc[q];
;                 bs += __shfl_xor(bs, 1); bs += __shfl_xor(bs, 2);
; #pragma unroll
;                 for (int j4 = 0; j4 < 4; ++j4) *(f32x4*)(R + o + j4 * 4) = (f32x4){r[j4 * 4], r[j4 * 4 + 1], r[j4 * 4 + 2], r[j4 * 4 + 3]};
;                 if ((lane & 3) == 0) BON[(size_t)(t0 + i) * 16 + (lane >> 2)] = bs;
;                 rp = rc; rc = rn;
	v_lshlrev_b32_e32 v144, 16, v208
	v_and_b32_e32 v145, 0xffff0000, v208
	v_lshlrev_b32_e32 v146, 16, v209
	v_and_b32_e32 v147, 0xffff0000, v209
	v_lshlrev_b32_e32 v148, 16, v210
	v_and_b32_e32 v149, 0xffff0000, v210
	v_lshlrev_b32_e32 v150, 16, v211
	v_and_b32_e32 v151, 0xffff0000, v211
	v_lshlrev_b32_e32 v152, 16, v212
	v_and_b32_e32 v153, 0xffff0000, v212
	v_lshlrev_b32_e32 v154, 16, v213
	v_and_b32_e32 v155, 0xffff0000, v213
	v_lshlrev_b32_e32 v156, 16, v214
	v_and_b32_e32 v157, 0xffff0000, v214
	v_lshlrev_b32_e32 v158, 16, v215
	v_and_b32_e32 v159, 0xffff0000, v215
	v_pk_mul_f32 v[144:145], v[192:193], v[144:145]
	v_pk_mul_f32 v[146:147], v[194:195], v[146:147]
	v_pk_mul_f32 v[148:149], v[196:197], v[148:149]
	v_pk_mul_f32 v[150:151], v[198:199], v[150:151]
	v_pk_mul_f32 v[152:153], v[200:201], v[152:153]
	v_pk_mul_f32 v[154:155], v[202:203], v[154:155]
	v_pk_mul_f32 v[156:157], v[204:205], v[156:157]
	v_pk_mul_f32 v[158:159], v[206:207], v[158:159]
	v_mul_f32_e32 v224, v144, v128
	v_fmac_f32_e32 v224, v145, v129
	v_fmac_f32_e32 v224, v146, v130
	v_fmac_f32_e32 v224, v147, v131
	v_fmac_f32_e32 v224, v148, v132
	v_fmac_f32_e32 v224, v149, v133
	v_fmac_f32_e32 v224, v150, v134
	v_fmac_f32_e32 v224, v151, v135
	v_fmac_f32_e32 v224, v152, v136
	v_fmac_f32_e32 v224, v153, v137
	v_fmac_f32_e32 v224, v154, v138
	v_fmac_f32_e32 v224, v155, v139
	v_fmac_f32_e32 v224, v156, v140
	v_fmac_f32_e32 v224, v157, v141
	v_fmac_f32_e32 v224, v158, v142
	v_fmac_f32_e32 v224, v159, v143
	s_nop 1
	v_add_f32_dpp v224, v224, v224 quad_perm:[1,0,3,2] row_mask:0xf bank_mask:0xf
	s_nop 1
	v_add_f32_dpp v224, v224, v224 quad_perm:[2,3,0,1] row_mask:0xf bank_mask:0xf
	buffer_store_dword v224, v239, s[68:71], s75 offen
	s_add_u32 s72, s72, 0x1000
	s_add_u32 s73, s73, 0x800
	s_add_u32 s74, s74, 0x200
	s_add_u32 s75, s75, 0x40
	s_waitcnt vmcnt(42)
	v_lshlrev_b32_e32 v144, 16, v84
	v_and_b32_e32 v145, 0xffff0000, v84
	v_lshlrev_b32_e32 v146, 16, v85
	v_and_b32_e32 v147, 0xffff0000, v85
	v_lshlrev_b32_e32 v148, 16, v86
	v_and_b32_e32 v149, 0xffff0000, v86
	v_lshlrev_b32_e32 v150, 16, v87
	v_and_b32_e32 v151, 0xffff0000, v87
	v_lshlrev_b32_e32 v152, 16, v88
	v_and_b32_e32 v153, 0xffff0000, v88
	v_lshlrev_b32_e32 v154, 16, v89
	v_and_b32_e32 v155, 0xffff0000, v89
	v_lshlrev_b32_e32 v156, 16, v90
	v_and_b32_e32 v157, 0xffff0000, v90
	v_lshlrev_b32_e32 v158, 16, v91
	v_and_b32_e32 v159, 0xffff0000, v91
	v_lshlrev_b32_e32 v160, 16, v0
	v_and_b32_e32 v161, 0xffff0000, v0
	v_lshlrev_b32_e32 v162, 16, v1
	v_and_b32_e32 v163, 0xffff0000, v1
	v_lshlrev_b32_e32 v164, 16, v2
	v_and_b32_e32 v165, 0xffff0000, v2
	v_lshlrev_b32_e32 v166, 16, v3
	v_and_b32_e32 v167, 0xffff0000, v3
	v_lshlrev_b32_e32 v168, 16, v4
	v_and_b32_e32 v169, 0xffff0000, v4
	v_lshlrev_b32_e32 v170, 16, v5
	v_and_b32_e32 v171, 0xffff0000, v5
	v_lshlrev_b32_e32 v172, 16, v6
	v_and_b32_e32 v173, 0xffff0000, v6
	v_lshlrev_b32_e32 v174, 16, v7
	v_and_b32_e32 v175, 0xffff0000, v7
	v_lshlrev_b32_e32 v176, 16, v12
	v_and_b32_e32 v177, 0xffff0000, v12
	v_lshlrev_b32_e32 v178, 16, v13
	v_and_b32_e32 v179, 0xffff0000, v13
	v_lshlrev_b32_e32 v180, 16, v14
	v_and_b32_e32 v181, 0xffff0000, v14
	v_lshlrev_b32_e32 v182, 16, v15
	v_and_b32_e32 v183, 0xffff0000, v15
	v_lshlrev_b32_e32 v184, 16, v16
	v_and_b32_e32 v185, 0xffff0000, v16
	v_lshlrev_b32_e32 v186, 16, v17
	v_and_b32_e32 v187, 0xffff0000, v17
	v_lshlrev_b32_e32 v188, 16, v18
	v_and_b32_e32 v189, 0xffff0000, v18
	v_lshlrev_b32_e32 v190, 16, v19
	v_and_b32_e32 v191, 0xffff0000, v19
	v_pk_add_f32 v[224:225], v[144:145], v[160:161] neg_lo:[0,1] neg_hi:[0,1]
	v_pk_add_f32 v[226:227], v[176:177], v[160:161] neg_lo:[0,1] neg_hi:[0,1]
	v_pk_fma_f32 v[192:193], v[96:97], v[224:225], v[160:161]
	v_pk_fma_f32 v[192:193], v[112:113], v[226:227], v[192:193]
	v_pk_add_f32 v[224:225], v[146:147], v[162:163] neg_lo:[0,1] neg_hi:[0,1]
	v_pk_add_f32 v[226:227], v[178:179], v[162:163] neg_lo:[0,1] neg_hi:[0,1]
	v_pk_fma_f32 v[194:195], v[98:99], v[224:225], v[162:163]
	v_pk_fma_f32 v[194:195], v[114:115], v[226:227], v[194:195]
	v_pk_add_f32 v[224:225], v[148:149], v[164:165] neg_lo:[0,1] neg_hi:[0,1]
	v_pk_add_f32 v[226:227], v[180:181], v[164:165] neg_lo:[0,1] neg_hi:[0,1]
	v_pk_fma_f32 v[196:197], v[100:101], v[224:225], v[164:165]
	v_pk_fma_f32 v[196:197], v[116:117], v[226:227], v[196:197]
	v_pk_add_f32 v[224:225], v[150:151], v[166:167] neg_lo:[0,1] neg_hi:[0,1]
	v_pk_add_f32 v[226:227], v[182:183], v[166:167] neg_lo:[0,1] neg_hi:[0,1]
	v_pk_fma_f32 v[198:199], v[102:103], v[224:225], v[166:167]
	v_pk_fma_f32 v[198:199], v[118:119], v[226:227], v[198:199]
	v_pk_add_f32 v[224:225], v[152:153], v[168:169] neg_lo:[0,1] neg_hi:[0,1]
	v_pk_add_f32 v[226:227], v[184:185], v[168:169] neg_lo:[0,1] neg_hi:[0,1]
	v_pk_fma_f32 v[200:201], v[104:105], v[224:225], v[168:169]
	v_pk_fma_f32 v[200:201], v[120:121], v[226:227], v[200:201]
	v_pk_add_f32 v[224:225], v[154:155], v[170:171] neg_lo:[0,1] neg_hi:[0,1]
	v_pk_add_f32 v[226:227], v[186:187], v[170:171] neg_lo:[0,1] neg_hi:[0,1]
	v_pk_fma_f32 v[202:203], v[106:107], v[224:225], v[170:171]
	v_pk_fma_f32 v[202:203], v[122:123], v[226:227], v[202:203]
	v_pk_add_f32 v[224:225], v[156:157], v[172:173] neg_lo:[0,1] neg_hi:[0,1]
	v_pk_add_f32 v[226:227], v[188:189], v[172:173] neg_lo:[0,1] neg_hi:[0,1]
	v_pk_fma_f32 v[204:205], v[108:109], v[224:225], v[172:173]
	v_pk_fma_f32 v[204:205], v[124:125], v[226:227], v[204:205]
	v_pk_add_f32 v[224:225], v[158:159], v[174:175] neg_lo:[0,1] neg_hi:[0,1]
	v_pk_add_f32 v[226:227], v[190:191], v[174:175] neg_lo:[0,1] neg_hi:[0,1]
	v_pk_fma_f32 v[206:207], v[110:111], v[224:225], v[174:175]
	v_pk_fma_f32 v[206:207], v[126:127], v[226:227], v[206:207]
	buffer_store_dwordx4 v[192:195], v235, s[68:71], s72 offen offset:0
	buffer_store_dwordx4 v[196:199], v235, s[68:71], s72 offen offset:16
	buffer_store_dwordx4 v[200:203], v235, s[68:71], s72 offen offset:32
	buffer_store_dwordx4 v[204:207], v235, s[68:71], s72 offen offset:48
	s_waitcnt vmcnt(9)
; __device__ __forceinline__ void prep_phase(const Params& p) {
;     ...
;                 float r[16], k[16]; mix16(rp, rc, rn, mpr, mnr, r); unz(ldz(Kb + o), k);
;                 float bs = 0.f;
; #pragma unroll
;                 for (int q = 0; q < 16; ++q) bs += r[q] * k[q] * rkc[q];
;                 bs += __shfl_xor(bs, 1); bs += __shfl_xor(bs, 2);
; #pragma unroll
;                 for (int j4 = 0; j4 < 4; ++j4) *(f32x4*)(R + o + j4 * 4) = (f32x4){r[j4 * 4], r[j4 * 4 + 1], r[j4 * 4 + 2], r[j4 * 4 + 3]};
;                 if ((lane & 3) == 0) BON[(size_t)(t0 + i) * 16 + (lane >> 2)] = bs;
;                 rp = rc; rc = rn;
;             }
;         }
;         {
;             float mpv[16], mnv[16]; ld16f(p.mu_prev + 2048 + c, mpv); ld16f(p.mu_next + 2048 + c, mnv);
;             const int cl = 3072 + lane * 4; const f32x4 la = *(const f32x4*)(p.mu_prev + cl), lb = *(const f32x4*)(p.mu_next + cl);
;             const int alc = ((lane >> 4) & 1) * 128 + (lane >> 5) * 64 + (lane & 15) * 4;
;             const u16* zc = ZS + (size_t)t0 * 3328;
;             Z16 vp = tt0 > 0 ? ldz(zc - 3328 + 2048 + c) : zz(), vc = ldz(zc + 2048 + c);
;             u32x2 lp = tt0 > 0 ? *(const u32x2*)(zc - 3328 + cl) : (u32x2){0u, 0u}, lc = *(const u32x2*)(zc + cl);
	v_lshlrev_b32_e32 v144, 16, v216
	v_and_b32_e32 v145, 0xffff0000, v216
	v_lshlrev_b32_e32 v146, 16, v217
	v_and_b32_e32 v147, 0xffff0000, v217
	v_lshlrev_b32_e32 v148, 16, v218
	v_and_b32_e32 v149, 0xffff0000, v218
	v_lshlrev_b32_e32 v150, 16, v219
	v_and_b32_e32 v151, 0xffff0000, v219
	v_lshlrev_b32_e32 v152, 16, v220
	v_and_b32_e32 v153, 0xffff0000, v220
	v_lshlrev_b32_e32 v154, 16, v221
	v_and_b32_e32 v155, 0xffff0000, v221
	v_lshlrev_b32_e32 v156, 16, v222
	v_and_b32_e32 v157, 0xffff0000, v222
	v_lshlrev_b32_e32 v158, 16, v223
	v_and_b32_e32 v159, 0xffff0000, v223
	v_pk_mul_f32 v[144:145], v[192:193], v[144:145]
	v_pk_mul_f32 v[146:147], v[194:195], v[146:147]
	v_pk_mul_f32 v[148:149], v[196:197], v[148:149]
	v_pk_mul_f32 v[150:151], v[198:199], v[150:151]
	v_pk_mul_f32 v[152:153], v[200:201], v[152:153]
	v_pk_mul_f32 v[154:155], v[202:203], v[154:155]
	v_pk_mul_f32 v[156:157], v[204:205], v[156:157]
	v_pk_mul_f32 v[158:159], v[206:207], v[158:159]
	v_mul_f32_e32 v224, v144, v128
	v_fmac_f32_e32 v224, v145, v129
	v_fmac_f32_e32 v224, v146, v130
	v_fmac_f32_e32 v224, v147, v131
	v_fmac_f32_e32 v224, v148, v132
	v_fmac_f32_e32 v224, v149, v133
	v_fmac_f32_e32 v224, v150, v134
	v_fmac_f32_e32 v224, v151, v135
	v_fmac_f32_e32 v224, v152, v136
	v_fmac_f32_e32 v224, v153, v137
	v_fmac_f32_e32 v224, v154, v138
	v_fmac_f32_e32 v224, v155, v139
	v_fmac_f32_e32 v224, v156, v140
	v_fmac_f32_e32 v224, v157, v141
	v_fmac_f32_e32 v224, v158, v142
	v_fmac_f32_e32 v224, v159, v143
	s_nop 1
	v_add_f32_dpp v224, v224, v224 quad_perm:[1,0,3,2] row_mask:0xf bank_mask:0xf
	s_nop 1
	v_add_f32_dpp v224, v224, v224 quad_perm:[2,3,0,1] row_mask:0xf bank_mask:0xf
	buffer_store_dword v224, v239, s[68:71], s75 offen
	s_waitcnt vmcnt(0)
	v_lshl_add_u32 v232, v240, 5, s5
	v_add_u32_e32 v232, 32, v232
	v_lshl_add_u32 v233, v240, 3, s5
	v_add_u32_e32 v233, 6144, v233
	v_lshlrev_b32_e32 v224, 6, v240
	v_lshlrev_b32_e32 v225, 4, v240
	v_add_u32_e32 v226, 0x2000, v224
	v_add_u32_e32 v225, 0x3000, v225
	global_load_dwordx4 v[96:99], v226, s[20:21] offset:0
	global_load_dwordx4 v[100:103], v226, s[20:21] offset:16
	global_load_dwordx4 v[104:107], v226, s[20:21] offset:32
	global_load_dwordx4 v[108:111], v226, s[20:21] offset:48
	global_load_dwordx4 v[112:115], v226, s[22:23] offset:0
	global_load_dwordx4 v[116:119], v226, s[22:23] offset:16
	global_load_dwordx4 v[120:123], v226, s[22:23] offset:32
	global_load_dwordx4 v[124:127], v226, s[22:23] offset:48
	global_load_dwordx4 v[128:131], v225, s[20:21] offset:0
	global_load_dwordx4 v[132:135], v225, s[22:23] offset:0
	buffer_load_dwordx4 v[0:3], v232, s[64:67], 0 offen offset:4064
	buffer_load_dwordx4 v[4:7], v232, s[64:67], 0 offen offset:4080
	buffer_load_dwordx2 v[8:9], v233, s[64:67], 0 offen
	v_add_u32_e32 v233, 6656, v233
	v_add_u32_e32 v232, 6656, v232
	buffer_load_dwordx4 v[12:15], v232, s[64:67], 0 offen offset:4064
	buffer_load_dwordx4 v[16:19], v232, s[64:67], 0 offen offset:4080
	buffer_load_dwordx2 v[20:21], v233, s[64:67], 0 offen
	v_add_u32_e32 v233, 6656, v233
	v_add_u32_e32 v232, 6656, v232
	buffer_load_dwordx4 v[24:27], v232, s[64:67], 0 offen offset:4064
	buffer_load_dwordx4 v[28:31], v232, s[64:67], 0 offen offset:4080
	buffer_load_dwordx2 v[32:33], v233, s[64:67], 0 offen
	v_add_u32_e32 v233, 6656, v233
	v_add_u32_e32 v232, 6656, v232
	buffer_load_dwordx4 v[36:39], v232, s[64:67], 0 offen offset:4064
	buffer_load_dwordx4 v[40:43], v232, s[64:67], 0 offen offset:4080
	buffer_load_dwordx2 v[44:45], v233, s[64:67], 0 offen
	v_add_u32_e32 v233, 6656, v233
	v_add_u32_e32 v232, 6656, v232
	buffer_load_dwordx4 v[48:51], v232, s[64:67], 0 offen offset:4064
	buffer_load_dwordx4 v[52:55], v232, s[64:67], 0 offen offset:4080
	buffer_load_dwordx2 v[56:57], v233, s[64:67], 0 offen
	v_add_u32_e32 v233, 6656, v233
	v_add_u32_e32 v232, 6656, v232
	buffer_load_dwordx4 v[60:63], v232, s[64:67], 0 offen offset:4064
	buffer_load_dwordx4 v[64:67], v232, s[64:67], 0 offen offset:4080
	buffer_load_dwordx2 v[68:69], v233, s[64:67], 0 offen
	v_add_u32_e32 v233, 6656, v233
	v_add_u32_e32 v232, 6656, v232
	buffer_load_dwordx4 v[72:75], v232, s[64:67], 0 offen offset:4064
	buffer_load_dwordx4 v[76:79], v232, s[64:67], 0 offen offset:4080
	buffer_load_dwordx2 v[80:81], v233, s[64:67], 0 offen
	v_add_u32_e32 v233, 6656, v233
	v_add_u32_e32 v232, 6656, v232
	buffer_load_dwordx4 v[84:87], v232, s[64:67], 0 offen offset:4064
	buffer_load_dwordx4 v[88:91], v232, s[64:67], 0 offen offset:4080
	buffer_load_dwordx2 v[92:93], v233, s[64:67], 0 offen
	v_add_u32_e32 v233, 6656, v233
	v_add_u32_e32 v232, 6656, v232
	s_lshl_b32 s72, s0, 12
	s_lshl_b32 s73, s0, 11
	s_lshl_b32 s74, s0, 9
	s_lshl_b32 s75, s0, 6
	s_waitcnt vmcnt(15)
; __device__ __forceinline__ float bflo(unsigned w) { return __uint_as_float(w << 16); }
; __device__ __forceinline__ float bfhi(unsigned w) { return __uint_as_float(w & 0xffff0000u); }
; __device__ __forceinline__ unsigned cvt_pk_bf16(float lo, float hi) { unsigned r; asm volatile("v_cvt_pk_bf16_f32 %0, %1, %2" : "=v"(r) : "v"(lo), "v"(hi)); return r; }
; __device__ __forceinline__ void prep_phase(const Params& p) {
;     ...
;             for (int i = 0; i < 16; ++i) {
;                 const bool hn = (tt0 + i) < SEQ - 1; const u16* zn = zc + (size_t)(i + 1) * 3328;
;                 const Z16 vn = hn ? ldz(zn + 2048 + c) : zz(); const u32x2 ln = hn ? *(const u32x2*)(zn + cl) : (u32x2){0u, 0u};
;                 float v[16]; mix16(vp, vc, vn, mpv, mnv, v);
;                 st16bf(V + (size_t)(t0 + i) * RW + c, v);
;                 const float z4[4] = {bflo(lc.x), bfhi(lc.x), bflo(lc.y), bfhi(lc.y)}, p4[4] = {bflo(lp.x), bfhi(lp.x), bflo(lp.y), bfhi(lp.y)}, n4[4] = {bflo(ln.x), bfhi(ln.x), bflo(ln.y), bfhi(ln.y)};
;                 float o4[4];
; #pragma unroll
;                 for (int j = 0; j < 4; ++j) { const float sft = z4[j] + la[j] * (p4[j] - z4[j]) + lb[j] * (n4[j] - z4[j]); o4[j] = (lane < 32) ? tanhf(sft) : sft; }
;                 u32x2 w; w.x = cvt_pk_bf16(o4[0], o4[1]); w.y = cvt_pk_bf16(o4[2], o4[3]); *(u32x2*)(AL + (size_t)(t0 + i) * 256 + alc) = w;
	v_lshlrev_b32_e32 v144, 16, v0
	v_and_b32_e32 v145, 0xffff0000, v0
	v_lshlrev_b32_e32 v146, 16, v1
	v_and_b32_e32 v147, 0xffff0000, v1
	v_lshlrev_b32_e32 v148, 16, v2
	v_and_b32_e32 v149, 0xffff0000, v2
	v_lshlrev_b32_e32 v150, 16, v3
	v_and_b32_e32 v151, 0xffff0000, v3
	v_lshlrev_b32_e32 v152, 16, v4
	v_and_b32_e32 v153, 0xffff0000, v4
	v_lshlrev_b32_e32 v154, 16, v5
	v_and_b32_e32 v155, 0xffff0000, v5
	v_lshlrev_b32_e32 v156, 16, v6
	v_and_b32_e32 v157, 0xffff0000, v6
	v_lshlrev_b32_e32 v158, 16, v7
	v_and_b32_e32 v159, 0xffff0000, v7
	v_lshlrev_b32_e32 v160, 16, v12
	v_and_b32_e32 v161, 0xffff0000, v12
	v_lshlrev_b32_e32 v162, 16, v13
	v_and_b32_e32 v163, 0xffff0000, v13
	v_lshlrev_b32_e32 v164, 16, v14
	v_and_b32_e32 v165, 0xffff0000, v14
	v_lshlrev_b32_e32 v166, 16, v15
	v_and_b32_e32 v167, 0xffff0000, v15
	v_lshlrev_b32_e32 v168, 16, v16
	v_and_b32_e32 v169, 0xffff0000, v16
	v_lshlrev_b32_e32 v170, 16, v17
	v_and_b32_e32 v171, 0xffff0000, v17
	v_lshlrev_b32_e32 v172, 16, v18
	v_and_b32_e32 v173, 0xffff0000, v18
	v_lshlrev_b32_e32 v174, 16, v19
	v_and_b32_e32 v175, 0xffff0000, v19
	v_lshlrev_b32_e32 v176, 16, v24
	v_and_b32_e32 v177, 0xffff0000, v24
	v_lshlrev_b32_e32 v178, 16, v25
	v_and_b32_e32 v179, 0xffff0000, v25
	v_lshlrev_b32_e32 v180, 16, v26
	v_and_b32_e32 v181, 0xffff0000, v26
	v_lshlrev_b32_e32 v182, 16, v27
	v_and_b32_e32 v183, 0xffff0000, v27
	v_lshlrev_b32_e32 v184, 16, v28
	v_and_b32_e32 v185, 0xffff0000, v28
	v_lshlrev_b32_e32 v186, 16, v29
	v_and_b32_e32 v187, 0xffff0000, v29
	v_lshlrev_b32_e32 v188, 16, v30
	v_and_b32_e32 v189, 0xffff0000, v30
	v_lshlrev_b32_e32 v190, 16, v31
	v_and_b32_e32 v191, 0xffff0000, v31
	v_lshlrev_b32_e32 v136, 16, v8
	v_and_b32_e32 v137, 0xffff0000, v8
	v_lshlrev_b32_e32 v138, 16, v9
	v_and_b32_e32 v139, 0xffff0000, v9
	v_lshlrev_b32_e32 v140, 16, v20
	v_and_b32_e32 v141, 0xffff0000, v20
	v_lshlrev_b32_e32 v142, 16, v21
	v_and_b32_e32 v143, 0xffff0000, v21
	v_lshlrev_b32_e32 v216, 16, v32
	v_and_b32_e32 v217, 0xffff0000, v32
	v_lshlrev_b32_e32 v218, 16, v33
	v_and_b32_e32 v219, 0xffff0000, v33
	buffer_load_dwordx4 v[0:3], v232, s[64:67], 0 offen offset:4064
	buffer_load_dwordx4 v[4:7], v232, s[64:67], 0 offen offset:4080
	buffer_load_dwordx2 v[8:9], v233, s[64:67], 0 offen
	v_add_u32_e32 v233, 6656, v233
	v_add_u32_e32 v232, 6656, v232
	v_pk_add_f32 v[224:225], v[144:145], v[160:161] neg_lo:[0,1] neg_hi:[0,1]
	v_pk_add_f32 v[226:227], v[176:177], v[160:161] neg_lo:[0,1] neg_hi:[0,1]
	v_pk_fma_f32 v[192:193], v[96:97], v[224:225], v[160:161]
	v_pk_fma_f32 v[192:193], v[112:113], v[226:227], v[192:193]
	v_pk_add_f32 v[224:225], v[146:147], v[162:163] neg_lo:[0,1] neg_hi:[0,1]
	v_pk_add_f32 v[226:227], v[178:179], v[162:163] neg_lo:[0,1] neg_hi:[0,1]
	v_pk_fma_f32 v[194:195], v[98:99], v[224:225], v[162:163]
	v_pk_fma_f32 v[194:195], v[114:115], v[226:227], v[194:195]
	v_pk_add_f32 v[224:225], v[148:149], v[164:165] neg_lo:[0,1] neg_hi:[0,1]
	v_pk_add_f32 v[226:227], v[180:181], v[164:165] neg_lo:[0,1] neg_hi:[0,1]
	v_pk_fma_f32 v[196:197], v[100:101], v[224:225], v[164:165]
	v_pk_fma_f32 v[196:197], v[116:117], v[226:227], v[196:197]
	v_pk_add_f32 v[224:225], v[150:151], v[166:167] neg_lo:[0,1] neg_hi:[0,1]
	v_pk_add_f32 v[226:227], v[182:183], v[166:167] neg_lo:[0,1] neg_hi:[0,1]
	v_pk_fma_f32 v[198:199], v[102:103], v[224:225], v[166:167]
	v_pk_fma_f32 v[198:199], v[118:119], v[226:227], v[198:199]
	v_pk_add_f32 v[224:225], v[152:153], v[168:169] neg_lo:[0,1] neg_hi:[0,1]
	v_pk_add_f32 v[226:227], v[184:185], v[168:169] neg_lo:[0,1] neg_hi:[0,1]
	v_pk_fma_f32 v[200:201], v[104:105], v[224:225], v[168:169]
	v_pk_fma_f32 v[200:201], v[120:121], v[226:227], v[200:201]
	v_pk_add_f32 v[224:225], v[154:155], v[170:171] neg_lo:[0,1] neg_hi:[0,1]
	v_pk_add_f32 v[226:227], v[186:187], v[170:171] neg_lo:[0,1] neg_hi:[0,1]
	v_pk_fma_f32 v[202:203], v[106:107], v[224:225], v[170:171]
	v_pk_fma_f32 v[202:203], v[122:123], v[226:227], v[202:203]
	v_pk_add_f32 v[224:225], v[156:157], v[172:173] neg_lo:[0,1] neg_hi:[0,1]
	v_pk_add_f32 v[226:227], v[188:189], v[172:173] neg_lo:[0,1] neg_hi:[0,1]
	v_pk_fma_f32 v[204:205], v[108:109], v[224:225], v[172:173]
	v_pk_fma_f32 v[204:205], v[124:125], v[226:227], v[204:205]
	v_pk_add_f32 v[224:225], v[158:159], v[174:175] neg_lo:[0,1] neg_hi:[0,1]
	v_pk_add_f32 v[226:227], v[190:191], v[174:175] neg_lo:[0,1] neg_hi:[0,1]
	v_pk_fma_f32 v[206:207], v[110:111], v[224:225], v[174:175]
	v_pk_fma_f32 v[206:207], v[126:127], v[226:227], v[206:207]
	v_cvt_pk_bf16_f32 v208, v192, v193
	v_cvt_pk_bf16_f32 v209, v194, v195
	v_cvt_pk_bf16_f32 v210, v196, v197
	v_cvt_pk_bf16_f32 v211, v198, v199
	v_cvt_pk_bf16_f32 v212, v200, v201
	v_cvt_pk_bf16_f32 v213, v202, v203
	v_cvt_pk_bf16_f32 v214, v204, v205
	v_cvt_pk_bf16_f32 v215, v206, v207
	buffer_store_dwordx4 v[208:211], v237, s[68:71], s73 offen offset:0
	buffer_store_dwordx4 v[212:215], v237, s[68:71], s73 offen offset:16
	v_sub_f32_e32 v224, v136, v140
	v_sub_f32_e32 v225, v216, v140
	v_fma_f32 v220, v128, v224, v140
	v_fma_f32 v220, v132, v225, v220
	v_sub_f32_e32 v224, v137, v141
	v_sub_f32_e32 v225, v217, v141
	v_fma_f32 v221, v129, v224, v141
	v_fma_f32 v221, v133, v225, v221
	v_sub_f32_e32 v224, v138, v142
	v_sub_f32_e32 v225, v218, v142
	v_fma_f32 v222, v130, v224, v142
	v_fma_f32 v222, v134, v225, v222
	v_sub_f32_e32 v224, v139, v143
	v_sub_f32_e32 v225, v219, v143
	v_fma_f32 v223, v131, v224, v143
	v_fma_f32 v223, v135, v225, v223
	v_and_b32_e32 v224, 0x7fffffff, v220
	v_mul_f32_e32 v225, 0x4038aa3b, v224
	v_exp_f32_e32 v225, v225
	v_mul_f32_e32 v226, v220, v220
	v_add_f32_e32 v225, 1.0, v225
	v_rcp_f32_e32 v225, v225
; __device__ __forceinline__ float bflo(unsigned w) { return __uint_as_float(w << 16); }
; __device__ __forceinline__ float bfhi(unsigned w) { return __uint_as_float(w & 0xffff0000u); }
; __device__ __forceinline__ unsigned cvt_pk_bf16(float lo, float hi) { unsigned r; asm volatile("v_cvt_pk_bf16_f32 %0, %1, %2" : "=v"(r) : "v"(lo), "v"(hi)); return r; }
; __device__ __forceinline__ void prep_phase(const Params& p) {
;     ...
;             for (int i = 0; i < 16; ++i) {
;                 const bool hn = (tt0 + i) < SEQ - 1; const u16* zn = zc + (size_t)(i + 1) * 3328;
;                 const Z16 vn = hn ? ldz(zn + 2048 + c) : zz(); const u32x2 ln = hn ? *(const u32x2*)(zn + cl) : (u32x2){0u, 0u};
;                 float v[16]; mix16(vp, vc, vn, mpv, mnv, v);
;                 st16bf(V + (size_t)(t0 + i) * RW + c, v);
;                 const float z4[4] = {bflo(lc.x), bfhi(lc.x), bflo(lc.y), bfhi(lc.y)}, p4[4] = {bflo(lp.x), bfhi(lp.x), bflo(lp.y), bfhi(lp.y)}, n4[4] = {bflo(ln.x), bfhi(ln.x), bflo(ln.y), bfhi(ln.y)};
;                 float o4[4];
; #pragma unroll
;                 for (int j = 0; j < 4; ++j) { const float sft = z4[j] + la[j] * (p4[j] - z4[j]) + lb[j] * (n4[j] - z4[j]); o4[j] = (lane < 32) ? tanhf(sft) : sft; }
;                 u32x2 w; w.x = cvt_pk_bf16(o4[0], o4[1]); w.y = cvt_pk_bf16(o4[2], o4[3]); *(u32x2*)(AL + (size_t)(t0 + i) * 256 + alc) = w;
;                 vp = vc; vc = vn; lp = lc; lc = ln;
	v_mul_f32_e32 v227, 0xbeaaaaab, v226
	v_fma_f32 v225, v225, -2.0, 1.0
	v_fma_f32 v227, v227, v220, v220
	v_bfi_b32 v225, v241, v225, v220
	v_cmp_gt_f32_e32 vcc, 0x3d000000, v224
	s_nop 1
	v_cndmask_b32_e32 v225, v225, v227, vcc
	v_cmp_gt_u32_e32 vcc, 32, v240
	s_nop 1
	v_cndmask_b32_e32 v220, v220, v225, vcc
	v_and_b32_e32 v224, 0x7fffffff, v221
	v_mul_f32_e32 v225, 0x4038aa3b, v224
	v_exp_f32_e32 v225, v225
	v_mul_f32_e32 v226, v221, v221
	v_add_f32_e32 v225, 1.0, v225
	v_rcp_f32_e32 v225, v225
	v_mul_f32_e32 v227, 0xbeaaaaab, v226
	v_fma_f32 v225, v225, -2.0, 1.0
	v_fma_f32 v227, v227, v221, v221
	v_bfi_b32 v225, v241, v225, v221
	v_cmp_gt_f32_e32 vcc, 0x3d000000, v224
	s_nop 1
	v_cndmask_b32_e32 v225, v225, v227, vcc
	v_cmp_gt_u32_e32 vcc, 32, v240
	s_nop 1
	v_cndmask_b32_e32 v221, v221, v225, vcc
	v_and_b32_e32 v224, 0x7fffffff, v222
	v_mul_f32_e32 v225, 0x4038aa3b, v224
	v_exp_f32_e32 v225, v225
	v_mul_f32_e32 v226, v222, v222
	v_add_f32_e32 v225, 1.0, v225
	v_rcp_f32_e32 v225, v225
	v_mul_f32_e32 v227, 0xbeaaaaab, v226
	v_fma_f32 v225, v225, -2.0, 1.0
	v_fma_f32 v227, v227, v222, v222
	v_bfi_b32 v225, v241, v225, v222
	v_cmp_gt_f32_e32 vcc, 0x3d000000, v224
	s_nop 1
	v_cndmask_b32_e32 v225, v225, v227, vcc
	v_cmp_gt_u32_e32 vcc, 32, v240
	s_nop 1
	v_cndmask_b32_e32 v222, v222, v225, vcc
	v_and_b32_e32 v224, 0x7fffffff, v223
	v_mul_f32_e32 v225, 0x4038aa3b, v224
	v_exp_f32_e32 v225, v225
	v_mul_f32_e32 v226, v223, v223
	v_add_f32_e32 v225, 1.0, v225
	v_rcp_f32_e32 v225, v225
	v_mul_f32_e32 v227, 0xbeaaaaab, v226
	v_fma_f32 v225, v225, -2.0, 1.0
	v_fma_f32 v227, v227, v223, v223
	v_bfi_b32 v225, v241, v225, v223
	v_cmp_gt_f32_e32 vcc, 0x3d000000, v224
	s_nop 1
	v_cndmask_b32_e32 v225, v225, v227, vcc
	v_cmp_gt_u32_e32 vcc, 32, v240
	s_nop 1
	v_cndmask_b32_e32 v223, v223, v225, vcc
	v_cvt_pk_bf16_f32 v224, v220, v221
	v_cvt_pk_bf16_f32 v225, v222, v223
	buffer_store_dwordx2 v[224:225], v238, s[68:71], s74 offen
	s_add_u32 s72, s72, 0x1000
	s_add_u32 s73, s73, 0x800
	s_add_u32 s74, s74, 0x200
	s_add_u32 s75, s75, 0x40
	s_waitcnt vmcnt(18)
	v_lshlrev_b32_e32 v144, 16, v12
	v_and_b32_e32 v145, 0xffff0000, v12
	v_lshlrev_b32_e32 v146, 16, v13
	v_and_b32_e32 v147, 0xffff0000, v13
	v_lshlrev_b32_e32 v148, 16, v14
	v_and_b32_e32 v149, 0xffff0000, v14
	v_lshlrev_b32_e32 v150, 16, v15
	v_and_b32_e32 v151, 0xffff0000, v15
	v_lshlrev_b32_e32 v152, 16, v16
	v_and_b32_e32 v153, 0xffff0000, v16
	v_lshlrev_b32_e32 v154, 16, v17
	v_and_b32_e32 v155, 0xffff0000, v17
	v_lshlrev_b32_e32 v156, 16, v18
	v_and_b32_e32 v157, 0xffff0000, v18
	v_lshlrev_b32_e32 v158, 16, v19
	v_and_b32_e32 v159, 0xffff0000, v19
	v_lshlrev_b32_e32 v160, 16, v24
	v_and_b32_e32 v161, 0xffff0000, v24
	v_lshlrev_b32_e32 v162, 16, v25
	v_and_b32_e32 v163, 0xffff0000, v25
	v_lshlrev_b32_e32 v164, 16, v26
	v_and_b32_e32 v165, 0xffff0000, v26
	v_lshlrev_b32_e32 v166, 16, v27
	v_and_b32_e32 v167, 0xffff0000, v27
	v_lshlrev_b32_e32 v168, 16, v28
	v_and_b32_e32 v169, 0xffff0000, v28
	v_lshlrev_b32_e32 v170, 16, v29
	v_and_b32_e32 v171, 0xffff0000, v29
	v_lshlrev_b32_e32 v172, 16, v30
	v_and_b32_e32 v173, 0xffff0000, v30
	v_lshlrev_b32_e32 v174, 16, v31
	v_and_b32_e32 v175, 0xffff0000, v31
	v_lshlrev_b32_e32 v176, 16, v36
	v_and_b32_e32 v177, 0xffff0000, v36
	v_lshlrev_b32_e32 v178, 16, v37
	v_and_b32_e32 v179, 0xffff0000, v37
	v_lshlrev_b32_e32 v180, 16, v38
	v_and_b32_e32 v181, 0xffff0000, v38
	v_lshlrev_b32_e32 v182, 16, v39
	v_and_b32_e32 v183, 0xffff0000, v39
	v_lshlrev_b32_e32 v184, 16, v40
	v_and_b32_e32 v185, 0xffff0000, v40
	v_lshlrev_b32_e32 v186, 16, v41
	v_and_b32_e32 v187, 0xffff0000, v41
	v_lshlrev_b32_e32 v188, 16, v42
	v_and_b32_e32 v189, 0xffff0000, v42
	v_lshlrev_b32_e32 v190, 16, v43
	v_and_b32_e32 v191, 0xffff0000, v43
	v_lshlrev_b32_e32 v136, 16, v20
	v_and_b32_e32 v137, 0xffff0000, v20
	v_lshlrev_b32_e32 v138, 16, v21
	v_and_b32_e32 v139, 0xffff0000, v21
	v_lshlrev_b32_e32 v140, 16, v32
	v_and_b32_e32 v141, 0xffff0000, v32
	v_lshlrev_b32_e32 v142, 16, v33
	v_and_b32_e32 v143, 0xffff0000, v33
	v_lshlrev_b32_e32 v216, 16, v44
	v_and_b32_e32 v217, 0xffff0000, v44
	v_lshlrev_b32_e32 v218, 16, v45
	v_and_b32_e32 v219, 0xffff0000, v45
	buffer_load_dwordx4 v[12:15], v232, s[64:67], 0 offen offset:4064
	buffer_load_dwordx4 v[16:19], v232, s[64:67], 0 offen offset:4080
	buffer_load_dwordx2 v[20:21], v233, s[64:67], 0 offen
	v_add_u32_e32 v233, 6656, v233
	v_add_u32_e32 v232, 6656, v232
	v_pk_add_f32 v[224:225], v[144:145], v[160:161] neg_lo:[0,1] neg_hi:[0,1]
	v_pk_add_f32 v[226:227], v[176:177], v[160:161] neg_lo:[0,1] neg_hi:[0,1]
	v_pk_fma_f32 v[192:193], v[96:97], v[224:225], v[160:161]
	v_pk_fma_f32 v[192:193], v[112:113], v[226:227], v[192:193]
	v_pk_add_f32 v[224:225], v[146:147], v[162:163] neg_lo:[0,1] neg_hi:[0,1]
	v_pk_add_f32 v[226:227], v[178:179], v[162:163] neg_lo:[0,1] neg_hi:[0,1]
	v_pk_fma_f32 v[194:195], v[98:99], v[224:225], v[162:163]
	v_pk_fma_f32 v[194:195], v[114:115], v[226:227], v[194:195]
	v_pk_add_f32 v[224:225], v[148:149], v[164:165] neg_lo:[0,1] neg_hi:[0,1]
	v_pk_add_f32 v[226:227], v[180:181], v[164:165] neg_lo:[0,1] neg_hi:[0,1]
	v_pk_fma_f32 v[196:197], v[100:101], v[224:225], v[164:165]
	v_pk_fma_f32 v[196:197], v[116:117], v[226:227], v[196:197]
	v_pk_add_f32 v[224:225], v[150:151], v[166:167] neg_lo:[0,1] neg_hi:[0,1]
	v_pk_add_f32 v[226:227], v[182:183], v[166:167] neg_lo:[0,1] neg_hi:[0,1]
	v_pk_fma_f32 v[198:199], v[102:103], v[224:225], v[166:167]
	v_pk_fma_f32 v[198:199], v[118:119], v[226:227], v[198:199]
	v_pk_add_f32 v[224:225], v[152:153], v[168:169] neg_lo:[0,1] neg_hi:[0,1]
	v_pk_add_f32 v[226:227], v[184:185], v[168:169] neg_lo:[0,1] neg_hi:[0,1]
; __device__ __forceinline__ float bflo(unsigned w) { return __uint_as_float(w << 16); }
; __device__ __forceinline__ float bfhi(unsigned w) { return __uint_as_float(w & 0xffff0000u); }
; __device__ __forceinline__ unsigned cvt_pk_bf16(float lo, float hi) { unsigned r; asm volatile("v_cvt_pk_bf16_f32 %0, %1, %2" : "=v"(r) : "v"(lo), "v"(hi)); return r; }
; __device__ __forceinline__ void prep_phase(const Params& p) {
;     ...
;             for (int i = 0; i < 16; ++i) {
;                 const bool hn = (tt0 + i) < SEQ - 1; const u16* zn = zc + (size_t)(i + 1) * 3328;
;                 const Z16 vn = hn ? ldz(zn + 2048 + c) : zz(); const u32x2 ln = hn ? *(const u32x2*)(zn + cl) : (u32x2){0u, 0u};
;                 float v[16]; mix16(vp, vc, vn, mpv, mnv, v);
;                 st16bf(V + (size_t)(t0 + i) * RW + c, v);
;                 const float z4[4] = {bflo(lc.x), bfhi(lc.x), bflo(lc.y), bfhi(lc.y)}, p4[4] = {bflo(lp.x), bfhi(lp.x), bflo(lp.y), bfhi(lp.y)}, n4[4] = {bflo(ln.x), bfhi(ln.x), bflo(ln.y), bfhi(ln.y)};
;                 float o4[4];
; #pragma unroll
;                 for (int j = 0; j < 4; ++j) { const float sft = z4[j] + la[j] * (p4[j] - z4[j]) + lb[j] * (n4[j] - z4[j]); o4[j] = (lane < 32) ? tanhf(sft) : sft; }
;                 u32x2 w; w.x = cvt_pk_bf16(o4[0], o4[1]); w.y = cvt_pk_bf16(o4[2], o4[3]); *(u32x2*)(AL + (size_t)(t0 + i) * 256 + alc) = w;
;                 vp = vc; vc = vn; lp = lc; lc = ln;
	v_pk_fma_f32 v[200:201], v[104:105], v[224:225], v[168:169]
	v_pk_fma_f32 v[200:201], v[120:121], v[226:227], v[200:201]
	v_pk_add_f32 v[224:225], v[154:155], v[170:171] neg_lo:[0,1] neg_hi:[0,1]
	v_pk_add_f32 v[226:227], v[186:187], v[170:171] neg_lo:[0,1] neg_hi:[0,1]
	v_pk_fma_f32 v[202:203], v[106:107], v[224:225], v[170:171]
	v_pk_fma_f32 v[202:203], v[122:123], v[226:227], v[202:203]
	v_pk_add_f32 v[224:225], v[156:157], v[172:173] neg_lo:[0,1] neg_hi:[0,1]
	v_pk_add_f32 v[226:227], v[188:189], v[172:173] neg_lo:[0,1] neg_hi:[0,1]
	v_pk_fma_f32 v[204:205], v[108:109], v[224:225], v[172:173]
	v_pk_fma_f32 v[204:205], v[124:125], v[226:227], v[204:205]
	v_pk_add_f32 v[224:225], v[158:159], v[174:175] neg_lo:[0,1] neg_hi:[0,1]
	v_pk_add_f32 v[226:227], v[190:191], v[174:175] neg_lo:[0,1] neg_hi:[0,1]
	v_pk_fma_f32 v[206:207], v[110:111], v[224:225], v[174:175]
	v_pk_fma_f32 v[206:207], v[126:127], v[226:227], v[206:207]
	v_cvt_pk_bf16_f32 v208, v192, v193
	v_cvt_pk_bf16_f32 v209, v194, v195
	v_cvt_pk_bf16_f32 v210, v196, v197
	v_cvt_pk_bf16_f32 v211, v198, v199
	v_cvt_pk_bf16_f32 v212, v200, v201
	v_cvt_pk_bf16_f32 v213, v202, v203
	v_cvt_pk_bf16_f32 v214, v204, v205
	v_cvt_pk_bf16_f32 v215, v206, v207
	buffer_store_dwordx4 v[208:211], v237, s[68:71], s73 offen offset:0
	buffer_store_dwordx4 v[212:215], v237, s[68:71], s73 offen offset:16
	v_sub_f32_e32 v224, v136, v140
	v_sub_f32_e32 v225, v216, v140
	v_fma_f32 v220, v128, v224, v140
	v_fma_f32 v220, v132, v225, v220
	v_sub_f32_e32 v224, v137, v141
	v_sub_f32_e32 v225, v217, v141
	v_fma_f32 v221, v129, v224, v141
	v_fma_f32 v221, v133, v225, v221
	v_sub_f32_e32 v224, v138, v142
	v_sub_f32_e32 v225, v218, v142
	v_fma_f32 v222, v130, v224, v142
	v_fma_f32 v222, v134, v225, v222
	v_sub_f32_e32 v224, v139, v143
	v_sub_f32_e32 v225, v219, v143
	v_fma_f32 v223, v131, v224, v143
	v_fma_f32 v223, v135, v225, v223
	v_and_b32_e32 v224, 0x7fffffff, v220
	v_mul_f32_e32 v225, 0x4038aa3b, v224
	v_exp_f32_e32 v225, v225
	v_mul_f32_e32 v226, v220, v220
	v_add_f32_e32 v225, 1.0, v225
	v_rcp_f32_e32 v225, v225
	v_mul_f32_e32 v227, 0xbeaaaaab, v226
	v_fma_f32 v225, v225, -2.0, 1.0
	v_fma_f32 v227, v227, v220, v220
	v_bfi_b32 v225, v241, v225, v220
	v_cmp_gt_f32_e32 vcc, 0x3d000000, v224
	s_nop 1
	v_cndmask_b32_e32 v225, v225, v227, vcc
	v_cmp_gt_u32_e32 vcc, 32, v240
	s_nop 1
	v_cndmask_b32_e32 v220, v220, v225, vcc
	v_and_b32_e32 v224, 0x7fffffff, v221
	v_mul_f32_e32 v225, 0x4038aa3b, v224
	v_exp_f32_e32 v225, v225
	v_mul_f32_e32 v226, v221, v221
	v_add_f32_e32 v225, 1.0, v225
	v_rcp_f32_e32 v225, v225
	v_mul_f32_e32 v227, 0xbeaaaaab, v226
	v_fma_f32 v225, v225, -2.0, 1.0
	v_fma_f32 v227, v227, v221, v221
	v_bfi_b32 v225, v241, v225, v221
	v_cmp_gt_f32_e32 vcc, 0x3d000000, v224
	s_nop 1
	v_cndmask_b32_e32 v225, v225, v227, vcc
	v_cmp_gt_u32_e32 vcc, 32, v240
	s_nop 1
	v_cndmask_b32_e32 v221, v221, v225, vcc
	v_and_b32_e32 v224, 0x7fffffff, v222
	v_mul_f32_e32 v225, 0x4038aa3b, v224
	v_exp_f32_e32 v225, v225
	v_mul_f32_e32 v226, v222, v222
	v_add_f32_e32 v225, 1.0, v225
	v_rcp_f32_e32 v225, v225
	v_mul_f32_e32 v227, 0xbeaaaaab, v226
	v_fma_f32 v225, v225, -2.0, 1.0
	v_fma_f32 v227, v227, v222, v222
	v_bfi_b32 v225, v241, v225, v222
	v_cmp_gt_f32_e32 vcc, 0x3d000000, v224
	s_nop 1
	v_cndmask_b32_e32 v225, v225, v227, vcc
	v_cmp_gt_u32_e32 vcc, 32, v240
	s_nop 1
	v_cndmask_b32_e32 v222, v222, v225, vcc
	v_and_b32_e32 v224, 0x7fffffff, v223
	v_mul_f32_e32 v225, 0x4038aa3b, v224
	v_exp_f32_e32 v225, v225
	v_mul_f32_e32 v226, v223, v223
	v_add_f32_e32 v225, 1.0, v225
	v_rcp_f32_e32 v225, v225
	v_mul_f32_e32 v227, 0xbeaaaaab, v226
	v_fma_f32 v225, v225, -2.0, 1.0
	v_fma_f32 v227, v227, v223, v223
	v_bfi_b32 v225, v241, v225, v223
	v_cmp_gt_f32_e32 vcc, 0x3d000000, v224
	s_nop 1
	v_cndmask_b32_e32 v225, v225, v227, vcc
	v_cmp_gt_u32_e32 vcc, 32, v240
	s_nop 1
	v_cndmask_b32_e32 v223, v223, v225, vcc
	v_cvt_pk_bf16_f32 v224, v220, v221
	v_cvt_pk_bf16_f32 v225, v222, v223
	buffer_store_dwordx2 v[224:225], v238, s[68:71], s74 offen
	s_add_u32 s72, s72, 0x1000
	s_add_u32 s73, s73, 0x800
	s_add_u32 s74, s74, 0x200
	s_add_u32 s75, s75, 0x40
	s_waitcnt vmcnt(21)
	v_lshlrev_b32_e32 v144, 16, v24
	v_and_b32_e32 v145, 0xffff0000, v24
	v_lshlrev_b32_e32 v146, 16, v25
	v_and_b32_e32 v147, 0xffff0000, v25
	v_lshlrev_b32_e32 v148, 16, v26
	v_and_b32_e32 v149, 0xffff0000, v26
	v_lshlrev_b32_e32 v150, 16, v27
	v_and_b32_e32 v151, 0xffff0000, v27
	v_lshlrev_b32_e32 v152, 16, v28
	v_and_b32_e32 v153, 0xffff0000, v28
	v_lshlrev_b32_e32 v154, 16, v29
	v_and_b32_e32 v155, 0xffff0000, v29
	v_lshlrev_b32_e32 v156, 16, v30
	v_and_b32_e32 v157, 0xffff0000, v30
	v_lshlrev_b32_e32 v158, 16, v31
	v_and_b32_e32 v159, 0xffff0000, v31
	v_lshlrev_b32_e32 v160, 16, v36
	v_and_b32_e32 v161, 0xffff0000, v36
	v_lshlrev_b32_e32 v162, 16, v37
	v_and_b32_e32 v163, 0xffff0000, v37
	v_lshlrev_b32_e32 v164, 16, v38
	v_and_b32_e32 v165, 0xffff0000, v38
	v_lshlrev_b32_e32 v166, 16, v39
	v_and_b32_e32 v167, 0xffff0000, v39
	v_lshlrev_b32_e32 v168, 16, v40
	v_and_b32_e32 v169, 0xffff0000, v40
	v_lshlrev_b32_e32 v170, 16, v41
	v_and_b32_e32 v171, 0xffff0000, v41
	v_lshlrev_b32_e32 v172, 16, v42
	v_and_b32_e32 v173, 0xffff0000, v42
	v_lshlrev_b32_e32 v174, 16, v43
	v_and_b32_e32 v175, 0xffff0000, v43
	v_lshlrev_b32_e32 v176, 16, v48
	v_and_b32_e32 v177, 0xffff0000, v48
	v_lshlrev_b32_e32 v178, 16, v49
	v_and_b32_e32 v179, 0xffff0000, v49
	v_lshlrev_b32_e32 v180, 16, v50
	v_and_b32_e32 v181, 0xffff0000, v50
	v_lshlrev_b32_e32 v182, 16, v51
	v_and_b32_e32 v183, 0xffff0000, v51
	v_lshlrev_b32_e32 v184, 16, v52
	v_and_b32_e32 v185, 0xffff0000, v52
; __device__ __forceinline__ float bflo(unsigned w) { return __uint_as_float(w << 16); }
; __device__ __forceinline__ float bfhi(unsigned w) { return __uint_as_float(w & 0xffff0000u); }
; __device__ __forceinline__ unsigned cvt_pk_bf16(float lo, float hi) { unsigned r; asm volatile("v_cvt_pk_bf16_f32 %0, %1, %2" : "=v"(r) : "v"(lo), "v"(hi)); return r; }
; __device__ __forceinline__ void prep_phase(const Params& p) {
;     ...
;             for (int i = 0; i < 16; ++i) {
;                 const bool hn = (tt0 + i) < SEQ - 1; const u16* zn = zc + (size_t)(i + 1) * 3328;
;                 const Z16 vn = hn ? ldz(zn + 2048 + c) : zz(); const u32x2 ln = hn ? *(const u32x2*)(zn + cl) : (u32x2){0u, 0u};
;                 float v[16]; mix16(vp, vc, vn, mpv, mnv, v);
;                 st16bf(V + (size_t)(t0 + i) * RW + c, v);
;                 const float z4[4] = {bflo(lc.x), bfhi(lc.x), bflo(lc.y), bfhi(lc.y)}, p4[4] = {bflo(lp.x), bfhi(lp.x), bflo(lp.y), bfhi(lp.y)}, n4[4] = {bflo(ln.x), bfhi(ln.x), bflo(ln.y), bfhi(ln.y)};
;                 float o4[4];
; #pragma unroll
;                 for (int j = 0; j < 4; ++j) { const float sft = z4[j] + la[j] * (p4[j] - z4[j]) + lb[j] * (n4[j] - z4[j]); o4[j] = (lane < 32) ? tanhf(sft) : sft; }
;                 u32x2 w; w.x = cvt_pk_bf16(o4[0], o4[1]); w.y = cvt_pk_bf16(o4[2], o4[3]); *(u32x2*)(AL + (size_t)(t0 + i) * 256 + alc) = w;
;                 vp = vc; vc = vn; lp = lc; lc = ln;
	v_lshlrev_b32_e32 v186, 16, v53
	v_and_b32_e32 v187, 0xffff0000, v53
	v_lshlrev_b32_e32 v188, 16, v54
	v_and_b32_e32 v189, 0xffff0000, v54
	v_lshlrev_b32_e32 v190, 16, v55
	v_and_b32_e32 v191, 0xffff0000, v55
	v_lshlrev_b32_e32 v136, 16, v32
	v_and_b32_e32 v137, 0xffff0000, v32
	v_lshlrev_b32_e32 v138, 16, v33
	v_and_b32_e32 v139, 0xffff0000, v33
	v_lshlrev_b32_e32 v140, 16, v44
	v_and_b32_e32 v141, 0xffff0000, v44
	v_lshlrev_b32_e32 v142, 16, v45
	v_and_b32_e32 v143, 0xffff0000, v45
	v_lshlrev_b32_e32 v216, 16, v56
	v_and_b32_e32 v217, 0xffff0000, v56
	v_lshlrev_b32_e32 v218, 16, v57
	v_and_b32_e32 v219, 0xffff0000, v57
	buffer_load_dwordx4 v[24:27], v232, s[64:67], 0 offen offset:4064
	buffer_load_dwordx4 v[28:31], v232, s[64:67], 0 offen offset:4080
	buffer_load_dwordx2 v[32:33], v233, s[64:67], 0 offen
	v_add_u32_e32 v233, 6656, v233
	v_add_u32_e32 v232, 6656, v232
	v_pk_add_f32 v[224:225], v[144:145], v[160:161] neg_lo:[0,1] neg_hi:[0,1]
	v_pk_add_f32 v[226:227], v[176:177], v[160:161] neg_lo:[0,1] neg_hi:[0,1]
	v_pk_fma_f32 v[192:193], v[96:97], v[224:225], v[160:161]
	v_pk_fma_f32 v[192:193], v[112:113], v[226:227], v[192:193]
	v_pk_add_f32 v[224:225], v[146:147], v[162:163] neg_lo:[0,1] neg_hi:[0,1]
	v_pk_add_f32 v[226:227], v[178:179], v[162:163] neg_lo:[0,1] neg_hi:[0,1]
	v_pk_fma_f32 v[194:195], v[98:99], v[224:225], v[162:163]
	v_pk_fma_f32 v[194:195], v[114:115], v[226:227], v[194:195]
	v_pk_add_f32 v[224:225], v[148:149], v[164:165] neg_lo:[0,1] neg_hi:[0,1]
	v_pk_add_f32 v[226:227], v[180:181], v[164:165] neg_lo:[0,1] neg_hi:[0,1]
	v_pk_fma_f32 v[196:197], v[100:101], v[224:225], v[164:165]
	v_pk_fma_f32 v[196:197], v[116:117], v[226:227], v[196:197]
	v_pk_add_f32 v[224:225], v[150:151], v[166:167] neg_lo:[0,1] neg_hi:[0,1]
	v_pk_add_f32 v[226:227], v[182:183], v[166:167] neg_lo:[0,1] neg_hi:[0,1]
	v_pk_fma_f32 v[198:199], v[102:103], v[224:225], v[166:167]
	v_pk_fma_f32 v[198:199], v[118:119], v[226:227], v[198:199]
	v_pk_add_f32 v[224:225], v[152:153], v[168:169] neg_lo:[0,1] neg_hi:[0,1]
	v_pk_add_f32 v[226:227], v[184:185], v[168:169] neg_lo:[0,1] neg_hi:[0,1]
	v_pk_fma_f32 v[200:201], v[104:105], v[224:225], v[168:169]
	v_pk_fma_f32 v[200:201], v[120:121], v[226:227], v[200:201]
	v_pk_add_f32 v[224:225], v[154:155], v[170:171] neg_lo:[0,1] neg_hi:[0,1]
	v_pk_add_f32 v[226:227], v[186:187], v[170:171] neg_lo:[0,1] neg_hi:[0,1]
	v_pk_fma_f32 v[202:203], v[106:107], v[224:225], v[170:171]
	v_pk_fma_f32 v[202:203], v[122:123], v[226:227], v[202:203]
	v_pk_add_f32 v[224:225], v[156:157], v[172:173] neg_lo:[0,1] neg_hi:[0,1]
	v_pk_add_f32 v[226:227], v[188:189], v[172:173] neg_lo:[0,1] neg_hi:[0,1]
	v_pk_fma_f32 v[204:205], v[108:109], v[224:225], v[172:173]
	v_pk_fma_f32 v[204:205], v[124:125], v[226:227], v[204:205]
	v_pk_add_f32 v[224:225], v[158:159], v[174:175] neg_lo:[0,1] neg_hi:[0,1]
	v_pk_add_f32 v[226:227], v[190:191], v[174:175] neg_lo:[0,1] neg_hi:[0,1]
	v_pk_fma_f32 v[206:207], v[110:111], v[224:225], v[174:175]
	v_pk_fma_f32 v[206:207], v[126:127], v[226:227], v[206:207]
	v_cvt_pk_bf16_f32 v208, v192, v193
	v_cvt_pk_bf16_f32 v209, v194, v195
	v_cvt_pk_bf16_f32 v210, v196, v197
	v_cvt_pk_bf16_f32 v211, v198, v199
	v_cvt_pk_bf16_f32 v212, v200, v201
	v_cvt_pk_bf16_f32 v213, v202, v203
	v_cvt_pk_bf16_f32 v214, v204, v205
	v_cvt_pk_bf16_f32 v215, v206, v207
	buffer_store_dwordx4 v[208:211], v237, s[68:71], s73 offen offset:0
	buffer_store_dwordx4 v[212:215], v237, s[68:71], s73 offen offset:16
	v_sub_f32_e32 v224, v136, v140
	v_sub_f32_e32 v225, v216, v140
	v_fma_f32 v220, v128, v224, v140
	v_fma_f32 v220, v132, v225, v220
	v_sub_f32_e32 v224, v137, v141
	v_sub_f32_e32 v225, v217, v141
	v_fma_f32 v221, v129, v224, v141
	v_fma_f32 v221, v133, v225, v221
	v_sub_f32_e32 v224, v138, v142
	v_sub_f32_e32 v225, v218, v142
	v_fma_f32 v222, v130, v224, v142
	v_fma_f32 v222, v134, v225, v222
	v_sub_f32_e32 v224, v139, v143
	v_sub_f32_e32 v225, v219, v143
	v_fma_f32 v223, v131, v224, v143
	v_fma_f32 v223, v135, v225, v223
	v_and_b32_e32 v224, 0x7fffffff, v220
	v_mul_f32_e32 v225, 0x4038aa3b, v224
	v_exp_f32_e32 v225, v225
	v_mul_f32_e32 v226, v220, v220
	v_add_f32_e32 v225, 1.0, v225
	v_rcp_f32_e32 v225, v225
	v_mul_f32_e32 v227, 0xbeaaaaab, v226
	v_fma_f32 v225, v225, -2.0, 1.0
	v_fma_f32 v227, v227, v220, v220
	v_bfi_b32 v225, v241, v225, v220
	v_cmp_gt_f32_e32 vcc, 0x3d000000, v224
	s_nop 1
	v_cndmask_b32_e32 v225, v225, v227, vcc
	v_cmp_gt_u32_e32 vcc, 32, v240
	s_nop 1
	v_cndmask_b32_e32 v220, v220, v225, vcc
	v_and_b32_e32 v224, 0x7fffffff, v221
	v_mul_f32_e32 v225, 0x4038aa3b, v224
	v_exp_f32_e32 v225, v225
	v_mul_f32_e32 v226, v221, v221
	v_add_f32_e32 v225, 1.0, v225
	v_rcp_f32_e32 v225, v225
	v_mul_f32_e32 v227, 0xbeaaaaab, v226
	v_fma_f32 v225, v225, -2.0, 1.0
	v_fma_f32 v227, v227, v221, v221
	v_bfi_b32 v225, v241, v225, v221
	v_cmp_gt_f32_e32 vcc, 0x3d000000, v224
	s_nop 1
	v_cndmask_b32_e32 v225, v225, v227, vcc
	v_cmp_gt_u32_e32 vcc, 32, v240
	s_nop 1
	v_cndmask_b32_e32 v221, v221, v225, vcc
	v_and_b32_e32 v224, 0x7fffffff, v222
	v_mul_f32_e32 v225, 0x4038aa3b, v224
	v_exp_f32_e32 v225, v225
	v_mul_f32_e32 v226, v222, v222
	v_add_f32_e32 v225, 1.0, v225
	v_rcp_f32_e32 v225, v225
	v_mul_f32_e32 v227, 0xbeaaaaab, v226
	v_fma_f32 v225, v225, -2.0, 1.0
	v_fma_f32 v227, v227, v222, v222
	v_bfi_b32 v225, v241, v225, v222
	v_cmp_gt_f32_e32 vcc, 0x3d000000, v224
	s_nop 1
	v_cndmask_b32_e32 v225, v225, v227, vcc
	v_cmp_gt_u32_e32 vcc, 32, v240
	s_nop 1
	v_cndmask_b32_e32 v222, v222, v225, vcc
	v_and_b32_e32 v224, 0x7fffffff, v223
	v_mul_f32_e32 v225, 0x4038aa3b, v224
	v_exp_f32_e32 v225, v225
	v_mul_f32_e32 v226, v223, v223
	v_add_f32_e32 v225, 1.0, v225
	v_rcp_f32_e32 v225, v225
	v_mul_f32_e32 v227, 0xbeaaaaab, v226
	v_fma_f32 v225, v225, -2.0, 1.0
	v_fma_f32 v227, v227, v223, v223
	v_bfi_b32 v225, v241, v225, v223
	v_cmp_gt_f32_e32 vcc, 0x3d000000, v224
	s_nop 1
	v_cndmask_b32_e32 v225, v225, v227, vcc
	v_cmp_gt_u32_e32 vcc, 32, v240
	s_nop 1
	v_cndmask_b32_e32 v223, v223, v225, vcc
	v_cvt_pk_bf16_f32 v224, v220, v221
	v_cvt_pk_bf16_f32 v225, v222, v223
	buffer_store_dwordx2 v[224:225], v238, s[68:71], s74 offen
	s_add_u32 s72, s72, 0x1000
	s_add_u32 s73, s73, 0x800
	s_add_u32 s74, s74, 0x200
	s_add_u32 s75, s75, 0x40
	s_waitcnt vmcnt(24)
; __device__ __forceinline__ float bflo(unsigned w) { return __uint_as_float(w << 16); }
; __device__ __forceinline__ float bfhi(unsigned w) { return __uint_as_float(w & 0xffff0000u); }
; __device__ __forceinline__ unsigned cvt_pk_bf16(float lo, float hi) { unsigned r; asm volatile("v_cvt_pk_bf16_f32 %0, %1, %2" : "=v"(r) : "v"(lo), "v"(hi)); return r; }
; __device__ __forceinline__ void prep_phase(const Params& p) {
;     ...
;             for (int i = 0; i < 16; ++i) {
;                 const bool hn = (tt0 + i) < SEQ - 1; const u16* zn = zc + (size_t)(i + 1) * 3328;
;                 const Z16 vn = hn ? ldz(zn + 2048 + c) : zz(); const u32x2 ln = hn ? *(const u32x2*)(zn + cl) : (u32x2){0u, 0u};
;                 float v[16]; mix16(vp, vc, vn, mpv, mnv, v);
;                 st16bf(V + (size_t)(t0 + i) * RW + c, v);
;                 const float z4[4] = {bflo(lc.x), bfhi(lc.x), bflo(lc.y), bfhi(lc.y)}, p4[4] = {bflo(lp.x), bfhi(lp.x), bflo(lp.y), bfhi(lp.y)}, n4[4] = {bflo(ln.x), bfhi(ln.x), bflo(ln.y), bfhi(ln.y)};
;                 float o4[4];
; #pragma unroll
;                 for (int j = 0; j < 4; ++j) { const float sft = z4[j] + la[j] * (p4[j] - z4[j]) + lb[j] * (n4[j] - z4[j]); o4[j] = (lane < 32) ? tanhf(sft) : sft; }
;                 u32x2 w; w.x = cvt_pk_bf16(o4[0], o4[1]); w.y = cvt_pk_bf16(o4[2], o4[3]); *(u32x2*)(AL + (size_t)(t0 + i) * 256 + alc) = w;
	v_lshlrev_b32_e32 v144, 16, v36
	v_and_b32_e32 v145, 0xffff0000, v36
	v_lshlrev_b32_e32 v146, 16, v37
	v_and_b32_e32 v147, 0xffff0000, v37
	v_lshlrev_b32_e32 v148, 16, v38
	v_and_b32_e32 v149, 0xffff0000, v38
	v_lshlrev_b32_e32 v150, 16, v39
	v_and_b32_e32 v151, 0xffff0000, v39
	v_lshlrev_b32_e32 v152, 16, v40
	v_and_b32_e32 v153, 0xffff0000, v40
	v_lshlrev_b32_e32 v154, 16, v41
	v_and_b32_e32 v155, 0xffff0000, v41
	v_lshlrev_b32_e32 v156, 16, v42
	v_and_b32_e32 v157, 0xffff0000, v42
	v_lshlrev_b32_e32 v158, 16, v43
	v_and_b32_e32 v159, 0xffff0000, v43
	v_lshlrev_b32_e32 v160, 16, v48
	v_and_b32_e32 v161, 0xffff0000, v48
	v_lshlrev_b32_e32 v162, 16, v49
	v_and_b32_e32 v163, 0xffff0000, v49
	v_lshlrev_b32_e32 v164, 16, v50
	v_and_b32_e32 v165, 0xffff0000, v50
	v_lshlrev_b32_e32 v166, 16, v51
	v_and_b32_e32 v167, 0xffff0000, v51
	v_lshlrev_b32_e32 v168, 16, v52
	v_and_b32_e32 v169, 0xffff0000, v52
	v_lshlrev_b32_e32 v170, 16, v53
	v_and_b32_e32 v171, 0xffff0000, v53
	v_lshlrev_b32_e32 v172, 16, v54
	v_and_b32_e32 v173, 0xffff0000, v54
	v_lshlrev_b32_e32 v174, 16, v55
	v_and_b32_e32 v175, 0xffff0000, v55
	v_lshlrev_b32_e32 v176, 16, v60
	v_and_b32_e32 v177, 0xffff0000, v60
	v_lshlrev_b32_e32 v178, 16, v61
	v_and_b32_e32 v179, 0xffff0000, v61
	v_lshlrev_b32_e32 v180, 16, v62
	v_and_b32_e32 v181, 0xffff0000, v62
	v_lshlrev_b32_e32 v182, 16, v63
	v_and_b32_e32 v183, 0xffff0000, v63
	v_lshlrev_b32_e32 v184, 16, v64
	v_and_b32_e32 v185, 0xffff0000, v64
	v_lshlrev_b32_e32 v186, 16, v65
	v_and_b32_e32 v187, 0xffff0000, v65
	v_lshlrev_b32_e32 v188, 16, v66
	v_and_b32_e32 v189, 0xffff0000, v66
	v_lshlrev_b32_e32 v190, 16, v67
	v_and_b32_e32 v191, 0xffff0000, v67
	v_lshlrev_b32_e32 v136, 16, v44
	v_and_b32_e32 v137, 0xffff0000, v44
	v_lshlrev_b32_e32 v138, 16, v45
	v_and_b32_e32 v139, 0xffff0000, v45
	v_lshlrev_b32_e32 v140, 16, v56
	v_and_b32_e32 v141, 0xffff0000, v56
	v_lshlrev_b32_e32 v142, 16, v57
	v_and_b32_e32 v143, 0xffff0000, v57
	v_lshlrev_b32_e32 v216, 16, v68
	v_and_b32_e32 v217, 0xffff0000, v68
	v_lshlrev_b32_e32 v218, 16, v69
	v_and_b32_e32 v219, 0xffff0000, v69
	buffer_load_dwordx4 v[36:39], v232, s[64:67], 0 offen offset:4064
	buffer_load_dwordx4 v[40:43], v232, s[64:67], 0 offen offset:4080
	buffer_load_dwordx2 v[44:45], v233, s[64:67], 0 offen
	v_add_u32_e32 v233, 6656, v233
	v_add_u32_e32 v232, 6656, v232
	v_pk_add_f32 v[224:225], v[144:145], v[160:161] neg_lo:[0,1] neg_hi:[0,1]
	v_pk_add_f32 v[226:227], v[176:177], v[160:161] neg_lo:[0,1] neg_hi:[0,1]
	v_pk_fma_f32 v[192:193], v[96:97], v[224:225], v[160:161]
	v_pk_fma_f32 v[192:193], v[112:113], v[226:227], v[192:193]
	v_pk_add_f32 v[224:225], v[146:147], v[162:163] neg_lo:[0,1] neg_hi:[0,1]
	v_pk_add_f32 v[226:227], v[178:179], v[162:163] neg_lo:[0,1] neg_hi:[0,1]
	v_pk_fma_f32 v[194:195], v[98:99], v[224:225], v[162:163]
	v_pk_fma_f32 v[194:195], v[114:115], v[226:227], v[194:195]
	v_pk_add_f32 v[224:225], v[148:149], v[164:165] neg_lo:[0,1] neg_hi:[0,1]
	v_pk_add_f32 v[226:227], v[180:181], v[164:165] neg_lo:[0,1] neg_hi:[0,1]
	v_pk_fma_f32 v[196:197], v[100:101], v[224:225], v[164:165]
	v_pk_fma_f32 v[196:197], v[116:117], v[226:227], v[196:197]
	v_pk_add_f32 v[224:225], v[150:151], v[166:167] neg_lo:[0,1] neg_hi:[0,1]
	v_pk_add_f32 v[226:227], v[182:183], v[166:167] neg_lo:[0,1] neg_hi:[0,1]
	v_pk_fma_f32 v[198:199], v[102:103], v[224:225], v[166:167]
	v_pk_fma_f32 v[198:199], v[118:119], v[226:227], v[198:199]
	v_pk_add_f32 v[224:225], v[152:153], v[168:169] neg_lo:[0,1] neg_hi:[0,1]
	v_pk_add_f32 v[226:227], v[184:185], v[168:169] neg_lo:[0,1] neg_hi:[0,1]
	v_pk_fma_f32 v[200:201], v[104:105], v[224:225], v[168:169]
	v_pk_fma_f32 v[200:201], v[120:121], v[226:227], v[200:201]
	v_pk_add_f32 v[224:225], v[154:155], v[170:171] neg_lo:[0,1] neg_hi:[0,1]
	v_pk_add_f32 v[226:227], v[186:187], v[170:171] neg_lo:[0,1] neg_hi:[0,1]
	v_pk_fma_f32 v[202:203], v[106:107], v[224:225], v[170:171]
	v_pk_fma_f32 v[202:203], v[122:123], v[226:227], v[202:203]
	v_pk_add_f32 v[224:225], v[156:157], v[172:173] neg_lo:[0,1] neg_hi:[0,1]
	v_pk_add_f32 v[226:227], v[188:189], v[172:173] neg_lo:[0,1] neg_hi:[0,1]
	v_pk_fma_f32 v[204:205], v[108:109], v[224:225], v[172:173]
	v_pk_fma_f32 v[204:205], v[124:125], v[226:227], v[204:205]
	v_pk_add_f32 v[224:225], v[158:159], v[174:175] neg_lo:[0,1] neg_hi:[0,1]
	v_pk_add_f32 v[226:227], v[190:191], v[174:175] neg_lo:[0,1] neg_hi:[0,1]
	v_pk_fma_f32 v[206:207], v[110:111], v[224:225], v[174:175]
	v_pk_fma_f32 v[206:207], v[126:127], v[226:227], v[206:207]
	v_cvt_pk_bf16_f32 v208, v192, v193
	v_cvt_pk_bf16_f32 v209, v194, v195
	v_cvt_pk_bf16_f32 v210, v196, v197
	v_cvt_pk_bf16_f32 v211, v198, v199
	v_cvt_pk_bf16_f32 v212, v200, v201
	v_cvt_pk_bf16_f32 v213, v202, v203
	v_cvt_pk_bf16_f32 v214, v204, v205
	v_cvt_pk_bf16_f32 v215, v206, v207
	buffer_store_dwordx4 v[208:211], v237, s[68:71], s73 offen offset:0
	buffer_store_dwordx4 v[212:215], v237, s[68:71], s73 offen offset:16
	v_sub_f32_e32 v224, v136, v140
	v_sub_f32_e32 v225, v216, v140
	v_fma_f32 v220, v128, v224, v140
	v_fma_f32 v220, v132, v225, v220
	v_sub_f32_e32 v224, v137, v141
	v_sub_f32_e32 v225, v217, v141
	v_fma_f32 v221, v129, v224, v141
	v_fma_f32 v221, v133, v225, v221
	v_sub_f32_e32 v224, v138, v142
	v_sub_f32_e32 v225, v218, v142
	v_fma_f32 v222, v130, v224, v142
	v_fma_f32 v222, v134, v225, v222
	v_sub_f32_e32 v224, v139, v143
	v_sub_f32_e32 v225, v219, v143
	v_fma_f32 v223, v131, v224, v143
	v_fma_f32 v223, v135, v225, v223
	v_and_b32_e32 v224, 0x7fffffff, v220
	v_mul_f32_e32 v225, 0x4038aa3b, v224
	v_exp_f32_e32 v225, v225
	v_mul_f32_e32 v226, v220, v220
	v_add_f32_e32 v225, 1.0, v225
; __device__ __forceinline__ float bflo(unsigned w) { return __uint_as_float(w << 16); }
; __device__ __forceinline__ float bfhi(unsigned w) { return __uint_as_float(w & 0xffff0000u); }
; __device__ __forceinline__ unsigned cvt_pk_bf16(float lo, float hi) { unsigned r; asm volatile("v_cvt_pk_bf16_f32 %0, %1, %2" : "=v"(r) : "v"(lo), "v"(hi)); return r; }
; __device__ __forceinline__ void prep_phase(const Params& p) {
;     ...
;             for (int i = 0; i < 16; ++i) {
;                 const bool hn = (tt0 + i) < SEQ - 1; const u16* zn = zc + (size_t)(i + 1) * 3328;
;                 const Z16 vn = hn ? ldz(zn + 2048 + c) : zz(); const u32x2 ln = hn ? *(const u32x2*)(zn + cl) : (u32x2){0u, 0u};
;                 float v[16]; mix16(vp, vc, vn, mpv, mnv, v);
;                 st16bf(V + (size_t)(t0 + i) * RW + c, v);
;                 const float z4[4] = {bflo(lc.x), bfhi(lc.x), bflo(lc.y), bfhi(lc.y)}, p4[4] = {bflo(lp.x), bfhi(lp.x), bflo(lp.y), bfhi(lp.y)}, n4[4] = {bflo(ln.x), bfhi(ln.x), bflo(ln.y), bfhi(ln.y)};
;                 float o4[4];
; #pragma unroll
;                 for (int j = 0; j < 4; ++j) { const float sft = z4[j] + la[j] * (p4[j] - z4[j]) + lb[j] * (n4[j] - z4[j]); o4[j] = (lane < 32) ? tanhf(sft) : sft; }
;                 u32x2 w; w.x = cvt_pk_bf16(o4[0], o4[1]); w.y = cvt_pk_bf16(o4[2], o4[3]); *(u32x2*)(AL + (size_t)(t0 + i) * 256 + alc) = w;
;                 vp = vc; vc = vn; lp = lc; lc = ln;
	v_rcp_f32_e32 v225, v225
	v_mul_f32_e32 v227, 0xbeaaaaab, v226
	v_fma_f32 v225, v225, -2.0, 1.0
	v_fma_f32 v227, v227, v220, v220
	v_bfi_b32 v225, v241, v225, v220
	v_cmp_gt_f32_e32 vcc, 0x3d000000, v224
	s_nop 1
	v_cndmask_b32_e32 v225, v225, v227, vcc
	v_cmp_gt_u32_e32 vcc, 32, v240
	s_nop 1
	v_cndmask_b32_e32 v220, v220, v225, vcc
	v_and_b32_e32 v224, 0x7fffffff, v221
	v_mul_f32_e32 v225, 0x4038aa3b, v224
	v_exp_f32_e32 v225, v225
	v_mul_f32_e32 v226, v221, v221
	v_add_f32_e32 v225, 1.0, v225
	v_rcp_f32_e32 v225, v225
	v_mul_f32_e32 v227, 0xbeaaaaab, v226
	v_fma_f32 v225, v225, -2.0, 1.0
	v_fma_f32 v227, v227, v221, v221
	v_bfi_b32 v225, v241, v225, v221
	v_cmp_gt_f32_e32 vcc, 0x3d000000, v224
	s_nop 1
	v_cndmask_b32_e32 v225, v225, v227, vcc
	v_cmp_gt_u32_e32 vcc, 32, v240
	s_nop 1
	v_cndmask_b32_e32 v221, v221, v225, vcc
	v_and_b32_e32 v224, 0x7fffffff, v222
	v_mul_f32_e32 v225, 0x4038aa3b, v224
	v_exp_f32_e32 v225, v225
	v_mul_f32_e32 v226, v222, v222
	v_add_f32_e32 v225, 1.0, v225
	v_rcp_f32_e32 v225, v225
	v_mul_f32_e32 v227, 0xbeaaaaab, v226
	v_fma_f32 v225, v225, -2.0, 1.0
	v_fma_f32 v227, v227, v222, v222
	v_bfi_b32 v225, v241, v225, v222
	v_cmp_gt_f32_e32 vcc, 0x3d000000, v224
	s_nop 1
	v_cndmask_b32_e32 v225, v225, v227, vcc
	v_cmp_gt_u32_e32 vcc, 32, v240
	s_nop 1
	v_cndmask_b32_e32 v222, v222, v225, vcc
	v_and_b32_e32 v224, 0x7fffffff, v223
	v_mul_f32_e32 v225, 0x4038aa3b, v224
	v_exp_f32_e32 v225, v225
	v_mul_f32_e32 v226, v223, v223
	v_add_f32_e32 v225, 1.0, v225
	v_rcp_f32_e32 v225, v225
	v_mul_f32_e32 v227, 0xbeaaaaab, v226
	v_fma_f32 v225, v225, -2.0, 1.0
	v_fma_f32 v227, v227, v223, v223
	v_bfi_b32 v225, v241, v225, v223
	v_cmp_gt_f32_e32 vcc, 0x3d000000, v224
	s_nop 1
	v_cndmask_b32_e32 v225, v225, v227, vcc
	v_cmp_gt_u32_e32 vcc, 32, v240
	s_nop 1
	v_cndmask_b32_e32 v223, v223, v225, vcc
	v_cvt_pk_bf16_f32 v224, v220, v221
	v_cvt_pk_bf16_f32 v225, v222, v223
	buffer_store_dwordx2 v[224:225], v238, s[68:71], s74 offen
	s_add_u32 s72, s72, 0x1000
	s_add_u32 s73, s73, 0x800
	s_add_u32 s74, s74, 0x200
	s_add_u32 s75, s75, 0x40
	s_waitcnt vmcnt(27)
	v_lshlrev_b32_e32 v144, 16, v48
	v_and_b32_e32 v145, 0xffff0000, v48
	v_lshlrev_b32_e32 v146, 16, v49
	v_and_b32_e32 v147, 0xffff0000, v49
	v_lshlrev_b32_e32 v148, 16, v50
	v_and_b32_e32 v149, 0xffff0000, v50
	v_lshlrev_b32_e32 v150, 16, v51
	v_and_b32_e32 v151, 0xffff0000, v51
	v_lshlrev_b32_e32 v152, 16, v52
	v_and_b32_e32 v153, 0xffff0000, v52
	v_lshlrev_b32_e32 v154, 16, v53
	v_and_b32_e32 v155, 0xffff0000, v53
	v_lshlrev_b32_e32 v156, 16, v54
	v_and_b32_e32 v157, 0xffff0000, v54
	v_lshlrev_b32_e32 v158, 16, v55
	v_and_b32_e32 v159, 0xffff0000, v55
	v_lshlrev_b32_e32 v160, 16, v60
	v_and_b32_e32 v161, 0xffff0000, v60
	v_lshlrev_b32_e32 v162, 16, v61
	v_and_b32_e32 v163, 0xffff0000, v61
	v_lshlrev_b32_e32 v164, 16, v62
	v_and_b32_e32 v165, 0xffff0000, v62
	v_lshlrev_b32_e32 v166, 16, v63
	v_and_b32_e32 v167, 0xffff0000, v63
	v_lshlrev_b32_e32 v168, 16, v64
	v_and_b32_e32 v169, 0xffff0000, v64
	v_lshlrev_b32_e32 v170, 16, v65
	v_and_b32_e32 v171, 0xffff0000, v65
	v_lshlrev_b32_e32 v172, 16, v66
	v_and_b32_e32 v173, 0xffff0000, v66
	v_lshlrev_b32_e32 v174, 16, v67
	v_and_b32_e32 v175, 0xffff0000, v67
	v_lshlrev_b32_e32 v176, 16, v72
	v_and_b32_e32 v177, 0xffff0000, v72
	v_lshlrev_b32_e32 v178, 16, v73
	v_and_b32_e32 v179, 0xffff0000, v73
	v_lshlrev_b32_e32 v180, 16, v74
	v_and_b32_e32 v181, 0xffff0000, v74
	v_lshlrev_b32_e32 v182, 16, v75
	v_and_b32_e32 v183, 0xffff0000, v75
	v_lshlrev_b32_e32 v184, 16, v76
	v_and_b32_e32 v185, 0xffff0000, v76
	v_lshlrev_b32_e32 v186, 16, v77
	v_and_b32_e32 v187, 0xffff0000, v77
	v_lshlrev_b32_e32 v188, 16, v78
	v_and_b32_e32 v189, 0xffff0000, v78
	v_lshlrev_b32_e32 v190, 16, v79
	v_and_b32_e32 v191, 0xffff0000, v79
	v_lshlrev_b32_e32 v136, 16, v56
	v_and_b32_e32 v137, 0xffff0000, v56
	v_lshlrev_b32_e32 v138, 16, v57
	v_and_b32_e32 v139, 0xffff0000, v57
	v_lshlrev_b32_e32 v140, 16, v68
	v_and_b32_e32 v141, 0xffff0000, v68
	v_lshlrev_b32_e32 v142, 16, v69
	v_and_b32_e32 v143, 0xffff0000, v69
	v_lshlrev_b32_e32 v216, 16, v80
	v_and_b32_e32 v217, 0xffff0000, v80
	v_lshlrev_b32_e32 v218, 16, v81
	v_and_b32_e32 v219, 0xffff0000, v81
	buffer_load_dwordx4 v[48:51], v232, s[64:67], 0 offen offset:4064
	buffer_load_dwordx4 v[52:55], v232, s[64:67], 0 offen offset:4080
	buffer_load_dwordx2 v[56:57], v233, s[64:67], 0 offen
	v_add_u32_e32 v233, 6656, v233
	v_add_u32_e32 v232, 6656, v232
	v_pk_add_f32 v[224:225], v[144:145], v[160:161] neg_lo:[0,1] neg_hi:[0,1]
	v_pk_add_f32 v[226:227], v[176:177], v[160:161] neg_lo:[0,1] neg_hi:[0,1]
	v_pk_fma_f32 v[192:193], v[96:97], v[224:225], v[160:161]
	v_pk_fma_f32 v[192:193], v[112:113], v[226:227], v[192:193]
	v_pk_add_f32 v[224:225], v[146:147], v[162:163] neg_lo:[0,1] neg_hi:[0,1]
	v_pk_add_f32 v[226:227], v[178:179], v[162:163] neg_lo:[0,1] neg_hi:[0,1]
	v_pk_fma_f32 v[194:195], v[98:99], v[224:225], v[162:163]
	v_pk_fma_f32 v[194:195], v[114:115], v[226:227], v[194:195]
	v_pk_add_f32 v[224:225], v[148:149], v[164:165] neg_lo:[0,1] neg_hi:[0,1]
	v_pk_add_f32 v[226:227], v[180:181], v[164:165] neg_lo:[0,1] neg_hi:[0,1]
	v_pk_fma_f32 v[196:197], v[100:101], v[224:225], v[164:165]
	v_pk_fma_f32 v[196:197], v[116:117], v[226:227], v[196:197]
	v_pk_add_f32 v[224:225], v[150:151], v[166:167] neg_lo:[0,1] neg_hi:[0,1]
	v_pk_add_f32 v[226:227], v[182:183], v[166:167] neg_lo:[0,1] neg_hi:[0,1]
	v_pk_fma_f32 v[198:199], v[102:103], v[224:225], v[166:167]
	v_pk_fma_f32 v[198:199], v[118:119], v[226:227], v[198:199]
	v_pk_add_f32 v[224:225], v[152:153], v[168:169] neg_lo:[0,1] neg_hi:[0,1]
; __device__ __forceinline__ float bflo(unsigned w) { return __uint_as_float(w << 16); }
; __device__ __forceinline__ float bfhi(unsigned w) { return __uint_as_float(w & 0xffff0000u); }
; __device__ __forceinline__ unsigned cvt_pk_bf16(float lo, float hi) { unsigned r; asm volatile("v_cvt_pk_bf16_f32 %0, %1, %2" : "=v"(r) : "v"(lo), "v"(hi)); return r; }
; __device__ __forceinline__ void prep_phase(const Params& p) {
;     ...
;             for (int i = 0; i < 16; ++i) {
;                 const bool hn = (tt0 + i) < SEQ - 1; const u16* zn = zc + (size_t)(i + 1) * 3328;
;                 const Z16 vn = hn ? ldz(zn + 2048 + c) : zz(); const u32x2 ln = hn ? *(const u32x2*)(zn + cl) : (u32x2){0u, 0u};
;                 float v[16]; mix16(vp, vc, vn, mpv, mnv, v);
;                 st16bf(V + (size_t)(t0 + i) * RW + c, v);
;                 const float z4[4] = {bflo(lc.x), bfhi(lc.x), bflo(lc.y), bfhi(lc.y)}, p4[4] = {bflo(lp.x), bfhi(lp.x), bflo(lp.y), bfhi(lp.y)}, n4[4] = {bflo(ln.x), bfhi(ln.x), bflo(ln.y), bfhi(ln.y)};
;                 float o4[4];
; #pragma unroll
;                 for (int j = 0; j < 4; ++j) { const float sft = z4[j] + la[j] * (p4[j] - z4[j]) + lb[j] * (n4[j] - z4[j]); o4[j] = (lane < 32) ? tanhf(sft) : sft; }
;                 u32x2 w; w.x = cvt_pk_bf16(o4[0], o4[1]); w.y = cvt_pk_bf16(o4[2], o4[3]); *(u32x2*)(AL + (size_t)(t0 + i) * 256 + alc) = w;
;                 vp = vc; vc = vn; lp = lc; lc = ln;
	v_pk_add_f32 v[226:227], v[184:185], v[168:169] neg_lo:[0,1] neg_hi:[0,1]
	v_pk_fma_f32 v[200:201], v[104:105], v[224:225], v[168:169]
	v_pk_fma_f32 v[200:201], v[120:121], v[226:227], v[200:201]
	v_pk_add_f32 v[224:225], v[154:155], v[170:171] neg_lo:[0,1] neg_hi:[0,1]
	v_pk_add_f32 v[226:227], v[186:187], v[170:171] neg_lo:[0,1] neg_hi:[0,1]
	v_pk_fma_f32 v[202:203], v[106:107], v[224:225], v[170:171]
	v_pk_fma_f32 v[202:203], v[122:123], v[226:227], v[202:203]
	v_pk_add_f32 v[224:225], v[156:157], v[172:173] neg_lo:[0,1] neg_hi:[0,1]
	v_pk_add_f32 v[226:227], v[188:189], v[172:173] neg_lo:[0,1] neg_hi:[0,1]
	v_pk_fma_f32 v[204:205], v[108:109], v[224:225], v[172:173]
	v_pk_fma_f32 v[204:205], v[124:125], v[226:227], v[204:205]
	v_pk_add_f32 v[224:225], v[158:159], v[174:175] neg_lo:[0,1] neg_hi:[0,1]
	v_pk_add_f32 v[226:227], v[190:191], v[174:175] neg_lo:[0,1] neg_hi:[0,1]
	v_pk_fma_f32 v[206:207], v[110:111], v[224:225], v[174:175]
	v_pk_fma_f32 v[206:207], v[126:127], v[226:227], v[206:207]
	v_cvt_pk_bf16_f32 v208, v192, v193
	v_cvt_pk_bf16_f32 v209, v194, v195
	v_cvt_pk_bf16_f32 v210, v196, v197
	v_cvt_pk_bf16_f32 v211, v198, v199
	v_cvt_pk_bf16_f32 v212, v200, v201
	v_cvt_pk_bf16_f32 v213, v202, v203
	v_cvt_pk_bf16_f32 v214, v204, v205
	v_cvt_pk_bf16_f32 v215, v206, v207
	buffer_store_dwordx4 v[208:211], v237, s[68:71], s73 offen offset:0
	buffer_store_dwordx4 v[212:215], v237, s[68:71], s73 offen offset:16
	v_sub_f32_e32 v224, v136, v140
	v_sub_f32_e32 v225, v216, v140
	v_fma_f32 v220, v128, v224, v140
	v_fma_f32 v220, v132, v225, v220
	v_sub_f32_e32 v224, v137, v141
	v_sub_f32_e32 v225, v217, v141
	v_fma_f32 v221, v129, v224, v141
	v_fma_f32 v221, v133, v225, v221
	v_sub_f32_e32 v224, v138, v142
	v_sub_f32_e32 v225, v218, v142
	v_fma_f32 v222, v130, v224, v142
	v_fma_f32 v222, v134, v225, v222
	v_sub_f32_e32 v224, v139, v143
	v_sub_f32_e32 v225, v219, v143
	v_fma_f32 v223, v131, v224, v143
	v_fma_f32 v223, v135, v225, v223
	v_and_b32_e32 v224, 0x7fffffff, v220
	v_mul_f32_e32 v225, 0x4038aa3b, v224
	v_exp_f32_e32 v225, v225
	v_mul_f32_e32 v226, v220, v220
	v_add_f32_e32 v225, 1.0, v225
	v_rcp_f32_e32 v225, v225
	v_mul_f32_e32 v227, 0xbeaaaaab, v226
	v_fma_f32 v225, v225, -2.0, 1.0
	v_fma_f32 v227, v227, v220, v220
	v_bfi_b32 v225, v241, v225, v220
	v_cmp_gt_f32_e32 vcc, 0x3d000000, v224
	s_nop 1
	v_cndmask_b32_e32 v225, v225, v227, vcc
	v_cmp_gt_u32_e32 vcc, 32, v240
	s_nop 1
	v_cndmask_b32_e32 v220, v220, v225, vcc
	v_and_b32_e32 v224, 0x7fffffff, v221
	v_mul_f32_e32 v225, 0x4038aa3b, v224
	v_exp_f32_e32 v225, v225
	v_mul_f32_e32 v226, v221, v221
	v_add_f32_e32 v225, 1.0, v225
	v_rcp_f32_e32 v225, v225
	v_mul_f32_e32 v227, 0xbeaaaaab, v226
	v_fma_f32 v225, v225, -2.0, 1.0
	v_fma_f32 v227, v227, v221, v221
	v_bfi_b32 v225, v241, v225, v221
	v_cmp_gt_f32_e32 vcc, 0x3d000000, v224
	s_nop 1
	v_cndmask_b32_e32 v225, v225, v227, vcc
	v_cmp_gt_u32_e32 vcc, 32, v240
	s_nop 1
	v_cndmask_b32_e32 v221, v221, v225, vcc
	v_and_b32_e32 v224, 0x7fffffff, v222
	v_mul_f32_e32 v225, 0x4038aa3b, v224
	v_exp_f32_e32 v225, v225
	v_mul_f32_e32 v226, v222, v222
	v_add_f32_e32 v225, 1.0, v225
	v_rcp_f32_e32 v225, v225
	v_mul_f32_e32 v227, 0xbeaaaaab, v226
	v_fma_f32 v225, v225, -2.0, 1.0
	v_fma_f32 v227, v227, v222, v222
	v_bfi_b32 v225, v241, v225, v222
	v_cmp_gt_f32_e32 vcc, 0x3d000000, v224
	s_nop 1
	v_cndmask_b32_e32 v225, v225, v227, vcc
	v_cmp_gt_u32_e32 vcc, 32, v240
	s_nop 1
	v_cndmask_b32_e32 v222, v222, v225, vcc
	v_and_b32_e32 v224, 0x7fffffff, v223
	v_mul_f32_e32 v225, 0x4038aa3b, v224
	v_exp_f32_e32 v225, v225
	v_mul_f32_e32 v226, v223, v223
	v_add_f32_e32 v225, 1.0, v225
	v_rcp_f32_e32 v225, v225
	v_mul_f32_e32 v227, 0xbeaaaaab, v226
	v_fma_f32 v225, v225, -2.0, 1.0
	v_fma_f32 v227, v227, v223, v223
	v_bfi_b32 v225, v241, v225, v223
	v_cmp_gt_f32_e32 vcc, 0x3d000000, v224
	s_nop 1
	v_cndmask_b32_e32 v225, v225, v227, vcc
	v_cmp_gt_u32_e32 vcc, 32, v240
	s_nop 1
	v_cndmask_b32_e32 v223, v223, v225, vcc
	v_cvt_pk_bf16_f32 v224, v220, v221
	v_cvt_pk_bf16_f32 v225, v222, v223
	buffer_store_dwordx2 v[224:225], v238, s[68:71], s74 offen
	s_add_u32 s72, s72, 0x1000
	s_add_u32 s73, s73, 0x800
	s_add_u32 s74, s74, 0x200
	s_add_u32 s75, s75, 0x40
	s_waitcnt vmcnt(30)
; __device__ __forceinline__ float bflo(unsigned w) { return __uint_as_float(w << 16); }
; __device__ __forceinline__ float bfhi(unsigned w) { return __uint_as_float(w & 0xffff0000u); }
; __device__ __forceinline__ unsigned cvt_pk_bf16(float lo, float hi) { unsigned r; asm volatile("v_cvt_pk_bf16_f32 %0, %1, %2" : "=v"(r) : "v"(lo), "v"(hi)); return r; }
; __device__ __forceinline__ void prep_phase(const Params& p) {
;     ...
;             for (int i = 0; i < 16; ++i) {
;                 const bool hn = (tt0 + i) < SEQ - 1; const u16* zn = zc + (size_t)(i + 1) * 3328;
;                 const Z16 vn = hn ? ldz(zn + 2048 + c) : zz(); const u32x2 ln = hn ? *(const u32x2*)(zn + cl) : (u32x2){0u, 0u};
;                 float v[16]; mix16(vp, vc, vn, mpv, mnv, v);
;                 st16bf(V + (size_t)(t0 + i) * RW + c, v);
;                 const float z4[4] = {bflo(lc.x), bfhi(lc.x), bflo(lc.y), bfhi(lc.y)}, p4[4] = {bflo(lp.x), bfhi(lp.x), bflo(lp.y), bfhi(lp.y)}, n4[4] = {bflo(ln.x), bfhi(ln.x), bflo(ln.y), bfhi(ln.y)};
;                 float o4[4];
; #pragma unroll
;                 for (int j = 0; j < 4; ++j) { const float sft = z4[j] + la[j] * (p4[j] - z4[j]) + lb[j] * (n4[j] - z4[j]); o4[j] = (lane < 32) ? tanhf(sft) : sft; }
;                 u32x2 w; w.x = cvt_pk_bf16(o4[0], o4[1]); w.y = cvt_pk_bf16(o4[2], o4[3]); *(u32x2*)(AL + (size_t)(t0 + i) * 256 + alc) = w;
	v_lshlrev_b32_e32 v144, 16, v60
	v_and_b32_e32 v145, 0xffff0000, v60
	v_lshlrev_b32_e32 v146, 16, v61
	v_and_b32_e32 v147, 0xffff0000, v61
	v_lshlrev_b32_e32 v148, 16, v62
	v_and_b32_e32 v149, 0xffff0000, v62
	v_lshlrev_b32_e32 v150, 16, v63
	v_and_b32_e32 v151, 0xffff0000, v63
	v_lshlrev_b32_e32 v152, 16, v64
	v_and_b32_e32 v153, 0xffff0000, v64
	v_lshlrev_b32_e32 v154, 16, v65
	v_and_b32_e32 v155, 0xffff0000, v65
	v_lshlrev_b32_e32 v156, 16, v66
	v_and_b32_e32 v157, 0xffff0000, v66
	v_lshlrev_b32_e32 v158, 16, v67
	v_and_b32_e32 v159, 0xffff0000, v67
	v_lshlrev_b32_e32 v160, 16, v72
	v_and_b32_e32 v161, 0xffff0000, v72
	v_lshlrev_b32_e32 v162, 16, v73
	v_and_b32_e32 v163, 0xffff0000, v73
	v_lshlrev_b32_e32 v164, 16, v74
	v_and_b32_e32 v165, 0xffff0000, v74
	v_lshlrev_b32_e32 v166, 16, v75
	v_and_b32_e32 v167, 0xffff0000, v75
	v_lshlrev_b32_e32 v168, 16, v76
	v_and_b32_e32 v169, 0xffff0000, v76
	v_lshlrev_b32_e32 v170, 16, v77
	v_and_b32_e32 v171, 0xffff0000, v77
	v_lshlrev_b32_e32 v172, 16, v78
	v_and_b32_e32 v173, 0xffff0000, v78
	v_lshlrev_b32_e32 v174, 16, v79
	v_and_b32_e32 v175, 0xffff0000, v79
	v_lshlrev_b32_e32 v176, 16, v84
	v_and_b32_e32 v177, 0xffff0000, v84
	v_lshlrev_b32_e32 v178, 16, v85
	v_and_b32_e32 v179, 0xffff0000, v85
	v_lshlrev_b32_e32 v180, 16, v86
	v_and_b32_e32 v181, 0xffff0000, v86
	v_lshlrev_b32_e32 v182, 16, v87
	v_and_b32_e32 v183, 0xffff0000, v87
	v_lshlrev_b32_e32 v184, 16, v88
	v_and_b32_e32 v185, 0xffff0000, v88
	v_lshlrev_b32_e32 v186, 16, v89
	v_and_b32_e32 v187, 0xffff0000, v89
	v_lshlrev_b32_e32 v188, 16, v90
	v_and_b32_e32 v189, 0xffff0000, v90
	v_lshlrev_b32_e32 v190, 16, v91
	v_and_b32_e32 v191, 0xffff0000, v91
	v_lshlrev_b32_e32 v136, 16, v68
	v_and_b32_e32 v137, 0xffff0000, v68
	v_lshlrev_b32_e32 v138, 16, v69
	v_and_b32_e32 v139, 0xffff0000, v69
	v_lshlrev_b32_e32 v140, 16, v80
	v_and_b32_e32 v141, 0xffff0000, v80
	v_lshlrev_b32_e32 v142, 16, v81
	v_and_b32_e32 v143, 0xffff0000, v81
	v_lshlrev_b32_e32 v216, 16, v92
	v_and_b32_e32 v217, 0xffff0000, v92
	v_lshlrev_b32_e32 v218, 16, v93
	v_and_b32_e32 v219, 0xffff0000, v93
	buffer_load_dwordx4 v[60:63], v232, s[64:67], 0 offen offset:4064
	buffer_load_dwordx4 v[64:67], v232, s[64:67], 0 offen offset:4080
	buffer_load_dwordx2 v[68:69], v233, s[64:67], 0 offen
	v_add_u32_e32 v233, 6656, v233
	v_add_u32_e32 v232, 6656, v232
	v_pk_add_f32 v[224:225], v[144:145], v[160:161] neg_lo:[0,1] neg_hi:[0,1]
	v_pk_add_f32 v[226:227], v[176:177], v[160:161] neg_lo:[0,1] neg_hi:[0,1]
	v_pk_fma_f32 v[192:193], v[96:97], v[224:225], v[160:161]
	v_pk_fma_f32 v[192:193], v[112:113], v[226:227], v[192:193]
	v_pk_add_f32 v[224:225], v[146:147], v[162:163] neg_lo:[0,1] neg_hi:[0,1]
	v_pk_add_f32 v[226:227], v[178:179], v[162:163] neg_lo:[0,1] neg_hi:[0,1]
	v_pk_fma_f32 v[194:195], v[98:99], v[224:225], v[162:163]
	v_pk_fma_f32 v[194:195], v[114:115], v[226:227], v[194:195]
	v_pk_add_f32 v[224:225], v[148:149], v[164:165] neg_lo:[0,1] neg_hi:[0,1]
	v_pk_add_f32 v[226:227], v[180:181], v[164:165] neg_lo:[0,1] neg_hi:[0,1]
	v_pk_fma_f32 v[196:197], v[100:101], v[224:225], v[164:165]
	v_pk_fma_f32 v[196:197], v[116:117], v[226:227], v[196:197]
	v_pk_add_f32 v[224:225], v[150:151], v[166:167] neg_lo:[0,1] neg_hi:[0,1]
	v_pk_add_f32 v[226:227], v[182:183], v[166:167] neg_lo:[0,1] neg_hi:[0,1]
	v_pk_fma_f32 v[198:199], v[102:103], v[224:225], v[166:167]
	v_pk_fma_f32 v[198:199], v[118:119], v[226:227], v[198:199]
	v_pk_add_f32 v[224:225], v[152:153], v[168:169] neg_lo:[0,1] neg_hi:[0,1]
	v_pk_add_f32 v[226:227], v[184:185], v[168:169] neg_lo:[0,1] neg_hi:[0,1]
	v_pk_fma_f32 v[200:201], v[104:105], v[224:225], v[168:169]
	v_pk_fma_f32 v[200:201], v[120:121], v[226:227], v[200:201]
	v_pk_add_f32 v[224:225], v[154:155], v[170:171] neg_lo:[0,1] neg_hi:[0,1]
	v_pk_add_f32 v[226:227], v[186:187], v[170:171] neg_lo:[0,1] neg_hi:[0,1]
	v_pk_fma_f32 v[202:203], v[106:107], v[224:225], v[170:171]
	v_pk_fma_f32 v[202:203], v[122:123], v[226:227], v[202:203]
	v_pk_add_f32 v[224:225], v[156:157], v[172:173] neg_lo:[0,1] neg_hi:[0,1]
	v_pk_add_f32 v[226:227], v[188:189], v[172:173] neg_lo:[0,1] neg_hi:[0,1]
	v_pk_fma_f32 v[204:205], v[108:109], v[224:225], v[172:173]
	v_pk_fma_f32 v[204:205], v[124:125], v[226:227], v[204:205]
	v_pk_add_f32 v[224:225], v[158:159], v[174:175] neg_lo:[0,1] neg_hi:[0,1]
	v_pk_add_f32 v[226:227], v[190:191], v[174:175] neg_lo:[0,1] neg_hi:[0,1]
	v_pk_fma_f32 v[206:207], v[110:111], v[224:225], v[174:175]
	v_pk_fma_f32 v[206:207], v[126:127], v[226:227], v[206:207]
	v_cvt_pk_bf16_f32 v208, v192, v193
	v_cvt_pk_bf16_f32 v209, v194, v195
	v_cvt_pk_bf16_f32 v210, v196, v197
	v_cvt_pk_bf16_f32 v211, v198, v199
	v_cvt_pk_bf16_f32 v212, v200, v201
	v_cvt_pk_bf16_f32 v213, v202, v203
	v_cvt_pk_bf16_f32 v214, v204, v205
	v_cvt_pk_bf16_f32 v215, v206, v207
	buffer_store_dwordx4 v[208:211], v237, s[68:71], s73 offen offset:0
	buffer_store_dwordx4 v[212:215], v237, s[68:71], s73 offen offset:16
	v_sub_f32_e32 v224, v136, v140
	v_sub_f32_e32 v225, v216, v140
	v_fma_f32 v220, v128, v224, v140
	v_fma_f32 v220, v132, v225, v220
	v_sub_f32_e32 v224, v137, v141
	v_sub_f32_e32 v225, v217, v141
	v_fma_f32 v221, v129, v224, v141
	v_fma_f32 v221, v133, v225, v221
	v_sub_f32_e32 v224, v138, v142
	v_sub_f32_e32 v225, v218, v142
	v_fma_f32 v222, v130, v224, v142
	v_fma_f32 v222, v134, v225, v222
	v_sub_f32_e32 v224, v139, v143
	v_sub_f32_e32 v225, v219, v143
	v_fma_f32 v223, v131, v224, v143
	v_fma_f32 v223, v135, v225, v223
	v_and_b32_e32 v224, 0x7fffffff, v220
	v_mul_f32_e32 v225, 0x4038aa3b, v224
	v_exp_f32_e32 v225, v225
	v_mul_f32_e32 v226, v220, v220
	v_add_f32_e32 v225, 1.0, v225
; __device__ __forceinline__ float bflo(unsigned w) { return __uint_as_float(w << 16); }
; __device__ __forceinline__ float bfhi(unsigned w) { return __uint_as_float(w & 0xffff0000u); }
; __device__ __forceinline__ unsigned cvt_pk_bf16(float lo, float hi) { unsigned r; asm volatile("v_cvt_pk_bf16_f32 %0, %1, %2" : "=v"(r) : "v"(lo), "v"(hi)); return r; }
; __device__ __forceinline__ void prep_phase(const Params& p) {
;     ...
;             for (int i = 0; i < 16; ++i) {
;                 const bool hn = (tt0 + i) < SEQ - 1; const u16* zn = zc + (size_t)(i + 1) * 3328;
;                 const Z16 vn = hn ? ldz(zn + 2048 + c) : zz(); const u32x2 ln = hn ? *(const u32x2*)(zn + cl) : (u32x2){0u, 0u};
;                 float v[16]; mix16(vp, vc, vn, mpv, mnv, v);
;                 st16bf(V + (size_t)(t0 + i) * RW + c, v);
;                 const float z4[4] = {bflo(lc.x), bfhi(lc.x), bflo(lc.y), bfhi(lc.y)}, p4[4] = {bflo(lp.x), bfhi(lp.x), bflo(lp.y), bfhi(lp.y)}, n4[4] = {bflo(ln.x), bfhi(ln.x), bflo(ln.y), bfhi(ln.y)};
;                 float o4[4];
; #pragma unroll
;                 for (int j = 0; j < 4; ++j) { const float sft = z4[j] + la[j] * (p4[j] - z4[j]) + lb[j] * (n4[j] - z4[j]); o4[j] = (lane < 32) ? tanhf(sft) : sft; }
;                 u32x2 w; w.x = cvt_pk_bf16(o4[0], o4[1]); w.y = cvt_pk_bf16(o4[2], o4[3]); *(u32x2*)(AL + (size_t)(t0 + i) * 256 + alc) = w;
;                 vp = vc; vc = vn; lp = lc; lc = ln;
	v_rcp_f32_e32 v225, v225
	v_mul_f32_e32 v227, 0xbeaaaaab, v226
	v_fma_f32 v225, v225, -2.0, 1.0
	v_fma_f32 v227, v227, v220, v220
	v_bfi_b32 v225, v241, v225, v220
	v_cmp_gt_f32_e32 vcc, 0x3d000000, v224
	s_nop 1
	v_cndmask_b32_e32 v225, v225, v227, vcc
	v_cmp_gt_u32_e32 vcc, 32, v240
	s_nop 1
	v_cndmask_b32_e32 v220, v220, v225, vcc
	v_and_b32_e32 v224, 0x7fffffff, v221
	v_mul_f32_e32 v225, 0x4038aa3b, v224
	v_exp_f32_e32 v225, v225
	v_mul_f32_e32 v226, v221, v221
	v_add_f32_e32 v225, 1.0, v225
	v_rcp_f32_e32 v225, v225
	v_mul_f32_e32 v227, 0xbeaaaaab, v226
	v_fma_f32 v225, v225, -2.0, 1.0
	v_fma_f32 v227, v227, v221, v221
	v_bfi_b32 v225, v241, v225, v221
	v_cmp_gt_f32_e32 vcc, 0x3d000000, v224
	s_nop 1
	v_cndmask_b32_e32 v225, v225, v227, vcc
	v_cmp_gt_u32_e32 vcc, 32, v240
	s_nop 1
	v_cndmask_b32_e32 v221, v221, v225, vcc
	v_and_b32_e32 v224, 0x7fffffff, v222
	v_mul_f32_e32 v225, 0x4038aa3b, v224
	v_exp_f32_e32 v225, v225
	v_mul_f32_e32 v226, v222, v222
	v_add_f32_e32 v225, 1.0, v225
	v_rcp_f32_e32 v225, v225
	v_mul_f32_e32 v227, 0xbeaaaaab, v226
	v_fma_f32 v225, v225, -2.0, 1.0
	v_fma_f32 v227, v227, v222, v222
	v_bfi_b32 v225, v241, v225, v222
	v_cmp_gt_f32_e32 vcc, 0x3d000000, v224
	s_nop 1
	v_cndmask_b32_e32 v225, v225, v227, vcc
	v_cmp_gt_u32_e32 vcc, 32, v240
	s_nop 1
	v_cndmask_b32_e32 v222, v222, v225, vcc
	v_and_b32_e32 v224, 0x7fffffff, v223
	v_mul_f32_e32 v225, 0x4038aa3b, v224
	v_exp_f32_e32 v225, v225
	v_mul_f32_e32 v226, v223, v223
	v_add_f32_e32 v225, 1.0, v225
	v_rcp_f32_e32 v225, v225
	v_mul_f32_e32 v227, 0xbeaaaaab, v226
	v_fma_f32 v225, v225, -2.0, 1.0
	v_fma_f32 v227, v227, v223, v223
	v_bfi_b32 v225, v241, v225, v223
	v_cmp_gt_f32_e32 vcc, 0x3d000000, v224
	s_nop 1
	v_cndmask_b32_e32 v225, v225, v227, vcc
	v_cmp_gt_u32_e32 vcc, 32, v240
	s_nop 1
	v_cndmask_b32_e32 v223, v223, v225, vcc
	v_cvt_pk_bf16_f32 v224, v220, v221
	v_cvt_pk_bf16_f32 v225, v222, v223
	buffer_store_dwordx2 v[224:225], v238, s[68:71], s74 offen
	s_add_u32 s72, s72, 0x1000
	s_add_u32 s73, s73, 0x800
	s_add_u32 s74, s74, 0x200
	s_add_u32 s75, s75, 0x40
	s_waitcnt vmcnt(33)
	v_lshlrev_b32_e32 v144, 16, v72
	v_and_b32_e32 v145, 0xffff0000, v72
	v_lshlrev_b32_e32 v146, 16, v73
	v_and_b32_e32 v147, 0xffff0000, v73
	v_lshlrev_b32_e32 v148, 16, v74
	v_and_b32_e32 v149, 0xffff0000, v74
	v_lshlrev_b32_e32 v150, 16, v75
	v_and_b32_e32 v151, 0xffff0000, v75
	v_lshlrev_b32_e32 v152, 16, v76
	v_and_b32_e32 v153, 0xffff0000, v76
	v_lshlrev_b32_e32 v154, 16, v77
	v_and_b32_e32 v155, 0xffff0000, v77
	v_lshlrev_b32_e32 v156, 16, v78
	v_and_b32_e32 v157, 0xffff0000, v78
	v_lshlrev_b32_e32 v158, 16, v79
	v_and_b32_e32 v159, 0xffff0000, v79
	v_lshlrev_b32_e32 v160, 16, v84
	v_and_b32_e32 v161, 0xffff0000, v84
	v_lshlrev_b32_e32 v162, 16, v85
	v_and_b32_e32 v163, 0xffff0000, v85
	v_lshlrev_b32_e32 v164, 16, v86
	v_and_b32_e32 v165, 0xffff0000, v86
	v_lshlrev_b32_e32 v166, 16, v87
	v_and_b32_e32 v167, 0xffff0000, v87
	v_lshlrev_b32_e32 v168, 16, v88
	v_and_b32_e32 v169, 0xffff0000, v88
	v_lshlrev_b32_e32 v170, 16, v89
	v_and_b32_e32 v171, 0xffff0000, v89
	v_lshlrev_b32_e32 v172, 16, v90
	v_and_b32_e32 v173, 0xffff0000, v90
	v_lshlrev_b32_e32 v174, 16, v91
	v_and_b32_e32 v175, 0xffff0000, v91
	v_lshlrev_b32_e32 v176, 16, v0
	v_and_b32_e32 v177, 0xffff0000, v0
	v_lshlrev_b32_e32 v178, 16, v1
	v_and_b32_e32 v179, 0xffff0000, v1
	v_lshlrev_b32_e32 v180, 16, v2
	v_and_b32_e32 v181, 0xffff0000, v2
	v_lshlrev_b32_e32 v182, 16, v3
	v_and_b32_e32 v183, 0xffff0000, v3
	v_lshlrev_b32_e32 v184, 16, v4
	v_and_b32_e32 v185, 0xffff0000, v4
	v_lshlrev_b32_e32 v186, 16, v5
	v_and_b32_e32 v187, 0xffff0000, v5
	v_lshlrev_b32_e32 v188, 16, v6
	v_and_b32_e32 v189, 0xffff0000, v6
	v_lshlrev_b32_e32 v190, 16, v7
	v_and_b32_e32 v191, 0xffff0000, v7
	v_lshlrev_b32_e32 v136, 16, v80
	v_and_b32_e32 v137, 0xffff0000, v80
	v_lshlrev_b32_e32 v138, 16, v81
	v_and_b32_e32 v139, 0xffff0000, v81
	v_lshlrev_b32_e32 v140, 16, v92
	v_and_b32_e32 v141, 0xffff0000, v92
	v_lshlrev_b32_e32 v142, 16, v93
	v_and_b32_e32 v143, 0xffff0000, v93
	v_lshlrev_b32_e32 v216, 16, v8
	v_and_b32_e32 v217, 0xffff0000, v8
	v_lshlrev_b32_e32 v218, 16, v9
	v_and_b32_e32 v219, 0xffff0000, v9
	buffer_load_dwordx4 v[72:75], v232, s[64:67], 0 offen offset:4064
	buffer_load_dwordx4 v[76:79], v232, s[64:67], 0 offen offset:4080
	buffer_load_dwordx2 v[80:81], v233, s[64:67], 0 offen
	v_add_u32_e32 v233, 6656, v233
	v_add_u32_e32 v232, 6656, v232
	v_pk_add_f32 v[224:225], v[144:145], v[160:161] neg_lo:[0,1] neg_hi:[0,1]
	v_pk_add_f32 v[226:227], v[176:177], v[160:161] neg_lo:[0,1] neg_hi:[0,1]
	v_pk_fma_f32 v[192:193], v[96:97], v[224:225], v[160:161]
	v_pk_fma_f32 v[192:193], v[112:113], v[226:227], v[192:193]
	v_pk_add_f32 v[224:225], v[146:147], v[162:163] neg_lo:[0,1] neg_hi:[0,1]
	v_pk_add_f32 v[226:227], v[178:179], v[162:163] neg_lo:[0,1] neg_hi:[0,1]
	v_pk_fma_f32 v[194:195], v[98:99], v[224:225], v[162:163]
	v_pk_fma_f32 v[194:195], v[114:115], v[226:227], v[194:195]
	v_pk_add_f32 v[224:225], v[148:149], v[164:165] neg_lo:[0,1] neg_hi:[0,1]
	v_pk_add_f32 v[226:227], v[180:181], v[164:165] neg_lo:[0,1] neg_hi:[0,1]
	v_pk_fma_f32 v[196:197], v[100:101], v[224:225], v[164:165]
	v_pk_fma_f32 v[196:197], v[116:117], v[226:227], v[196:197]
	v_pk_add_f32 v[224:225], v[150:151], v[166:167] neg_lo:[0,1] neg_hi:[0,1]
	v_pk_add_f32 v[226:227], v[182:183], v[166:167] neg_lo:[0,1] neg_hi:[0,1]
	v_pk_fma_f32 v[198:199], v[102:103], v[224:225], v[166:167]
	v_pk_fma_f32 v[198:199], v[118:119], v[226:227], v[198:199]
	v_pk_add_f32 v[224:225], v[152:153], v[168:169] neg_lo:[0,1] neg_hi:[0,1]
	v_pk_add_f32 v[226:227], v[184:185], v[168:169] neg_lo:[0,1] neg_hi:[0,1]
; __device__ __forceinline__ float bflo(unsigned w) { return __uint_as_float(w << 16); }
; __device__ __forceinline__ float bfhi(unsigned w) { return __uint_as_float(w & 0xffff0000u); }
; __device__ __forceinline__ unsigned cvt_pk_bf16(float lo, float hi) { unsigned r; asm volatile("v_cvt_pk_bf16_f32 %0, %1, %2" : "=v"(r) : "v"(lo), "v"(hi)); return r; }
; __device__ __forceinline__ void prep_phase(const Params& p) {
;     ...
;             for (int i = 0; i < 16; ++i) {
;                 const bool hn = (tt0 + i) < SEQ - 1; const u16* zn = zc + (size_t)(i + 1) * 3328;
;                 const Z16 vn = hn ? ldz(zn + 2048 + c) : zz(); const u32x2 ln = hn ? *(const u32x2*)(zn + cl) : (u32x2){0u, 0u};
;                 float v[16]; mix16(vp, vc, vn, mpv, mnv, v);
;                 st16bf(V + (size_t)(t0 + i) * RW + c, v);
;                 const float z4[4] = {bflo(lc.x), bfhi(lc.x), bflo(lc.y), bfhi(lc.y)}, p4[4] = {bflo(lp.x), bfhi(lp.x), bflo(lp.y), bfhi(lp.y)}, n4[4] = {bflo(ln.x), bfhi(ln.x), bflo(ln.y), bfhi(ln.y)};
;                 float o4[4];
; #pragma unroll
;                 for (int j = 0; j < 4; ++j) { const float sft = z4[j] + la[j] * (p4[j] - z4[j]) + lb[j] * (n4[j] - z4[j]); o4[j] = (lane < 32) ? tanhf(sft) : sft; }
;                 u32x2 w; w.x = cvt_pk_bf16(o4[0], o4[1]); w.y = cvt_pk_bf16(o4[2], o4[3]); *(u32x2*)(AL + (size_t)(t0 + i) * 256 + alc) = w;
;                 vp = vc; vc = vn; lp = lc; lc = ln;
	v_pk_fma_f32 v[200:201], v[104:105], v[224:225], v[168:169]
	v_pk_fma_f32 v[200:201], v[120:121], v[226:227], v[200:201]
	v_pk_add_f32 v[224:225], v[154:155], v[170:171] neg_lo:[0,1] neg_hi:[0,1]
	v_pk_add_f32 v[226:227], v[186:187], v[170:171] neg_lo:[0,1] neg_hi:[0,1]
	v_pk_fma_f32 v[202:203], v[106:107], v[224:225], v[170:171]
	v_pk_fma_f32 v[202:203], v[122:123], v[226:227], v[202:203]
	v_pk_add_f32 v[224:225], v[156:157], v[172:173] neg_lo:[0,1] neg_hi:[0,1]
	v_pk_add_f32 v[226:227], v[188:189], v[172:173] neg_lo:[0,1] neg_hi:[0,1]
	v_pk_fma_f32 v[204:205], v[108:109], v[224:225], v[172:173]
	v_pk_fma_f32 v[204:205], v[124:125], v[226:227], v[204:205]
	v_pk_add_f32 v[224:225], v[158:159], v[174:175] neg_lo:[0,1] neg_hi:[0,1]
	v_pk_add_f32 v[226:227], v[190:191], v[174:175] neg_lo:[0,1] neg_hi:[0,1]
	v_pk_fma_f32 v[206:207], v[110:111], v[224:225], v[174:175]
	v_pk_fma_f32 v[206:207], v[126:127], v[226:227], v[206:207]
	v_cvt_pk_bf16_f32 v208, v192, v193
	v_cvt_pk_bf16_f32 v209, v194, v195
	v_cvt_pk_bf16_f32 v210, v196, v197
	v_cvt_pk_bf16_f32 v211, v198, v199
	v_cvt_pk_bf16_f32 v212, v200, v201
	v_cvt_pk_bf16_f32 v213, v202, v203
	v_cvt_pk_bf16_f32 v214, v204, v205
	v_cvt_pk_bf16_f32 v215, v206, v207
	buffer_store_dwordx4 v[208:211], v237, s[68:71], s73 offen offset:0
	buffer_store_dwordx4 v[212:215], v237, s[68:71], s73 offen offset:16
	v_sub_f32_e32 v224, v136, v140
	v_sub_f32_e32 v225, v216, v140
	v_fma_f32 v220, v128, v224, v140
	v_fma_f32 v220, v132, v225, v220
	v_sub_f32_e32 v224, v137, v141
	v_sub_f32_e32 v225, v217, v141
	v_fma_f32 v221, v129, v224, v141
	v_fma_f32 v221, v133, v225, v221
	v_sub_f32_e32 v224, v138, v142
	v_sub_f32_e32 v225, v218, v142
	v_fma_f32 v222, v130, v224, v142
	v_fma_f32 v222, v134, v225, v222
	v_sub_f32_e32 v224, v139, v143
	v_sub_f32_e32 v225, v219, v143
	v_fma_f32 v223, v131, v224, v143
	v_fma_f32 v223, v135, v225, v223
	v_and_b32_e32 v224, 0x7fffffff, v220
	v_mul_f32_e32 v225, 0x4038aa3b, v224
	v_exp_f32_e32 v225, v225
	v_mul_f32_e32 v226, v220, v220
	v_add_f32_e32 v225, 1.0, v225
	v_rcp_f32_e32 v225, v225
	v_mul_f32_e32 v227, 0xbeaaaaab, v226
	v_fma_f32 v225, v225, -2.0, 1.0
	v_fma_f32 v227, v227, v220, v220
	v_bfi_b32 v225, v241, v225, v220
	v_cmp_gt_f32_e32 vcc, 0x3d000000, v224
	s_nop 1
	v_cndmask_b32_e32 v225, v225, v227, vcc
	v_cmp_gt_u32_e32 vcc, 32, v240
	s_nop 1
	v_cndmask_b32_e32 v220, v220, v225, vcc
	v_and_b32_e32 v224, 0x7fffffff, v221
	v_mul_f32_e32 v225, 0x4038aa3b, v224
	v_exp_f32_e32 v225, v225
	v_mul_f32_e32 v226, v221, v221
	v_add_f32_e32 v225, 1.0, v225
	v_rcp_f32_e32 v225, v225
	v_mul_f32_e32 v227, 0xbeaaaaab, v226
	v_fma_f32 v225, v225, -2.0, 1.0
	v_fma_f32 v227, v227, v221, v221
	v_bfi_b32 v225, v241, v225, v221
	v_cmp_gt_f32_e32 vcc, 0x3d000000, v224
	s_nop 1
	v_cndmask_b32_e32 v225, v225, v227, vcc
	v_cmp_gt_u32_e32 vcc, 32, v240
	s_nop 1
	v_cndmask_b32_e32 v221, v221, v225, vcc
	v_and_b32_e32 v224, 0x7fffffff, v222
	v_mul_f32_e32 v225, 0x4038aa3b, v224
	v_exp_f32_e32 v225, v225
	v_mul_f32_e32 v226, v222, v222
	v_add_f32_e32 v225, 1.0, v225
	v_rcp_f32_e32 v225, v225
	v_mul_f32_e32 v227, 0xbeaaaaab, v226
	v_fma_f32 v225, v225, -2.0, 1.0
	v_fma_f32 v227, v227, v222, v222
	v_bfi_b32 v225, v241, v225, v222
	v_cmp_gt_f32_e32 vcc, 0x3d000000, v224
	s_nop 1
	v_cndmask_b32_e32 v225, v225, v227, vcc
	v_cmp_gt_u32_e32 vcc, 32, v240
	s_nop 1
	v_cndmask_b32_e32 v222, v222, v225, vcc
	v_and_b32_e32 v224, 0x7fffffff, v223
	v_mul_f32_e32 v225, 0x4038aa3b, v224
	v_exp_f32_e32 v225, v225
	v_mul_f32_e32 v226, v223, v223
	v_add_f32_e32 v225, 1.0, v225
	v_rcp_f32_e32 v225, v225
	v_mul_f32_e32 v227, 0xbeaaaaab, v226
	v_fma_f32 v225, v225, -2.0, 1.0
	v_fma_f32 v227, v227, v223, v223
	v_bfi_b32 v225, v241, v225, v223
	v_cmp_gt_f32_e32 vcc, 0x3d000000, v224
	s_nop 1
	v_cndmask_b32_e32 v225, v225, v227, vcc
	v_cmp_gt_u32_e32 vcc, 32, v240
	s_nop 1
	v_cndmask_b32_e32 v223, v223, v225, vcc
	v_cvt_pk_bf16_f32 v224, v220, v221
	v_cvt_pk_bf16_f32 v225, v222, v223
	buffer_store_dwordx2 v[224:225], v238, s[68:71], s74 offen
	s_add_u32 s72, s72, 0x1000
	s_add_u32 s73, s73, 0x800
	s_add_u32 s74, s74, 0x200
	s_add_u32 s75, s75, 0x40
	s_waitcnt vmcnt(33)
	v_lshlrev_b32_e32 v144, 16, v84
	v_and_b32_e32 v145, 0xffff0000, v84
	v_lshlrev_b32_e32 v146, 16, v85
	v_and_b32_e32 v147, 0xffff0000, v85
	v_lshlrev_b32_e32 v148, 16, v86
	v_and_b32_e32 v149, 0xffff0000, v86
	v_lshlrev_b32_e32 v150, 16, v87
	v_and_b32_e32 v151, 0xffff0000, v87
	v_lshlrev_b32_e32 v152, 16, v88
	v_and_b32_e32 v153, 0xffff0000, v88
	v_lshlrev_b32_e32 v154, 16, v89
	v_and_b32_e32 v155, 0xffff0000, v89
	v_lshlrev_b32_e32 v156, 16, v90
	v_and_b32_e32 v157, 0xffff0000, v90
	v_lshlrev_b32_e32 v158, 16, v91
	v_and_b32_e32 v159, 0xffff0000, v91
	v_lshlrev_b32_e32 v160, 16, v0
	v_and_b32_e32 v161, 0xffff0000, v0
	v_lshlrev_b32_e32 v162, 16, v1
	v_and_b32_e32 v163, 0xffff0000, v1
	v_lshlrev_b32_e32 v164, 16, v2
	v_and_b32_e32 v165, 0xffff0000, v2
	v_lshlrev_b32_e32 v166, 16, v3
	v_and_b32_e32 v167, 0xffff0000, v3
	v_lshlrev_b32_e32 v168, 16, v4
	v_and_b32_e32 v169, 0xffff0000, v4
	v_lshlrev_b32_e32 v170, 16, v5
	v_and_b32_e32 v171, 0xffff0000, v5
	v_lshlrev_b32_e32 v172, 16, v6
	v_and_b32_e32 v173, 0xffff0000, v6
	v_lshlrev_b32_e32 v174, 16, v7
	v_and_b32_e32 v175, 0xffff0000, v7
	v_lshlrev_b32_e32 v176, 16, v12
	v_and_b32_e32 v177, 0xffff0000, v12
	v_lshlrev_b32_e32 v178, 16, v13
	v_and_b32_e32 v179, 0xffff0000, v13
	v_lshlrev_b32_e32 v180, 16, v14
	v_and_b32_e32 v181, 0xffff0000, v14
	v_lshlrev_b32_e32 v182, 16, v15
	v_and_b32_e32 v183, 0xffff0000, v15
	v_lshlrev_b32_e32 v184, 16, v16
	v_and_b32_e32 v185, 0xffff0000, v16
	v_lshlrev_b32_e32 v186, 16, v17
; __device__ __forceinline__ float bflo(unsigned w) { return __uint_as_float(w << 16); }
; __device__ __forceinline__ float bfhi(unsigned w) { return __uint_as_float(w & 0xffff0000u); }
; __device__ __forceinline__ unsigned cvt_pk_bf16(float lo, float hi) { unsigned r; asm volatile("v_cvt_pk_bf16_f32 %0, %1, %2" : "=v"(r) : "v"(lo), "v"(hi)); return r; }
; __device__ __forceinline__ void prep_phase(const Params& p) {
;     ...
;             for (int i = 0; i < 16; ++i) {
;                 const bool hn = (tt0 + i) < SEQ - 1; const u16* zn = zc + (size_t)(i + 1) * 3328;
;                 const Z16 vn = hn ? ldz(zn + 2048 + c) : zz(); const u32x2 ln = hn ? *(const u32x2*)(zn + cl) : (u32x2){0u, 0u};
;                 float v[16]; mix16(vp, vc, vn, mpv, mnv, v);
;                 st16bf(V + (size_t)(t0 + i) * RW + c, v);
;                 const float z4[4] = {bflo(lc.x), bfhi(lc.x), bflo(lc.y), bfhi(lc.y)}, p4[4] = {bflo(lp.x), bfhi(lp.x), bflo(lp.y), bfhi(lp.y)}, n4[4] = {bflo(ln.x), bfhi(ln.x), bflo(ln.y), bfhi(ln.y)};
;                 float o4[4];
; #pragma unroll
;                 for (int j = 0; j < 4; ++j) { const float sft = z4[j] + la[j] * (p4[j] - z4[j]) + lb[j] * (n4[j] - z4[j]); o4[j] = (lane < 32) ? tanhf(sft) : sft; }
;                 u32x2 w; w.x = cvt_pk_bf16(o4[0], o4[1]); w.y = cvt_pk_bf16(o4[2], o4[3]); *(u32x2*)(AL + (size_t)(t0 + i) * 256 + alc) = w;
;                 vp = vc; vc = vn; lp = lc; lc = ln;
	v_and_b32_e32 v187, 0xffff0000, v17
	v_lshlrev_b32_e32 v188, 16, v18
	v_and_b32_e32 v189, 0xffff0000, v18
	v_lshlrev_b32_e32 v190, 16, v19
	v_and_b32_e32 v191, 0xffff0000, v19
	v_lshlrev_b32_e32 v136, 16, v92
	v_and_b32_e32 v137, 0xffff0000, v92
	v_lshlrev_b32_e32 v138, 16, v93
	v_and_b32_e32 v139, 0xffff0000, v93
	v_lshlrev_b32_e32 v140, 16, v8
	v_and_b32_e32 v141, 0xffff0000, v8
	v_lshlrev_b32_e32 v142, 16, v9
	v_and_b32_e32 v143, 0xffff0000, v9
	v_lshlrev_b32_e32 v216, 16, v20
	v_and_b32_e32 v217, 0xffff0000, v20
	v_lshlrev_b32_e32 v218, 16, v21
	v_and_b32_e32 v219, 0xffff0000, v21
	buffer_load_dwordx4 v[84:87], v232, s[64:67], 0 offen offset:4064
	buffer_load_dwordx4 v[88:91], v232, s[64:67], 0 offen offset:4080
	buffer_load_dwordx2 v[92:93], v233, s[64:67], 0 offen
	v_add_u32_e32 v233, 6656, v233
	v_add_u32_e32 v232, 6656, v232
	v_pk_add_f32 v[224:225], v[144:145], v[160:161] neg_lo:[0,1] neg_hi:[0,1]
	v_pk_add_f32 v[226:227], v[176:177], v[160:161] neg_lo:[0,1] neg_hi:[0,1]
	v_pk_fma_f32 v[192:193], v[96:97], v[224:225], v[160:161]
	v_pk_fma_f32 v[192:193], v[112:113], v[226:227], v[192:193]
	v_pk_add_f32 v[224:225], v[146:147], v[162:163] neg_lo:[0,1] neg_hi:[0,1]
	v_pk_add_f32 v[226:227], v[178:179], v[162:163] neg_lo:[0,1] neg_hi:[0,1]
	v_pk_fma_f32 v[194:195], v[98:99], v[224:225], v[162:163]
	v_pk_fma_f32 v[194:195], v[114:115], v[226:227], v[194:195]
	v_pk_add_f32 v[224:225], v[148:149], v[164:165] neg_lo:[0,1] neg_hi:[0,1]
	v_pk_add_f32 v[226:227], v[180:181], v[164:165] neg_lo:[0,1] neg_hi:[0,1]
	v_pk_fma_f32 v[196:197], v[100:101], v[224:225], v[164:165]
	v_pk_fma_f32 v[196:197], v[116:117], v[226:227], v[196:197]
	v_pk_add_f32 v[224:225], v[150:151], v[166:167] neg_lo:[0,1] neg_hi:[0,1]
	v_pk_add_f32 v[226:227], v[182:183], v[166:167] neg_lo:[0,1] neg_hi:[0,1]
	v_pk_fma_f32 v[198:199], v[102:103], v[224:225], v[166:167]
	v_pk_fma_f32 v[198:199], v[118:119], v[226:227], v[198:199]
	v_pk_add_f32 v[224:225], v[152:153], v[168:169] neg_lo:[0,1] neg_hi:[0,1]
	v_pk_add_f32 v[226:227], v[184:185], v[168:169] neg_lo:[0,1] neg_hi:[0,1]
	v_pk_fma_f32 v[200:201], v[104:105], v[224:225], v[168:169]
	v_pk_fma_f32 v[200:201], v[120:121], v[226:227], v[200:201]
	v_pk_add_f32 v[224:225], v[154:155], v[170:171] neg_lo:[0,1] neg_hi:[0,1]
	v_pk_add_f32 v[226:227], v[186:187], v[170:171] neg_lo:[0,1] neg_hi:[0,1]
	v_pk_fma_f32 v[202:203], v[106:107], v[224:225], v[170:171]
	v_pk_fma_f32 v[202:203], v[122:123], v[226:227], v[202:203]
	v_pk_add_f32 v[224:225], v[156:157], v[172:173] neg_lo:[0,1] neg_hi:[0,1]
	v_pk_add_f32 v[226:227], v[188:189], v[172:173] neg_lo:[0,1] neg_hi:[0,1]
	v_pk_fma_f32 v[204:205], v[108:109], v[224:225], v[172:173]
	v_pk_fma_f32 v[204:205], v[124:125], v[226:227], v[204:205]
	v_pk_add_f32 v[224:225], v[158:159], v[174:175] neg_lo:[0,1] neg_hi:[0,1]
	v_pk_add_f32 v[226:227], v[190:191], v[174:175] neg_lo:[0,1] neg_hi:[0,1]
	v_pk_fma_f32 v[206:207], v[110:111], v[224:225], v[174:175]
	v_pk_fma_f32 v[206:207], v[126:127], v[226:227], v[206:207]
	v_cvt_pk_bf16_f32 v208, v192, v193
	v_cvt_pk_bf16_f32 v209, v194, v195
	v_cvt_pk_bf16_f32 v210, v196, v197
	v_cvt_pk_bf16_f32 v211, v198, v199
	v_cvt_pk_bf16_f32 v212, v200, v201
	v_cvt_pk_bf16_f32 v213, v202, v203
	v_cvt_pk_bf16_f32 v214, v204, v205
	v_cvt_pk_bf16_f32 v215, v206, v207
	buffer_store_dwordx4 v[208:211], v237, s[68:71], s73 offen offset:0
	buffer_store_dwordx4 v[212:215], v237, s[68:71], s73 offen offset:16
	v_sub_f32_e32 v224, v136, v140
	v_sub_f32_e32 v225, v216, v140
	v_fma_f32 v220, v128, v224, v140
	v_fma_f32 v220, v132, v225, v220
	v_sub_f32_e32 v224, v137, v141
	v_sub_f32_e32 v225, v217, v141
	v_fma_f32 v221, v129, v224, v141
	v_fma_f32 v221, v133, v225, v221
	v_sub_f32_e32 v224, v138, v142
	v_sub_f32_e32 v225, v218, v142
	v_fma_f32 v222, v130, v224, v142
	v_fma_f32 v222, v134, v225, v222
	v_sub_f32_e32 v224, v139, v143
	v_sub_f32_e32 v225, v219, v143
	v_fma_f32 v223, v131, v224, v143
	v_fma_f32 v223, v135, v225, v223
	v_and_b32_e32 v224, 0x7fffffff, v220
	v_mul_f32_e32 v225, 0x4038aa3b, v224
	v_exp_f32_e32 v225, v225
	v_mul_f32_e32 v226, v220, v220
	v_add_f32_e32 v225, 1.0, v225
	v_rcp_f32_e32 v225, v225
	v_mul_f32_e32 v227, 0xbeaaaaab, v226
	v_fma_f32 v225, v225, -2.0, 1.0
	v_fma_f32 v227, v227, v220, v220
	v_bfi_b32 v225, v241, v225, v220
	v_cmp_gt_f32_e32 vcc, 0x3d000000, v224
	s_nop 1
	v_cndmask_b32_e32 v225, v225, v227, vcc
	v_cmp_gt_u32_e32 vcc, 32, v240
	s_nop 1
	v_cndmask_b32_e32 v220, v220, v225, vcc
	v_and_b32_e32 v224, 0x7fffffff, v221
	v_mul_f32_e32 v225, 0x4038aa3b, v224
	v_exp_f32_e32 v225, v225
	v_mul_f32_e32 v226, v221, v221
	v_add_f32_e32 v225, 1.0, v225
	v_rcp_f32_e32 v225, v225
	v_mul_f32_e32 v227, 0xbeaaaaab, v226
	v_fma_f32 v225, v225, -2.0, 1.0
	v_fma_f32 v227, v227, v221, v221
	v_bfi_b32 v225, v241, v225, v221
	v_cmp_gt_f32_e32 vcc, 0x3d000000, v224
	s_nop 1
	v_cndmask_b32_e32 v225, v225, v227, vcc
	v_cmp_gt_u32_e32 vcc, 32, v240
	s_nop 1
	v_cndmask_b32_e32 v221, v221, v225, vcc
	v_and_b32_e32 v224, 0x7fffffff, v222
	v_mul_f32_e32 v225, 0x4038aa3b, v224
	v_exp_f32_e32 v225, v225
	v_mul_f32_e32 v226, v222, v222
	v_add_f32_e32 v225, 1.0, v225
	v_rcp_f32_e32 v225, v225
	v_mul_f32_e32 v227, 0xbeaaaaab, v226
	v_fma_f32 v225, v225, -2.0, 1.0
	v_fma_f32 v227, v227, v222, v222
	v_bfi_b32 v225, v241, v225, v222
	v_cmp_gt_f32_e32 vcc, 0x3d000000, v224
	s_nop 1
	v_cndmask_b32_e32 v225, v225, v227, vcc
	v_cmp_gt_u32_e32 vcc, 32, v240
	s_nop 1
	v_cndmask_b32_e32 v222, v222, v225, vcc
	v_and_b32_e32 v224, 0x7fffffff, v223
	v_mul_f32_e32 v225, 0x4038aa3b, v224
	v_exp_f32_e32 v225, v225
	v_mul_f32_e32 v226, v223, v223
	v_add_f32_e32 v225, 1.0, v225
	v_rcp_f32_e32 v225, v225
	v_mul_f32_e32 v227, 0xbeaaaaab, v226
	v_fma_f32 v225, v225, -2.0, 1.0
	v_fma_f32 v227, v227, v223, v223
	v_bfi_b32 v225, v241, v225, v223
	v_cmp_gt_f32_e32 vcc, 0x3d000000, v224
	s_nop 1
	v_cndmask_b32_e32 v225, v225, v227, vcc
	v_cmp_gt_u32_e32 vcc, 32, v240
	s_nop 1
	v_cndmask_b32_e32 v223, v223, v225, vcc
	v_cvt_pk_bf16_f32 v224, v220, v221
	v_cvt_pk_bf16_f32 v225, v222, v223
	buffer_store_dwordx2 v[224:225], v238, s[68:71], s74 offen
	s_add_u32 s72, s72, 0x1000
	s_add_u32 s73, s73, 0x800
	s_add_u32 s74, s74, 0x200
	s_add_u32 s75, s75, 0x40
	s_waitcnt vmcnt(33)
; __device__ __forceinline__ float bflo(unsigned w) { return __uint_as_float(w << 16); }
; __device__ __forceinline__ float bfhi(unsigned w) { return __uint_as_float(w & 0xffff0000u); }
; __device__ __forceinline__ unsigned cvt_pk_bf16(float lo, float hi) { unsigned r; asm volatile("v_cvt_pk_bf16_f32 %0, %1, %2" : "=v"(r) : "v"(lo), "v"(hi)); return r; }
; __device__ __forceinline__ void prep_phase(const Params& p) {
;     ...
;             for (int i = 0; i < 16; ++i) {
;                 const bool hn = (tt0 + i) < SEQ - 1; const u16* zn = zc + (size_t)(i + 1) * 3328;
;                 const Z16 vn = hn ? ldz(zn + 2048 + c) : zz(); const u32x2 ln = hn ? *(const u32x2*)(zn + cl) : (u32x2){0u, 0u};
;                 float v[16]; mix16(vp, vc, vn, mpv, mnv, v);
;                 st16bf(V + (size_t)(t0 + i) * RW + c, v);
;                 const float z4[4] = {bflo(lc.x), bfhi(lc.x), bflo(lc.y), bfhi(lc.y)}, p4[4] = {bflo(lp.x), bfhi(lp.x), bflo(lp.y), bfhi(lp.y)}, n4[4] = {bflo(ln.x), bfhi(ln.x), bflo(ln.y), bfhi(ln.y)};
;                 float o4[4];
; #pragma unroll
;                 for (int j = 0; j < 4; ++j) { const float sft = z4[j] + la[j] * (p4[j] - z4[j]) + lb[j] * (n4[j] - z4[j]); o4[j] = (lane < 32) ? tanhf(sft) : sft; }
;                 u32x2 w; w.x = cvt_pk_bf16(o4[0], o4[1]); w.y = cvt_pk_bf16(o4[2], o4[3]); *(u32x2*)(AL + (size_t)(t0 + i) * 256 + alc) = w;
	v_lshlrev_b32_e32 v144, 16, v0
	v_and_b32_e32 v145, 0xffff0000, v0
	v_lshlrev_b32_e32 v146, 16, v1
	v_and_b32_e32 v147, 0xffff0000, v1
	v_lshlrev_b32_e32 v148, 16, v2
	v_and_b32_e32 v149, 0xffff0000, v2
	v_lshlrev_b32_e32 v150, 16, v3
	v_and_b32_e32 v151, 0xffff0000, v3
	v_lshlrev_b32_e32 v152, 16, v4
	v_and_b32_e32 v153, 0xffff0000, v4
	v_lshlrev_b32_e32 v154, 16, v5
	v_and_b32_e32 v155, 0xffff0000, v5
	v_lshlrev_b32_e32 v156, 16, v6
	v_and_b32_e32 v157, 0xffff0000, v6
	v_lshlrev_b32_e32 v158, 16, v7
	v_and_b32_e32 v159, 0xffff0000, v7
	v_lshlrev_b32_e32 v160, 16, v12
	v_and_b32_e32 v161, 0xffff0000, v12
	v_lshlrev_b32_e32 v162, 16, v13
	v_and_b32_e32 v163, 0xffff0000, v13
	v_lshlrev_b32_e32 v164, 16, v14
	v_and_b32_e32 v165, 0xffff0000, v14
	v_lshlrev_b32_e32 v166, 16, v15
	v_and_b32_e32 v167, 0xffff0000, v15
	v_lshlrev_b32_e32 v168, 16, v16
	v_and_b32_e32 v169, 0xffff0000, v16
	v_lshlrev_b32_e32 v170, 16, v17
	v_and_b32_e32 v171, 0xffff0000, v17
	v_lshlrev_b32_e32 v172, 16, v18
	v_and_b32_e32 v173, 0xffff0000, v18
	v_lshlrev_b32_e32 v174, 16, v19
	v_and_b32_e32 v175, 0xffff0000, v19
	v_lshlrev_b32_e32 v176, 16, v24
	v_and_b32_e32 v177, 0xffff0000, v24
	v_lshlrev_b32_e32 v178, 16, v25
	v_and_b32_e32 v179, 0xffff0000, v25
	v_lshlrev_b32_e32 v180, 16, v26
	v_and_b32_e32 v181, 0xffff0000, v26
	v_lshlrev_b32_e32 v182, 16, v27
	v_and_b32_e32 v183, 0xffff0000, v27
	v_lshlrev_b32_e32 v184, 16, v28
	v_and_b32_e32 v185, 0xffff0000, v28
	v_lshlrev_b32_e32 v186, 16, v29
	v_and_b32_e32 v187, 0xffff0000, v29
	v_lshlrev_b32_e32 v188, 16, v30
	v_and_b32_e32 v189, 0xffff0000, v30
	v_lshlrev_b32_e32 v190, 16, v31
	v_and_b32_e32 v191, 0xffff0000, v31
	v_lshlrev_b32_e32 v136, 16, v8
	v_and_b32_e32 v137, 0xffff0000, v8
	v_lshlrev_b32_e32 v138, 16, v9
	v_and_b32_e32 v139, 0xffff0000, v9
	v_lshlrev_b32_e32 v140, 16, v20
	v_and_b32_e32 v141, 0xffff0000, v20
	v_lshlrev_b32_e32 v142, 16, v21
	v_and_b32_e32 v143, 0xffff0000, v21
	v_lshlrev_b32_e32 v216, 16, v32
	v_and_b32_e32 v217, 0xffff0000, v32
	v_lshlrev_b32_e32 v218, 16, v33
	v_and_b32_e32 v219, 0xffff0000, v33
	buffer_load_dwordx4 v[0:3], v232, s[64:67], 0 offen offset:4064
	buffer_load_dwordx4 v[4:7], v232, s[64:67], 0 offen offset:4080
	buffer_load_dwordx2 v[8:9], v233, s[64:67], 0 offen
	v_add_u32_e32 v233, 6656, v233
	v_add_u32_e32 v232, 6656, v232
	v_pk_add_f32 v[224:225], v[144:145], v[160:161] neg_lo:[0,1] neg_hi:[0,1]
	v_pk_add_f32 v[226:227], v[176:177], v[160:161] neg_lo:[0,1] neg_hi:[0,1]
	v_pk_fma_f32 v[192:193], v[96:97], v[224:225], v[160:161]
	v_pk_fma_f32 v[192:193], v[112:113], v[226:227], v[192:193]
	v_pk_add_f32 v[224:225], v[146:147], v[162:163] neg_lo:[0,1] neg_hi:[0,1]
	v_pk_add_f32 v[226:227], v[178:179], v[162:163] neg_lo:[0,1] neg_hi:[0,1]
	v_pk_fma_f32 v[194:195], v[98:99], v[224:225], v[162:163]
	v_pk_fma_f32 v[194:195], v[114:115], v[226:227], v[194:195]
	v_pk_add_f32 v[224:225], v[148:149], v[164:165] neg_lo:[0,1] neg_hi:[0,1]
	v_pk_add_f32 v[226:227], v[180:181], v[164:165] neg_lo:[0,1] neg_hi:[0,1]
	v_pk_fma_f32 v[196:197], v[100:101], v[224:225], v[164:165]
	v_pk_fma_f32 v[196:197], v[116:117], v[226:227], v[196:197]
	v_pk_add_f32 v[224:225], v[150:151], v[166:167] neg_lo:[0,1] neg_hi:[0,1]
	v_pk_add_f32 v[226:227], v[182:183], v[166:167] neg_lo:[0,1] neg_hi:[0,1]
	v_pk_fma_f32 v[198:199], v[102:103], v[224:225], v[166:167]
	v_pk_fma_f32 v[198:199], v[118:119], v[226:227], v[198:199]
	v_pk_add_f32 v[224:225], v[152:153], v[168:169] neg_lo:[0,1] neg_hi:[0,1]
	v_pk_add_f32 v[226:227], v[184:185], v[168:169] neg_lo:[0,1] neg_hi:[0,1]
	v_pk_fma_f32 v[200:201], v[104:105], v[224:225], v[168:169]
	v_pk_fma_f32 v[200:201], v[120:121], v[226:227], v[200:201]
	v_pk_add_f32 v[224:225], v[154:155], v[170:171] neg_lo:[0,1] neg_hi:[0,1]
	v_pk_add_f32 v[226:227], v[186:187], v[170:171] neg_lo:[0,1] neg_hi:[0,1]
	v_pk_fma_f32 v[202:203], v[106:107], v[224:225], v[170:171]
	v_pk_fma_f32 v[202:203], v[122:123], v[226:227], v[202:203]
	v_pk_add_f32 v[224:225], v[156:157], v[172:173] neg_lo:[0,1] neg_hi:[0,1]
	v_pk_add_f32 v[226:227], v[188:189], v[172:173] neg_lo:[0,1] neg_hi:[0,1]
	v_pk_fma_f32 v[204:205], v[108:109], v[224:225], v[172:173]
	v_pk_fma_f32 v[204:205], v[124:125], v[226:227], v[204:205]
	v_pk_add_f32 v[224:225], v[158:159], v[174:175] neg_lo:[0,1] neg_hi:[0,1]
	v_pk_add_f32 v[226:227], v[190:191], v[174:175] neg_lo:[0,1] neg_hi:[0,1]
	v_pk_fma_f32 v[206:207], v[110:111], v[224:225], v[174:175]
	v_pk_fma_f32 v[206:207], v[126:127], v[226:227], v[206:207]
	v_cvt_pk_bf16_f32 v208, v192, v193
	v_cvt_pk_bf16_f32 v209, v194, v195
	v_cvt_pk_bf16_f32 v210, v196, v197
	v_cvt_pk_bf16_f32 v211, v198, v199
	v_cvt_pk_bf16_f32 v212, v200, v201
	v_cvt_pk_bf16_f32 v213, v202, v203
	v_cvt_pk_bf16_f32 v214, v204, v205
	v_cvt_pk_bf16_f32 v215, v206, v207
	buffer_store_dwordx4 v[208:211], v237, s[68:71], s73 offen offset:0
	buffer_store_dwordx4 v[212:215], v237, s[68:71], s73 offen offset:16
	v_sub_f32_e32 v224, v136, v140
	v_sub_f32_e32 v225, v216, v140
	v_fma_f32 v220, v128, v224, v140
	v_fma_f32 v220, v132, v225, v220
	v_sub_f32_e32 v224, v137, v141
	v_sub_f32_e32 v225, v217, v141
	v_fma_f32 v221, v129, v224, v141
	v_fma_f32 v221, v133, v225, v221
	v_sub_f32_e32 v224, v138, v142
	v_sub_f32_e32 v225, v218, v142
	v_fma_f32 v222, v130, v224, v142
	v_fma_f32 v222, v134, v225, v222
	v_sub_f32_e32 v224, v139, v143
	v_sub_f32_e32 v225, v219, v143
	v_fma_f32 v223, v131, v224, v143
	v_fma_f32 v223, v135, v225, v223
	v_and_b32_e32 v224, 0x7fffffff, v220
	v_mul_f32_e32 v225, 0x4038aa3b, v224
	v_exp_f32_e32 v225, v225
	v_mul_f32_e32 v226, v220, v220
	v_add_f32_e32 v225, 1.0, v225
	v_rcp_f32_e32 v225, v225
; __device__ __forceinline__ float bflo(unsigned w) { return __uint_as_float(w << 16); }
; __device__ __forceinline__ float bfhi(unsigned w) { return __uint_as_float(w & 0xffff0000u); }
; __device__ __forceinline__ unsigned cvt_pk_bf16(float lo, float hi) { unsigned r; asm volatile("v_cvt_pk_bf16_f32 %0, %1, %2" : "=v"(r) : "v"(lo), "v"(hi)); return r; }
; __device__ __forceinline__ void prep_phase(const Params& p) {
;     ...
;             for (int i = 0; i < 16; ++i) {
;                 const bool hn = (tt0 + i) < SEQ - 1; const u16* zn = zc + (size_t)(i + 1) * 3328;
;                 const Z16 vn = hn ? ldz(zn + 2048 + c) : zz(); const u32x2 ln = hn ? *(const u32x2*)(zn + cl) : (u32x2){0u, 0u};
;                 float v[16]; mix16(vp, vc, vn, mpv, mnv, v);
;                 st16bf(V + (size_t)(t0 + i) * RW + c, v);
;                 const float z4[4] = {bflo(lc.x), bfhi(lc.x), bflo(lc.y), bfhi(lc.y)}, p4[4] = {bflo(lp.x), bfhi(lp.x), bflo(lp.y), bfhi(lp.y)}, n4[4] = {bflo(ln.x), bfhi(ln.x), bflo(ln.y), bfhi(ln.y)};
;                 float o4[4];
; #pragma unroll
;                 for (int j = 0; j < 4; ++j) { const float sft = z4[j] + la[j] * (p4[j] - z4[j]) + lb[j] * (n4[j] - z4[j]); o4[j] = (lane < 32) ? tanhf(sft) : sft; }
;                 u32x2 w; w.x = cvt_pk_bf16(o4[0], o4[1]); w.y = cvt_pk_bf16(o4[2], o4[3]); *(u32x2*)(AL + (size_t)(t0 + i) * 256 + alc) = w;
;                 vp = vc; vc = vn; lp = lc; lc = ln;
	v_mul_f32_e32 v227, 0xbeaaaaab, v226
	v_fma_f32 v225, v225, -2.0, 1.0
	v_fma_f32 v227, v227, v220, v220
	v_bfi_b32 v225, v241, v225, v220
	v_cmp_gt_f32_e32 vcc, 0x3d000000, v224
	s_nop 1
	v_cndmask_b32_e32 v225, v225, v227, vcc
	v_cmp_gt_u32_e32 vcc, 32, v240
	s_nop 1
	v_cndmask_b32_e32 v220, v220, v225, vcc
	v_and_b32_e32 v224, 0x7fffffff, v221
	v_mul_f32_e32 v225, 0x4038aa3b, v224
	v_exp_f32_e32 v225, v225
	v_mul_f32_e32 v226, v221, v221
	v_add_f32_e32 v225, 1.0, v225
	v_rcp_f32_e32 v225, v225
	v_mul_f32_e32 v227, 0xbeaaaaab, v226
	v_fma_f32 v225, v225, -2.0, 1.0
	v_fma_f32 v227, v227, v221, v221
	v_bfi_b32 v225, v241, v225, v221
	v_cmp_gt_f32_e32 vcc, 0x3d000000, v224
	s_nop 1
	v_cndmask_b32_e32 v225, v225, v227, vcc
	v_cmp_gt_u32_e32 vcc, 32, v240
	s_nop 1
	v_cndmask_b32_e32 v221, v221, v225, vcc
	v_and_b32_e32 v224, 0x7fffffff, v222
	v_mul_f32_e32 v225, 0x4038aa3b, v224
	v_exp_f32_e32 v225, v225
	v_mul_f32_e32 v226, v222, v222
	v_add_f32_e32 v225, 1.0, v225
	v_rcp_f32_e32 v225, v225
	v_mul_f32_e32 v227, 0xbeaaaaab, v226
	v_fma_f32 v225, v225, -2.0, 1.0
	v_fma_f32 v227, v227, v222, v222
	v_bfi_b32 v225, v241, v225, v222
	v_cmp_gt_f32_e32 vcc, 0x3d000000, v224
	s_nop 1
	v_cndmask_b32_e32 v225, v225, v227, vcc
	v_cmp_gt_u32_e32 vcc, 32, v240
	s_nop 1
	v_cndmask_b32_e32 v222, v222, v225, vcc
	v_and_b32_e32 v224, 0x7fffffff, v223
	v_mul_f32_e32 v225, 0x4038aa3b, v224
	v_exp_f32_e32 v225, v225
	v_mul_f32_e32 v226, v223, v223
	v_add_f32_e32 v225, 1.0, v225
	v_rcp_f32_e32 v225, v225
	v_mul_f32_e32 v227, 0xbeaaaaab, v226
	v_fma_f32 v225, v225, -2.0, 1.0
	v_fma_f32 v227, v227, v223, v223
	v_bfi_b32 v225, v241, v225, v223
	v_cmp_gt_f32_e32 vcc, 0x3d000000, v224
	s_nop 1
	v_cndmask_b32_e32 v225, v225, v227, vcc
	v_cmp_gt_u32_e32 vcc, 32, v240
	s_nop 1
	v_cndmask_b32_e32 v223, v223, v225, vcc
	v_cvt_pk_bf16_f32 v224, v220, v221
	v_cvt_pk_bf16_f32 v225, v222, v223
	buffer_store_dwordx2 v[224:225], v238, s[68:71], s74 offen
	s_add_u32 s72, s72, 0x1000
	s_add_u32 s73, s73, 0x800
	s_add_u32 s74, s74, 0x200
	s_add_u32 s75, s75, 0x40
	s_waitcnt vmcnt(33)
	v_lshlrev_b32_e32 v144, 16, v12
	v_and_b32_e32 v145, 0xffff0000, v12
	v_lshlrev_b32_e32 v146, 16, v13
	v_and_b32_e32 v147, 0xffff0000, v13
	v_lshlrev_b32_e32 v148, 16, v14
	v_and_b32_e32 v149, 0xffff0000, v14
	v_lshlrev_b32_e32 v150, 16, v15
	v_and_b32_e32 v151, 0xffff0000, v15
	v_lshlrev_b32_e32 v152, 16, v16
	v_and_b32_e32 v153, 0xffff0000, v16
	v_lshlrev_b32_e32 v154, 16, v17
	v_and_b32_e32 v155, 0xffff0000, v17
	v_lshlrev_b32_e32 v156, 16, v18
	v_and_b32_e32 v157, 0xffff0000, v18
	v_lshlrev_b32_e32 v158, 16, v19
	v_and_b32_e32 v159, 0xffff0000, v19
	v_lshlrev_b32_e32 v160, 16, v24
	v_and_b32_e32 v161, 0xffff0000, v24
	v_lshlrev_b32_e32 v162, 16, v25
	v_and_b32_e32 v163, 0xffff0000, v25
	v_lshlrev_b32_e32 v164, 16, v26
	v_and_b32_e32 v165, 0xffff0000, v26
	v_lshlrev_b32_e32 v166, 16, v27
	v_and_b32_e32 v167, 0xffff0000, v27
	v_lshlrev_b32_e32 v168, 16, v28
	v_and_b32_e32 v169, 0xffff0000, v28
	v_lshlrev_b32_e32 v170, 16, v29
	v_and_b32_e32 v171, 0xffff0000, v29
	v_lshlrev_b32_e32 v172, 16, v30
	v_and_b32_e32 v173, 0xffff0000, v30
	v_lshlrev_b32_e32 v174, 16, v31
	v_and_b32_e32 v175, 0xffff0000, v31
	v_lshlrev_b32_e32 v176, 16, v36
	v_and_b32_e32 v177, 0xffff0000, v36
	v_lshlrev_b32_e32 v178, 16, v37
	v_and_b32_e32 v179, 0xffff0000, v37
	v_lshlrev_b32_e32 v180, 16, v38
	v_and_b32_e32 v181, 0xffff0000, v38
	v_lshlrev_b32_e32 v182, 16, v39
	v_and_b32_e32 v183, 0xffff0000, v39
	v_lshlrev_b32_e32 v184, 16, v40
	v_and_b32_e32 v185, 0xffff0000, v40
	v_lshlrev_b32_e32 v186, 16, v41
	v_and_b32_e32 v187, 0xffff0000, v41
	v_lshlrev_b32_e32 v188, 16, v42
	v_and_b32_e32 v189, 0xffff0000, v42
	v_lshlrev_b32_e32 v190, 16, v43
	v_and_b32_e32 v191, 0xffff0000, v43
	v_lshlrev_b32_e32 v136, 16, v20
	v_and_b32_e32 v137, 0xffff0000, v20
	v_lshlrev_b32_e32 v138, 16, v21
	v_and_b32_e32 v139, 0xffff0000, v21
	v_lshlrev_b32_e32 v140, 16, v32
	v_and_b32_e32 v141, 0xffff0000, v32
	v_lshlrev_b32_e32 v142, 16, v33
	v_and_b32_e32 v143, 0xffff0000, v33
	v_lshlrev_b32_e32 v216, 16, v44
	v_and_b32_e32 v217, 0xffff0000, v44
	v_lshlrev_b32_e32 v218, 16, v45
	v_and_b32_e32 v219, 0xffff0000, v45
	buffer_load_dwordx4 v[12:15], v232, s[64:67], 0 offen offset:4064
	buffer_load_dwordx4 v[16:19], v232, s[64:67], 0 offen offset:4080
	buffer_load_dwordx2 v[20:21], v233, s[64:67], 0 offen
	v_add_u32_e32 v233, 6656, v233
	v_add_u32_e32 v232, 6656, v232
	v_pk_add_f32 v[224:225], v[144:145], v[160:161] neg_lo:[0,1] neg_hi:[0,1]
	v_pk_add_f32 v[226:227], v[176:177], v[160:161] neg_lo:[0,1] neg_hi:[0,1]
	v_pk_fma_f32 v[192:193], v[96:97], v[224:225], v[160:161]
	v_pk_fma_f32 v[192:193], v[112:113], v[226:227], v[192:193]
	v_pk_add_f32 v[224:225], v[146:147], v[162:163] neg_lo:[0,1] neg_hi:[0,1]
	v_pk_add_f32 v[226:227], v[178:179], v[162:163] neg_lo:[0,1] neg_hi:[0,1]
	v_pk_fma_f32 v[194:195], v[98:99], v[224:225], v[162:163]
	v_pk_fma_f32 v[194:195], v[114:115], v[226:227], v[194:195]
	v_pk_add_f32 v[224:225], v[148:149], v[164:165] neg_lo:[0,1] neg_hi:[0,1]
	v_pk_add_f32 v[226:227], v[180:181], v[164:165] neg_lo:[0,1] neg_hi:[0,1]
	v_pk_fma_f32 v[196:197], v[100:101], v[224:225], v[164:165]
	v_pk_fma_f32 v[196:197], v[116:117], v[226:227], v[196:197]
	v_pk_add_f32 v[224:225], v[150:151], v[166:167] neg_lo:[0,1] neg_hi:[0,1]
	v_pk_add_f32 v[226:227], v[182:183], v[166:167] neg_lo:[0,1] neg_hi:[0,1]
	v_pk_fma_f32 v[198:199], v[102:103], v[224:225], v[166:167]
	v_pk_fma_f32 v[198:199], v[118:119], v[226:227], v[198:199]
	v_pk_add_f32 v[224:225], v[152:153], v[168:169] neg_lo:[0,1] neg_hi:[0,1]
	v_pk_add_f32 v[226:227], v[184:185], v[168:169] neg_lo:[0,1] neg_hi:[0,1]
; __device__ __forceinline__ float bflo(unsigned w) { return __uint_as_float(w << 16); }
; __device__ __forceinline__ float bfhi(unsigned w) { return __uint_as_float(w & 0xffff0000u); }
; __device__ __forceinline__ unsigned cvt_pk_bf16(float lo, float hi) { unsigned r; asm volatile("v_cvt_pk_bf16_f32 %0, %1, %2" : "=v"(r) : "v"(lo), "v"(hi)); return r; }
; __device__ __forceinline__ void prep_phase(const Params& p) {
;     ...
;             for (int i = 0; i < 16; ++i) {
;                 const bool hn = (tt0 + i) < SEQ - 1; const u16* zn = zc + (size_t)(i + 1) * 3328;
;                 const Z16 vn = hn ? ldz(zn + 2048 + c) : zz(); const u32x2 ln = hn ? *(const u32x2*)(zn + cl) : (u32x2){0u, 0u};
;                 float v[16]; mix16(vp, vc, vn, mpv, mnv, v);
;                 st16bf(V + (size_t)(t0 + i) * RW + c, v);
;                 const float z4[4] = {bflo(lc.x), bfhi(lc.x), bflo(lc.y), bfhi(lc.y)}, p4[4] = {bflo(lp.x), bfhi(lp.x), bflo(lp.y), bfhi(lp.y)}, n4[4] = {bflo(ln.x), bfhi(ln.x), bflo(ln.y), bfhi(ln.y)};
;                 float o4[4];
; #pragma unroll
;                 for (int j = 0; j < 4; ++j) { const float sft = z4[j] + la[j] * (p4[j] - z4[j]) + lb[j] * (n4[j] - z4[j]); o4[j] = (lane < 32) ? tanhf(sft) : sft; }
;                 u32x2 w; w.x = cvt_pk_bf16(o4[0], o4[1]); w.y = cvt_pk_bf16(o4[2], o4[3]); *(u32x2*)(AL + (size_t)(t0 + i) * 256 + alc) = w;
;                 vp = vc; vc = vn; lp = lc; lc = ln;
	v_pk_fma_f32 v[200:201], v[104:105], v[224:225], v[168:169]
	v_pk_fma_f32 v[200:201], v[120:121], v[226:227], v[200:201]
	v_pk_add_f32 v[224:225], v[154:155], v[170:171] neg_lo:[0,1] neg_hi:[0,1]
	v_pk_add_f32 v[226:227], v[186:187], v[170:171] neg_lo:[0,1] neg_hi:[0,1]
	v_pk_fma_f32 v[202:203], v[106:107], v[224:225], v[170:171]
	v_pk_fma_f32 v[202:203], v[122:123], v[226:227], v[202:203]
	v_pk_add_f32 v[224:225], v[156:157], v[172:173] neg_lo:[0,1] neg_hi:[0,1]
	v_pk_add_f32 v[226:227], v[188:189], v[172:173] neg_lo:[0,1] neg_hi:[0,1]
	v_pk_fma_f32 v[204:205], v[108:109], v[224:225], v[172:173]
	v_pk_fma_f32 v[204:205], v[124:125], v[226:227], v[204:205]
	v_pk_add_f32 v[224:225], v[158:159], v[174:175] neg_lo:[0,1] neg_hi:[0,1]
	v_pk_add_f32 v[226:227], v[190:191], v[174:175] neg_lo:[0,1] neg_hi:[0,1]
	v_pk_fma_f32 v[206:207], v[110:111], v[224:225], v[174:175]
	v_pk_fma_f32 v[206:207], v[126:127], v[226:227], v[206:207]
	v_cvt_pk_bf16_f32 v208, v192, v193
	v_cvt_pk_bf16_f32 v209, v194, v195
	v_cvt_pk_bf16_f32 v210, v196, v197
	v_cvt_pk_bf16_f32 v211, v198, v199
	v_cvt_pk_bf16_f32 v212, v200, v201
	v_cvt_pk_bf16_f32 v213, v202, v203
	v_cvt_pk_bf16_f32 v214, v204, v205
	v_cvt_pk_bf16_f32 v215, v206, v207
	buffer_store_dwordx4 v[208:211], v237, s[68:71], s73 offen offset:0
	buffer_store_dwordx4 v[212:215], v237, s[68:71], s73 offen offset:16
	v_sub_f32_e32 v224, v136, v140
	v_sub_f32_e32 v225, v216, v140
	v_fma_f32 v220, v128, v224, v140
	v_fma_f32 v220, v132, v225, v220
	v_sub_f32_e32 v224, v137, v141
	v_sub_f32_e32 v225, v217, v141
	v_fma_f32 v221, v129, v224, v141
	v_fma_f32 v221, v133, v225, v221
	v_sub_f32_e32 v224, v138, v142
	v_sub_f32_e32 v225, v218, v142
	v_fma_f32 v222, v130, v224, v142
	v_fma_f32 v222, v134, v225, v222
	v_sub_f32_e32 v224, v139, v143
	v_sub_f32_e32 v225, v219, v143
	v_fma_f32 v223, v131, v224, v143
	v_fma_f32 v223, v135, v225, v223
	v_and_b32_e32 v224, 0x7fffffff, v220
	v_mul_f32_e32 v225, 0x4038aa3b, v224
	v_exp_f32_e32 v225, v225
	v_mul_f32_e32 v226, v220, v220
	v_add_f32_e32 v225, 1.0, v225
	v_rcp_f32_e32 v225, v225
	v_mul_f32_e32 v227, 0xbeaaaaab, v226
	v_fma_f32 v225, v225, -2.0, 1.0
	v_fma_f32 v227, v227, v220, v220
	v_bfi_b32 v225, v241, v225, v220
	v_cmp_gt_f32_e32 vcc, 0x3d000000, v224
	s_nop 1
	v_cndmask_b32_e32 v225, v225, v227, vcc
	v_cmp_gt_u32_e32 vcc, 32, v240
	s_nop 1
	v_cndmask_b32_e32 v220, v220, v225, vcc
	v_and_b32_e32 v224, 0x7fffffff, v221
	v_mul_f32_e32 v225, 0x4038aa3b, v224
	v_exp_f32_e32 v225, v225
	v_mul_f32_e32 v226, v221, v221
	v_add_f32_e32 v225, 1.0, v225
	v_rcp_f32_e32 v225, v225
	v_mul_f32_e32 v227, 0xbeaaaaab, v226
	v_fma_f32 v225, v225, -2.0, 1.0
	v_fma_f32 v227, v227, v221, v221
	v_bfi_b32 v225, v241, v225, v221
	v_cmp_gt_f32_e32 vcc, 0x3d000000, v224
	s_nop 1
	v_cndmask_b32_e32 v225, v225, v227, vcc
	v_cmp_gt_u32_e32 vcc, 32, v240
	s_nop 1
	v_cndmask_b32_e32 v221, v221, v225, vcc
	v_and_b32_e32 v224, 0x7fffffff, v222
	v_mul_f32_e32 v225, 0x4038aa3b, v224
	v_exp_f32_e32 v225, v225
	v_mul_f32_e32 v226, v222, v222
	v_add_f32_e32 v225, 1.0, v225
	v_rcp_f32_e32 v225, v225
	v_mul_f32_e32 v227, 0xbeaaaaab, v226
	v_fma_f32 v225, v225, -2.0, 1.0
	v_fma_f32 v227, v227, v222, v222
	v_bfi_b32 v225, v241, v225, v222
	v_cmp_gt_f32_e32 vcc, 0x3d000000, v224
	s_nop 1
	v_cndmask_b32_e32 v225, v225, v227, vcc
	v_cmp_gt_u32_e32 vcc, 32, v240
	s_nop 1
	v_cndmask_b32_e32 v222, v222, v225, vcc
	v_and_b32_e32 v224, 0x7fffffff, v223
	v_mul_f32_e32 v225, 0x4038aa3b, v224
	v_exp_f32_e32 v225, v225
	v_mul_f32_e32 v226, v223, v223
	v_add_f32_e32 v225, 1.0, v225
	v_rcp_f32_e32 v225, v225
	v_mul_f32_e32 v227, 0xbeaaaaab, v226
	v_fma_f32 v225, v225, -2.0, 1.0
	v_fma_f32 v227, v227, v223, v223
	v_bfi_b32 v225, v241, v225, v223
	v_cmp_gt_f32_e32 vcc, 0x3d000000, v224
	s_nop 1
	v_cndmask_b32_e32 v225, v225, v227, vcc
	v_cmp_gt_u32_e32 vcc, 32, v240
	s_nop 1
	v_cndmask_b32_e32 v223, v223, v225, vcc
	v_cvt_pk_bf16_f32 v224, v220, v221
	v_cvt_pk_bf16_f32 v225, v222, v223
	buffer_store_dwordx2 v[224:225], v238, s[68:71], s74 offen
	s_add_u32 s72, s72, 0x1000
	s_add_u32 s73, s73, 0x800
	s_add_u32 s74, s74, 0x200
	s_add_u32 s75, s75, 0x40
	s_waitcnt vmcnt(33)
	v_lshlrev_b32_e32 v144, 16, v24
	v_and_b32_e32 v145, 0xffff0000, v24
	v_lshlrev_b32_e32 v146, 16, v25
	v_and_b32_e32 v147, 0xffff0000, v25
	v_lshlrev_b32_e32 v148, 16, v26
	v_and_b32_e32 v149, 0xffff0000, v26
	v_lshlrev_b32_e32 v150, 16, v27
	v_and_b32_e32 v151, 0xffff0000, v27
	v_lshlrev_b32_e32 v152, 16, v28
	v_and_b32_e32 v153, 0xffff0000, v28
	v_lshlrev_b32_e32 v154, 16, v29
	v_and_b32_e32 v155, 0xffff0000, v29
	v_lshlrev_b32_e32 v156, 16, v30
	v_and_b32_e32 v157, 0xffff0000, v30
	v_lshlrev_b32_e32 v158, 16, v31
	v_and_b32_e32 v159, 0xffff0000, v31
	v_lshlrev_b32_e32 v160, 16, v36
	v_and_b32_e32 v161, 0xffff0000, v36
	v_lshlrev_b32_e32 v162, 16, v37
	v_and_b32_e32 v163, 0xffff0000, v37
	v_lshlrev_b32_e32 v164, 16, v38
	v_and_b32_e32 v165, 0xffff0000, v38
	v_lshlrev_b32_e32 v166, 16, v39
	v_and_b32_e32 v167, 0xffff0000, v39
	v_lshlrev_b32_e32 v168, 16, v40
	v_and_b32_e32 v169, 0xffff0000, v40
	v_lshlrev_b32_e32 v170, 16, v41
	v_and_b32_e32 v171, 0xffff0000, v41
	v_lshlrev_b32_e32 v172, 16, v42
	v_and_b32_e32 v173, 0xffff0000, v42
	v_lshlrev_b32_e32 v174, 16, v43
	v_and_b32_e32 v175, 0xffff0000, v43
	v_lshlrev_b32_e32 v176, 16, v48
	v_and_b32_e32 v177, 0xffff0000, v48
	v_lshlrev_b32_e32 v178, 16, v49
	v_and_b32_e32 v179, 0xffff0000, v49
	v_lshlrev_b32_e32 v180, 16, v50
	v_and_b32_e32 v181, 0xffff0000, v50
	v_lshlrev_b32_e32 v182, 16, v51
	v_and_b32_e32 v183, 0xffff0000, v51
	v_lshlrev_b32_e32 v184, 16, v52
	v_and_b32_e32 v185, 0xffff0000, v52
; __device__ __forceinline__ float bflo(unsigned w) { return __uint_as_float(w << 16); }
; __device__ __forceinline__ float bfhi(unsigned w) { return __uint_as_float(w & 0xffff0000u); }
; __device__ __forceinline__ unsigned cvt_pk_bf16(float lo, float hi) { unsigned r; asm volatile("v_cvt_pk_bf16_f32 %0, %1, %2" : "=v"(r) : "v"(lo), "v"(hi)); return r; }
; __device__ __forceinline__ void prep_phase(const Params& p) {
;     ...
;             for (int i = 0; i < 16; ++i) {
;                 const bool hn = (tt0 + i) < SEQ - 1; const u16* zn = zc + (size_t)(i + 1) * 3328;
;                 const Z16 vn = hn ? ldz(zn + 2048 + c) : zz(); const u32x2 ln = hn ? *(const u32x2*)(zn + cl) : (u32x2){0u, 0u};
;                 float v[16]; mix16(vp, vc, vn, mpv, mnv, v);
;                 st16bf(V + (size_t)(t0 + i) * RW + c, v);
;                 const float z4[4] = {bflo(lc.x), bfhi(lc.x), bflo(lc.y), bfhi(lc.y)}, p4[4] = {bflo(lp.x), bfhi(lp.x), bflo(lp.y), bfhi(lp.y)}, n4[4] = {bflo(ln.x), bfhi(ln.x), bflo(ln.y), bfhi(ln.y)};
;                 float o4[4];
; #pragma unroll
;                 for (int j = 0; j < 4; ++j) { const float sft = z4[j] + la[j] * (p4[j] - z4[j]) + lb[j] * (n4[j] - z4[j]); o4[j] = (lane < 32) ? tanhf(sft) : sft; }
;                 u32x2 w; w.x = cvt_pk_bf16(o4[0], o4[1]); w.y = cvt_pk_bf16(o4[2], o4[3]); *(u32x2*)(AL + (size_t)(t0 + i) * 256 + alc) = w;
;                 vp = vc; vc = vn; lp = lc; lc = ln;
	v_lshlrev_b32_e32 v186, 16, v53
	v_and_b32_e32 v187, 0xffff0000, v53
	v_lshlrev_b32_e32 v188, 16, v54
	v_and_b32_e32 v189, 0xffff0000, v54
	v_lshlrev_b32_e32 v190, 16, v55
	v_and_b32_e32 v191, 0xffff0000, v55
	v_lshlrev_b32_e32 v136, 16, v32
	v_and_b32_e32 v137, 0xffff0000, v32
	v_lshlrev_b32_e32 v138, 16, v33
	v_and_b32_e32 v139, 0xffff0000, v33
	v_lshlrev_b32_e32 v140, 16, v44
	v_and_b32_e32 v141, 0xffff0000, v44
	v_lshlrev_b32_e32 v142, 16, v45
	v_and_b32_e32 v143, 0xffff0000, v45
	v_lshlrev_b32_e32 v216, 16, v56
	v_and_b32_e32 v217, 0xffff0000, v56
	v_lshlrev_b32_e32 v218, 16, v57
	v_and_b32_e32 v219, 0xffff0000, v57
	v_pk_add_f32 v[224:225], v[144:145], v[160:161] neg_lo:[0,1] neg_hi:[0,1]
	v_pk_add_f32 v[226:227], v[176:177], v[160:161] neg_lo:[0,1] neg_hi:[0,1]
	v_pk_fma_f32 v[192:193], v[96:97], v[224:225], v[160:161]
	v_pk_fma_f32 v[192:193], v[112:113], v[226:227], v[192:193]
	v_pk_add_f32 v[224:225], v[146:147], v[162:163] neg_lo:[0,1] neg_hi:[0,1]
	v_pk_add_f32 v[226:227], v[178:179], v[162:163] neg_lo:[0,1] neg_hi:[0,1]
	v_pk_fma_f32 v[194:195], v[98:99], v[224:225], v[162:163]
	v_pk_fma_f32 v[194:195], v[114:115], v[226:227], v[194:195]
	v_pk_add_f32 v[224:225], v[148:149], v[164:165] neg_lo:[0,1] neg_hi:[0,1]
	v_pk_add_f32 v[226:227], v[180:181], v[164:165] neg_lo:[0,1] neg_hi:[0,1]
	v_pk_fma_f32 v[196:197], v[100:101], v[224:225], v[164:165]
	v_pk_fma_f32 v[196:197], v[116:117], v[226:227], v[196:197]
	v_pk_add_f32 v[224:225], v[150:151], v[166:167] neg_lo:[0,1] neg_hi:[0,1]
	v_pk_add_f32 v[226:227], v[182:183], v[166:167] neg_lo:[0,1] neg_hi:[0,1]
	v_pk_fma_f32 v[198:199], v[102:103], v[224:225], v[166:167]
	v_pk_fma_f32 v[198:199], v[118:119], v[226:227], v[198:199]
	v_pk_add_f32 v[224:225], v[152:153], v[168:169] neg_lo:[0,1] neg_hi:[0,1]
	v_pk_add_f32 v[226:227], v[184:185], v[168:169] neg_lo:[0,1] neg_hi:[0,1]
	v_pk_fma_f32 v[200:201], v[104:105], v[224:225], v[168:169]
	v_pk_fma_f32 v[200:201], v[120:121], v[226:227], v[200:201]
	v_pk_add_f32 v[224:225], v[154:155], v[170:171] neg_lo:[0,1] neg_hi:[0,1]
	v_pk_add_f32 v[226:227], v[186:187], v[170:171] neg_lo:[0,1] neg_hi:[0,1]
	v_pk_fma_f32 v[202:203], v[106:107], v[224:225], v[170:171]
	v_pk_fma_f32 v[202:203], v[122:123], v[226:227], v[202:203]
	v_pk_add_f32 v[224:225], v[156:157], v[172:173] neg_lo:[0,1] neg_hi:[0,1]
	v_pk_add_f32 v[226:227], v[188:189], v[172:173] neg_lo:[0,1] neg_hi:[0,1]
	v_pk_fma_f32 v[204:205], v[108:109], v[224:225], v[172:173]
	v_pk_fma_f32 v[204:205], v[124:125], v[226:227], v[204:205]
	v_pk_add_f32 v[224:225], v[158:159], v[174:175] neg_lo:[0,1] neg_hi:[0,1]
	v_pk_add_f32 v[226:227], v[190:191], v[174:175] neg_lo:[0,1] neg_hi:[0,1]
	v_pk_fma_f32 v[206:207], v[110:111], v[224:225], v[174:175]
	v_pk_fma_f32 v[206:207], v[126:127], v[226:227], v[206:207]
	v_cvt_pk_bf16_f32 v208, v192, v193
	v_cvt_pk_bf16_f32 v209, v194, v195
	v_cvt_pk_bf16_f32 v210, v196, v197
	v_cvt_pk_bf16_f32 v211, v198, v199
	v_cvt_pk_bf16_f32 v212, v200, v201
	v_cvt_pk_bf16_f32 v213, v202, v203
	v_cvt_pk_bf16_f32 v214, v204, v205
	v_cvt_pk_bf16_f32 v215, v206, v207
	buffer_store_dwordx4 v[208:211], v237, s[68:71], s73 offen offset:0
	buffer_store_dwordx4 v[212:215], v237, s[68:71], s73 offen offset:16
	v_sub_f32_e32 v224, v136, v140
	v_sub_f32_e32 v225, v216, v140
	v_fma_f32 v220, v128, v224, v140
	v_fma_f32 v220, v132, v225, v220
	v_sub_f32_e32 v224, v137, v141
	v_sub_f32_e32 v225, v217, v141
	v_fma_f32 v221, v129, v224, v141
	v_fma_f32 v221, v133, v225, v221
	v_sub_f32_e32 v224, v138, v142
	v_sub_f32_e32 v225, v218, v142
	v_fma_f32 v222, v130, v224, v142
	v_fma_f32 v222, v134, v225, v222
	v_sub_f32_e32 v224, v139, v143
	v_sub_f32_e32 v225, v219, v143
	v_fma_f32 v223, v131, v224, v143
	v_fma_f32 v223, v135, v225, v223
	v_and_b32_e32 v224, 0x7fffffff, v220
	v_mul_f32_e32 v225, 0x4038aa3b, v224
	v_exp_f32_e32 v225, v225
	v_mul_f32_e32 v226, v220, v220
	v_add_f32_e32 v225, 1.0, v225
	v_rcp_f32_e32 v225, v225
	v_mul_f32_e32 v227, 0xbeaaaaab, v226
	v_fma_f32 v225, v225, -2.0, 1.0
	v_fma_f32 v227, v227, v220, v220
	v_bfi_b32 v225, v241, v225, v220
	v_cmp_gt_f32_e32 vcc, 0x3d000000, v224
	s_nop 1
	v_cndmask_b32_e32 v225, v225, v227, vcc
	v_cmp_gt_u32_e32 vcc, 32, v240
	s_nop 1
	v_cndmask_b32_e32 v220, v220, v225, vcc
	v_and_b32_e32 v224, 0x7fffffff, v221
	v_mul_f32_e32 v225, 0x4038aa3b, v224
	v_exp_f32_e32 v225, v225
	v_mul_f32_e32 v226, v221, v221
	v_add_f32_e32 v225, 1.0, v225
	v_rcp_f32_e32 v225, v225
	v_mul_f32_e32 v227, 0xbeaaaaab, v226
	v_fma_f32 v225, v225, -2.0, 1.0
	v_fma_f32 v227, v227, v221, v221
	v_bfi_b32 v225, v241, v225, v221
	v_cmp_gt_f32_e32 vcc, 0x3d000000, v224
	s_nop 1
	v_cndmask_b32_e32 v225, v225, v227, vcc
	v_cmp_gt_u32_e32 vcc, 32, v240
	s_nop 1
	v_cndmask_b32_e32 v221, v221, v225, vcc
	v_and_b32_e32 v224, 0x7fffffff, v222
	v_mul_f32_e32 v225, 0x4038aa3b, v224
	v_exp_f32_e32 v225, v225
	v_mul_f32_e32 v226, v222, v222
	v_add_f32_e32 v225, 1.0, v225
	v_rcp_f32_e32 v225, v225
	v_mul_f32_e32 v227, 0xbeaaaaab, v226
	v_fma_f32 v225, v225, -2.0, 1.0
	v_fma_f32 v227, v227, v222, v222
	v_bfi_b32 v225, v241, v225, v222
	v_cmp_gt_f32_e32 vcc, 0x3d000000, v224
	s_nop 1
	v_cndmask_b32_e32 v225, v225, v227, vcc
	v_cmp_gt_u32_e32 vcc, 32, v240
	s_nop 1
	v_cndmask_b32_e32 v222, v222, v225, vcc
	v_and_b32_e32 v224, 0x7fffffff, v223
	v_mul_f32_e32 v225, 0x4038aa3b, v224
	v_exp_f32_e32 v225, v225
	v_mul_f32_e32 v226, v223, v223
	v_add_f32_e32 v225, 1.0, v225
	v_rcp_f32_e32 v225, v225
	v_mul_f32_e32 v227, 0xbeaaaaab, v226
	v_fma_f32 v225, v225, -2.0, 1.0
	v_fma_f32 v227, v227, v223, v223
	v_bfi_b32 v225, v241, v225, v223
	v_cmp_gt_f32_e32 vcc, 0x3d000000, v224
	s_nop 1
	v_cndmask_b32_e32 v225, v225, v227, vcc
	v_cmp_gt_u32_e32 vcc, 32, v240
	s_nop 1
	v_cndmask_b32_e32 v223, v223, v225, vcc
	v_cvt_pk_bf16_f32 v224, v220, v221
	v_cvt_pk_bf16_f32 v225, v222, v223
	buffer_store_dwordx2 v[224:225], v238, s[68:71], s74 offen
	s_add_u32 s72, s72, 0x1000
	s_add_u32 s73, s73, 0x800
	s_add_u32 s74, s74, 0x200
	s_add_u32 s75, s75, 0x40
	s_waitcnt vmcnt(30)
; __device__ __forceinline__ float bflo(unsigned w) { return __uint_as_float(w << 16); }
; __device__ __forceinline__ float bfhi(unsigned w) { return __uint_as_float(w & 0xffff0000u); }
; __device__ __forceinline__ unsigned cvt_pk_bf16(float lo, float hi) { unsigned r; asm volatile("v_cvt_pk_bf16_f32 %0, %1, %2" : "=v"(r) : "v"(lo), "v"(hi)); return r; }
; __device__ __forceinline__ void prep_phase(const Params& p) {
;     ...
;             for (int i = 0; i < 16; ++i) {
;                 const bool hn = (tt0 + i) < SEQ - 1; const u16* zn = zc + (size_t)(i + 1) * 3328;
;                 const Z16 vn = hn ? ldz(zn + 2048 + c) : zz(); const u32x2 ln = hn ? *(const u32x2*)(zn + cl) : (u32x2){0u, 0u};
;                 float v[16]; mix16(vp, vc, vn, mpv, mnv, v);
;                 st16bf(V + (size_t)(t0 + i) * RW + c, v);
;                 const float z4[4] = {bflo(lc.x), bfhi(lc.x), bflo(lc.y), bfhi(lc.y)}, p4[4] = {bflo(lp.x), bfhi(lp.x), bflo(lp.y), bfhi(lp.y)}, n4[4] = {bflo(ln.x), bfhi(ln.x), bflo(ln.y), bfhi(ln.y)};
;                 float o4[4];
; #pragma unroll
;                 for (int j = 0; j < 4; ++j) { const float sft = z4[j] + la[j] * (p4[j] - z4[j]) + lb[j] * (n4[j] - z4[j]); o4[j] = (lane < 32) ? tanhf(sft) : sft; }
;                 u32x2 w; w.x = cvt_pk_bf16(o4[0], o4[1]); w.y = cvt_pk_bf16(o4[2], o4[3]); *(u32x2*)(AL + (size_t)(t0 + i) * 256 + alc) = w;
	v_lshlrev_b32_e32 v144, 16, v36
	v_and_b32_e32 v145, 0xffff0000, v36
	v_lshlrev_b32_e32 v146, 16, v37
	v_and_b32_e32 v147, 0xffff0000, v37
	v_lshlrev_b32_e32 v148, 16, v38
	v_and_b32_e32 v149, 0xffff0000, v38
	v_lshlrev_b32_e32 v150, 16, v39
	v_and_b32_e32 v151, 0xffff0000, v39
	v_lshlrev_b32_e32 v152, 16, v40
	v_and_b32_e32 v153, 0xffff0000, v40
	v_lshlrev_b32_e32 v154, 16, v41
	v_and_b32_e32 v155, 0xffff0000, v41
	v_lshlrev_b32_e32 v156, 16, v42
	v_and_b32_e32 v157, 0xffff0000, v42
	v_lshlrev_b32_e32 v158, 16, v43
	v_and_b32_e32 v159, 0xffff0000, v43
	v_lshlrev_b32_e32 v160, 16, v48
	v_and_b32_e32 v161, 0xffff0000, v48
	v_lshlrev_b32_e32 v162, 16, v49
	v_and_b32_e32 v163, 0xffff0000, v49
	v_lshlrev_b32_e32 v164, 16, v50
	v_and_b32_e32 v165, 0xffff0000, v50
	v_lshlrev_b32_e32 v166, 16, v51
	v_and_b32_e32 v167, 0xffff0000, v51
	v_lshlrev_b32_e32 v168, 16, v52
	v_and_b32_e32 v169, 0xffff0000, v52
	v_lshlrev_b32_e32 v170, 16, v53
	v_and_b32_e32 v171, 0xffff0000, v53
	v_lshlrev_b32_e32 v172, 16, v54
	v_and_b32_e32 v173, 0xffff0000, v54
	v_lshlrev_b32_e32 v174, 16, v55
	v_and_b32_e32 v175, 0xffff0000, v55
	v_lshlrev_b32_e32 v176, 16, v60
	v_and_b32_e32 v177, 0xffff0000, v60
	v_lshlrev_b32_e32 v178, 16, v61
	v_and_b32_e32 v179, 0xffff0000, v61
	v_lshlrev_b32_e32 v180, 16, v62
	v_and_b32_e32 v181, 0xffff0000, v62
	v_lshlrev_b32_e32 v182, 16, v63
	v_and_b32_e32 v183, 0xffff0000, v63
	v_lshlrev_b32_e32 v184, 16, v64
	v_and_b32_e32 v185, 0xffff0000, v64
	v_lshlrev_b32_e32 v186, 16, v65
	v_and_b32_e32 v187, 0xffff0000, v65
	v_lshlrev_b32_e32 v188, 16, v66
	v_and_b32_e32 v189, 0xffff0000, v66
	v_lshlrev_b32_e32 v190, 16, v67
	v_and_b32_e32 v191, 0xffff0000, v67
	v_lshlrev_b32_e32 v136, 16, v44
	v_and_b32_e32 v137, 0xffff0000, v44
	v_lshlrev_b32_e32 v138, 16, v45
	v_and_b32_e32 v139, 0xffff0000, v45
	v_lshlrev_b32_e32 v140, 16, v56
	v_and_b32_e32 v141, 0xffff0000, v56
	v_lshlrev_b32_e32 v142, 16, v57
	v_and_b32_e32 v143, 0xffff0000, v57
	v_lshlrev_b32_e32 v216, 16, v68
	v_and_b32_e32 v217, 0xffff0000, v68
	v_lshlrev_b32_e32 v218, 16, v69
	v_and_b32_e32 v219, 0xffff0000, v69
	v_pk_add_f32 v[224:225], v[144:145], v[160:161] neg_lo:[0,1] neg_hi:[0,1]
	v_pk_add_f32 v[226:227], v[176:177], v[160:161] neg_lo:[0,1] neg_hi:[0,1]
	v_pk_fma_f32 v[192:193], v[96:97], v[224:225], v[160:161]
	v_pk_fma_f32 v[192:193], v[112:113], v[226:227], v[192:193]
	v_pk_add_f32 v[224:225], v[146:147], v[162:163] neg_lo:[0,1] neg_hi:[0,1]
	v_pk_add_f32 v[226:227], v[178:179], v[162:163] neg_lo:[0,1] neg_hi:[0,1]
	v_pk_fma_f32 v[194:195], v[98:99], v[224:225], v[162:163]
	v_pk_fma_f32 v[194:195], v[114:115], v[226:227], v[194:195]
	v_pk_add_f32 v[224:225], v[148:149], v[164:165] neg_lo:[0,1] neg_hi:[0,1]
	v_pk_add_f32 v[226:227], v[180:181], v[164:165] neg_lo:[0,1] neg_hi:[0,1]
	v_pk_fma_f32 v[196:197], v[100:101], v[224:225], v[164:165]
	v_pk_fma_f32 v[196:197], v[116:117], v[226:227], v[196:197]
	v_pk_add_f32 v[224:225], v[150:151], v[166:167] neg_lo:[0,1] neg_hi:[0,1]
	v_pk_add_f32 v[226:227], v[182:183], v[166:167] neg_lo:[0,1] neg_hi:[0,1]
	v_pk_fma_f32 v[198:199], v[102:103], v[224:225], v[166:167]
	v_pk_fma_f32 v[198:199], v[118:119], v[226:227], v[198:199]
	v_pk_add_f32 v[224:225], v[152:153], v[168:169] neg_lo:[0,1] neg_hi:[0,1]
	v_pk_add_f32 v[226:227], v[184:185], v[168:169] neg_lo:[0,1] neg_hi:[0,1]
	v_pk_fma_f32 v[200:201], v[104:105], v[224:225], v[168:169]
	v_pk_fma_f32 v[200:201], v[120:121], v[226:227], v[200:201]
	v_pk_add_f32 v[224:225], v[154:155], v[170:171] neg_lo:[0,1] neg_hi:[0,1]
	v_pk_add_f32 v[226:227], v[186:187], v[170:171] neg_lo:[0,1] neg_hi:[0,1]
	v_pk_fma_f32 v[202:203], v[106:107], v[224:225], v[170:171]
	v_pk_fma_f32 v[202:203], v[122:123], v[226:227], v[202:203]
	v_pk_add_f32 v[224:225], v[156:157], v[172:173] neg_lo:[0,1] neg_hi:[0,1]
	v_pk_add_f32 v[226:227], v[188:189], v[172:173] neg_lo:[0,1] neg_hi:[0,1]
	v_pk_fma_f32 v[204:205], v[108:109], v[224:225], v[172:173]
	v_pk_fma_f32 v[204:205], v[124:125], v[226:227], v[204:205]
	v_pk_add_f32 v[224:225], v[158:159], v[174:175] neg_lo:[0,1] neg_hi:[0,1]
	v_pk_add_f32 v[226:227], v[190:191], v[174:175] neg_lo:[0,1] neg_hi:[0,1]
	v_pk_fma_f32 v[206:207], v[110:111], v[224:225], v[174:175]
	v_pk_fma_f32 v[206:207], v[126:127], v[226:227], v[206:207]
	v_cvt_pk_bf16_f32 v208, v192, v193
	v_cvt_pk_bf16_f32 v209, v194, v195
	v_cvt_pk_bf16_f32 v210, v196, v197
	v_cvt_pk_bf16_f32 v211, v198, v199
	v_cvt_pk_bf16_f32 v212, v200, v201
	v_cvt_pk_bf16_f32 v213, v202, v203
	v_cvt_pk_bf16_f32 v214, v204, v205
	v_cvt_pk_bf16_f32 v215, v206, v207
	buffer_store_dwordx4 v[208:211], v237, s[68:71], s73 offen offset:0
	buffer_store_dwordx4 v[212:215], v237, s[68:71], s73 offen offset:16
	v_sub_f32_e32 v224, v136, v140
	v_sub_f32_e32 v225, v216, v140
	v_fma_f32 v220, v128, v224, v140
	v_fma_f32 v220, v132, v225, v220
	v_sub_f32_e32 v224, v137, v141
	v_sub_f32_e32 v225, v217, v141
	v_fma_f32 v221, v129, v224, v141
	v_fma_f32 v221, v133, v225, v221
	v_sub_f32_e32 v224, v138, v142
	v_sub_f32_e32 v225, v218, v142
	v_fma_f32 v222, v130, v224, v142
	v_fma_f32 v222, v134, v225, v222
	v_sub_f32_e32 v224, v139, v143
	v_sub_f32_e32 v225, v219, v143
	v_fma_f32 v223, v131, v224, v143
	v_fma_f32 v223, v135, v225, v223
	v_and_b32_e32 v224, 0x7fffffff, v220
	v_mul_f32_e32 v225, 0x4038aa3b, v224
	v_exp_f32_e32 v225, v225
	v_mul_f32_e32 v226, v220, v220
	v_add_f32_e32 v225, 1.0, v225
	v_rcp_f32_e32 v225, v225
	v_mul_f32_e32 v227, 0xbeaaaaab, v226
	v_fma_f32 v225, v225, -2.0, 1.0
	v_fma_f32 v227, v227, v220, v220
	v_bfi_b32 v225, v241, v225, v220
	v_cmp_gt_f32_e32 vcc, 0x3d000000, v224
	s_nop 1
	v_cndmask_b32_e32 v225, v225, v227, vcc
; __device__ __forceinline__ float bflo(unsigned w) { return __uint_as_float(w << 16); }
; __device__ __forceinline__ float bfhi(unsigned w) { return __uint_as_float(w & 0xffff0000u); }
; __device__ __forceinline__ unsigned cvt_pk_bf16(float lo, float hi) { unsigned r; asm volatile("v_cvt_pk_bf16_f32 %0, %1, %2" : "=v"(r) : "v"(lo), "v"(hi)); return r; }
; __device__ __forceinline__ void prep_phase(const Params& p) {
;     ...
;             for (int i = 0; i < 16; ++i) {
;                 const bool hn = (tt0 + i) < SEQ - 1; const u16* zn = zc + (size_t)(i + 1) * 3328;
;                 const Z16 vn = hn ? ldz(zn + 2048 + c) : zz(); const u32x2 ln = hn ? *(const u32x2*)(zn + cl) : (u32x2){0u, 0u};
;                 float v[16]; mix16(vp, vc, vn, mpv, mnv, v);
;                 st16bf(V + (size_t)(t0 + i) * RW + c, v);
;                 const float z4[4] = {bflo(lc.x), bfhi(lc.x), bflo(lc.y), bfhi(lc.y)}, p4[4] = {bflo(lp.x), bfhi(lp.x), bflo(lp.y), bfhi(lp.y)}, n4[4] = {bflo(ln.x), bfhi(ln.x), bflo(ln.y), bfhi(ln.y)};
;                 float o4[4];
; #pragma unroll
;                 for (int j = 0; j < 4; ++j) { const float sft = z4[j] + la[j] * (p4[j] - z4[j]) + lb[j] * (n4[j] - z4[j]); o4[j] = (lane < 32) ? tanhf(sft) : sft; }
;                 u32x2 w; w.x = cvt_pk_bf16(o4[0], o4[1]); w.y = cvt_pk_bf16(o4[2], o4[3]); *(u32x2*)(AL + (size_t)(t0 + i) * 256 + alc) = w;
;                 vp = vc; vc = vn; lp = lc; lc = ln;
	v_cmp_gt_u32_e32 vcc, 32, v240
	s_nop 1
	v_cndmask_b32_e32 v220, v220, v225, vcc
	v_and_b32_e32 v224, 0x7fffffff, v221
	v_mul_f32_e32 v225, 0x4038aa3b, v224
	v_exp_f32_e32 v225, v225
	v_mul_f32_e32 v226, v221, v221
	v_add_f32_e32 v225, 1.0, v225
	v_rcp_f32_e32 v225, v225
	v_mul_f32_e32 v227, 0xbeaaaaab, v226
	v_fma_f32 v225, v225, -2.0, 1.0
	v_fma_f32 v227, v227, v221, v221
	v_bfi_b32 v225, v241, v225, v221
	v_cmp_gt_f32_e32 vcc, 0x3d000000, v224
	s_nop 1
	v_cndmask_b32_e32 v225, v225, v227, vcc
	v_cmp_gt_u32_e32 vcc, 32, v240
	s_nop 1
	v_cndmask_b32_e32 v221, v221, v225, vcc
	v_and_b32_e32 v224, 0x7fffffff, v222
	v_mul_f32_e32 v225, 0x4038aa3b, v224
	v_exp_f32_e32 v225, v225
	v_mul_f32_e32 v226, v222, v222
	v_add_f32_e32 v225, 1.0, v225
	v_rcp_f32_e32 v225, v225
	v_mul_f32_e32 v227, 0xbeaaaaab, v226
	v_fma_f32 v225, v225, -2.0, 1.0
	v_fma_f32 v227, v227, v222, v222
	v_bfi_b32 v225, v241, v225, v222
	v_cmp_gt_f32_e32 vcc, 0x3d000000, v224
	s_nop 1
	v_cndmask_b32_e32 v225, v225, v227, vcc
	v_cmp_gt_u32_e32 vcc, 32, v240
	s_nop 1
	v_cndmask_b32_e32 v222, v222, v225, vcc
	v_and_b32_e32 v224, 0x7fffffff, v223
	v_mul_f32_e32 v225, 0x4038aa3b, v224
	v_exp_f32_e32 v225, v225
	v_mul_f32_e32 v226, v223, v223
	v_add_f32_e32 v225, 1.0, v225
	v_rcp_f32_e32 v225, v225
	v_mul_f32_e32 v227, 0xbeaaaaab, v226
	v_fma_f32 v225, v225, -2.0, 1.0
	v_fma_f32 v227, v227, v223, v223
	v_bfi_b32 v225, v241, v225, v223
	v_cmp_gt_f32_e32 vcc, 0x3d000000, v224
	s_nop 1
	v_cndmask_b32_e32 v225, v225, v227, vcc
	v_cmp_gt_u32_e32 vcc, 32, v240
	s_nop 1
	v_cndmask_b32_e32 v223, v223, v225, vcc
	v_cvt_pk_bf16_f32 v224, v220, v221
	v_cvt_pk_bf16_f32 v225, v222, v223
	buffer_store_dwordx2 v[224:225], v238, s[68:71], s74 offen
	s_add_u32 s72, s72, 0x1000
	s_add_u32 s73, s73, 0x800
	s_add_u32 s74, s74, 0x200
	s_add_u32 s75, s75, 0x40
	s_waitcnt vmcnt(27)
	v_lshlrev_b32_e32 v144, 16, v48
	v_and_b32_e32 v145, 0xffff0000, v48
	v_lshlrev_b32_e32 v146, 16, v49
	v_and_b32_e32 v147, 0xffff0000, v49
	v_lshlrev_b32_e32 v148, 16, v50
	v_and_b32_e32 v149, 0xffff0000, v50
	v_lshlrev_b32_e32 v150, 16, v51
	v_and_b32_e32 v151, 0xffff0000, v51
	v_lshlrev_b32_e32 v152, 16, v52
	v_and_b32_e32 v153, 0xffff0000, v52
	v_lshlrev_b32_e32 v154, 16, v53
	v_and_b32_e32 v155, 0xffff0000, v53
	v_lshlrev_b32_e32 v156, 16, v54
	v_and_b32_e32 v157, 0xffff0000, v54
	v_lshlrev_b32_e32 v158, 16, v55
	v_and_b32_e32 v159, 0xffff0000, v55
	v_lshlrev_b32_e32 v160, 16, v60
	v_and_b32_e32 v161, 0xffff0000, v60
	v_lshlrev_b32_e32 v162, 16, v61
	v_and_b32_e32 v163, 0xffff0000, v61
	v_lshlrev_b32_e32 v164, 16, v62
	v_and_b32_e32 v165, 0xffff0000, v62
	v_lshlrev_b32_e32 v166, 16, v63
	v_and_b32_e32 v167, 0xffff0000, v63
	v_lshlrev_b32_e32 v168, 16, v64
	v_and_b32_e32 v169, 0xffff0000, v64
	v_lshlrev_b32_e32 v170, 16, v65
	v_and_b32_e32 v171, 0xffff0000, v65
	v_lshlrev_b32_e32 v172, 16, v66
	v_and_b32_e32 v173, 0xffff0000, v66
	v_lshlrev_b32_e32 v174, 16, v67
	v_and_b32_e32 v175, 0xffff0000, v67
	v_lshlrev_b32_e32 v176, 16, v72
	v_and_b32_e32 v177, 0xffff0000, v72
	v_lshlrev_b32_e32 v178, 16, v73
	v_and_b32_e32 v179, 0xffff0000, v73
	v_lshlrev_b32_e32 v180, 16, v74
	v_and_b32_e32 v181, 0xffff0000, v74
	v_lshlrev_b32_e32 v182, 16, v75
	v_and_b32_e32 v183, 0xffff0000, v75
	v_lshlrev_b32_e32 v184, 16, v76
	v_and_b32_e32 v185, 0xffff0000, v76
	v_lshlrev_b32_e32 v186, 16, v77
	v_and_b32_e32 v187, 0xffff0000, v77
	v_lshlrev_b32_e32 v188, 16, v78
	v_and_b32_e32 v189, 0xffff0000, v78
	v_lshlrev_b32_e32 v190, 16, v79
	v_and_b32_e32 v191, 0xffff0000, v79
	v_lshlrev_b32_e32 v136, 16, v56
	v_and_b32_e32 v137, 0xffff0000, v56
	v_lshlrev_b32_e32 v138, 16, v57
	v_and_b32_e32 v139, 0xffff0000, v57
	v_lshlrev_b32_e32 v140, 16, v68
	v_and_b32_e32 v141, 0xffff0000, v68
	v_lshlrev_b32_e32 v142, 16, v69
	v_and_b32_e32 v143, 0xffff0000, v69
	v_lshlrev_b32_e32 v216, 16, v80
	v_and_b32_e32 v217, 0xffff0000, v80
	v_lshlrev_b32_e32 v218, 16, v81
	v_and_b32_e32 v219, 0xffff0000, v81
	v_pk_add_f32 v[224:225], v[144:145], v[160:161] neg_lo:[0,1] neg_hi:[0,1]
	v_pk_add_f32 v[226:227], v[176:177], v[160:161] neg_lo:[0,1] neg_hi:[0,1]
	v_pk_fma_f32 v[192:193], v[96:97], v[224:225], v[160:161]
	v_pk_fma_f32 v[192:193], v[112:113], v[226:227], v[192:193]
	v_pk_add_f32 v[224:225], v[146:147], v[162:163] neg_lo:[0,1] neg_hi:[0,1]
	v_pk_add_f32 v[226:227], v[178:179], v[162:163] neg_lo:[0,1] neg_hi:[0,1]
	v_pk_fma_f32 v[194:195], v[98:99], v[224:225], v[162:163]
	v_pk_fma_f32 v[194:195], v[114:115], v[226:227], v[194:195]
	v_pk_add_f32 v[224:225], v[148:149], v[164:165] neg_lo:[0,1] neg_hi:[0,1]
	v_pk_add_f32 v[226:227], v[180:181], v[164:165] neg_lo:[0,1] neg_hi:[0,1]
	v_pk_fma_f32 v[196:197], v[100:101], v[224:225], v[164:165]
	v_pk_fma_f32 v[196:197], v[116:117], v[226:227], v[196:197]
	v_pk_add_f32 v[224:225], v[150:151], v[166:167] neg_lo:[0,1] neg_hi:[0,1]
	v_pk_add_f32 v[226:227], v[182:183], v[166:167] neg_lo:[0,1] neg_hi:[0,1]
	v_pk_fma_f32 v[198:199], v[102:103], v[224:225], v[166:167]
	v_pk_fma_f32 v[198:199], v[118:119], v[226:227], v[198:199]
	v_pk_add_f32 v[224:225], v[152:153], v[168:169] neg_lo:[0,1] neg_hi:[0,1]
	v_pk_add_f32 v[226:227], v[184:185], v[168:169] neg_lo:[0,1] neg_hi:[0,1]
	v_pk_fma_f32 v[200:201], v[104:105], v[224:225], v[168:169]
	v_pk_fma_f32 v[200:201], v[120:121], v[226:227], v[200:201]
	v_pk_add_f32 v[224:225], v[154:155], v[170:171] neg_lo:[0,1] neg_hi:[0,1]
	v_pk_add_f32 v[226:227], v[186:187], v[170:171] neg_lo:[0,1] neg_hi:[0,1]
	v_pk_fma_f32 v[202:203], v[106:107], v[224:225], v[170:171]
	v_pk_fma_f32 v[202:203], v[122:123], v[226:227], v[202:203]
	v_pk_add_f32 v[224:225], v[156:157], v[172:173] neg_lo:[0,1] neg_hi:[0,1]
; __device__ __forceinline__ float bflo(unsigned w) { return __uint_as_float(w << 16); }
; __device__ __forceinline__ float bfhi(unsigned w) { return __uint_as_float(w & 0xffff0000u); }
; __device__ __forceinline__ unsigned cvt_pk_bf16(float lo, float hi) { unsigned r; asm volatile("v_cvt_pk_bf16_f32 %0, %1, %2" : "=v"(r) : "v"(lo), "v"(hi)); return r; }
; __device__ __forceinline__ void prep_phase(const Params& p) {
;     ...
;             for (int i = 0; i < 16; ++i) {
;                 const bool hn = (tt0 + i) < SEQ - 1; const u16* zn = zc + (size_t)(i + 1) * 3328;
;                 const Z16 vn = hn ? ldz(zn + 2048 + c) : zz(); const u32x2 ln = hn ? *(const u32x2*)(zn + cl) : (u32x2){0u, 0u};
;                 float v[16]; mix16(vp, vc, vn, mpv, mnv, v);
;                 st16bf(V + (size_t)(t0 + i) * RW + c, v);
;                 const float z4[4] = {bflo(lc.x), bfhi(lc.x), bflo(lc.y), bfhi(lc.y)}, p4[4] = {bflo(lp.x), bfhi(lp.x), bflo(lp.y), bfhi(lp.y)}, n4[4] = {bflo(ln.x), bfhi(ln.x), bflo(ln.y), bfhi(ln.y)};
;                 float o4[4];
; #pragma unroll
;                 for (int j = 0; j < 4; ++j) { const float sft = z4[j] + la[j] * (p4[j] - z4[j]) + lb[j] * (n4[j] - z4[j]); o4[j] = (lane < 32) ? tanhf(sft) : sft; }
;                 u32x2 w; w.x = cvt_pk_bf16(o4[0], o4[1]); w.y = cvt_pk_bf16(o4[2], o4[3]); *(u32x2*)(AL + (size_t)(t0 + i) * 256 + alc) = w;
;                 vp = vc; vc = vn; lp = lc; lc = ln;
	v_pk_add_f32 v[226:227], v[188:189], v[172:173] neg_lo:[0,1] neg_hi:[0,1]
	v_pk_fma_f32 v[204:205], v[108:109], v[224:225], v[172:173]
	v_pk_fma_f32 v[204:205], v[124:125], v[226:227], v[204:205]
	v_pk_add_f32 v[224:225], v[158:159], v[174:175] neg_lo:[0,1] neg_hi:[0,1]
	v_pk_add_f32 v[226:227], v[190:191], v[174:175] neg_lo:[0,1] neg_hi:[0,1]
	v_pk_fma_f32 v[206:207], v[110:111], v[224:225], v[174:175]
	v_pk_fma_f32 v[206:207], v[126:127], v[226:227], v[206:207]
	v_cvt_pk_bf16_f32 v208, v192, v193
	v_cvt_pk_bf16_f32 v209, v194, v195
	v_cvt_pk_bf16_f32 v210, v196, v197
	v_cvt_pk_bf16_f32 v211, v198, v199
	v_cvt_pk_bf16_f32 v212, v200, v201
	v_cvt_pk_bf16_f32 v213, v202, v203
	v_cvt_pk_bf16_f32 v214, v204, v205
	v_cvt_pk_bf16_f32 v215, v206, v207
	buffer_store_dwordx4 v[208:211], v237, s[68:71], s73 offen offset:0
	buffer_store_dwordx4 v[212:215], v237, s[68:71], s73 offen offset:16
	v_sub_f32_e32 v224, v136, v140
	v_sub_f32_e32 v225, v216, v140
	v_fma_f32 v220, v128, v224, v140
	v_fma_f32 v220, v132, v225, v220
	v_sub_f32_e32 v224, v137, v141
	v_sub_f32_e32 v225, v217, v141
	v_fma_f32 v221, v129, v224, v141
	v_fma_f32 v221, v133, v225, v221
	v_sub_f32_e32 v224, v138, v142
	v_sub_f32_e32 v225, v218, v142
	v_fma_f32 v222, v130, v224, v142
	v_fma_f32 v222, v134, v225, v222
	v_sub_f32_e32 v224, v139, v143
	v_sub_f32_e32 v225, v219, v143
	v_fma_f32 v223, v131, v224, v143
	v_fma_f32 v223, v135, v225, v223
	v_and_b32_e32 v224, 0x7fffffff, v220
	v_mul_f32_e32 v225, 0x4038aa3b, v224
	v_exp_f32_e32 v225, v225
	v_mul_f32_e32 v226, v220, v220
	v_add_f32_e32 v225, 1.0, v225
	v_rcp_f32_e32 v225, v225
	v_mul_f32_e32 v227, 0xbeaaaaab, v226
	v_fma_f32 v225, v225, -2.0, 1.0
	v_fma_f32 v227, v227, v220, v220
	v_bfi_b32 v225, v241, v225, v220
	v_cmp_gt_f32_e32 vcc, 0x3d000000, v224
	s_nop 1
	v_cndmask_b32_e32 v225, v225, v227, vcc
	v_cmp_gt_u32_e32 vcc, 32, v240
	s_nop 1
	v_cndmask_b32_e32 v220, v220, v225, vcc
	v_and_b32_e32 v224, 0x7fffffff, v221
	v_mul_f32_e32 v225, 0x4038aa3b, v224
	v_exp_f32_e32 v225, v225
	v_mul_f32_e32 v226, v221, v221
	v_add_f32_e32 v225, 1.0, v225
	v_rcp_f32_e32 v225, v225
	v_mul_f32_e32 v227, 0xbeaaaaab, v226
	v_fma_f32 v225, v225, -2.0, 1.0
	v_fma_f32 v227, v227, v221, v221
	v_bfi_b32 v225, v241, v225, v221
	v_cmp_gt_f32_e32 vcc, 0x3d000000, v224
	s_nop 1
	v_cndmask_b32_e32 v225, v225, v227, vcc
	v_cmp_gt_u32_e32 vcc, 32, v240
	s_nop 1
	v_cndmask_b32_e32 v221, v221, v225, vcc
	v_and_b32_e32 v224, 0x7fffffff, v222
	v_mul_f32_e32 v225, 0x4038aa3b, v224
	v_exp_f32_e32 v225, v225
	v_mul_f32_e32 v226, v222, v222
	v_add_f32_e32 v225, 1.0, v225
	v_rcp_f32_e32 v225, v225
	v_mul_f32_e32 v227, 0xbeaaaaab, v226
	v_fma_f32 v225, v225, -2.0, 1.0
	v_fma_f32 v227, v227, v222, v222
	v_bfi_b32 v225, v241, v225, v222
	v_cmp_gt_f32_e32 vcc, 0x3d000000, v224
	s_nop 1
	v_cndmask_b32_e32 v225, v225, v227, vcc
	v_cmp_gt_u32_e32 vcc, 32, v240
	s_nop 1
	v_cndmask_b32_e32 v222, v222, v225, vcc
	v_and_b32_e32 v224, 0x7fffffff, v223
	v_mul_f32_e32 v225, 0x4038aa3b, v224
	v_exp_f32_e32 v225, v225
	v_mul_f32_e32 v226, v223, v223
	v_add_f32_e32 v225, 1.0, v225
	v_rcp_f32_e32 v225, v225
	v_mul_f32_e32 v227, 0xbeaaaaab, v226
	v_fma_f32 v225, v225, -2.0, 1.0
	v_fma_f32 v227, v227, v223, v223
	v_bfi_b32 v225, v241, v225, v223
	v_cmp_gt_f32_e32 vcc, 0x3d000000, v224
	s_nop 1
	v_cndmask_b32_e32 v225, v225, v227, vcc
	v_cmp_gt_u32_e32 vcc, 32, v240
	s_nop 1
	v_cndmask_b32_e32 v223, v223, v225, vcc
	v_cvt_pk_bf16_f32 v224, v220, v221
	v_cvt_pk_bf16_f32 v225, v222, v223
	buffer_store_dwordx2 v[224:225], v238, s[68:71], s74 offen
	s_add_u32 s72, s72, 0x1000
	s_add_u32 s73, s73, 0x800
	s_add_u32 s74, s74, 0x200
	s_add_u32 s75, s75, 0x40
	s_waitcnt vmcnt(24)
	v_lshlrev_b32_e32 v144, 16, v60
	v_and_b32_e32 v145, 0xffff0000, v60
	v_lshlrev_b32_e32 v146, 16, v61
	v_and_b32_e32 v147, 0xffff0000, v61
	v_lshlrev_b32_e32 v148, 16, v62
	v_and_b32_e32 v149, 0xffff0000, v62
	v_lshlrev_b32_e32 v150, 16, v63
	v_and_b32_e32 v151, 0xffff0000, v63
	v_lshlrev_b32_e32 v152, 16, v64
	v_and_b32_e32 v153, 0xffff0000, v64
	v_lshlrev_b32_e32 v154, 16, v65
	v_and_b32_e32 v155, 0xffff0000, v65
	v_lshlrev_b32_e32 v156, 16, v66
	v_and_b32_e32 v157, 0xffff0000, v66
	v_lshlrev_b32_e32 v158, 16, v67
	v_and_b32_e32 v159, 0xffff0000, v67
	v_lshlrev_b32_e32 v160, 16, v72
	v_and_b32_e32 v161, 0xffff0000, v72
	v_lshlrev_b32_e32 v162, 16, v73
	v_and_b32_e32 v163, 0xffff0000, v73
	v_lshlrev_b32_e32 v164, 16, v74
	v_and_b32_e32 v165, 0xffff0000, v74
	v_lshlrev_b32_e32 v166, 16, v75
	v_and_b32_e32 v167, 0xffff0000, v75
	v_lshlrev_b32_e32 v168, 16, v76
	v_and_b32_e32 v169, 0xffff0000, v76
	v_lshlrev_b32_e32 v170, 16, v77
	v_and_b32_e32 v171, 0xffff0000, v77
	v_lshlrev_b32_e32 v172, 16, v78
	v_and_b32_e32 v173, 0xffff0000, v78
	v_lshlrev_b32_e32 v174, 16, v79
	v_and_b32_e32 v175, 0xffff0000, v79
	v_lshlrev_b32_e32 v176, 16, v84
	v_and_b32_e32 v177, 0xffff0000, v84
	v_lshlrev_b32_e32 v178, 16, v85
	v_and_b32_e32 v179, 0xffff0000, v85
	v_lshlrev_b32_e32 v180, 16, v86
	v_and_b32_e32 v181, 0xffff0000, v86
	v_lshlrev_b32_e32 v182, 16, v87
	v_and_b32_e32 v183, 0xffff0000, v87
	v_lshlrev_b32_e32 v184, 16, v88
	v_and_b32_e32 v185, 0xffff0000, v88
	v_lshlrev_b32_e32 v186, 16, v89
	v_and_b32_e32 v187, 0xffff0000, v89
	v_lshlrev_b32_e32 v188, 16, v90
	v_and_b32_e32 v189, 0xffff0000, v90
	v_lshlrev_b32_e32 v190, 16, v91
	v_and_b32_e32 v191, 0xffff0000, v91
	v_lshlrev_b32_e32 v136, 16, v68
	v_and_b32_e32 v137, 0xffff0000, v68
	v_lshlrev_b32_e32 v138, 16, v69
	v_and_b32_e32 v139, 0xffff0000, v69
	v_lshlrev_b32_e32 v140, 16, v80
	v_and_b32_e32 v141, 0xffff0000, v80
	v_lshlrev_b32_e32 v142, 16, v81
	v_and_b32_e32 v143, 0xffff0000, v81
; __device__ __forceinline__ float bflo(unsigned w) { return __uint_as_float(w << 16); }
; __device__ __forceinline__ float bfhi(unsigned w) { return __uint_as_float(w & 0xffff0000u); }
; __device__ __forceinline__ unsigned cvt_pk_bf16(float lo, float hi) { unsigned r; asm volatile("v_cvt_pk_bf16_f32 %0, %1, %2" : "=v"(r) : "v"(lo), "v"(hi)); return r; }
; __device__ __forceinline__ void prep_phase(const Params& p) {
;     ...
;             for (int i = 0; i < 16; ++i) {
;                 const bool hn = (tt0 + i) < SEQ - 1; const u16* zn = zc + (size_t)(i + 1) * 3328;
;                 const Z16 vn = hn ? ldz(zn + 2048 + c) : zz(); const u32x2 ln = hn ? *(const u32x2*)(zn + cl) : (u32x2){0u, 0u};
;                 float v[16]; mix16(vp, vc, vn, mpv, mnv, v);
;                 st16bf(V + (size_t)(t0 + i) * RW + c, v);
;                 const float z4[4] = {bflo(lc.x), bfhi(lc.x), bflo(lc.y), bfhi(lc.y)}, p4[4] = {bflo(lp.x), bfhi(lp.x), bflo(lp.y), bfhi(lp.y)}, n4[4] = {bflo(ln.x), bfhi(ln.x), bflo(ln.y), bfhi(ln.y)};
;                 float o4[4];
; #pragma unroll
;                 for (int j = 0; j < 4; ++j) { const float sft = z4[j] + la[j] * (p4[j] - z4[j]) + lb[j] * (n4[j] - z4[j]); o4[j] = (lane < 32) ? tanhf(sft) : sft; }
;                 u32x2 w; w.x = cvt_pk_bf16(o4[0], o4[1]); w.y = cvt_pk_bf16(o4[2], o4[3]); *(u32x2*)(AL + (size_t)(t0 + i) * 256 + alc) = w;
;                 vp = vc; vc = vn; lp = lc; lc = ln;
	v_lshlrev_b32_e32 v216, 16, v92
	v_and_b32_e32 v217, 0xffff0000, v92
	v_lshlrev_b32_e32 v218, 16, v93
	v_and_b32_e32 v219, 0xffff0000, v93
	v_pk_add_f32 v[224:225], v[144:145], v[160:161] neg_lo:[0,1] neg_hi:[0,1]
	v_pk_add_f32 v[226:227], v[176:177], v[160:161] neg_lo:[0,1] neg_hi:[0,1]
	v_pk_fma_f32 v[192:193], v[96:97], v[224:225], v[160:161]
	v_pk_fma_f32 v[192:193], v[112:113], v[226:227], v[192:193]
	v_pk_add_f32 v[224:225], v[146:147], v[162:163] neg_lo:[0,1] neg_hi:[0,1]
	v_pk_add_f32 v[226:227], v[178:179], v[162:163] neg_lo:[0,1] neg_hi:[0,1]
	v_pk_fma_f32 v[194:195], v[98:99], v[224:225], v[162:163]
	v_pk_fma_f32 v[194:195], v[114:115], v[226:227], v[194:195]
	v_pk_add_f32 v[224:225], v[148:149], v[164:165] neg_lo:[0,1] neg_hi:[0,1]
	v_pk_add_f32 v[226:227], v[180:181], v[164:165] neg_lo:[0,1] neg_hi:[0,1]
	v_pk_fma_f32 v[196:197], v[100:101], v[224:225], v[164:165]
	v_pk_fma_f32 v[196:197], v[116:117], v[226:227], v[196:197]
	v_pk_add_f32 v[224:225], v[150:151], v[166:167] neg_lo:[0,1] neg_hi:[0,1]
	v_pk_add_f32 v[226:227], v[182:183], v[166:167] neg_lo:[0,1] neg_hi:[0,1]
	v_pk_fma_f32 v[198:199], v[102:103], v[224:225], v[166:167]
	v_pk_fma_f32 v[198:199], v[118:119], v[226:227], v[198:199]
	v_pk_add_f32 v[224:225], v[152:153], v[168:169] neg_lo:[0,1] neg_hi:[0,1]
	v_pk_add_f32 v[226:227], v[184:185], v[168:169] neg_lo:[0,1] neg_hi:[0,1]
	v_pk_fma_f32 v[200:201], v[104:105], v[224:225], v[168:169]
	v_pk_fma_f32 v[200:201], v[120:121], v[226:227], v[200:201]
	v_pk_add_f32 v[224:225], v[154:155], v[170:171] neg_lo:[0,1] neg_hi:[0,1]
	v_pk_add_f32 v[226:227], v[186:187], v[170:171] neg_lo:[0,1] neg_hi:[0,1]
	v_pk_fma_f32 v[202:203], v[106:107], v[224:225], v[170:171]
	v_pk_fma_f32 v[202:203], v[122:123], v[226:227], v[202:203]
	v_pk_add_f32 v[224:225], v[156:157], v[172:173] neg_lo:[0,1] neg_hi:[0,1]
	v_pk_add_f32 v[226:227], v[188:189], v[172:173] neg_lo:[0,1] neg_hi:[0,1]
	v_pk_fma_f32 v[204:205], v[108:109], v[224:225], v[172:173]
	v_pk_fma_f32 v[204:205], v[124:125], v[226:227], v[204:205]
	v_pk_add_f32 v[224:225], v[158:159], v[174:175] neg_lo:[0,1] neg_hi:[0,1]
	v_pk_add_f32 v[226:227], v[190:191], v[174:175] neg_lo:[0,1] neg_hi:[0,1]
	v_pk_fma_f32 v[206:207], v[110:111], v[224:225], v[174:175]
	v_pk_fma_f32 v[206:207], v[126:127], v[226:227], v[206:207]
	v_cvt_pk_bf16_f32 v208, v192, v193
	v_cvt_pk_bf16_f32 v209, v194, v195
	v_cvt_pk_bf16_f32 v210, v196, v197
	v_cvt_pk_bf16_f32 v211, v198, v199
	v_cvt_pk_bf16_f32 v212, v200, v201
	v_cvt_pk_bf16_f32 v213, v202, v203
	v_cvt_pk_bf16_f32 v214, v204, v205
	v_cvt_pk_bf16_f32 v215, v206, v207
	buffer_store_dwordx4 v[208:211], v237, s[68:71], s73 offen offset:0
	buffer_store_dwordx4 v[212:215], v237, s[68:71], s73 offen offset:16
	v_sub_f32_e32 v224, v136, v140
	v_sub_f32_e32 v225, v216, v140
	v_fma_f32 v220, v128, v224, v140
	v_fma_f32 v220, v132, v225, v220
	v_sub_f32_e32 v224, v137, v141
	v_sub_f32_e32 v225, v217, v141
	v_fma_f32 v221, v129, v224, v141
	v_fma_f32 v221, v133, v225, v221
	v_sub_f32_e32 v224, v138, v142
	v_sub_f32_e32 v225, v218, v142
	v_fma_f32 v222, v130, v224, v142
	v_fma_f32 v222, v134, v225, v222
	v_sub_f32_e32 v224, v139, v143
	v_sub_f32_e32 v225, v219, v143
	v_fma_f32 v223, v131, v224, v143
	v_fma_f32 v223, v135, v225, v223
	v_and_b32_e32 v224, 0x7fffffff, v220
	v_mul_f32_e32 v225, 0x4038aa3b, v224
	v_exp_f32_e32 v225, v225
	v_mul_f32_e32 v226, v220, v220
	v_add_f32_e32 v225, 1.0, v225
	v_rcp_f32_e32 v225, v225
	v_mul_f32_e32 v227, 0xbeaaaaab, v226
	v_fma_f32 v225, v225, -2.0, 1.0
	v_fma_f32 v227, v227, v220, v220
	v_bfi_b32 v225, v241, v225, v220
	v_cmp_gt_f32_e32 vcc, 0x3d000000, v224
	s_nop 1
	v_cndmask_b32_e32 v225, v225, v227, vcc
	v_cmp_gt_u32_e32 vcc, 32, v240
	s_nop 1
	v_cndmask_b32_e32 v220, v220, v225, vcc
	v_and_b32_e32 v224, 0x7fffffff, v221
	v_mul_f32_e32 v225, 0x4038aa3b, v224
	v_exp_f32_e32 v225, v225
	v_mul_f32_e32 v226, v221, v221
	v_add_f32_e32 v225, 1.0, v225
	v_rcp_f32_e32 v225, v225
	v_mul_f32_e32 v227, 0xbeaaaaab, v226
	v_fma_f32 v225, v225, -2.0, 1.0
	v_fma_f32 v227, v227, v221, v221
	v_bfi_b32 v225, v241, v225, v221
	v_cmp_gt_f32_e32 vcc, 0x3d000000, v224
	s_nop 1
	v_cndmask_b32_e32 v225, v225, v227, vcc
	v_cmp_gt_u32_e32 vcc, 32, v240
	s_nop 1
	v_cndmask_b32_e32 v221, v221, v225, vcc
	v_and_b32_e32 v224, 0x7fffffff, v222
	v_mul_f32_e32 v225, 0x4038aa3b, v224
	v_exp_f32_e32 v225, v225
	v_mul_f32_e32 v226, v222, v222
	v_add_f32_e32 v225, 1.0, v225
	v_rcp_f32_e32 v225, v225
	v_mul_f32_e32 v227, 0xbeaaaaab, v226
	v_fma_f32 v225, v225, -2.0, 1.0
	v_fma_f32 v227, v227, v222, v222
	v_bfi_b32 v225, v241, v225, v222
	v_cmp_gt_f32_e32 vcc, 0x3d000000, v224
	s_nop 1
	v_cndmask_b32_e32 v225, v225, v227, vcc
	v_cmp_gt_u32_e32 vcc, 32, v240
	s_nop 1
	v_cndmask_b32_e32 v222, v222, v225, vcc
	v_and_b32_e32 v224, 0x7fffffff, v223
	v_mul_f32_e32 v225, 0x4038aa3b, v224
	v_exp_f32_e32 v225, v225
	v_mul_f32_e32 v226, v223, v223
	v_add_f32_e32 v225, 1.0, v225
	v_rcp_f32_e32 v225, v225
	v_mul_f32_e32 v227, 0xbeaaaaab, v226
	v_fma_f32 v225, v225, -2.0, 1.0
	v_fma_f32 v227, v227, v223, v223
	v_bfi_b32 v225, v241, v225, v223
	v_cmp_gt_f32_e32 vcc, 0x3d000000, v224
	s_nop 1
	v_cndmask_b32_e32 v225, v225, v227, vcc
	v_cmp_gt_u32_e32 vcc, 32, v240
	s_nop 1
	v_cndmask_b32_e32 v223, v223, v225, vcc
	v_cvt_pk_bf16_f32 v224, v220, v221
	v_cvt_pk_bf16_f32 v225, v222, v223
	buffer_store_dwordx2 v[224:225], v238, s[68:71], s74 offen
	s_add_u32 s72, s72, 0x1000
	s_add_u32 s73, s73, 0x800
	s_add_u32 s74, s74, 0x200
	s_add_u32 s75, s75, 0x40
	s_waitcnt vmcnt(21)
; __device__ __forceinline__ float bflo(unsigned w) { return __uint_as_float(w << 16); }
; __device__ __forceinline__ float bfhi(unsigned w) { return __uint_as_float(w & 0xffff0000u); }
; __device__ __forceinline__ unsigned cvt_pk_bf16(float lo, float hi) { unsigned r; asm volatile("v_cvt_pk_bf16_f32 %0, %1, %2" : "=v"(r) : "v"(lo), "v"(hi)); return r; }
; __device__ __forceinline__ void prep_phase(const Params& p) {
;     ...
;             for (int i = 0; i < 16; ++i) {
;                 const bool hn = (tt0 + i) < SEQ - 1; const u16* zn = zc + (size_t)(i + 1) * 3328;
;                 const Z16 vn = hn ? ldz(zn + 2048 + c) : zz(); const u32x2 ln = hn ? *(const u32x2*)(zn + cl) : (u32x2){0u, 0u};
;                 float v[16]; mix16(vp, vc, vn, mpv, mnv, v);
;                 st16bf(V + (size_t)(t0 + i) * RW + c, v);
;                 const float z4[4] = {bflo(lc.x), bfhi(lc.x), bflo(lc.y), bfhi(lc.y)}, p4[4] = {bflo(lp.x), bfhi(lp.x), bflo(lp.y), bfhi(lp.y)}, n4[4] = {bflo(ln.x), bfhi(ln.x), bflo(ln.y), bfhi(ln.y)};
;                 float o4[4];
; #pragma unroll
;                 for (int j = 0; j < 4; ++j) { const float sft = z4[j] + la[j] * (p4[j] - z4[j]) + lb[j] * (n4[j] - z4[j]); o4[j] = (lane < 32) ? tanhf(sft) : sft; }
;                 u32x2 w; w.x = cvt_pk_bf16(o4[0], o4[1]); w.y = cvt_pk_bf16(o4[2], o4[3]); *(u32x2*)(AL + (size_t)(t0 + i) * 256 + alc) = w;
;                 vp = vc; vc = vn; lp = lc; lc = ln;
	v_lshlrev_b32_e32 v144, 16, v72
	v_and_b32_e32 v145, 0xffff0000, v72
	v_lshlrev_b32_e32 v146, 16, v73
	v_and_b32_e32 v147, 0xffff0000, v73
	v_lshlrev_b32_e32 v148, 16, v74
	v_and_b32_e32 v149, 0xffff0000, v74
	v_lshlrev_b32_e32 v150, 16, v75
	v_and_b32_e32 v151, 0xffff0000, v75
	v_lshlrev_b32_e32 v152, 16, v76
	v_and_b32_e32 v153, 0xffff0000, v76
	v_lshlrev_b32_e32 v154, 16, v77
	v_and_b32_e32 v155, 0xffff0000, v77
	v_lshlrev_b32_e32 v156, 16, v78
	v_and_b32_e32 v157, 0xffff0000, v78
	v_lshlrev_b32_e32 v158, 16, v79
	v_and_b32_e32 v159, 0xffff0000, v79
	v_lshlrev_b32_e32 v160, 16, v84
	v_and_b32_e32 v161, 0xffff0000, v84
	v_lshlrev_b32_e32 v162, 16, v85
	v_and_b32_e32 v163, 0xffff0000, v85
	v_lshlrev_b32_e32 v164, 16, v86
	v_and_b32_e32 v165, 0xffff0000, v86
	v_lshlrev_b32_e32 v166, 16, v87
	v_and_b32_e32 v167, 0xffff0000, v87
	v_lshlrev_b32_e32 v168, 16, v88
	v_and_b32_e32 v169, 0xffff0000, v88
	v_lshlrev_b32_e32 v170, 16, v89
	v_and_b32_e32 v171, 0xffff0000, v89
	v_lshlrev_b32_e32 v172, 16, v90
	v_and_b32_e32 v173, 0xffff0000, v90
	v_lshlrev_b32_e32 v174, 16, v91
	v_and_b32_e32 v175, 0xffff0000, v91
	v_lshlrev_b32_e32 v176, 16, v0
	v_and_b32_e32 v177, 0xffff0000, v0
	v_lshlrev_b32_e32 v178, 16, v1
	v_and_b32_e32 v179, 0xffff0000, v1
	v_lshlrev_b32_e32 v180, 16, v2
	v_and_b32_e32 v181, 0xffff0000, v2
	v_lshlrev_b32_e32 v182, 16, v3
	v_and_b32_e32 v183, 0xffff0000, v3
	v_lshlrev_b32_e32 v184, 16, v4
	v_and_b32_e32 v185, 0xffff0000, v4
	v_lshlrev_b32_e32 v186, 16, v5
	v_and_b32_e32 v187, 0xffff0000, v5
	v_lshlrev_b32_e32 v188, 16, v6
	v_and_b32_e32 v189, 0xffff0000, v6
	v_lshlrev_b32_e32 v190, 16, v7
	v_and_b32_e32 v191, 0xffff0000, v7
	v_lshlrev_b32_e32 v136, 16, v80
	v_and_b32_e32 v137, 0xffff0000, v80
	v_lshlrev_b32_e32 v138, 16, v81
	v_and_b32_e32 v139, 0xffff0000, v81
	v_lshlrev_b32_e32 v140, 16, v92
	v_and_b32_e32 v141, 0xffff0000, v92
	v_lshlrev_b32_e32 v142, 16, v93
	v_and_b32_e32 v143, 0xffff0000, v93
	v_lshlrev_b32_e32 v216, 16, v8
	v_and_b32_e32 v217, 0xffff0000, v8
	v_lshlrev_b32_e32 v218, 16, v9
	v_and_b32_e32 v219, 0xffff0000, v9
	v_pk_add_f32 v[224:225], v[144:145], v[160:161] neg_lo:[0,1] neg_hi:[0,1]
	v_pk_add_f32 v[226:227], v[176:177], v[160:161] neg_lo:[0,1] neg_hi:[0,1]
	v_pk_fma_f32 v[192:193], v[96:97], v[224:225], v[160:161]
	v_pk_fma_f32 v[192:193], v[112:113], v[226:227], v[192:193]
	v_pk_add_f32 v[224:225], v[146:147], v[162:163] neg_lo:[0,1] neg_hi:[0,1]
	v_pk_add_f32 v[226:227], v[178:179], v[162:163] neg_lo:[0,1] neg_hi:[0,1]
	v_pk_fma_f32 v[194:195], v[98:99], v[224:225], v[162:163]
	v_pk_fma_f32 v[194:195], v[114:115], v[226:227], v[194:195]
	v_pk_add_f32 v[224:225], v[148:149], v[164:165] neg_lo:[0,1] neg_hi:[0,1]
	v_pk_add_f32 v[226:227], v[180:181], v[164:165] neg_lo:[0,1] neg_hi:[0,1]
	v_pk_fma_f32 v[196:197], v[100:101], v[224:225], v[164:165]
	v_pk_fma_f32 v[196:197], v[116:117], v[226:227], v[196:197]
	v_pk_add_f32 v[224:225], v[150:151], v[166:167] neg_lo:[0,1] neg_hi:[0,1]
	v_pk_add_f32 v[226:227], v[182:183], v[166:167] neg_lo:[0,1] neg_hi:[0,1]
	v_pk_fma_f32 v[198:199], v[102:103], v[224:225], v[166:167]
	v_pk_fma_f32 v[198:199], v[118:119], v[226:227], v[198:199]
	v_pk_add_f32 v[224:225], v[152:153], v[168:169] neg_lo:[0,1] neg_hi:[0,1]
	v_pk_add_f32 v[226:227], v[184:185], v[168:169] neg_lo:[0,1] neg_hi:[0,1]
	v_pk_fma_f32 v[200:201], v[104:105], v[224:225], v[168:169]
	v_pk_fma_f32 v[200:201], v[120:121], v[226:227], v[200:201]
	v_pk_add_f32 v[224:225], v[154:155], v[170:171] neg_lo:[0,1] neg_hi:[0,1]
	v_pk_add_f32 v[226:227], v[186:187], v[170:171] neg_lo:[0,1] neg_hi:[0,1]
	v_pk_fma_f32 v[202:203], v[106:107], v[224:225], v[170:171]
	v_pk_fma_f32 v[202:203], v[122:123], v[226:227], v[202:203]
	v_pk_add_f32 v[224:225], v[156:157], v[172:173] neg_lo:[0,1] neg_hi:[0,1]
	v_pk_add_f32 v[226:227], v[188:189], v[172:173] neg_lo:[0,1] neg_hi:[0,1]
	v_pk_fma_f32 v[204:205], v[108:109], v[224:225], v[172:173]
	v_pk_fma_f32 v[204:205], v[124:125], v[226:227], v[204:205]
	v_pk_add_f32 v[224:225], v[158:159], v[174:175] neg_lo:[0,1] neg_hi:[0,1]
	v_pk_add_f32 v[226:227], v[190:191], v[174:175] neg_lo:[0,1] neg_hi:[0,1]
	v_pk_fma_f32 v[206:207], v[110:111], v[224:225], v[174:175]
	v_pk_fma_f32 v[206:207], v[126:127], v[226:227], v[206:207]
	v_cvt_pk_bf16_f32 v208, v192, v193
	v_cvt_pk_bf16_f32 v209, v194, v195
	v_cvt_pk_bf16_f32 v210, v196, v197
	v_cvt_pk_bf16_f32 v211, v198, v199
	v_cvt_pk_bf16_f32 v212, v200, v201
	v_cvt_pk_bf16_f32 v213, v202, v203
	v_cvt_pk_bf16_f32 v214, v204, v205
	v_cvt_pk_bf16_f32 v215, v206, v207
	buffer_store_dwordx4 v[208:211], v237, s[68:71], s73 offen offset:0
	buffer_store_dwordx4 v[212:215], v237, s[68:71], s73 offen offset:16
	v_sub_f32_e32 v224, v136, v140
	v_sub_f32_e32 v225, v216, v140
	v_fma_f32 v220, v128, v224, v140
	v_fma_f32 v220, v132, v225, v220
	v_sub_f32_e32 v224, v137, v141
	v_sub_f32_e32 v225, v217, v141
	v_fma_f32 v221, v129, v224, v141
	v_fma_f32 v221, v133, v225, v221
	v_sub_f32_e32 v224, v138, v142
	v_sub_f32_e32 v225, v218, v142
	v_fma_f32 v222, v130, v224, v142
	v_fma_f32 v222, v134, v225, v222
	v_sub_f32_e32 v224, v139, v143
	v_sub_f32_e32 v225, v219, v143
	v_fma_f32 v223, v131, v224, v143
	v_fma_f32 v223, v135, v225, v223
	v_and_b32_e32 v224, 0x7fffffff, v220
	v_mul_f32_e32 v225, 0x4038aa3b, v224
	v_exp_f32_e32 v225, v225
	v_mul_f32_e32 v226, v220, v220
	v_add_f32_e32 v225, 1.0, v225
	v_rcp_f32_e32 v225, v225
	v_mul_f32_e32 v227, 0xbeaaaaab, v226
	v_fma_f32 v225, v225, -2.0, 1.0
	v_fma_f32 v227, v227, v220, v220
	v_bfi_b32 v225, v241, v225, v220
	v_cmp_gt_f32_e32 vcc, 0x3d000000, v224
	s_nop 1
	v_cndmask_b32_e32 v225, v225, v227, vcc
; __device__ __forceinline__ float bflo(unsigned w) { return __uint_as_float(w << 16); }
; __device__ __forceinline__ float bfhi(unsigned w) { return __uint_as_float(w & 0xffff0000u); }
; __device__ __forceinline__ unsigned cvt_pk_bf16(float lo, float hi) { unsigned r; asm volatile("v_cvt_pk_bf16_f32 %0, %1, %2" : "=v"(r) : "v"(lo), "v"(hi)); return r; }
; __device__ __forceinline__ void prep_phase(const Params& p) {
;     ...
;             for (int i = 0; i < 16; ++i) {
;                 const bool hn = (tt0 + i) < SEQ - 1; const u16* zn = zc + (size_t)(i + 1) * 3328;
;                 const Z16 vn = hn ? ldz(zn + 2048 + c) : zz(); const u32x2 ln = hn ? *(const u32x2*)(zn + cl) : (u32x2){0u, 0u};
;                 float v[16]; mix16(vp, vc, vn, mpv, mnv, v);
;                 st16bf(V + (size_t)(t0 + i) * RW + c, v);
;                 const float z4[4] = {bflo(lc.x), bfhi(lc.x), bflo(lc.y), bfhi(lc.y)}, p4[4] = {bflo(lp.x), bfhi(lp.x), bflo(lp.y), bfhi(lp.y)}, n4[4] = {bflo(ln.x), bfhi(ln.x), bflo(ln.y), bfhi(ln.y)};
;                 float o4[4];
; #pragma unroll
;                 for (int j = 0; j < 4; ++j) { const float sft = z4[j] + la[j] * (p4[j] - z4[j]) + lb[j] * (n4[j] - z4[j]); o4[j] = (lane < 32) ? tanhf(sft) : sft; }
;                 u32x2 w; w.x = cvt_pk_bf16(o4[0], o4[1]); w.y = cvt_pk_bf16(o4[2], o4[3]); *(u32x2*)(AL + (size_t)(t0 + i) * 256 + alc) = w;
;                 vp = vc; vc = vn; lp = lc; lc = ln;
	v_cmp_gt_u32_e32 vcc, 32, v240
	s_nop 1
	v_cndmask_b32_e32 v220, v220, v225, vcc
	v_and_b32_e32 v224, 0x7fffffff, v221
	v_mul_f32_e32 v225, 0x4038aa3b, v224
	v_exp_f32_e32 v225, v225
	v_mul_f32_e32 v226, v221, v221
	v_add_f32_e32 v225, 1.0, v225
	v_rcp_f32_e32 v225, v225
	v_mul_f32_e32 v227, 0xbeaaaaab, v226
	v_fma_f32 v225, v225, -2.0, 1.0
	v_fma_f32 v227, v227, v221, v221
	v_bfi_b32 v225, v241, v225, v221
	v_cmp_gt_f32_e32 vcc, 0x3d000000, v224
	s_nop 1
	v_cndmask_b32_e32 v225, v225, v227, vcc
	v_cmp_gt_u32_e32 vcc, 32, v240
	s_nop 1
	v_cndmask_b32_e32 v221, v221, v225, vcc
	v_and_b32_e32 v224, 0x7fffffff, v222
	v_mul_f32_e32 v225, 0x4038aa3b, v224
	v_exp_f32_e32 v225, v225
	v_mul_f32_e32 v226, v222, v222
	v_add_f32_e32 v225, 1.0, v225
	v_rcp_f32_e32 v225, v225
	v_mul_f32_e32 v227, 0xbeaaaaab, v226
	v_fma_f32 v225, v225, -2.0, 1.0
	v_fma_f32 v227, v227, v222, v222
	v_bfi_b32 v225, v241, v225, v222
	v_cmp_gt_f32_e32 vcc, 0x3d000000, v224
	s_nop 1
	v_cndmask_b32_e32 v225, v225, v227, vcc
	v_cmp_gt_u32_e32 vcc, 32, v240
	s_nop 1
	v_cndmask_b32_e32 v222, v222, v225, vcc
	v_and_b32_e32 v224, 0x7fffffff, v223
	v_mul_f32_e32 v225, 0x4038aa3b, v224
	v_exp_f32_e32 v225, v225
	v_mul_f32_e32 v226, v223, v223
	v_add_f32_e32 v225, 1.0, v225
	v_rcp_f32_e32 v225, v225
	v_mul_f32_e32 v227, 0xbeaaaaab, v226
	v_fma_f32 v225, v225, -2.0, 1.0
	v_fma_f32 v227, v227, v223, v223
	v_bfi_b32 v225, v241, v225, v223
	v_cmp_gt_f32_e32 vcc, 0x3d000000, v224
	s_nop 1
	v_cndmask_b32_e32 v225, v225, v227, vcc
	v_cmp_gt_u32_e32 vcc, 32, v240
	s_nop 1
	v_cndmask_b32_e32 v223, v223, v225, vcc
	v_cvt_pk_bf16_f32 v224, v220, v221
	v_cvt_pk_bf16_f32 v225, v222, v223
	buffer_store_dwordx2 v[224:225], v238, s[68:71], s74 offen
	s_add_u32 s72, s72, 0x1000
	s_add_u32 s73, s73, 0x800
	s_add_u32 s74, s74, 0x200
	s_add_u32 s75, s75, 0x40
	s_waitcnt vmcnt(18)
	v_lshlrev_b32_e32 v144, 16, v84
	v_and_b32_e32 v145, 0xffff0000, v84
	v_lshlrev_b32_e32 v146, 16, v85
	v_and_b32_e32 v147, 0xffff0000, v85
	v_lshlrev_b32_e32 v148, 16, v86
	v_and_b32_e32 v149, 0xffff0000, v86
	v_lshlrev_b32_e32 v150, 16, v87
	v_and_b32_e32 v151, 0xffff0000, v87
	v_lshlrev_b32_e32 v152, 16, v88
	v_and_b32_e32 v153, 0xffff0000, v88
	v_lshlrev_b32_e32 v154, 16, v89
	v_and_b32_e32 v155, 0xffff0000, v89
	v_lshlrev_b32_e32 v156, 16, v90
	v_and_b32_e32 v157, 0xffff0000, v90
	v_lshlrev_b32_e32 v158, 16, v91
	v_and_b32_e32 v159, 0xffff0000, v91
	v_lshlrev_b32_e32 v160, 16, v0
	v_and_b32_e32 v161, 0xffff0000, v0
	v_lshlrev_b32_e32 v162, 16, v1
	v_and_b32_e32 v163, 0xffff0000, v1
	v_lshlrev_b32_e32 v164, 16, v2
	v_and_b32_e32 v165, 0xffff0000, v2
	v_lshlrev_b32_e32 v166, 16, v3
	v_and_b32_e32 v167, 0xffff0000, v3
	v_lshlrev_b32_e32 v168, 16, v4
	v_and_b32_e32 v169, 0xffff0000, v4
	v_lshlrev_b32_e32 v170, 16, v5
	v_and_b32_e32 v171, 0xffff0000, v5
	v_lshlrev_b32_e32 v172, 16, v6
	v_and_b32_e32 v173, 0xffff0000, v6
	v_lshlrev_b32_e32 v174, 16, v7
	v_and_b32_e32 v175, 0xffff0000, v7
	v_lshlrev_b32_e32 v176, 16, v12
	v_and_b32_e32 v177, 0xffff0000, v12
	v_lshlrev_b32_e32 v178, 16, v13
	v_and_b32_e32 v179, 0xffff0000, v13
	v_lshlrev_b32_e32 v180, 16, v14
	v_and_b32_e32 v181, 0xffff0000, v14
	v_lshlrev_b32_e32 v182, 16, v15
	v_and_b32_e32 v183, 0xffff0000, v15
	v_lshlrev_b32_e32 v184, 16, v16
	v_and_b32_e32 v185, 0xffff0000, v16
	v_lshlrev_b32_e32 v186, 16, v17
	v_and_b32_e32 v187, 0xffff0000, v17
	v_lshlrev_b32_e32 v188, 16, v18
	v_and_b32_e32 v189, 0xffff0000, v18
	v_lshlrev_b32_e32 v190, 16, v19
	v_and_b32_e32 v191, 0xffff0000, v19
	v_lshlrev_b32_e32 v136, 16, v92
	v_and_b32_e32 v137, 0xffff0000, v92
	v_lshlrev_b32_e32 v138, 16, v93
	v_and_b32_e32 v139, 0xffff0000, v93
	v_lshlrev_b32_e32 v140, 16, v8
	v_and_b32_e32 v141, 0xffff0000, v8
	v_lshlrev_b32_e32 v142, 16, v9
	v_and_b32_e32 v143, 0xffff0000, v9
	v_lshlrev_b32_e32 v216, 16, v20
	v_and_b32_e32 v217, 0xffff0000, v20
	v_lshlrev_b32_e32 v218, 16, v21
	v_and_b32_e32 v219, 0xffff0000, v21
	v_pk_add_f32 v[224:225], v[144:145], v[160:161] neg_lo:[0,1] neg_hi:[0,1]
	v_pk_add_f32 v[226:227], v[176:177], v[160:161] neg_lo:[0,1] neg_hi:[0,1]
	v_pk_fma_f32 v[192:193], v[96:97], v[224:225], v[160:161]
	v_pk_fma_f32 v[192:193], v[112:113], v[226:227], v[192:193]
	v_pk_add_f32 v[224:225], v[146:147], v[162:163] neg_lo:[0,1] neg_hi:[0,1]
	v_pk_add_f32 v[226:227], v[178:179], v[162:163] neg_lo:[0,1] neg_hi:[0,1]
	v_pk_fma_f32 v[194:195], v[98:99], v[224:225], v[162:163]
	v_pk_fma_f32 v[194:195], v[114:115], v[226:227], v[194:195]
	v_pk_add_f32 v[224:225], v[148:149], v[164:165] neg_lo:[0,1] neg_hi:[0,1]
	v_pk_add_f32 v[226:227], v[180:181], v[164:165] neg_lo:[0,1] neg_hi:[0,1]
	v_pk_fma_f32 v[196:197], v[100:101], v[224:225], v[164:165]
	v_pk_fma_f32 v[196:197], v[116:117], v[226:227], v[196:197]
	v_pk_add_f32 v[224:225], v[150:151], v[166:167] neg_lo:[0,1] neg_hi:[0,1]
	v_pk_add_f32 v[226:227], v[182:183], v[166:167] neg_lo:[0,1] neg_hi:[0,1]
	v_pk_fma_f32 v[198:199], v[102:103], v[224:225], v[166:167]
	v_pk_fma_f32 v[198:199], v[118:119], v[226:227], v[198:199]
	v_pk_add_f32 v[224:225], v[152:153], v[168:169] neg_lo:[0,1] neg_hi:[0,1]
	v_pk_add_f32 v[226:227], v[184:185], v[168:169] neg_lo:[0,1] neg_hi:[0,1]
	v_pk_fma_f32 v[200:201], v[104:105], v[224:225], v[168:169]
	v_pk_fma_f32 v[200:201], v[120:121], v[226:227], v[200:201]
	v_pk_add_f32 v[224:225], v[154:155], v[170:171] neg_lo:[0,1] neg_hi:[0,1]
	v_pk_add_f32 v[226:227], v[186:187], v[170:171] neg_lo:[0,1] neg_hi:[0,1]
; __device__ __forceinline__ float bflo(unsigned w) { return __uint_as_float(w << 16); }
; __device__ __forceinline__ float bfhi(unsigned w) { return __uint_as_float(w & 0xffff0000u); }
; __device__ __forceinline__ unsigned cvt_pk_bf16(float lo, float hi) { unsigned r; asm volatile("v_cvt_pk_bf16_f32 %0, %1, %2" : "=v"(r) : "v"(lo), "v"(hi)); return r; }
; __device__ __forceinline__ unsigned xb_add(unsigned* p, unsigned v) { return __hip_atomic_fetch_add(p, v, __ATOMIC_RELAXED, __HIP_MEMORY_SCOPE_AGENT); }
; __device__ __forceinline__ void prep_phase(const Params& p) {
;     ...
;     for (int t0 = (blockIdx.x * 8 + wid) * 16; t0 < NTOK; t0 += gridDim.x * 8 * 16) {
;     ...
;                 float v[16]; mix16(vp, vc, vn, mpv, mnv, v);
;                 st16bf(V + (size_t)(t0 + i) * RW + c, v);
;                 const float z4[4] = {bflo(lc.x), bfhi(lc.x), bflo(lc.y), bfhi(lc.y)}, p4[4] = {bflo(lp.x), bfhi(lp.x), bflo(lp.y), bfhi(lp.y)}, n4[4] = {bflo(ln.x), bfhi(ln.x), bflo(ln.y), bfhi(ln.y)};
;                 float o4[4];
; #pragma unroll
;                 for (int j = 0; j < 4; ++j) { const float sft = z4[j] + la[j] * (p4[j] - z4[j]) + lb[j] * (n4[j] - z4[j]); o4[j] = (lane < 32) ? tanhf(sft) : sft; }
;                 u32x2 w; w.x = cvt_pk_bf16(o4[0], o4[1]); w.y = cvt_pk_bf16(o4[2], o4[3]); *(u32x2*)(AL + (size_t)(t0 + i) * 256 + alc) = w;
;                 vp = vc; vc = vn; lp = lc; lc = ln;
; __device__ __forceinline__ void xcd_barrier(const XcdBarrier& b) {
;     asm volatile("s_waitcnt vmcnt(0)" ::: "memory");
;     __syncthreads();
;     if (threadIdx.x == 0) {
;         unsigned* bar = b.bar;
;         __builtin_amdgcn_s_waitcnt(0);
;         unsigned nloc = b.st[0], nx = b.st[1];
;         if (nloc == 0u) { xcd_barrier_complete(bar, b.x, nloc, nx); b.st[0] = nloc; b.st[1] = nx; }
;         const unsigned old = xb_add(&bar[XB_XSUB(b.x)], 1u);
	v_pk_fma_f32 v[202:203], v[106:107], v[224:225], v[170:171]
	v_pk_fma_f32 v[202:203], v[122:123], v[226:227], v[202:203]
	v_pk_add_f32 v[224:225], v[156:157], v[172:173] neg_lo:[0,1] neg_hi:[0,1]
	v_pk_add_f32 v[226:227], v[188:189], v[172:173] neg_lo:[0,1] neg_hi:[0,1]
	v_pk_fma_f32 v[204:205], v[108:109], v[224:225], v[172:173]
	v_pk_fma_f32 v[204:205], v[124:125], v[226:227], v[204:205]
	v_pk_add_f32 v[224:225], v[158:159], v[174:175] neg_lo:[0,1] neg_hi:[0,1]
	v_pk_add_f32 v[226:227], v[190:191], v[174:175] neg_lo:[0,1] neg_hi:[0,1]
	v_pk_fma_f32 v[206:207], v[110:111], v[224:225], v[174:175]
	v_pk_fma_f32 v[206:207], v[126:127], v[226:227], v[206:207]
	v_cvt_pk_bf16_f32 v208, v192, v193
	v_cvt_pk_bf16_f32 v209, v194, v195
	v_cvt_pk_bf16_f32 v210, v196, v197
	v_cvt_pk_bf16_f32 v211, v198, v199
	v_cvt_pk_bf16_f32 v212, v200, v201
	v_cvt_pk_bf16_f32 v213, v202, v203
	v_cvt_pk_bf16_f32 v214, v204, v205
	v_cvt_pk_bf16_f32 v215, v206, v207
	buffer_store_dwordx4 v[208:211], v237, s[68:71], s73 offen offset:0
	buffer_store_dwordx4 v[212:215], v237, s[68:71], s73 offen offset:16
	v_sub_f32_e32 v224, v136, v140
	v_sub_f32_e32 v225, v216, v140
	v_fma_f32 v220, v128, v224, v140
	v_fma_f32 v220, v132, v225, v220
	v_sub_f32_e32 v224, v137, v141
	v_sub_f32_e32 v225, v217, v141
	v_fma_f32 v221, v129, v224, v141
	v_fma_f32 v221, v133, v225, v221
	v_sub_f32_e32 v224, v138, v142
	v_sub_f32_e32 v225, v218, v142
	v_fma_f32 v222, v130, v224, v142
	v_fma_f32 v222, v134, v225, v222
	v_sub_f32_e32 v224, v139, v143
	v_sub_f32_e32 v225, v219, v143
	v_fma_f32 v223, v131, v224, v143
	v_fma_f32 v223, v135, v225, v223
	v_and_b32_e32 v224, 0x7fffffff, v220
	v_mul_f32_e32 v225, 0x4038aa3b, v224
	v_exp_f32_e32 v225, v225
	v_mul_f32_e32 v226, v220, v220
	v_add_f32_e32 v225, 1.0, v225
	v_rcp_f32_e32 v225, v225
	v_mul_f32_e32 v227, 0xbeaaaaab, v226
	v_fma_f32 v225, v225, -2.0, 1.0
	v_fma_f32 v227, v227, v220, v220
	v_bfi_b32 v225, v241, v225, v220
	v_cmp_gt_f32_e32 vcc, 0x3d000000, v224
	s_nop 1
	v_cndmask_b32_e32 v225, v225, v227, vcc
	v_cmp_gt_u32_e32 vcc, 32, v240
	s_nop 1
	v_cndmask_b32_e32 v220, v220, v225, vcc
	v_and_b32_e32 v224, 0x7fffffff, v221
	v_mul_f32_e32 v225, 0x4038aa3b, v224
	v_exp_f32_e32 v225, v225
	v_mul_f32_e32 v226, v221, v221
	v_add_f32_e32 v225, 1.0, v225
	v_rcp_f32_e32 v225, v225
	v_mul_f32_e32 v227, 0xbeaaaaab, v226
	v_fma_f32 v225, v225, -2.0, 1.0
	v_fma_f32 v227, v227, v221, v221
	v_bfi_b32 v225, v241, v225, v221
	v_cmp_gt_f32_e32 vcc, 0x3d000000, v224
	s_nop 1
	v_cndmask_b32_e32 v225, v225, v227, vcc
	v_cmp_gt_u32_e32 vcc, 32, v240
	s_nop 1
	v_cndmask_b32_e32 v221, v221, v225, vcc
	v_and_b32_e32 v224, 0x7fffffff, v222
	v_mul_f32_e32 v225, 0x4038aa3b, v224
	v_exp_f32_e32 v225, v225
	v_mul_f32_e32 v226, v222, v222
	v_add_f32_e32 v225, 1.0, v225
	v_rcp_f32_e32 v225, v225
	v_mul_f32_e32 v227, 0xbeaaaaab, v226
	v_fma_f32 v225, v225, -2.0, 1.0
	v_fma_f32 v227, v227, v222, v222
	v_bfi_b32 v225, v241, v225, v222
	v_cmp_gt_f32_e32 vcc, 0x3d000000, v224
	s_nop 1
	v_cndmask_b32_e32 v225, v225, v227, vcc
	v_cmp_gt_u32_e32 vcc, 32, v240
	s_nop 1
	v_cndmask_b32_e32 v222, v222, v225, vcc
	v_and_b32_e32 v224, 0x7fffffff, v223
	v_mul_f32_e32 v225, 0x4038aa3b, v224
	v_exp_f32_e32 v225, v225
	v_mul_f32_e32 v226, v223, v223
	v_add_f32_e32 v225, 1.0, v225
	v_rcp_f32_e32 v225, v225
	v_mul_f32_e32 v227, 0xbeaaaaab, v226
	v_fma_f32 v225, v225, -2.0, 1.0
	v_fma_f32 v227, v227, v223, v223
	v_bfi_b32 v225, v241, v225, v223
	v_cmp_gt_f32_e32 vcc, 0x3d000000, v224
	s_nop 1
	v_cndmask_b32_e32 v225, v225, v227, vcc
	v_cmp_gt_u32_e32 vcc, 32, v240
	s_nop 1
	v_cndmask_b32_e32 v223, v223, v225, vcc
	v_cvt_pk_bf16_f32 v224, v220, v221
	v_cvt_pk_bf16_f32 v225, v222, v223
	buffer_store_dwordx2 v[224:225], v238, s[68:71], s74 offen
	s_waitcnt vmcnt(0)
	s_lshl_b32 s4, s96, 7
	s_add_u32 s0, s0, s4
	s_branch .Lmy_prep_item
.Lmy_prep_end:
	s_cmp_lt_i32 s59, 4
	s_cbranch_scc1 .LBB0_336
	s_waitcnt vmcnt(0)
	s_waitcnt lgkmcnt(0)
	s_barrier
	s_and_saveexec_b64 s[0:1], s[10:11]
	s_cbranch_execz .LBB0_335
	s_add_i32 s3, 0, 0x20000
	v_mov_b32_e32 v0, s3
	s_waitcnt vmcnt(0) expcnt(0) lgkmcnt(0)
	ds_read_b32 v2, v0
	s_add_i32 s3, 0, 0x20004
	v_mov_b32_e32 v0, s3
	ds_read_b32 v0, v0
	s_waitcnt lgkmcnt(1)
	v_cmp_ne_u32_e32 vcc, 0, v2
	s_cbranch_vccnz .LBB0_299
	s_add_u32 s4, s56, 0x3fa00200
	s_addc_u32 s5, s57, 0
	s_add_u32 s6, s56, 0x3fa00400
	s_addc_u32 s7, s57, 0
	s_add_u32 s8, s56, 0x3fa00500
	s_addc_u32 s9, s57, 0
	s_add_u32 s16, s56, 0x3fa00600
	s_addc_u32 s17, s57, 0
	s_add_u32 s18, s56, 0x3fa00700
	s_addc_u32 s19, s57, 0
	s_add_u32 s20, s56, 0x3fa00800
	s_addc_u32 s21, s57, 0
	s_add_u32 s22, s56, 0x3fa00900
	s_addc_u32 s23, s57, 0
	s_add_u32 s26, s56, 0x3fa00a00
	s_addc_u32 s27, s57, 0
	s_add_u32 s28, s56, 0x3fa00b00
	s_addc_u32 s29, s57, 0
	s_add_u32 s30, s56, 0x3fa00c00
	s_addc_u32 s31, s57, 0
	s_add_u32 s38, s56, 0x3fa00d00
	s_addc_u32 s39, s57, 0
	s_add_u32 s40, s56, 0x3fa00e00
	s_addc_u32 s41, s57, 0
	s_add_u32 s44, s56, 0x3fa00f00
	s_addc_u32 s45, s57, 0
	s_add_u32 s60, s56, 0x3fa01000
	s_addc_u32 s61, s57, 0
	s_add_u32 s64, s56, 0x3fa01100
	s_addc_u32 s65, s57, 0
	s_add_u32 s66, s56, 0x3fa01200
	v_readlane_b32 s3, v255, 0
	s_addc_u32 s67, s57, 0
	s_mul_i32 s3, s97, s3
	s_add_u32 s68, s56, 0x3fa01300
	s_mul_i32 s3, s3, s96
	s_addc_u32 s69, s57, 0
	s_mov_b32 s76, 1
	v_mov_b32_e32 v16, 0
	s_branch .LBB0_287
